# outproj phases fully hand-written: pipelined main loop + de-serialised epilogue (gate loads ahead of K-tile 0, residual x tile prefetched into registers during the main loop, single LDS transpose pass
# speedup vs baseline: 1.0066x; 1.0066x over previous
.LBB0_313:
	s_or_b64 exec, exec, s[0:1]
	s_cmpk_lt_i32 s2, 0x400
	s_cselect_b64 s[16:17], -1, 0
	s_cmpk_gt_i32 s2, 0x3ff
	s_waitcnt lgkmcnt(0)
	s_barrier
	s_cbranch_scc1 .LBB0_318
	v_lshrrev_b32_e32 v141, 4, v129
	v_and_b32_e32 v0, 15, v141
	v_bfe_u32 v1, v141, 4, 2
	v_bfe_u32 v2, v141, 1, 3
	v_xor_b32_e32 v2, v1, v2
	v_lshlrev_b32_e32 v2, 4, v2
	v_lshl_or_b32 v162, v0, 7, v2
	v_xor_b32_e32 v163, 64, v162
	v_lshrrev_b32_e32 v2, 6, v141
	v_lshl_add_u32 v150, v2, 12, v162
	v_lshl_add_u32 v151, v2, 12, v163
	v_bfe_u32 v3, v141, 4, 3
	v_and_b32_e32 v4, 7, v141
	v_xor_b32_e32 v3, v3, v4
	v_lshlrev_b32_e32 v3, 4, v3
	v_lshrrev_b32_e32 v4, 3, v141
	v_lshl_or_b32 v164, v4, 12, v3
	v_add_u32_e32 v165, 131072, v164
	v_add_u32_e32 v166, 262144, v164
	v_add_u32_e32 v167, 393216, v164
	v_lshlrev_b32_e32 v148, 5, v0
	v_lshlrev_b32_e32 v5, 17, v2
	v_lshl_add_u32 v5, v1, 12, v5
	v_add_u32_e32 v168, v5, v148
	v_lshlrev_b32_e32 v5, 13, v2
	v_lshl_add_u32 v6, v1, 3, v0
	v_lshl_add_u32 v7, v1, 11, v5
	v_lshl_add_u32 v169, v6, 2, v7
	v_add_u32_e32 v8, 0x60, v6
	v_and_b32_e32 v8, 0x7f, v8
	v_lshl_add_u32 v170, v8, 2, v7
	v_add_u32_e32 v8, 0x70, v6
	v_and_b32_e32 v8, 0x7f, v8
	v_lshl_add_u32 v171, v8, 2, v7
	v_lshlrev_b32_e32 v8, 3, v0
	v_lshl_add_u32 v10, v1, 9, v5
	v_add_u32_e32 v9, 0, v8
	v_and_b32_e32 v9, 0x7f, v9
	v_lshl_add_u32 v220, v9, 2, v10
	v_add_u32_e32 v9, 8, v8
	v_and_b32_e32 v9, 0x7f, v9
	v_lshl_add_u32 v222, v9, 2, v10
	v_add_u32_e32 v222, 2048, v222
	v_add_u32_e32 v9, 16, v8
	v_and_b32_e32 v9, 0x7f, v9
	v_lshl_add_u32 v224, v9, 2, v10
	v_add_u32_e32 v224, 4096, v224
	v_add_u32_e32 v9, 24, v8
	v_and_b32_e32 v9, 0x7f, v9
	v_lshl_add_u32 v226, v9, 2, v10
	v_add_u32_e32 v226, 6144, v226
	v_readfirstlane_b32 s38, v129
	s_mov_b32 s52, s2
.Lmy_op0_tile:
	s_and_b32 s10, s52, 7
	s_lshr_b32 s11, s52, 9
	s_lshl_b32 s11, s11, 3
	s_add_i32 s10, s10, s11
	s_bfe_u32 s11, s52, 0x30003
	s_lshl_b32 s12, s10, 3
	s_or_b32 s12, s12, s11
	s_bfe_u32 s13, s52, 0x30006
	s_lshl_b32 s10, s12, 19
	s_add_u32 s98, s50, s10
	s_addc_u32 s99, s51, 0
	s_add_u32 s98, s98, 0x5a00000
	s_addc_u32 s99, s99, 0
	s_lshl_b32 s11, s13, 19
	s_add_u32 s100, s50, s11
	s_addc_u32 s101, s51, 0
	s_add_u32 s100, s100, 0x2800000
	s_addc_u32 s101, s101, 0
	s_lshr_b32 s11, s12, 5
	s_mul_i32 s11, s11, 0x3000
	s_lshl_b32 s20, s13, 9
	s_add_i32 s11, s11, s20
	s_add_i32 s11, s11, 0x10c2000
	s_add_u32 s4, s50, s11
	s_addc_u32 s5, s51, 0
	s_add_i32 s10, s10, s20
	s_add_u32 s6, s68, s10
	s_addc_u32 s7, s69, 0
	s_add_u32 s8, s48, s10
	s_addc_u32 s9, s49, 0
	s_mov_b32 s14, s6
	s_mov_b32 s15, s7
	s_mov_b32 s18, s8
	s_mov_b32 s19, s9
	global_load_dwordx4 v[172:175], v148, s[4:5]
	global_load_dwordx4 v[176:179], v148, s[4:5] offset:16
	s_add_u32 s4, s4, 0xc000
	s_addc_u32 s5, s5, 0
	global_load_dwordx4 v[180:183], v148, s[4:5]
	global_load_dwordx4 v[184:187], v148, s[4:5] offset:16
	s_add_u32 s4, s4, 0xc000
	s_addc_u32 s5, s5, 0
	global_load_dwordx4 v[188:191], v148, s[4:5]
	global_load_dwordx4 v[192:195], v148, s[4:5] offset:16
	s_add_u32 s4, s4, 0xc000
	s_addc_u32 s5, s5, 0
	global_load_dwordx4 v[196:199], v148, s[4:5]
	global_load_dwordx4 v[200:203], v148, s[4:5] offset:16
	s_add_u32 s4, s4, 0xc000
	s_addc_u32 s5, s5, 0
	global_load_dwordx4 v[204:207], v148, s[4:5]
	global_load_dwordx4 v[208:211], v148, s[4:5] offset:16
	s_add_u32 s4, s4, 0xc000
	s_addc_u32 s5, s5, 0
	global_load_dwordx4 v[212:215], v148, s[4:5]
	global_load_dwordx4 v[216:219], v148, s[4:5] offset:16
	s_add_u32 s4, s4, 0xc000
	s_addc_u32 s5, s5, 0
	global_load_dwordx4 v[230:233], v148, s[4:5]
	global_load_dwordx4 v[234:237], v148, s[4:5] offset:16
	s_add_u32 s4, s4, 0xc000
	s_addc_u32 s5, s5, 0
	global_load_dwordx4 v[238:241], v148, s[4:5]
	global_load_dwordx4 v[242:245], v148, s[4:5] offset:16
	s_barrier
	s_add_u32 m0, s38, 0
	v_mov_b32_e32 v0, 0
	v_mov_b32_e32 v1, 0
	global_load_lds_dwordx4 v164, s[98:99]
	s_add_u32 m0, s38, 4096
	v_mov_b32_e32 v2, 0
	v_mov_b32_e32 v3, 0
	global_load_lds_dwordx4 v165, s[98:99]
	s_add_u32 m0, s38, 8192
	v_mov_b32_e32 v4, 0
	v_mov_b32_e32 v5, 0
	global_load_lds_dwordx4 v166, s[98:99]
	s_add_u32 m0, s38, 12288
	v_mov_b32_e32 v6, 0
	v_mov_b32_e32 v7, 0
	global_load_lds_dwordx4 v167, s[98:99]
	s_add_u32 s98, s98, 128
	s_addc_u32 s99, s99, 0
	s_add_u32 m0, s38, 16384
	v_mov_b32_e32 v8, 0
	v_mov_b32_e32 v9, 0
	global_load_lds_dwordx4 v164, s[100:101]
	s_add_u32 m0, s38, 20480
	v_mov_b32_e32 v10, 0
	v_mov_b32_e32 v11, 0
	global_load_lds_dwordx4 v165, s[100:101]
	s_add_u32 m0, s38, 24576
	v_mov_b32_e32 v12, 0
	v_mov_b32_e32 v13, 0
	global_load_lds_dwordx4 v166, s[100:101]
	s_add_u32 m0, s38, 28672
	v_mov_b32_e32 v14, 0
	v_mov_b32_e32 v15, 0
	global_load_lds_dwordx4 v167, s[100:101]
	s_add_u32 s100, s100, 128
	s_addc_u32 s101, s101, 0
	s_add_u32 m0, s38, 32768
	v_mov_b32_e32 v16, 0
	v_mov_b32_e32 v17, 0
	global_load_lds_dwordx4 v164, s[98:99]
	s_add_u32 m0, s38, 36864
	v_mov_b32_e32 v18, 0
	v_mov_b32_e32 v19, 0
	global_load_lds_dwordx4 v165, s[98:99]
	s_add_u32 m0, s38, 40960
	v_mov_b32_e32 v20, 0
	v_mov_b32_e32 v21, 0
	global_load_lds_dwordx4 v166, s[98:99]
	s_add_u32 m0, s38, 45056
	v_mov_b32_e32 v22, 0
	v_mov_b32_e32 v23, 0
	global_load_lds_dwordx4 v167, s[98:99]
	s_add_u32 s98, s98, 128
	s_addc_u32 s99, s99, 0
	s_add_u32 m0, s38, 49152
	v_mov_b32_e32 v24, 0
	v_mov_b32_e32 v25, 0
	global_load_lds_dwordx4 v164, s[100:101]
	s_add_u32 m0, s38, 53248
	v_mov_b32_e32 v26, 0
	v_mov_b32_e32 v27, 0
	global_load_lds_dwordx4 v165, s[100:101]
	s_add_u32 m0, s38, 57344
	v_mov_b32_e32 v28, 0
	v_mov_b32_e32 v29, 0
	global_load_lds_dwordx4 v166, s[100:101]
	s_add_u32 m0, s38, 61440
	v_mov_b32_e32 v30, 0
	v_mov_b32_e32 v31, 0
	global_load_lds_dwordx4 v167, s[100:101]
	s_add_u32 s100, s100, 128
	s_addc_u32 s101, s101, 0
	v_mov_b32_e32 v32, 0
	v_mov_b32_e32 v33, 0
	v_mov_b32_e32 v34, 0
	v_mov_b32_e32 v35, 0
	v_mov_b32_e32 v36, 0
	v_mov_b32_e32 v37, 0
	v_mov_b32_e32 v38, 0
	v_mov_b32_e32 v39, 0
	v_mov_b32_e32 v40, 0
	v_mov_b32_e32 v41, 0
	v_mov_b32_e32 v42, 0
	v_mov_b32_e32 v43, 0
	v_mov_b32_e32 v44, 0
	v_mov_b32_e32 v45, 0
	v_mov_b32_e32 v46, 0
	v_mov_b32_e32 v47, 0
	v_mov_b32_e32 v48, 0
	v_mov_b32_e32 v49, 0
	v_mov_b32_e32 v50, 0
	v_mov_b32_e32 v51, 0
	v_mov_b32_e32 v52, 0
	v_mov_b32_e32 v53, 0
	v_mov_b32_e32 v54, 0
	v_mov_b32_e32 v55, 0
	v_mov_b32_e32 v56, 0
	v_mov_b32_e32 v57, 0
	v_mov_b32_e32 v58, 0
	v_mov_b32_e32 v59, 0
	v_mov_b32_e32 v60, 0
	v_mov_b32_e32 v61, 0
	v_mov_b32_e32 v62, 0
	v_mov_b32_e32 v63, 0
	s_waitcnt vmcnt(8)
	s_barrier
	ds_read_b128 v[64:67], v150 offset:0
	ds_read_b128 v[68:71], v150 offset:2048
	ds_read_b128 v[80:83], v162 offset:16384
	ds_read_b128 v[84:87], v162 offset:18432
	ds_read_b128 v[88:91], v162 offset:20480
	ds_read_b128 v[92:95], v162 offset:22528
	ds_read_b128 v[96:99], v162 offset:24576
	ds_read_b128 v[100:103], v162 offset:26624
	ds_read_b128 v[104:107], v162 offset:28672
	v_add_f32_e32 v142, 0, v172
	v_add_f32_e32 v143, 0, v173
	v_add_f32_e32 v144, 0, v174
	v_add_f32_e32 v145, 0, v175
	s_waitcnt lgkmcnt(6)
	v_mfma_f32_16x16x32_bf16 v[0:3], v[64:67], v[80:83], v[0:3]
	v_mfma_f32_16x16x32_bf16 v[32:35], v[68:71], v[80:83], v[32:35]
	ds_read_b128 v[108:111], v162 offset:30720
	v_add_f32_e32 v146, 0, v176
	v_add_f32_e32 v147, 0, v177
	v_add_f32_e32 v160, 0, v178
	v_add_f32_e32 v161, 0, v179
	s_waitcnt lgkmcnt(6)
	v_mfma_f32_16x16x32_bf16 v[4:7], v[64:67], v[84:87], v[4:7]
	v_mfma_f32_16x16x32_bf16 v[36:39], v[68:71], v[84:87], v[36:39]
	ds_read_b128 v[72:75], v151 offset:0
	ds_read_b128 v[76:79], v151 offset:2048
	ds_read_b128 v[112:115], v163 offset:16384
	v_add_f32_e32 v142, v142, v180
	v_add_f32_e32 v143, v143, v181
	v_add_f32_e32 v144, v144, v182
	v_add_f32_e32 v145, v145, v183
	s_waitcnt lgkmcnt(8)
	v_mfma_f32_16x16x32_bf16 v[8:11], v[64:67], v[88:91], v[8:11]
	v_mfma_f32_16x16x32_bf16 v[40:43], v[68:71], v[88:91], v[40:43]
	ds_read_b128 v[116:119], v163 offset:18432
	v_add_f32_e32 v146, v146, v184
	v_add_f32_e32 v147, v147, v185
	v_add_f32_e32 v160, v160, v186
	v_add_f32_e32 v161, v161, v187
	s_waitcnt lgkmcnt(8)
	v_mfma_f32_16x16x32_bf16 v[12:15], v[64:67], v[92:95], v[12:15]
	v_mfma_f32_16x16x32_bf16 v[44:47], v[68:71], v[92:95], v[44:47]
	ds_read_b128 v[120:123], v163 offset:20480
	v_add_f32_e32 v142, v142, v188
	v_add_f32_e32 v143, v143, v189
	v_add_f32_e32 v144, v144, v190
	v_add_f32_e32 v145, v145, v191
	s_waitcnt lgkmcnt(8)
	v_mfma_f32_16x16x32_bf16 v[16:19], v[64:67], v[96:99], v[16:19]
	v_mfma_f32_16x16x32_bf16 v[48:51], v[68:71], v[96:99], v[48:51]
	ds_read_b128 v[124:127], v163 offset:22528
	v_add_f32_e32 v146, v146, v192
	v_add_f32_e32 v147, v147, v193
	v_add_f32_e32 v160, v160, v194
	v_add_f32_e32 v161, v161, v195
	s_waitcnt lgkmcnt(8)
	v_mfma_f32_16x16x32_bf16 v[20:23], v[64:67], v[100:103], v[20:23]
	v_mfma_f32_16x16x32_bf16 v[52:55], v[68:71], v[100:103], v[52:55]
	ds_read_b128 v[80:83], v163 offset:24576
	v_add_f32_e32 v142, v142, v196
	v_add_f32_e32 v143, v143, v197
	v_add_f32_e32 v144, v144, v198
	v_add_f32_e32 v145, v145, v199
	s_waitcnt lgkmcnt(8)
	v_mfma_f32_16x16x32_bf16 v[24:27], v[64:67], v[104:107], v[24:27]
	v_mfma_f32_16x16x32_bf16 v[56:59], v[68:71], v[104:107], v[56:59]
	ds_read_b128 v[84:87], v163 offset:26624
	v_add_f32_e32 v146, v146, v200
	v_add_f32_e32 v147, v147, v201
	v_add_f32_e32 v160, v160, v202
	v_add_f32_e32 v161, v161, v203
	s_waitcnt lgkmcnt(8)
	v_mfma_f32_16x16x32_bf16 v[28:31], v[64:67], v[108:111], v[28:31]
	v_mfma_f32_16x16x32_bf16 v[60:63], v[68:71], v[108:111], v[60:63]
	ds_read_b128 v[88:91], v163 offset:28672
	v_add_f32_e32 v142, v142, v204
	v_add_f32_e32 v143, v143, v205
	v_add_f32_e32 v144, v144, v206
	v_add_f32_e32 v145, v145, v207
	s_waitcnt lgkmcnt(6)
	v_mfma_f32_16x16x32_bf16 v[0:3], v[72:75], v[112:115], v[0:3]
	v_mfma_f32_16x16x32_bf16 v[32:35], v[76:79], v[112:115], v[32:35]
	ds_read_b128 v[92:95], v163 offset:30720
	s_waitcnt vmcnt(0) lgkmcnt(0)
	s_barrier
	s_add_u32 m0, s38, 0
	s_nop 0
	global_load_lds_dwordx4 v164, s[98:99]
	v_add_f32_e32 v146, v146, v208
	v_add_f32_e32 v147, v147, v209
	v_add_f32_e32 v160, v160, v210
	v_add_f32_e32 v161, v161, v211
	s_waitcnt lgkmcnt(6)
	v_mfma_f32_16x16x32_bf16 v[4:7], v[72:75], v[116:119], v[4:7]
	v_mfma_f32_16x16x32_bf16 v[36:39], v[76:79], v[116:119], v[36:39]
	ds_read_b128 v[64:67], v150 offset:32768
	ds_read_b128 v[68:71], v150 offset:34816
	ds_read_b128 v[96:99], v162 offset:49152
	s_add_u32 m0, s38, 4096
	s_nop 0
	global_load_lds_dwordx4 v165, s[98:99]
	v_add_f32_e32 v142, v142, v212
	v_add_f32_e32 v143, v143, v213
	v_add_f32_e32 v144, v144, v214
	v_add_f32_e32 v145, v145, v215
	s_waitcnt lgkmcnt(8)
	v_mfma_f32_16x16x32_bf16 v[8:11], v[72:75], v[120:123], v[8:11]
	v_mfma_f32_16x16x32_bf16 v[40:43], v[76:79], v[120:123], v[40:43]
	ds_read_b128 v[100:103], v162 offset:51200
	s_add_u32 m0, s38, 8192
	s_nop 0
	global_load_lds_dwordx4 v166, s[98:99]
	v_add_f32_e32 v146, v146, v216
	v_add_f32_e32 v147, v147, v217
	v_add_f32_e32 v160, v160, v218
	v_add_f32_e32 v161, v161, v219
	s_waitcnt lgkmcnt(8)
	v_mfma_f32_16x16x32_bf16 v[12:15], v[72:75], v[124:127], v[12:15]
	v_mfma_f32_16x16x32_bf16 v[44:47], v[76:79], v[124:127], v[44:47]
	ds_read_b128 v[104:107], v162 offset:53248
	s_add_u32 m0, s38, 12288
	s_nop 0
	global_load_lds_dwordx4 v167, s[98:99]
	s_add_u32 s98, s98, 128
	s_addc_u32 s99, s99, 0
	v_add_f32_e32 v142, v142, v230
	v_add_f32_e32 v143, v143, v231
	v_add_f32_e32 v144, v144, v232
	v_add_f32_e32 v145, v145, v233
	s_waitcnt lgkmcnt(8)
	v_mfma_f32_16x16x32_bf16 v[16:19], v[72:75], v[80:83], v[16:19]
	v_mfma_f32_16x16x32_bf16 v[48:51], v[76:79], v[80:83], v[48:51]
	ds_read_b128 v[108:111], v162 offset:55296
	s_add_u32 m0, s38, 16384
	s_nop 0
	global_load_lds_dwordx4 v164, s[100:101]
	v_add_f32_e32 v146, v146, v234
	v_add_f32_e32 v147, v147, v235
	v_add_f32_e32 v160, v160, v236
	v_add_f32_e32 v161, v161, v237
	s_waitcnt lgkmcnt(8)
	v_mfma_f32_16x16x32_bf16 v[20:23], v[72:75], v[84:87], v[20:23]
	v_mfma_f32_16x16x32_bf16 v[52:55], v[76:79], v[84:87], v[52:55]
	ds_read_b128 v[112:115], v162 offset:57344
	s_add_u32 m0, s38, 20480
	s_nop 0
	global_load_lds_dwordx4 v165, s[100:101]
	v_add_f32_e32 v142, v142, v238
	v_add_f32_e32 v143, v143, v239
	v_add_f32_e32 v144, v144, v240
	v_add_f32_e32 v145, v145, v241
	s_waitcnt lgkmcnt(8)
	v_mfma_f32_16x16x32_bf16 v[24:27], v[72:75], v[88:91], v[24:27]
	v_mfma_f32_16x16x32_bf16 v[56:59], v[76:79], v[88:91], v[56:59]
	ds_read_b128 v[116:119], v162 offset:59392
	s_add_u32 m0, s38, 24576
	s_nop 0
	global_load_lds_dwordx4 v166, s[100:101]
	v_add_f32_e32 v146, v146, v242
	v_add_f32_e32 v147, v147, v243
	v_add_f32_e32 v160, v160, v244
	v_add_f32_e32 v161, v161, v245
	s_waitcnt lgkmcnt(8)
	v_mfma_f32_16x16x32_bf16 v[28:31], v[72:75], v[92:95], v[28:31]
	v_mfma_f32_16x16x32_bf16 v[60:63], v[76:79], v[92:95], v[60:63]
	ds_read_b128 v[120:123], v162 offset:61440
	s_add_u32 m0, s38, 28672
	s_nop 0
	global_load_lds_dwordx4 v167, s[100:101]
	s_add_u32 s100, s100, 128
	s_addc_u32 s101, s101, 0
	s_waitcnt lgkmcnt(6)
	v_mfma_f32_16x16x32_bf16 v[0:3], v[64:67], v[96:99], v[0:3]
	v_mfma_f32_16x16x32_bf16 v[32:35], v[68:71], v[96:99], v[32:35]
	ds_read_b128 v[124:127], v162 offset:63488
	s_waitcnt lgkmcnt(6)
	v_mfma_f32_16x16x32_bf16 v[4:7], v[64:67], v[100:103], v[4:7]
	v_mfma_f32_16x16x32_bf16 v[36:39], v[68:71], v[100:103], v[36:39]
	ds_read_b128 v[72:75], v151 offset:32768
	ds_read_b128 v[76:79], v151 offset:34816
	ds_read_b128 v[80:83], v163 offset:49152
	s_waitcnt lgkmcnt(8)
	v_mfma_f32_16x16x32_bf16 v[8:11], v[64:67], v[104:107], v[8:11]
	v_mfma_f32_16x16x32_bf16 v[40:43], v[68:71], v[104:107], v[40:43]
	ds_read_b128 v[84:87], v163 offset:51200
	s_waitcnt lgkmcnt(8)
	v_mfma_f32_16x16x32_bf16 v[12:15], v[64:67], v[108:111], v[12:15]
	v_mfma_f32_16x16x32_bf16 v[44:47], v[68:71], v[108:111], v[44:47]
	ds_read_b128 v[88:91], v163 offset:53248
	s_waitcnt lgkmcnt(8)
	v_mfma_f32_16x16x32_bf16 v[16:19], v[64:67], v[112:115], v[16:19]
	v_mfma_f32_16x16x32_bf16 v[48:51], v[68:71], v[112:115], v[48:51]
	ds_read_b128 v[92:95], v163 offset:55296
	s_waitcnt lgkmcnt(8)
	v_mfma_f32_16x16x32_bf16 v[20:23], v[64:67], v[116:119], v[20:23]
	v_mfma_f32_16x16x32_bf16 v[52:55], v[68:71], v[116:119], v[52:55]
	ds_read_b128 v[96:99], v163 offset:57344
	s_waitcnt lgkmcnt(8)
	v_mfma_f32_16x16x32_bf16 v[24:27], v[64:67], v[120:123], v[24:27]
	v_mfma_f32_16x16x32_bf16 v[56:59], v[68:71], v[120:123], v[56:59]
	ds_read_b128 v[100:103], v163 offset:59392
	s_waitcnt lgkmcnt(8)
	v_mfma_f32_16x16x32_bf16 v[28:31], v[64:67], v[124:127], v[28:31]
	v_mfma_f32_16x16x32_bf16 v[60:63], v[68:71], v[124:127], v[60:63]
	ds_read_b128 v[104:107], v163 offset:61440
	s_waitcnt lgkmcnt(6)
	v_mfma_f32_16x16x32_bf16 v[0:3], v[72:75], v[80:83], v[0:3]
	v_mfma_f32_16x16x32_bf16 v[32:35], v[76:79], v[80:83], v[32:35]
	ds_read_b128 v[108:111], v163 offset:63488
	s_waitcnt vmcnt(0) lgkmcnt(0)
	s_barrier
	s_add_u32 m0, s38, 32768
	s_nop 0
	global_load_lds_dwordx4 v164, s[98:99]
	s_waitcnt lgkmcnt(6)
	v_mfma_f32_16x16x32_bf16 v[4:7], v[72:75], v[84:87], v[4:7]
	v_mfma_f32_16x16x32_bf16 v[36:39], v[76:79], v[84:87], v[36:39]
	ds_read_b128 v[64:67], v150 offset:0
	ds_read_b128 v[68:71], v150 offset:2048
	ds_read_b128 v[112:115], v162 offset:16384
	s_add_u32 m0, s38, 36864
	s_nop 0
	global_load_lds_dwordx4 v165, s[98:99]
	s_waitcnt lgkmcnt(8)
	v_mfma_f32_16x16x32_bf16 v[8:11], v[72:75], v[88:91], v[8:11]
	v_mfma_f32_16x16x32_bf16 v[40:43], v[76:79], v[88:91], v[40:43]
	ds_read_b128 v[116:119], v162 offset:18432
	s_add_u32 m0, s38, 40960
	s_nop 0
	global_load_lds_dwordx4 v166, s[98:99]
	s_waitcnt lgkmcnt(8)
	v_mfma_f32_16x16x32_bf16 v[12:15], v[72:75], v[92:95], v[12:15]
	v_mfma_f32_16x16x32_bf16 v[44:47], v[76:79], v[92:95], v[44:47]
	ds_read_b128 v[120:123], v162 offset:20480
	s_add_u32 m0, s38, 45056
	s_nop 0
	global_load_lds_dwordx4 v167, s[98:99]
	s_add_u32 s98, s98, 128
	s_addc_u32 s99, s99, 0
	s_waitcnt lgkmcnt(8)
	v_mfma_f32_16x16x32_bf16 v[16:19], v[72:75], v[96:99], v[16:19]
	v_mfma_f32_16x16x32_bf16 v[48:51], v[76:79], v[96:99], v[48:51]
	ds_read_b128 v[124:127], v162 offset:22528
	s_add_u32 m0, s38, 49152
	s_nop 0
	global_load_lds_dwordx4 v164, s[100:101]
	s_waitcnt lgkmcnt(8)
	v_mfma_f32_16x16x32_bf16 v[20:23], v[72:75], v[100:103], v[20:23]
	v_mfma_f32_16x16x32_bf16 v[52:55], v[76:79], v[100:103], v[52:55]
	ds_read_b128 v[80:83], v162 offset:24576
	s_add_u32 m0, s38, 53248
	s_nop 0
	global_load_lds_dwordx4 v165, s[100:101]
	s_waitcnt lgkmcnt(8)
	v_mfma_f32_16x16x32_bf16 v[24:27], v[72:75], v[104:107], v[24:27]
	v_mfma_f32_16x16x32_bf16 v[56:59], v[76:79], v[104:107], v[56:59]
	ds_read_b128 v[84:87], v162 offset:26624
	s_add_u32 m0, s38, 57344
	s_nop 0
	global_load_lds_dwordx4 v166, s[100:101]
	s_waitcnt lgkmcnt(8)
	v_mfma_f32_16x16x32_bf16 v[28:31], v[72:75], v[108:111], v[28:31]
	v_mfma_f32_16x16x32_bf16 v[60:63], v[76:79], v[108:111], v[60:63]
	ds_read_b128 v[88:91], v162 offset:28672
	s_add_u32 m0, s38, 61440
	s_nop 0
	global_load_lds_dwordx4 v167, s[100:101]
	s_add_u32 s100, s100, 128
	s_addc_u32 s101, s101, 0
	s_waitcnt lgkmcnt(6)
	v_mfma_f32_16x16x32_bf16 v[0:3], v[64:67], v[112:115], v[0:3]
	v_mfma_f32_16x16x32_bf16 v[32:35], v[68:71], v[112:115], v[32:35]
	ds_read_b128 v[92:95], v162 offset:30720
	s_waitcnt lgkmcnt(6)
	v_mfma_f32_16x16x32_bf16 v[4:7], v[64:67], v[116:119], v[4:7]
	v_mfma_f32_16x16x32_bf16 v[36:39], v[68:71], v[116:119], v[36:39]
	ds_read_b128 v[72:75], v151 offset:0
	ds_read_b128 v[76:79], v151 offset:2048
	ds_read_b128 v[96:99], v163 offset:16384
	s_waitcnt lgkmcnt(8)
	v_mfma_f32_16x16x32_bf16 v[8:11], v[64:67], v[120:123], v[8:11]
	v_mfma_f32_16x16x32_bf16 v[40:43], v[68:71], v[120:123], v[40:43]
	ds_read_b128 v[100:103], v163 offset:18432
	s_waitcnt lgkmcnt(8)
	v_mfma_f32_16x16x32_bf16 v[12:15], v[64:67], v[124:127], v[12:15]
	v_mfma_f32_16x16x32_bf16 v[44:47], v[68:71], v[124:127], v[44:47]
	ds_read_b128 v[104:107], v163 offset:20480
	s_waitcnt lgkmcnt(8)
	v_mfma_f32_16x16x32_bf16 v[16:19], v[64:67], v[80:83], v[16:19]
	v_mfma_f32_16x16x32_bf16 v[48:51], v[68:71], v[80:83], v[48:51]
	ds_read_b128 v[108:111], v163 offset:22528
	s_waitcnt lgkmcnt(8)
	v_mfma_f32_16x16x32_bf16 v[20:23], v[64:67], v[84:87], v[20:23]
	v_mfma_f32_16x16x32_bf16 v[52:55], v[68:71], v[84:87], v[52:55]
	ds_read_b128 v[112:115], v163 offset:24576
	s_waitcnt lgkmcnt(8)
	v_mfma_f32_16x16x32_bf16 v[24:27], v[64:67], v[88:91], v[24:27]
	v_mfma_f32_16x16x32_bf16 v[56:59], v[68:71], v[88:91], v[56:59]
	ds_read_b128 v[116:119], v163 offset:26624
	s_waitcnt lgkmcnt(8)
	v_mfma_f32_16x16x32_bf16 v[28:31], v[64:67], v[92:95], v[28:31]
	v_mfma_f32_16x16x32_bf16 v[60:63], v[68:71], v[92:95], v[60:63]
	ds_read_b128 v[120:123], v163 offset:28672
	s_waitcnt lgkmcnt(6)
	v_mfma_f32_16x16x32_bf16 v[0:3], v[72:75], v[96:99], v[0:3]
	v_mfma_f32_16x16x32_bf16 v[32:35], v[76:79], v[96:99], v[32:35]
	ds_read_b128 v[124:127], v163 offset:30720
	s_waitcnt vmcnt(0) lgkmcnt(0)
	s_barrier
	s_add_u32 m0, s38, 0
	s_nop 0
	global_load_lds_dwordx4 v164, s[98:99]
	s_waitcnt lgkmcnt(6)
	v_mfma_f32_16x16x32_bf16 v[4:7], v[72:75], v[100:103], v[4:7]
	v_mfma_f32_16x16x32_bf16 v[36:39], v[76:79], v[100:103], v[36:39]
	ds_read_b128 v[64:67], v150 offset:32768
	ds_read_b128 v[68:71], v150 offset:34816
	ds_read_b128 v[80:83], v162 offset:49152
	s_add_u32 m0, s38, 4096
	s_nop 0
	global_load_lds_dwordx4 v165, s[98:99]
	s_waitcnt lgkmcnt(8)
	v_mfma_f32_16x16x32_bf16 v[8:11], v[72:75], v[104:107], v[8:11]
	v_mfma_f32_16x16x32_bf16 v[40:43], v[76:79], v[104:107], v[40:43]
	ds_read_b128 v[84:87], v162 offset:51200
	s_add_u32 m0, s38, 8192
	s_nop 0
	global_load_lds_dwordx4 v166, s[98:99]
	s_waitcnt lgkmcnt(8)
	v_mfma_f32_16x16x32_bf16 v[12:15], v[72:75], v[108:111], v[12:15]
	v_mfma_f32_16x16x32_bf16 v[44:47], v[76:79], v[108:111], v[44:47]
	ds_read_b128 v[88:91], v162 offset:53248
	s_add_u32 m0, s38, 12288
	s_nop 0
	global_load_lds_dwordx4 v167, s[98:99]
	s_add_u32 s98, s98, 128
	s_addc_u32 s99, s99, 0
	s_waitcnt lgkmcnt(8)
	v_mfma_f32_16x16x32_bf16 v[16:19], v[72:75], v[112:115], v[16:19]
	v_mfma_f32_16x16x32_bf16 v[48:51], v[76:79], v[112:115], v[48:51]
	ds_read_b128 v[92:95], v162 offset:55296
	s_add_u32 m0, s38, 16384
	s_nop 0
	global_load_lds_dwordx4 v164, s[100:101]
	s_waitcnt lgkmcnt(8)
	v_mfma_f32_16x16x32_bf16 v[20:23], v[72:75], v[116:119], v[20:23]
	v_mfma_f32_16x16x32_bf16 v[52:55], v[76:79], v[116:119], v[52:55]
	ds_read_b128 v[96:99], v162 offset:57344
	s_add_u32 m0, s38, 20480
	s_nop 0
	global_load_lds_dwordx4 v165, s[100:101]
	s_waitcnt lgkmcnt(8)
	v_mfma_f32_16x16x32_bf16 v[24:27], v[72:75], v[120:123], v[24:27]
	v_mfma_f32_16x16x32_bf16 v[56:59], v[76:79], v[120:123], v[56:59]
	ds_read_b128 v[100:103], v162 offset:59392
	s_add_u32 m0, s38, 24576
	s_nop 0
	global_load_lds_dwordx4 v166, s[100:101]
	s_waitcnt lgkmcnt(8)
	v_mfma_f32_16x16x32_bf16 v[28:31], v[72:75], v[124:127], v[28:31]
	v_mfma_f32_16x16x32_bf16 v[60:63], v[76:79], v[124:127], v[60:63]
	ds_read_b128 v[104:107], v162 offset:61440
	s_add_u32 m0, s38, 28672
	s_nop 0
	global_load_lds_dwordx4 v167, s[100:101]
	s_add_u32 s100, s100, 128
	s_addc_u32 s101, s101, 0
	s_waitcnt lgkmcnt(6)
	v_mfma_f32_16x16x32_bf16 v[0:3], v[64:67], v[80:83], v[0:3]
	v_mfma_f32_16x16x32_bf16 v[32:35], v[68:71], v[80:83], v[32:35]
	ds_read_b128 v[108:111], v162 offset:63488
	s_waitcnt lgkmcnt(6)
	v_mfma_f32_16x16x32_bf16 v[4:7], v[64:67], v[84:87], v[4:7]
	v_mfma_f32_16x16x32_bf16 v[36:39], v[68:71], v[84:87], v[36:39]
	ds_read_b128 v[72:75], v151 offset:32768
	ds_read_b128 v[76:79], v151 offset:34816
	ds_read_b128 v[112:115], v163 offset:49152
	s_waitcnt lgkmcnt(8)
	v_mfma_f32_16x16x32_bf16 v[8:11], v[64:67], v[88:91], v[8:11]
	v_mfma_f32_16x16x32_bf16 v[40:43], v[68:71], v[88:91], v[40:43]
	ds_read_b128 v[116:119], v163 offset:51200
	s_waitcnt lgkmcnt(8)
	v_mfma_f32_16x16x32_bf16 v[12:15], v[64:67], v[92:95], v[12:15]
	v_mfma_f32_16x16x32_bf16 v[44:47], v[68:71], v[92:95], v[44:47]
	ds_read_b128 v[120:123], v163 offset:53248
	s_waitcnt lgkmcnt(8)
	v_mfma_f32_16x16x32_bf16 v[16:19], v[64:67], v[96:99], v[16:19]
	v_mfma_f32_16x16x32_bf16 v[48:51], v[68:71], v[96:99], v[48:51]
	ds_read_b128 v[124:127], v163 offset:55296
	s_waitcnt lgkmcnt(8)
	v_mfma_f32_16x16x32_bf16 v[20:23], v[64:67], v[100:103], v[20:23]
	v_mfma_f32_16x16x32_bf16 v[52:55], v[68:71], v[100:103], v[52:55]
	ds_read_b128 v[80:83], v163 offset:57344
	s_waitcnt lgkmcnt(8)
	v_mfma_f32_16x16x32_bf16 v[24:27], v[64:67], v[104:107], v[24:27]
	v_mfma_f32_16x16x32_bf16 v[56:59], v[68:71], v[104:107], v[56:59]
	ds_read_b128 v[84:87], v163 offset:59392
	s_waitcnt lgkmcnt(8)
	v_mfma_f32_16x16x32_bf16 v[28:31], v[64:67], v[108:111], v[28:31]
	v_mfma_f32_16x16x32_bf16 v[60:63], v[68:71], v[108:111], v[60:63]
	ds_read_b128 v[88:91], v163 offset:61440
	s_waitcnt lgkmcnt(6)
	v_mfma_f32_16x16x32_bf16 v[0:3], v[72:75], v[112:115], v[0:3]
	v_mfma_f32_16x16x32_bf16 v[32:35], v[76:79], v[112:115], v[32:35]
	ds_read_b128 v[92:95], v163 offset:63488
	s_waitcnt vmcnt(0) lgkmcnt(0)
	s_barrier
	s_add_u32 m0, s38, 32768
	s_nop 0
	global_load_lds_dwordx4 v164, s[98:99]
	s_waitcnt lgkmcnt(6)
	v_mfma_f32_16x16x32_bf16 v[4:7], v[72:75], v[116:119], v[4:7]
	v_mfma_f32_16x16x32_bf16 v[36:39], v[76:79], v[116:119], v[36:39]
	ds_read_b128 v[64:67], v150 offset:0
	ds_read_b128 v[68:71], v150 offset:2048
	ds_read_b128 v[96:99], v162 offset:16384
	s_add_u32 m0, s38, 36864
	s_nop 0
	global_load_lds_dwordx4 v165, s[98:99]
	s_waitcnt lgkmcnt(8)
	v_mfma_f32_16x16x32_bf16 v[8:11], v[72:75], v[120:123], v[8:11]
	v_mfma_f32_16x16x32_bf16 v[40:43], v[76:79], v[120:123], v[40:43]
	ds_read_b128 v[100:103], v162 offset:18432
	s_add_u32 m0, s38, 40960
	s_nop 0
	global_load_lds_dwordx4 v166, s[98:99]
	s_waitcnt lgkmcnt(8)
	v_mfma_f32_16x16x32_bf16 v[12:15], v[72:75], v[124:127], v[12:15]
	v_mfma_f32_16x16x32_bf16 v[44:47], v[76:79], v[124:127], v[44:47]
	ds_read_b128 v[104:107], v162 offset:20480
	s_add_u32 m0, s38, 45056
	s_nop 0
	global_load_lds_dwordx4 v167, s[98:99]
	s_add_u32 s98, s98, 128
	s_addc_u32 s99, s99, 0
	s_waitcnt lgkmcnt(8)
	v_mfma_f32_16x16x32_bf16 v[16:19], v[72:75], v[80:83], v[16:19]
	v_mfma_f32_16x16x32_bf16 v[48:51], v[76:79], v[80:83], v[48:51]
	ds_read_b128 v[108:111], v162 offset:22528
	s_add_u32 m0, s38, 49152
	s_nop 0
	global_load_lds_dwordx4 v164, s[100:101]
	s_waitcnt lgkmcnt(8)
	v_mfma_f32_16x16x32_bf16 v[20:23], v[72:75], v[84:87], v[20:23]
	v_mfma_f32_16x16x32_bf16 v[52:55], v[76:79], v[84:87], v[52:55]
	ds_read_b128 v[112:115], v162 offset:24576
	s_add_u32 m0, s38, 53248
	s_nop 0
	global_load_lds_dwordx4 v165, s[100:101]
	s_waitcnt lgkmcnt(8)
	v_mfma_f32_16x16x32_bf16 v[24:27], v[72:75], v[88:91], v[24:27]
	v_mfma_f32_16x16x32_bf16 v[56:59], v[76:79], v[88:91], v[56:59]
	ds_read_b128 v[116:119], v162 offset:26624
	s_add_u32 m0, s38, 57344
	s_nop 0
	global_load_lds_dwordx4 v166, s[100:101]
	s_waitcnt lgkmcnt(8)
	v_mfma_f32_16x16x32_bf16 v[28:31], v[72:75], v[92:95], v[28:31]
	v_mfma_f32_16x16x32_bf16 v[60:63], v[76:79], v[92:95], v[60:63]
	ds_read_b128 v[120:123], v162 offset:28672
	s_add_u32 m0, s38, 61440
	s_nop 0
	global_load_lds_dwordx4 v167, s[100:101]
	s_add_u32 s100, s100, 128
	s_addc_u32 s101, s101, 0
	s_waitcnt lgkmcnt(6)
	v_mfma_f32_16x16x32_bf16 v[0:3], v[64:67], v[96:99], v[0:3]
	v_mfma_f32_16x16x32_bf16 v[32:35], v[68:71], v[96:99], v[32:35]
	ds_read_b128 v[124:127], v162 offset:30720
	s_waitcnt lgkmcnt(6)
	v_mfma_f32_16x16x32_bf16 v[4:7], v[64:67], v[100:103], v[4:7]
	v_mfma_f32_16x16x32_bf16 v[36:39], v[68:71], v[100:103], v[36:39]
	ds_read_b128 v[72:75], v151 offset:0
	ds_read_b128 v[76:79], v151 offset:2048
	ds_read_b128 v[80:83], v163 offset:16384
	s_waitcnt lgkmcnt(8)
	v_mfma_f32_16x16x32_bf16 v[8:11], v[64:67], v[104:107], v[8:11]
	v_mfma_f32_16x16x32_bf16 v[40:43], v[68:71], v[104:107], v[40:43]
	ds_read_b128 v[84:87], v163 offset:18432
	s_waitcnt lgkmcnt(8)
	v_mfma_f32_16x16x32_bf16 v[12:15], v[64:67], v[108:111], v[12:15]
	v_mfma_f32_16x16x32_bf16 v[44:47], v[68:71], v[108:111], v[44:47]
	ds_read_b128 v[88:91], v163 offset:20480
	s_waitcnt lgkmcnt(8)
	v_mfma_f32_16x16x32_bf16 v[16:19], v[64:67], v[112:115], v[16:19]
	v_mfma_f32_16x16x32_bf16 v[48:51], v[68:71], v[112:115], v[48:51]
	ds_read_b128 v[92:95], v163 offset:22528
	s_waitcnt lgkmcnt(8)
	v_mfma_f32_16x16x32_bf16 v[20:23], v[64:67], v[116:119], v[20:23]
	v_mfma_f32_16x16x32_bf16 v[52:55], v[68:71], v[116:119], v[52:55]
	ds_read_b128 v[96:99], v163 offset:24576
	s_waitcnt lgkmcnt(8)
	v_mfma_f32_16x16x32_bf16 v[24:27], v[64:67], v[120:123], v[24:27]
	v_mfma_f32_16x16x32_bf16 v[56:59], v[68:71], v[120:123], v[56:59]
	ds_read_b128 v[100:103], v163 offset:26624
	s_waitcnt lgkmcnt(8)
	v_mfma_f32_16x16x32_bf16 v[28:31], v[64:67], v[124:127], v[28:31]
	v_mfma_f32_16x16x32_bf16 v[60:63], v[68:71], v[124:127], v[60:63]
	ds_read_b128 v[104:107], v163 offset:28672
	s_waitcnt lgkmcnt(6)
	v_mfma_f32_16x16x32_bf16 v[0:3], v[72:75], v[80:83], v[0:3]
	v_mfma_f32_16x16x32_bf16 v[32:35], v[76:79], v[80:83], v[32:35]
	ds_read_b128 v[108:111], v163 offset:30720
	s_waitcnt vmcnt(0) lgkmcnt(0)
	s_barrier
	s_add_u32 m0, s38, 0
	s_nop 0
	global_load_lds_dwordx4 v164, s[98:99]
	s_waitcnt lgkmcnt(6)
	v_mfma_f32_16x16x32_bf16 v[4:7], v[72:75], v[84:87], v[4:7]
	v_mfma_f32_16x16x32_bf16 v[36:39], v[76:79], v[84:87], v[36:39]
	ds_read_b128 v[64:67], v150 offset:32768
	ds_read_b128 v[68:71], v150 offset:34816
	ds_read_b128 v[112:115], v162 offset:49152
	s_add_u32 m0, s38, 4096
	s_nop 0
	global_load_lds_dwordx4 v165, s[98:99]
	s_waitcnt lgkmcnt(8)
	v_mfma_f32_16x16x32_bf16 v[8:11], v[72:75], v[88:91], v[8:11]
	v_mfma_f32_16x16x32_bf16 v[40:43], v[76:79], v[88:91], v[40:43]
	ds_read_b128 v[116:119], v162 offset:51200
	s_add_u32 m0, s38, 8192
	s_nop 0
	global_load_lds_dwordx4 v166, s[98:99]
	s_waitcnt lgkmcnt(8)
	v_mfma_f32_16x16x32_bf16 v[12:15], v[72:75], v[92:95], v[12:15]
	v_mfma_f32_16x16x32_bf16 v[44:47], v[76:79], v[92:95], v[44:47]
	ds_read_b128 v[120:123], v162 offset:53248
	s_add_u32 m0, s38, 12288
	s_nop 0
	global_load_lds_dwordx4 v167, s[98:99]
	s_add_u32 s98, s98, 128
	s_addc_u32 s99, s99, 0
	s_waitcnt lgkmcnt(8)
	v_mfma_f32_16x16x32_bf16 v[16:19], v[72:75], v[96:99], v[16:19]
	v_mfma_f32_16x16x32_bf16 v[48:51], v[76:79], v[96:99], v[48:51]
	ds_read_b128 v[124:127], v162 offset:55296
	s_add_u32 m0, s38, 16384
	s_nop 0
	global_load_lds_dwordx4 v164, s[100:101]
	s_waitcnt lgkmcnt(8)
	v_mfma_f32_16x16x32_bf16 v[20:23], v[72:75], v[100:103], v[20:23]
	v_mfma_f32_16x16x32_bf16 v[52:55], v[76:79], v[100:103], v[52:55]
	ds_read_b128 v[80:83], v162 offset:57344
	s_add_u32 m0, s38, 20480
	s_nop 0
	global_load_lds_dwordx4 v165, s[100:101]
	s_waitcnt lgkmcnt(8)
	v_mfma_f32_16x16x32_bf16 v[24:27], v[72:75], v[104:107], v[24:27]
	v_mfma_f32_16x16x32_bf16 v[56:59], v[76:79], v[104:107], v[56:59]
	ds_read_b128 v[84:87], v162 offset:59392
	s_add_u32 m0, s38, 24576
	s_nop 0
	global_load_lds_dwordx4 v166, s[100:101]
	s_waitcnt lgkmcnt(8)
	v_mfma_f32_16x16x32_bf16 v[28:31], v[72:75], v[108:111], v[28:31]
	v_mfma_f32_16x16x32_bf16 v[60:63], v[76:79], v[108:111], v[60:63]
	ds_read_b128 v[88:91], v162 offset:61440
	s_add_u32 m0, s38, 28672
	s_nop 0
	global_load_lds_dwordx4 v167, s[100:101]
	s_add_u32 s100, s100, 128
	s_addc_u32 s101, s101, 0
	s_waitcnt lgkmcnt(6)
	v_mfma_f32_16x16x32_bf16 v[0:3], v[64:67], v[112:115], v[0:3]
	v_mfma_f32_16x16x32_bf16 v[32:35], v[68:71], v[112:115], v[32:35]
	ds_read_b128 v[92:95], v162 offset:63488
	s_waitcnt lgkmcnt(6)
	v_mfma_f32_16x16x32_bf16 v[4:7], v[64:67], v[116:119], v[4:7]
	v_mfma_f32_16x16x32_bf16 v[36:39], v[68:71], v[116:119], v[36:39]
	ds_read_b128 v[72:75], v151 offset:32768
	ds_read_b128 v[76:79], v151 offset:34816
	ds_read_b128 v[96:99], v163 offset:49152
	s_waitcnt lgkmcnt(8)
	v_mfma_f32_16x16x32_bf16 v[8:11], v[64:67], v[120:123], v[8:11]
	v_mfma_f32_16x16x32_bf16 v[40:43], v[68:71], v[120:123], v[40:43]
	ds_read_b128 v[100:103], v163 offset:51200
	s_waitcnt lgkmcnt(8)
	v_mfma_f32_16x16x32_bf16 v[12:15], v[64:67], v[124:127], v[12:15]
	v_mfma_f32_16x16x32_bf16 v[44:47], v[68:71], v[124:127], v[44:47]
	ds_read_b128 v[104:107], v163 offset:53248
	s_waitcnt lgkmcnt(8)
	v_mfma_f32_16x16x32_bf16 v[16:19], v[64:67], v[80:83], v[16:19]
	v_mfma_f32_16x16x32_bf16 v[48:51], v[68:71], v[80:83], v[48:51]
	ds_read_b128 v[108:111], v163 offset:55296
	s_waitcnt lgkmcnt(8)
	v_mfma_f32_16x16x32_bf16 v[20:23], v[64:67], v[84:87], v[20:23]
	v_mfma_f32_16x16x32_bf16 v[52:55], v[68:71], v[84:87], v[52:55]
	ds_read_b128 v[112:115], v163 offset:57344
	s_waitcnt lgkmcnt(8)
	v_mfma_f32_16x16x32_bf16 v[24:27], v[64:67], v[88:91], v[24:27]
	v_mfma_f32_16x16x32_bf16 v[56:59], v[68:71], v[88:91], v[56:59]
	ds_read_b128 v[116:119], v163 offset:59392
	s_waitcnt lgkmcnt(8)
	v_mfma_f32_16x16x32_bf16 v[28:31], v[64:67], v[92:95], v[28:31]
	v_mfma_f32_16x16x32_bf16 v[60:63], v[68:71], v[92:95], v[60:63]
	ds_read_b128 v[120:123], v163 offset:61440
	s_waitcnt lgkmcnt(6)
	v_mfma_f32_16x16x32_bf16 v[0:3], v[72:75], v[96:99], v[0:3]
	v_mfma_f32_16x16x32_bf16 v[32:35], v[76:79], v[96:99], v[32:35]
	ds_read_b128 v[124:127], v163 offset:63488
	s_waitcnt vmcnt(0) lgkmcnt(0)
	s_barrier
	s_add_u32 m0, s38, 32768
	s_nop 0
	global_load_lds_dwordx4 v164, s[98:99]
	s_waitcnt lgkmcnt(6)
	v_mfma_f32_16x16x32_bf16 v[4:7], v[72:75], v[100:103], v[4:7]
	v_mfma_f32_16x16x32_bf16 v[36:39], v[76:79], v[100:103], v[36:39]
	ds_read_b128 v[64:67], v150 offset:0
	ds_read_b128 v[68:71], v150 offset:2048
	ds_read_b128 v[80:83], v162 offset:16384
	s_add_u32 m0, s38, 36864
	s_nop 0
	global_load_lds_dwordx4 v165, s[98:99]
	s_waitcnt lgkmcnt(8)
	v_mfma_f32_16x16x32_bf16 v[8:11], v[72:75], v[104:107], v[8:11]
	v_mfma_f32_16x16x32_bf16 v[40:43], v[76:79], v[104:107], v[40:43]
	ds_read_b128 v[84:87], v162 offset:18432
	s_add_u32 m0, s38, 40960
	s_nop 0
	global_load_lds_dwordx4 v166, s[98:99]
	s_waitcnt lgkmcnt(8)
	v_mfma_f32_16x16x32_bf16 v[12:15], v[72:75], v[108:111], v[12:15]
	v_mfma_f32_16x16x32_bf16 v[44:47], v[76:79], v[108:111], v[44:47]
	ds_read_b128 v[88:91], v162 offset:20480
	s_add_u32 m0, s38, 45056
	s_nop 0
	global_load_lds_dwordx4 v167, s[98:99]
	s_add_u32 s98, s98, 128
	s_addc_u32 s99, s99, 0
	s_waitcnt lgkmcnt(8)
	v_mfma_f32_16x16x32_bf16 v[16:19], v[72:75], v[112:115], v[16:19]
	v_mfma_f32_16x16x32_bf16 v[48:51], v[76:79], v[112:115], v[48:51]
	ds_read_b128 v[92:95], v162 offset:22528
	s_add_u32 m0, s38, 49152
	s_nop 0
	global_load_lds_dwordx4 v164, s[100:101]
	s_waitcnt lgkmcnt(8)
	v_mfma_f32_16x16x32_bf16 v[20:23], v[72:75], v[116:119], v[20:23]
	v_mfma_f32_16x16x32_bf16 v[52:55], v[76:79], v[116:119], v[52:55]
	ds_read_b128 v[96:99], v162 offset:24576
	s_add_u32 m0, s38, 53248
	s_nop 0
	global_load_lds_dwordx4 v165, s[100:101]
	s_waitcnt lgkmcnt(8)
	v_mfma_f32_16x16x32_bf16 v[24:27], v[72:75], v[120:123], v[24:27]
	v_mfma_f32_16x16x32_bf16 v[56:59], v[76:79], v[120:123], v[56:59]
	ds_read_b128 v[100:103], v162 offset:26624
	s_add_u32 m0, s38, 57344
	s_nop 0
	global_load_lds_dwordx4 v166, s[100:101]
	s_waitcnt lgkmcnt(8)
	v_mfma_f32_16x16x32_bf16 v[28:31], v[72:75], v[124:127], v[28:31]
	v_mfma_f32_16x16x32_bf16 v[60:63], v[76:79], v[124:127], v[60:63]
	ds_read_b128 v[104:107], v162 offset:28672
	s_add_u32 m0, s38, 61440
	s_nop 0
	global_load_lds_dwordx4 v167, s[100:101]
	s_add_u32 s100, s100, 128
	s_addc_u32 s101, s101, 0
	s_waitcnt lgkmcnt(6)
	v_mfma_f32_16x16x32_bf16 v[0:3], v[64:67], v[80:83], v[0:3]
	v_mfma_f32_16x16x32_bf16 v[32:35], v[68:71], v[80:83], v[32:35]
	ds_read_b128 v[108:111], v162 offset:30720
	s_waitcnt lgkmcnt(6)
	v_mfma_f32_16x16x32_bf16 v[4:7], v[64:67], v[84:87], v[4:7]
	v_mfma_f32_16x16x32_bf16 v[36:39], v[68:71], v[84:87], v[36:39]
	ds_read_b128 v[72:75], v151 offset:0
	ds_read_b128 v[76:79], v151 offset:2048
	ds_read_b128 v[112:115], v163 offset:16384
	s_waitcnt lgkmcnt(8)
	v_mfma_f32_16x16x32_bf16 v[8:11], v[64:67], v[88:91], v[8:11]
	v_mfma_f32_16x16x32_bf16 v[40:43], v[68:71], v[88:91], v[40:43]
	ds_read_b128 v[116:119], v163 offset:18432
	s_waitcnt lgkmcnt(8)
	v_mfma_f32_16x16x32_bf16 v[12:15], v[64:67], v[92:95], v[12:15]
	v_mfma_f32_16x16x32_bf16 v[44:47], v[68:71], v[92:95], v[44:47]
	ds_read_b128 v[120:123], v163 offset:20480
	s_waitcnt lgkmcnt(8)
	v_mfma_f32_16x16x32_bf16 v[16:19], v[64:67], v[96:99], v[16:19]
	v_mfma_f32_16x16x32_bf16 v[48:51], v[68:71], v[96:99], v[48:51]
	ds_read_b128 v[124:127], v163 offset:22528
	s_waitcnt lgkmcnt(8)
	v_mfma_f32_16x16x32_bf16 v[20:23], v[64:67], v[100:103], v[20:23]
	v_mfma_f32_16x16x32_bf16 v[52:55], v[68:71], v[100:103], v[52:55]
	ds_read_b128 v[80:83], v163 offset:24576
	s_waitcnt lgkmcnt(8)
	v_mfma_f32_16x16x32_bf16 v[24:27], v[64:67], v[104:107], v[24:27]
	v_mfma_f32_16x16x32_bf16 v[56:59], v[68:71], v[104:107], v[56:59]
	ds_read_b128 v[84:87], v163 offset:26624
	s_waitcnt lgkmcnt(8)
	v_mfma_f32_16x16x32_bf16 v[28:31], v[64:67], v[108:111], v[28:31]
	v_mfma_f32_16x16x32_bf16 v[60:63], v[68:71], v[108:111], v[60:63]
	ds_read_b128 v[88:91], v163 offset:28672
	s_waitcnt lgkmcnt(6)
	v_mfma_f32_16x16x32_bf16 v[0:3], v[72:75], v[112:115], v[0:3]
	v_mfma_f32_16x16x32_bf16 v[32:35], v[76:79], v[112:115], v[32:35]
	ds_read_b128 v[92:95], v163 offset:30720
	s_waitcnt vmcnt(0) lgkmcnt(0)
	s_barrier
	s_add_u32 m0, s38, 0
	s_nop 0
	global_load_lds_dwordx4 v164, s[98:99]
	s_waitcnt lgkmcnt(6)
	v_mfma_f32_16x16x32_bf16 v[4:7], v[72:75], v[116:119], v[4:7]
	v_mfma_f32_16x16x32_bf16 v[36:39], v[76:79], v[116:119], v[36:39]
	ds_read_b128 v[64:67], v150 offset:32768
	ds_read_b128 v[68:71], v150 offset:34816
	ds_read_b128 v[96:99], v162 offset:49152
	s_add_u32 m0, s38, 4096
	s_nop 0
	global_load_lds_dwordx4 v165, s[98:99]
	s_waitcnt lgkmcnt(8)
	v_mfma_f32_16x16x32_bf16 v[8:11], v[72:75], v[120:123], v[8:11]
	v_mfma_f32_16x16x32_bf16 v[40:43], v[76:79], v[120:123], v[40:43]
	ds_read_b128 v[100:103], v162 offset:51200
	s_add_u32 m0, s38, 8192
	s_nop 0
	global_load_lds_dwordx4 v166, s[98:99]
	s_waitcnt lgkmcnt(8)
	v_mfma_f32_16x16x32_bf16 v[12:15], v[72:75], v[124:127], v[12:15]
	v_mfma_f32_16x16x32_bf16 v[44:47], v[76:79], v[124:127], v[44:47]
	ds_read_b128 v[104:107], v162 offset:53248
	s_add_u32 m0, s38, 12288
	s_nop 0
	global_load_lds_dwordx4 v167, s[98:99]
	s_add_u32 s98, s98, 128
	s_addc_u32 s99, s99, 0
	s_waitcnt lgkmcnt(8)
	v_mfma_f32_16x16x32_bf16 v[16:19], v[72:75], v[80:83], v[16:19]
	v_mfma_f32_16x16x32_bf16 v[48:51], v[76:79], v[80:83], v[48:51]
	ds_read_b128 v[108:111], v162 offset:55296
	s_add_u32 m0, s38, 16384
	s_nop 0
	global_load_lds_dwordx4 v164, s[100:101]
	s_waitcnt lgkmcnt(8)
	v_mfma_f32_16x16x32_bf16 v[20:23], v[72:75], v[84:87], v[20:23]
	v_mfma_f32_16x16x32_bf16 v[52:55], v[76:79], v[84:87], v[52:55]
	ds_read_b128 v[112:115], v162 offset:57344
	s_add_u32 m0, s38, 20480
	s_nop 0
	global_load_lds_dwordx4 v165, s[100:101]
	s_waitcnt lgkmcnt(8)
	v_mfma_f32_16x16x32_bf16 v[24:27], v[72:75], v[88:91], v[24:27]
	v_mfma_f32_16x16x32_bf16 v[56:59], v[76:79], v[88:91], v[56:59]
	ds_read_b128 v[116:119], v162 offset:59392
	s_add_u32 m0, s38, 24576
	s_nop 0
	global_load_lds_dwordx4 v166, s[100:101]
	s_waitcnt lgkmcnt(8)
	v_mfma_f32_16x16x32_bf16 v[28:31], v[72:75], v[92:95], v[28:31]
	v_mfma_f32_16x16x32_bf16 v[60:63], v[76:79], v[92:95], v[60:63]
	ds_read_b128 v[120:123], v162 offset:61440
	s_add_u32 m0, s38, 28672
	s_nop 0
	global_load_lds_dwordx4 v167, s[100:101]
	s_add_u32 s100, s100, 128
	s_addc_u32 s101, s101, 0
	s_waitcnt lgkmcnt(6)
	v_mfma_f32_16x16x32_bf16 v[0:3], v[64:67], v[96:99], v[0:3]
	v_mfma_f32_16x16x32_bf16 v[32:35], v[68:71], v[96:99], v[32:35]
	ds_read_b128 v[124:127], v162 offset:63488
	s_waitcnt lgkmcnt(6)
	v_mfma_f32_16x16x32_bf16 v[4:7], v[64:67], v[100:103], v[4:7]
	v_mfma_f32_16x16x32_bf16 v[36:39], v[68:71], v[100:103], v[36:39]
	ds_read_b128 v[72:75], v151 offset:32768
	ds_read_b128 v[76:79], v151 offset:34816
	ds_read_b128 v[80:83], v163 offset:49152
	s_waitcnt lgkmcnt(8)
	v_mfma_f32_16x16x32_bf16 v[8:11], v[64:67], v[104:107], v[8:11]
	v_mfma_f32_16x16x32_bf16 v[40:43], v[68:71], v[104:107], v[40:43]
	ds_read_b128 v[84:87], v163 offset:51200
	s_waitcnt lgkmcnt(8)
	v_mfma_f32_16x16x32_bf16 v[12:15], v[64:67], v[108:111], v[12:15]
	v_mfma_f32_16x16x32_bf16 v[44:47], v[68:71], v[108:111], v[44:47]
	ds_read_b128 v[88:91], v163 offset:53248
	s_waitcnt lgkmcnt(8)
	v_mfma_f32_16x16x32_bf16 v[16:19], v[64:67], v[112:115], v[16:19]
	v_mfma_f32_16x16x32_bf16 v[48:51], v[68:71], v[112:115], v[48:51]
	ds_read_b128 v[92:95], v163 offset:55296
	s_waitcnt lgkmcnt(8)
	v_mfma_f32_16x16x32_bf16 v[20:23], v[64:67], v[116:119], v[20:23]
	v_mfma_f32_16x16x32_bf16 v[52:55], v[68:71], v[116:119], v[52:55]
	ds_read_b128 v[96:99], v163 offset:57344
	s_waitcnt lgkmcnt(8)
	v_mfma_f32_16x16x32_bf16 v[24:27], v[64:67], v[120:123], v[24:27]
	v_mfma_f32_16x16x32_bf16 v[56:59], v[68:71], v[120:123], v[56:59]
	ds_read_b128 v[100:103], v163 offset:59392
	s_waitcnt lgkmcnt(8)
	v_mfma_f32_16x16x32_bf16 v[28:31], v[64:67], v[124:127], v[28:31]
	v_mfma_f32_16x16x32_bf16 v[60:63], v[68:71], v[124:127], v[60:63]
	ds_read_b128 v[104:107], v163 offset:61440
	s_waitcnt lgkmcnt(6)
	v_mfma_f32_16x16x32_bf16 v[0:3], v[72:75], v[80:83], v[0:3]
	v_mfma_f32_16x16x32_bf16 v[32:35], v[76:79], v[80:83], v[32:35]
	ds_read_b128 v[108:111], v163 offset:63488
	s_waitcnt vmcnt(0) lgkmcnt(0)
	s_barrier
	s_add_u32 m0, s38, 32768
	s_nop 0
	global_load_lds_dwordx4 v164, s[98:99]
	s_waitcnt lgkmcnt(6)
	v_mfma_f32_16x16x32_bf16 v[4:7], v[72:75], v[84:87], v[4:7]
	v_mfma_f32_16x16x32_bf16 v[36:39], v[76:79], v[84:87], v[36:39]
	ds_read_b128 v[64:67], v150 offset:0
	ds_read_b128 v[68:71], v150 offset:2048
	ds_read_b128 v[112:115], v162 offset:16384
	s_add_u32 m0, s38, 36864
	s_nop 0
	global_load_lds_dwordx4 v165, s[98:99]
	s_waitcnt lgkmcnt(8)
	v_mfma_f32_16x16x32_bf16 v[8:11], v[72:75], v[88:91], v[8:11]
	v_mfma_f32_16x16x32_bf16 v[40:43], v[76:79], v[88:91], v[40:43]
	ds_read_b128 v[116:119], v162 offset:18432
	s_add_u32 m0, s38, 40960
	s_nop 0
	global_load_lds_dwordx4 v166, s[98:99]
	s_waitcnt lgkmcnt(8)
	v_mfma_f32_16x16x32_bf16 v[12:15], v[72:75], v[92:95], v[12:15]
	v_mfma_f32_16x16x32_bf16 v[44:47], v[76:79], v[92:95], v[44:47]
	ds_read_b128 v[120:123], v162 offset:20480
	s_add_u32 m0, s38, 45056
	s_nop 0
	global_load_lds_dwordx4 v167, s[98:99]
	s_add_u32 s98, s98, 128
	s_addc_u32 s99, s99, 0
	s_waitcnt lgkmcnt(8)
	v_mfma_f32_16x16x32_bf16 v[16:19], v[72:75], v[96:99], v[16:19]
	v_mfma_f32_16x16x32_bf16 v[48:51], v[76:79], v[96:99], v[48:51]
	ds_read_b128 v[124:127], v162 offset:22528
	s_add_u32 m0, s38, 49152
	s_nop 0
	global_load_lds_dwordx4 v164, s[100:101]
	s_waitcnt lgkmcnt(8)
	v_mfma_f32_16x16x32_bf16 v[20:23], v[72:75], v[100:103], v[20:23]
	v_mfma_f32_16x16x32_bf16 v[52:55], v[76:79], v[100:103], v[52:55]
	ds_read_b128 v[80:83], v162 offset:24576
	s_add_u32 m0, s38, 53248
	s_nop 0
	global_load_lds_dwordx4 v165, s[100:101]
	s_waitcnt lgkmcnt(8)
	v_mfma_f32_16x16x32_bf16 v[24:27], v[72:75], v[104:107], v[24:27]
	v_mfma_f32_16x16x32_bf16 v[56:59], v[76:79], v[104:107], v[56:59]
	ds_read_b128 v[84:87], v162 offset:26624
	s_add_u32 m0, s38, 57344
	s_nop 0
	global_load_lds_dwordx4 v166, s[100:101]
	s_waitcnt lgkmcnt(8)
	v_mfma_f32_16x16x32_bf16 v[28:31], v[72:75], v[108:111], v[28:31]
	v_mfma_f32_16x16x32_bf16 v[60:63], v[76:79], v[108:111], v[60:63]
	ds_read_b128 v[88:91], v162 offset:28672
	s_add_u32 m0, s38, 61440
	s_nop 0
	global_load_lds_dwordx4 v167, s[100:101]
	s_add_u32 s100, s100, 128
	s_addc_u32 s101, s101, 0
	s_waitcnt lgkmcnt(6)
	v_mfma_f32_16x16x32_bf16 v[0:3], v[64:67], v[112:115], v[0:3]
	v_mfma_f32_16x16x32_bf16 v[32:35], v[68:71], v[112:115], v[32:35]
	ds_read_b128 v[92:95], v162 offset:30720
	s_waitcnt lgkmcnt(6)
	v_mfma_f32_16x16x32_bf16 v[4:7], v[64:67], v[116:119], v[4:7]
	v_mfma_f32_16x16x32_bf16 v[36:39], v[68:71], v[116:119], v[36:39]
	ds_read_b128 v[72:75], v151 offset:0
	ds_read_b128 v[76:79], v151 offset:2048
	ds_read_b128 v[96:99], v163 offset:16384
	s_waitcnt lgkmcnt(8)
	v_mfma_f32_16x16x32_bf16 v[8:11], v[64:67], v[120:123], v[8:11]
	v_mfma_f32_16x16x32_bf16 v[40:43], v[68:71], v[120:123], v[40:43]
	ds_read_b128 v[100:103], v163 offset:18432
	s_waitcnt lgkmcnt(8)
	v_mfma_f32_16x16x32_bf16 v[12:15], v[64:67], v[124:127], v[12:15]
	v_mfma_f32_16x16x32_bf16 v[44:47], v[68:71], v[124:127], v[44:47]
	ds_read_b128 v[104:107], v163 offset:20480
	s_waitcnt lgkmcnt(8)
	v_mfma_f32_16x16x32_bf16 v[16:19], v[64:67], v[80:83], v[16:19]
	v_mfma_f32_16x16x32_bf16 v[48:51], v[68:71], v[80:83], v[48:51]
	ds_read_b128 v[108:111], v163 offset:22528
	s_waitcnt lgkmcnt(8)
	v_mfma_f32_16x16x32_bf16 v[20:23], v[64:67], v[84:87], v[20:23]
	v_mfma_f32_16x16x32_bf16 v[52:55], v[68:71], v[84:87], v[52:55]
	ds_read_b128 v[112:115], v163 offset:24576
	s_waitcnt lgkmcnt(8)
	v_mfma_f32_16x16x32_bf16 v[24:27], v[64:67], v[88:91], v[24:27]
	v_mfma_f32_16x16x32_bf16 v[56:59], v[68:71], v[88:91], v[56:59]
	ds_read_b128 v[116:119], v163 offset:26624
	s_waitcnt lgkmcnt(8)
	v_mfma_f32_16x16x32_bf16 v[28:31], v[64:67], v[92:95], v[28:31]
	v_mfma_f32_16x16x32_bf16 v[60:63], v[68:71], v[92:95], v[60:63]
	ds_read_b128 v[120:123], v163 offset:28672
	s_waitcnt lgkmcnt(6)
	v_mfma_f32_16x16x32_bf16 v[0:3], v[72:75], v[96:99], v[0:3]
	v_mfma_f32_16x16x32_bf16 v[32:35], v[76:79], v[96:99], v[32:35]
	ds_read_b128 v[124:127], v163 offset:30720
	s_waitcnt vmcnt(0) lgkmcnt(0)
	s_barrier
	s_add_u32 m0, s38, 0
	s_nop 0
	global_load_lds_dwordx4 v164, s[98:99]
	s_waitcnt lgkmcnt(6)
	v_mfma_f32_16x16x32_bf16 v[4:7], v[72:75], v[100:103], v[4:7]
	v_mfma_f32_16x16x32_bf16 v[36:39], v[76:79], v[100:103], v[36:39]
	ds_read_b128 v[64:67], v150 offset:32768
	ds_read_b128 v[68:71], v150 offset:34816
	ds_read_b128 v[80:83], v162 offset:49152
	s_add_u32 m0, s38, 4096
	s_nop 0
	global_load_lds_dwordx4 v165, s[98:99]
	s_waitcnt lgkmcnt(8)
	v_mfma_f32_16x16x32_bf16 v[8:11], v[72:75], v[104:107], v[8:11]
	v_mfma_f32_16x16x32_bf16 v[40:43], v[76:79], v[104:107], v[40:43]
	ds_read_b128 v[84:87], v162 offset:51200
	s_add_u32 m0, s38, 8192
	s_nop 0
	global_load_lds_dwordx4 v166, s[98:99]
	s_waitcnt lgkmcnt(8)
	v_mfma_f32_16x16x32_bf16 v[12:15], v[72:75], v[108:111], v[12:15]
	v_mfma_f32_16x16x32_bf16 v[44:47], v[76:79], v[108:111], v[44:47]
	ds_read_b128 v[88:91], v162 offset:53248
	s_add_u32 m0, s38, 12288
	s_nop 0
	global_load_lds_dwordx4 v167, s[98:99]
	s_add_u32 s98, s98, 128
	s_addc_u32 s99, s99, 0
	s_waitcnt lgkmcnt(8)
	v_mfma_f32_16x16x32_bf16 v[16:19], v[72:75], v[112:115], v[16:19]
	v_mfma_f32_16x16x32_bf16 v[48:51], v[76:79], v[112:115], v[48:51]
	ds_read_b128 v[92:95], v162 offset:55296
	s_add_u32 m0, s38, 16384
	s_nop 0
	global_load_lds_dwordx4 v164, s[100:101]
	s_waitcnt lgkmcnt(8)
	v_mfma_f32_16x16x32_bf16 v[20:23], v[72:75], v[116:119], v[20:23]
	v_mfma_f32_16x16x32_bf16 v[52:55], v[76:79], v[116:119], v[52:55]
	ds_read_b128 v[96:99], v162 offset:57344
	s_add_u32 m0, s38, 20480
	s_nop 0
	global_load_lds_dwordx4 v165, s[100:101]
	s_waitcnt lgkmcnt(8)
	v_mfma_f32_16x16x32_bf16 v[24:27], v[72:75], v[120:123], v[24:27]
	v_mfma_f32_16x16x32_bf16 v[56:59], v[76:79], v[120:123], v[56:59]
	ds_read_b128 v[100:103], v162 offset:59392
	s_add_u32 m0, s38, 24576
	s_nop 0
	global_load_lds_dwordx4 v166, s[100:101]
	s_waitcnt lgkmcnt(8)
	v_mfma_f32_16x16x32_bf16 v[28:31], v[72:75], v[124:127], v[28:31]
	v_mfma_f32_16x16x32_bf16 v[60:63], v[76:79], v[124:127], v[60:63]
	ds_read_b128 v[104:107], v162 offset:61440
	s_add_u32 m0, s38, 28672
	s_nop 0
	global_load_lds_dwordx4 v167, s[100:101]
	s_add_u32 s100, s100, 128
	s_addc_u32 s101, s101, 0
	s_waitcnt lgkmcnt(6)
	v_mfma_f32_16x16x32_bf16 v[0:3], v[64:67], v[80:83], v[0:3]
	v_mfma_f32_16x16x32_bf16 v[32:35], v[68:71], v[80:83], v[32:35]
	ds_read_b128 v[108:111], v162 offset:63488
	s_waitcnt lgkmcnt(6)
	v_mfma_f32_16x16x32_bf16 v[4:7], v[64:67], v[84:87], v[4:7]
	v_mfma_f32_16x16x32_bf16 v[36:39], v[68:71], v[84:87], v[36:39]
	ds_read_b128 v[72:75], v151 offset:32768
	ds_read_b128 v[76:79], v151 offset:34816
	ds_read_b128 v[112:115], v163 offset:49152
	s_waitcnt lgkmcnt(8)
	v_mfma_f32_16x16x32_bf16 v[8:11], v[64:67], v[88:91], v[8:11]
	v_mfma_f32_16x16x32_bf16 v[40:43], v[68:71], v[88:91], v[40:43]
	ds_read_b128 v[116:119], v163 offset:51200
	s_waitcnt lgkmcnt(8)
	v_mfma_f32_16x16x32_bf16 v[12:15], v[64:67], v[92:95], v[12:15]
	v_mfma_f32_16x16x32_bf16 v[44:47], v[68:71], v[92:95], v[44:47]
	ds_read_b128 v[120:123], v163 offset:53248
	s_waitcnt lgkmcnt(8)
	v_mfma_f32_16x16x32_bf16 v[16:19], v[64:67], v[96:99], v[16:19]
	v_mfma_f32_16x16x32_bf16 v[48:51], v[68:71], v[96:99], v[48:51]
	ds_read_b128 v[124:127], v163 offset:55296
	s_waitcnt lgkmcnt(8)
	v_mfma_f32_16x16x32_bf16 v[20:23], v[64:67], v[100:103], v[20:23]
	v_mfma_f32_16x16x32_bf16 v[52:55], v[68:71], v[100:103], v[52:55]
	ds_read_b128 v[80:83], v163 offset:57344
	s_waitcnt lgkmcnt(8)
	v_mfma_f32_16x16x32_bf16 v[24:27], v[64:67], v[104:107], v[24:27]
	v_mfma_f32_16x16x32_bf16 v[56:59], v[68:71], v[104:107], v[56:59]
	ds_read_b128 v[84:87], v163 offset:59392
	s_waitcnt lgkmcnt(8)
	v_mfma_f32_16x16x32_bf16 v[28:31], v[64:67], v[108:111], v[28:31]
	v_mfma_f32_16x16x32_bf16 v[60:63], v[68:71], v[108:111], v[60:63]
	ds_read_b128 v[88:91], v163 offset:61440
	s_waitcnt lgkmcnt(6)
	v_mfma_f32_16x16x32_bf16 v[0:3], v[72:75], v[112:115], v[0:3]
	v_mfma_f32_16x16x32_bf16 v[32:35], v[76:79], v[112:115], v[32:35]
	ds_read_b128 v[92:95], v163 offset:63488
	s_waitcnt vmcnt(0) lgkmcnt(0)
	s_barrier
	s_add_u32 m0, s38, 32768
	s_nop 0
	global_load_lds_dwordx4 v164, s[98:99]
	s_waitcnt lgkmcnt(6)
	v_mfma_f32_16x16x32_bf16 v[4:7], v[72:75], v[116:119], v[4:7]
	v_mfma_f32_16x16x32_bf16 v[36:39], v[76:79], v[116:119], v[36:39]
	ds_read_b128 v[64:67], v150 offset:0
	ds_read_b128 v[68:71], v150 offset:2048
	ds_read_b128 v[96:99], v162 offset:16384
	s_add_u32 m0, s38, 36864
	s_nop 0
	global_load_lds_dwordx4 v165, s[98:99]
	s_waitcnt lgkmcnt(8)
	v_mfma_f32_16x16x32_bf16 v[8:11], v[72:75], v[120:123], v[8:11]
	v_mfma_f32_16x16x32_bf16 v[40:43], v[76:79], v[120:123], v[40:43]
	ds_read_b128 v[100:103], v162 offset:18432
	s_add_u32 m0, s38, 40960
	s_nop 0
	global_load_lds_dwordx4 v166, s[98:99]
	s_waitcnt lgkmcnt(8)
	v_mfma_f32_16x16x32_bf16 v[12:15], v[72:75], v[124:127], v[12:15]
	v_mfma_f32_16x16x32_bf16 v[44:47], v[76:79], v[124:127], v[44:47]
	ds_read_b128 v[104:107], v162 offset:20480
	s_add_u32 m0, s38, 45056
	s_nop 0
	global_load_lds_dwordx4 v167, s[98:99]
	s_add_u32 s98, s98, 128
	s_addc_u32 s99, s99, 0
	s_waitcnt lgkmcnt(8)
	v_mfma_f32_16x16x32_bf16 v[16:19], v[72:75], v[80:83], v[16:19]
	v_mfma_f32_16x16x32_bf16 v[48:51], v[76:79], v[80:83], v[48:51]
	ds_read_b128 v[108:111], v162 offset:22528
	s_add_u32 m0, s38, 49152
	s_nop 0
	global_load_lds_dwordx4 v164, s[100:101]
	s_waitcnt lgkmcnt(8)
	v_mfma_f32_16x16x32_bf16 v[20:23], v[72:75], v[84:87], v[20:23]
	v_mfma_f32_16x16x32_bf16 v[52:55], v[76:79], v[84:87], v[52:55]
	ds_read_b128 v[112:115], v162 offset:24576
	s_add_u32 m0, s38, 53248
	s_nop 0
	global_load_lds_dwordx4 v165, s[100:101]
	s_waitcnt lgkmcnt(8)
	v_mfma_f32_16x16x32_bf16 v[24:27], v[72:75], v[88:91], v[24:27]
	v_mfma_f32_16x16x32_bf16 v[56:59], v[76:79], v[88:91], v[56:59]
	ds_read_b128 v[116:119], v162 offset:26624
	s_add_u32 m0, s38, 57344
	s_nop 0
	global_load_lds_dwordx4 v166, s[100:101]
	s_waitcnt lgkmcnt(8)
	v_mfma_f32_16x16x32_bf16 v[28:31], v[72:75], v[92:95], v[28:31]
	v_mfma_f32_16x16x32_bf16 v[60:63], v[76:79], v[92:95], v[60:63]
	ds_read_b128 v[120:123], v162 offset:28672
	s_add_u32 m0, s38, 61440
	s_nop 0
	global_load_lds_dwordx4 v167, s[100:101]
	s_add_u32 s100, s100, 128
	s_addc_u32 s101, s101, 0
	s_waitcnt lgkmcnt(6)
	v_mfma_f32_16x16x32_bf16 v[0:3], v[64:67], v[96:99], v[0:3]
	v_mfma_f32_16x16x32_bf16 v[32:35], v[68:71], v[96:99], v[32:35]
	ds_read_b128 v[124:127], v162 offset:30720
	s_waitcnt lgkmcnt(6)
	v_mfma_f32_16x16x32_bf16 v[4:7], v[64:67], v[100:103], v[4:7]
	v_mfma_f32_16x16x32_bf16 v[36:39], v[68:71], v[100:103], v[36:39]
	ds_read_b128 v[72:75], v151 offset:0
	ds_read_b128 v[76:79], v151 offset:2048
	ds_read_b128 v[80:83], v163 offset:16384
	s_waitcnt lgkmcnt(8)
	v_mfma_f32_16x16x32_bf16 v[8:11], v[64:67], v[104:107], v[8:11]
	v_mfma_f32_16x16x32_bf16 v[40:43], v[68:71], v[104:107], v[40:43]
	ds_read_b128 v[84:87], v163 offset:18432
	s_waitcnt lgkmcnt(8)
	v_mfma_f32_16x16x32_bf16 v[12:15], v[64:67], v[108:111], v[12:15]
	v_mfma_f32_16x16x32_bf16 v[44:47], v[68:71], v[108:111], v[44:47]
	ds_read_b128 v[88:91], v163 offset:20480
	s_waitcnt lgkmcnt(8)
	v_mfma_f32_16x16x32_bf16 v[16:19], v[64:67], v[112:115], v[16:19]
	v_mfma_f32_16x16x32_bf16 v[48:51], v[68:71], v[112:115], v[48:51]
	ds_read_b128 v[92:95], v163 offset:22528
	s_waitcnt lgkmcnt(8)
	v_mfma_f32_16x16x32_bf16 v[20:23], v[64:67], v[116:119], v[20:23]
	v_mfma_f32_16x16x32_bf16 v[52:55], v[68:71], v[116:119], v[52:55]
	ds_read_b128 v[96:99], v163 offset:24576
	s_waitcnt lgkmcnt(8)
	v_mfma_f32_16x16x32_bf16 v[24:27], v[64:67], v[120:123], v[24:27]
	v_mfma_f32_16x16x32_bf16 v[56:59], v[68:71], v[120:123], v[56:59]
	ds_read_b128 v[100:103], v163 offset:26624
	s_waitcnt lgkmcnt(8)
	v_mfma_f32_16x16x32_bf16 v[28:31], v[64:67], v[124:127], v[28:31]
	v_mfma_f32_16x16x32_bf16 v[60:63], v[68:71], v[124:127], v[60:63]
	ds_read_b128 v[104:107], v163 offset:28672
	s_waitcnt lgkmcnt(6)
	v_mfma_f32_16x16x32_bf16 v[0:3], v[72:75], v[80:83], v[0:3]
	v_mfma_f32_16x16x32_bf16 v[32:35], v[76:79], v[80:83], v[32:35]
	ds_read_b128 v[108:111], v163 offset:30720
	s_waitcnt vmcnt(0) lgkmcnt(0)
	s_barrier
	s_add_u32 m0, s38, 0
	s_nop 0
	global_load_lds_dwordx4 v164, s[98:99]
	s_waitcnt lgkmcnt(6)
	v_mfma_f32_16x16x32_bf16 v[4:7], v[72:75], v[84:87], v[4:7]
	v_mfma_f32_16x16x32_bf16 v[36:39], v[76:79], v[84:87], v[36:39]
	ds_read_b128 v[64:67], v150 offset:32768
	ds_read_b128 v[68:71], v150 offset:34816
	ds_read_b128 v[112:115], v162 offset:49152
	s_add_u32 m0, s38, 4096
	s_nop 0
	global_load_lds_dwordx4 v165, s[98:99]
	s_waitcnt lgkmcnt(8)
	v_mfma_f32_16x16x32_bf16 v[8:11], v[72:75], v[88:91], v[8:11]
	v_mfma_f32_16x16x32_bf16 v[40:43], v[76:79], v[88:91], v[40:43]
	ds_read_b128 v[116:119], v162 offset:51200
	s_add_u32 m0, s38, 8192
	s_nop 0
	global_load_lds_dwordx4 v166, s[98:99]
	s_waitcnt lgkmcnt(8)
	v_mfma_f32_16x16x32_bf16 v[12:15], v[72:75], v[92:95], v[12:15]
	v_mfma_f32_16x16x32_bf16 v[44:47], v[76:79], v[92:95], v[44:47]
	ds_read_b128 v[120:123], v162 offset:53248
	s_add_u32 m0, s38, 12288
	s_nop 0
	global_load_lds_dwordx4 v167, s[98:99]
	s_add_u32 s98, s98, 128
	s_addc_u32 s99, s99, 0
	s_waitcnt lgkmcnt(8)
	v_mfma_f32_16x16x32_bf16 v[16:19], v[72:75], v[96:99], v[16:19]
	v_mfma_f32_16x16x32_bf16 v[48:51], v[76:79], v[96:99], v[48:51]
	ds_read_b128 v[124:127], v162 offset:55296
	s_add_u32 m0, s38, 16384
	s_nop 0
	global_load_lds_dwordx4 v164, s[100:101]
	s_waitcnt lgkmcnt(8)
	v_mfma_f32_16x16x32_bf16 v[20:23], v[72:75], v[100:103], v[20:23]
	v_mfma_f32_16x16x32_bf16 v[52:55], v[76:79], v[100:103], v[52:55]
	ds_read_b128 v[80:83], v162 offset:57344
	s_add_u32 m0, s38, 20480
	s_nop 0
	global_load_lds_dwordx4 v165, s[100:101]
	s_waitcnt lgkmcnt(8)
	v_mfma_f32_16x16x32_bf16 v[24:27], v[72:75], v[104:107], v[24:27]
	v_mfma_f32_16x16x32_bf16 v[56:59], v[76:79], v[104:107], v[56:59]
	ds_read_b128 v[84:87], v162 offset:59392
	s_add_u32 m0, s38, 24576
	s_nop 0
	global_load_lds_dwordx4 v166, s[100:101]
	s_waitcnt lgkmcnt(8)
	v_mfma_f32_16x16x32_bf16 v[28:31], v[72:75], v[108:111], v[28:31]
	v_mfma_f32_16x16x32_bf16 v[60:63], v[76:79], v[108:111], v[60:63]
	ds_read_b128 v[88:91], v162 offset:61440
	s_add_u32 m0, s38, 28672
	s_nop 0
	global_load_lds_dwordx4 v167, s[100:101]
	s_add_u32 s100, s100, 128
	s_addc_u32 s101, s101, 0
	s_waitcnt lgkmcnt(6)
	v_mfma_f32_16x16x32_bf16 v[0:3], v[64:67], v[112:115], v[0:3]
	v_mfma_f32_16x16x32_bf16 v[32:35], v[68:71], v[112:115], v[32:35]
	ds_read_b128 v[92:95], v162 offset:63488
	s_waitcnt lgkmcnt(6)
	v_mfma_f32_16x16x32_bf16 v[4:7], v[64:67], v[116:119], v[4:7]
	v_mfma_f32_16x16x32_bf16 v[36:39], v[68:71], v[116:119], v[36:39]
	ds_read_b128 v[72:75], v151 offset:32768
	ds_read_b128 v[76:79], v151 offset:34816
	ds_read_b128 v[96:99], v163 offset:49152
	s_waitcnt lgkmcnt(8)
	v_mfma_f32_16x16x32_bf16 v[8:11], v[64:67], v[120:123], v[8:11]
	v_mfma_f32_16x16x32_bf16 v[40:43], v[68:71], v[120:123], v[40:43]
	ds_read_b128 v[100:103], v163 offset:51200
	s_waitcnt lgkmcnt(8)
	v_mfma_f32_16x16x32_bf16 v[12:15], v[64:67], v[124:127], v[12:15]
	v_mfma_f32_16x16x32_bf16 v[44:47], v[68:71], v[124:127], v[44:47]
	ds_read_b128 v[104:107], v163 offset:53248
	s_waitcnt lgkmcnt(8)
	v_mfma_f32_16x16x32_bf16 v[16:19], v[64:67], v[80:83], v[16:19]
	v_mfma_f32_16x16x32_bf16 v[48:51], v[68:71], v[80:83], v[48:51]
	ds_read_b128 v[108:111], v163 offset:55296
	s_waitcnt lgkmcnt(8)
	v_mfma_f32_16x16x32_bf16 v[20:23], v[64:67], v[84:87], v[20:23]
	v_mfma_f32_16x16x32_bf16 v[52:55], v[68:71], v[84:87], v[52:55]
	ds_read_b128 v[112:115], v163 offset:57344
	s_waitcnt lgkmcnt(8)
	v_mfma_f32_16x16x32_bf16 v[24:27], v[64:67], v[88:91], v[24:27]
	v_mfma_f32_16x16x32_bf16 v[56:59], v[68:71], v[88:91], v[56:59]
	ds_read_b128 v[116:119], v163 offset:59392
	s_waitcnt lgkmcnt(8)
	v_mfma_f32_16x16x32_bf16 v[28:31], v[64:67], v[92:95], v[28:31]
	v_mfma_f32_16x16x32_bf16 v[60:63], v[68:71], v[92:95], v[60:63]
	ds_read_b128 v[120:123], v163 offset:61440
	s_waitcnt lgkmcnt(6)
	v_mfma_f32_16x16x32_bf16 v[0:3], v[72:75], v[96:99], v[0:3]
	v_mfma_f32_16x16x32_bf16 v[32:35], v[76:79], v[96:99], v[32:35]
	ds_read_b128 v[124:127], v163 offset:63488
	s_waitcnt vmcnt(0) lgkmcnt(0)
	s_barrier
	s_add_u32 m0, s38, 32768
	s_nop 0
	global_load_lds_dwordx4 v164, s[98:99]
	s_waitcnt lgkmcnt(6)
	v_mfma_f32_16x16x32_bf16 v[4:7], v[72:75], v[100:103], v[4:7]
	v_mfma_f32_16x16x32_bf16 v[36:39], v[76:79], v[100:103], v[36:39]
	ds_read_b128 v[64:67], v150 offset:0
	ds_read_b128 v[68:71], v150 offset:2048
	ds_read_b128 v[80:83], v162 offset:16384
	s_add_u32 m0, s38, 36864
	s_nop 0
	global_load_lds_dwordx4 v165, s[98:99]
	s_waitcnt lgkmcnt(8)
	v_mfma_f32_16x16x32_bf16 v[8:11], v[72:75], v[104:107], v[8:11]
	v_mfma_f32_16x16x32_bf16 v[40:43], v[76:79], v[104:107], v[40:43]
	ds_read_b128 v[84:87], v162 offset:18432
	s_add_u32 m0, s38, 40960
	s_nop 0
	global_load_lds_dwordx4 v166, s[98:99]
	s_waitcnt lgkmcnt(8)
	v_mfma_f32_16x16x32_bf16 v[12:15], v[72:75], v[108:111], v[12:15]
	v_mfma_f32_16x16x32_bf16 v[44:47], v[76:79], v[108:111], v[44:47]
	ds_read_b128 v[88:91], v162 offset:20480
	s_add_u32 m0, s38, 45056
	s_nop 0
	global_load_lds_dwordx4 v167, s[98:99]
	s_add_u32 s98, s98, 128
	s_addc_u32 s99, s99, 0
	s_waitcnt lgkmcnt(8)
	v_mfma_f32_16x16x32_bf16 v[16:19], v[72:75], v[112:115], v[16:19]
	v_mfma_f32_16x16x32_bf16 v[48:51], v[76:79], v[112:115], v[48:51]
	ds_read_b128 v[92:95], v162 offset:22528
	s_add_u32 m0, s38, 49152
	s_nop 0
	global_load_lds_dwordx4 v164, s[100:101]
	s_waitcnt lgkmcnt(8)
	v_mfma_f32_16x16x32_bf16 v[20:23], v[72:75], v[116:119], v[20:23]
	v_mfma_f32_16x16x32_bf16 v[52:55], v[76:79], v[116:119], v[52:55]
	ds_read_b128 v[96:99], v162 offset:24576
	s_add_u32 m0, s38, 53248
	s_nop 0
	global_load_lds_dwordx4 v165, s[100:101]
	s_waitcnt lgkmcnt(8)
	v_mfma_f32_16x16x32_bf16 v[24:27], v[72:75], v[120:123], v[24:27]
	v_mfma_f32_16x16x32_bf16 v[56:59], v[76:79], v[120:123], v[56:59]
	ds_read_b128 v[100:103], v162 offset:26624
	s_add_u32 m0, s38, 57344
	s_nop 0
	global_load_lds_dwordx4 v166, s[100:101]
	s_waitcnt lgkmcnt(8)
	v_mfma_f32_16x16x32_bf16 v[28:31], v[72:75], v[124:127], v[28:31]
	v_mfma_f32_16x16x32_bf16 v[60:63], v[76:79], v[124:127], v[60:63]
	ds_read_b128 v[104:107], v162 offset:28672
	s_add_u32 m0, s38, 61440
	s_nop 0
	global_load_lds_dwordx4 v167, s[100:101]
	s_add_u32 s100, s100, 128
	s_addc_u32 s101, s101, 0
	s_waitcnt lgkmcnt(6)
	v_mfma_f32_16x16x32_bf16 v[0:3], v[64:67], v[80:83], v[0:3]
	v_mfma_f32_16x16x32_bf16 v[32:35], v[68:71], v[80:83], v[32:35]
	ds_read_b128 v[108:111], v162 offset:30720
	s_waitcnt lgkmcnt(6)
	v_mfma_f32_16x16x32_bf16 v[4:7], v[64:67], v[84:87], v[4:7]
	v_mfma_f32_16x16x32_bf16 v[36:39], v[68:71], v[84:87], v[36:39]
	ds_read_b128 v[72:75], v151 offset:0
	ds_read_b128 v[76:79], v151 offset:2048
	ds_read_b128 v[112:115], v163 offset:16384
	s_waitcnt lgkmcnt(8)
	v_mfma_f32_16x16x32_bf16 v[8:11], v[64:67], v[88:91], v[8:11]
	v_mfma_f32_16x16x32_bf16 v[40:43], v[68:71], v[88:91], v[40:43]
	ds_read_b128 v[116:119], v163 offset:18432
	s_waitcnt lgkmcnt(8)
	v_mfma_f32_16x16x32_bf16 v[12:15], v[64:67], v[92:95], v[12:15]
	v_mfma_f32_16x16x32_bf16 v[44:47], v[68:71], v[92:95], v[44:47]
	ds_read_b128 v[120:123], v163 offset:20480
	s_waitcnt lgkmcnt(8)
	v_mfma_f32_16x16x32_bf16 v[16:19], v[64:67], v[96:99], v[16:19]
	v_mfma_f32_16x16x32_bf16 v[48:51], v[68:71], v[96:99], v[48:51]
	ds_read_b128 v[124:127], v163 offset:22528
	s_waitcnt lgkmcnt(8)
	v_mfma_f32_16x16x32_bf16 v[20:23], v[64:67], v[100:103], v[20:23]
	v_mfma_f32_16x16x32_bf16 v[52:55], v[68:71], v[100:103], v[52:55]
	ds_read_b128 v[80:83], v163 offset:24576
	s_waitcnt lgkmcnt(8)
	v_mfma_f32_16x16x32_bf16 v[24:27], v[64:67], v[104:107], v[24:27]
	v_mfma_f32_16x16x32_bf16 v[56:59], v[68:71], v[104:107], v[56:59]
	ds_read_b128 v[84:87], v163 offset:26624
	s_waitcnt lgkmcnt(8)
	v_mfma_f32_16x16x32_bf16 v[28:31], v[64:67], v[108:111], v[28:31]
	v_mfma_f32_16x16x32_bf16 v[60:63], v[68:71], v[108:111], v[60:63]
	ds_read_b128 v[88:91], v163 offset:28672
	s_waitcnt lgkmcnt(6)
	v_mfma_f32_16x16x32_bf16 v[0:3], v[72:75], v[112:115], v[0:3]
	v_mfma_f32_16x16x32_bf16 v[32:35], v[76:79], v[112:115], v[32:35]
	ds_read_b128 v[92:95], v163 offset:30720
	s_waitcnt vmcnt(0) lgkmcnt(0)
	s_barrier
	s_add_u32 m0, s38, 0
	s_nop 0
	global_load_lds_dwordx4 v164, s[98:99]
	s_waitcnt lgkmcnt(6)
	v_mfma_f32_16x16x32_bf16 v[4:7], v[72:75], v[116:119], v[4:7]
	v_mfma_f32_16x16x32_bf16 v[36:39], v[76:79], v[116:119], v[36:39]
	ds_read_b128 v[64:67], v150 offset:32768
	ds_read_b128 v[68:71], v150 offset:34816
	ds_read_b128 v[96:99], v162 offset:49152
	s_add_u32 m0, s38, 4096
	s_nop 0
	global_load_lds_dwordx4 v165, s[98:99]
	s_waitcnt lgkmcnt(8)
	v_mfma_f32_16x16x32_bf16 v[8:11], v[72:75], v[120:123], v[8:11]
	v_mfma_f32_16x16x32_bf16 v[40:43], v[76:79], v[120:123], v[40:43]
	ds_read_b128 v[100:103], v162 offset:51200
	s_add_u32 m0, s38, 8192
	s_nop 0
	global_load_lds_dwordx4 v166, s[98:99]
	s_waitcnt lgkmcnt(8)
	v_mfma_f32_16x16x32_bf16 v[12:15], v[72:75], v[124:127], v[12:15]
	v_mfma_f32_16x16x32_bf16 v[44:47], v[76:79], v[124:127], v[44:47]
	ds_read_b128 v[104:107], v162 offset:53248
	s_add_u32 m0, s38, 12288
	s_nop 0
	global_load_lds_dwordx4 v167, s[98:99]
	s_add_u32 s98, s98, 128
	s_addc_u32 s99, s99, 0
	s_waitcnt lgkmcnt(8)
	v_mfma_f32_16x16x32_bf16 v[16:19], v[72:75], v[80:83], v[16:19]
	v_mfma_f32_16x16x32_bf16 v[48:51], v[76:79], v[80:83], v[48:51]
	ds_read_b128 v[108:111], v162 offset:55296
	s_add_u32 m0, s38, 16384
	s_nop 0
	global_load_lds_dwordx4 v164, s[100:101]
	s_waitcnt lgkmcnt(8)
	v_mfma_f32_16x16x32_bf16 v[20:23], v[72:75], v[84:87], v[20:23]
	v_mfma_f32_16x16x32_bf16 v[52:55], v[76:79], v[84:87], v[52:55]
	ds_read_b128 v[112:115], v162 offset:57344
	s_add_u32 m0, s38, 20480
	s_nop 0
	global_load_lds_dwordx4 v165, s[100:101]
	s_waitcnt lgkmcnt(8)
	v_mfma_f32_16x16x32_bf16 v[24:27], v[72:75], v[88:91], v[24:27]
	v_mfma_f32_16x16x32_bf16 v[56:59], v[76:79], v[88:91], v[56:59]
	ds_read_b128 v[116:119], v162 offset:59392
	s_add_u32 m0, s38, 24576
	s_nop 0
	global_load_lds_dwordx4 v166, s[100:101]
	s_waitcnt lgkmcnt(8)
	v_mfma_f32_16x16x32_bf16 v[28:31], v[72:75], v[92:95], v[28:31]
	v_mfma_f32_16x16x32_bf16 v[60:63], v[76:79], v[92:95], v[60:63]
	ds_read_b128 v[120:123], v162 offset:61440
	s_add_u32 m0, s38, 28672
	s_nop 0
	global_load_lds_dwordx4 v167, s[100:101]
	s_add_u32 s100, s100, 128
	s_addc_u32 s101, s101, 0
	s_waitcnt lgkmcnt(6)
	v_mfma_f32_16x16x32_bf16 v[0:3], v[64:67], v[96:99], v[0:3]
	v_mfma_f32_16x16x32_bf16 v[32:35], v[68:71], v[96:99], v[32:35]
	ds_read_b128 v[124:127], v162 offset:63488
	s_waitcnt lgkmcnt(6)
	v_mfma_f32_16x16x32_bf16 v[4:7], v[64:67], v[100:103], v[4:7]
	v_mfma_f32_16x16x32_bf16 v[36:39], v[68:71], v[100:103], v[36:39]
	ds_read_b128 v[72:75], v151 offset:32768
	ds_read_b128 v[76:79], v151 offset:34816
	ds_read_b128 v[80:83], v163 offset:49152
	s_waitcnt lgkmcnt(8)
	v_mfma_f32_16x16x32_bf16 v[8:11], v[64:67], v[104:107], v[8:11]
	v_mfma_f32_16x16x32_bf16 v[40:43], v[68:71], v[104:107], v[40:43]
	ds_read_b128 v[84:87], v163 offset:51200
	s_waitcnt lgkmcnt(8)
	v_mfma_f32_16x16x32_bf16 v[12:15], v[64:67], v[108:111], v[12:15]
	v_mfma_f32_16x16x32_bf16 v[44:47], v[68:71], v[108:111], v[44:47]
	ds_read_b128 v[88:91], v163 offset:53248
	s_waitcnt lgkmcnt(8)
	v_mfma_f32_16x16x32_bf16 v[16:19], v[64:67], v[112:115], v[16:19]
	v_mfma_f32_16x16x32_bf16 v[48:51], v[68:71], v[112:115], v[48:51]
	ds_read_b128 v[92:95], v163 offset:55296
	s_waitcnt lgkmcnt(8)
	v_mfma_f32_16x16x32_bf16 v[20:23], v[64:67], v[116:119], v[20:23]
	v_mfma_f32_16x16x32_bf16 v[52:55], v[68:71], v[116:119], v[52:55]
	ds_read_b128 v[96:99], v163 offset:57344
	s_waitcnt lgkmcnt(8)
	v_mfma_f32_16x16x32_bf16 v[24:27], v[64:67], v[120:123], v[24:27]
	v_mfma_f32_16x16x32_bf16 v[56:59], v[68:71], v[120:123], v[56:59]
	ds_read_b128 v[100:103], v163 offset:59392
	s_waitcnt lgkmcnt(8)
	v_mfma_f32_16x16x32_bf16 v[28:31], v[64:67], v[124:127], v[28:31]
	v_mfma_f32_16x16x32_bf16 v[60:63], v[68:71], v[124:127], v[60:63]
	ds_read_b128 v[104:107], v163 offset:61440
	s_waitcnt lgkmcnt(6)
	v_mfma_f32_16x16x32_bf16 v[0:3], v[72:75], v[80:83], v[0:3]
	v_mfma_f32_16x16x32_bf16 v[32:35], v[76:79], v[80:83], v[32:35]
	ds_read_b128 v[108:111], v163 offset:63488
	s_waitcnt vmcnt(0) lgkmcnt(0)
	s_barrier
	s_add_u32 m0, s38, 32768
	s_nop 0
	global_load_lds_dwordx4 v164, s[98:99]
	s_waitcnt lgkmcnt(6)
	v_mfma_f32_16x16x32_bf16 v[4:7], v[72:75], v[84:87], v[4:7]
	v_mfma_f32_16x16x32_bf16 v[36:39], v[76:79], v[84:87], v[36:39]
	ds_read_b128 v[64:67], v150 offset:0
	ds_read_b128 v[68:71], v150 offset:2048
	ds_read_b128 v[112:115], v162 offset:16384
	s_add_u32 m0, s38, 36864
	s_nop 0
	global_load_lds_dwordx4 v165, s[98:99]
	s_waitcnt lgkmcnt(8)
	v_mfma_f32_16x16x32_bf16 v[8:11], v[72:75], v[88:91], v[8:11]
	v_mfma_f32_16x16x32_bf16 v[40:43], v[76:79], v[88:91], v[40:43]
	ds_read_b128 v[116:119], v162 offset:18432
	s_add_u32 m0, s38, 40960
	s_nop 0
	global_load_lds_dwordx4 v166, s[98:99]
	s_waitcnt lgkmcnt(8)
	v_mfma_f32_16x16x32_bf16 v[12:15], v[72:75], v[92:95], v[12:15]
	v_mfma_f32_16x16x32_bf16 v[44:47], v[76:79], v[92:95], v[44:47]
	ds_read_b128 v[120:123], v162 offset:20480
	s_add_u32 m0, s38, 45056
	s_nop 0
	global_load_lds_dwordx4 v167, s[98:99]
	s_add_u32 s98, s98, 128
	s_addc_u32 s99, s99, 0
	s_waitcnt lgkmcnt(8)
	v_mfma_f32_16x16x32_bf16 v[16:19], v[72:75], v[96:99], v[16:19]
	v_mfma_f32_16x16x32_bf16 v[48:51], v[76:79], v[96:99], v[48:51]
	ds_read_b128 v[124:127], v162 offset:22528
	s_add_u32 m0, s38, 49152
	s_nop 0
	global_load_lds_dwordx4 v164, s[100:101]
	s_waitcnt lgkmcnt(8)
	v_mfma_f32_16x16x32_bf16 v[20:23], v[72:75], v[100:103], v[20:23]
	v_mfma_f32_16x16x32_bf16 v[52:55], v[76:79], v[100:103], v[52:55]
	ds_read_b128 v[80:83], v162 offset:24576
	s_add_u32 m0, s38, 53248
	s_nop 0
	global_load_lds_dwordx4 v165, s[100:101]
	s_waitcnt lgkmcnt(8)
	v_mfma_f32_16x16x32_bf16 v[24:27], v[72:75], v[104:107], v[24:27]
	v_mfma_f32_16x16x32_bf16 v[56:59], v[76:79], v[104:107], v[56:59]
	ds_read_b128 v[84:87], v162 offset:26624
	s_add_u32 m0, s38, 57344
	s_nop 0
	global_load_lds_dwordx4 v166, s[100:101]
	s_waitcnt lgkmcnt(8)
	v_mfma_f32_16x16x32_bf16 v[28:31], v[72:75], v[108:111], v[28:31]
	v_mfma_f32_16x16x32_bf16 v[60:63], v[76:79], v[108:111], v[60:63]
	ds_read_b128 v[88:91], v162 offset:28672
	s_add_u32 m0, s38, 61440
	s_nop 0
	global_load_lds_dwordx4 v167, s[100:101]
	s_add_u32 s100, s100, 128
	s_addc_u32 s101, s101, 0
	s_waitcnt lgkmcnt(6)
	v_mfma_f32_16x16x32_bf16 v[0:3], v[64:67], v[112:115], v[0:3]
	v_mfma_f32_16x16x32_bf16 v[32:35], v[68:71], v[112:115], v[32:35]
	ds_read_b128 v[92:95], v162 offset:30720
	s_waitcnt lgkmcnt(6)
	v_mfma_f32_16x16x32_bf16 v[4:7], v[64:67], v[116:119], v[4:7]
	v_mfma_f32_16x16x32_bf16 v[36:39], v[68:71], v[116:119], v[36:39]
	ds_read_b128 v[72:75], v151 offset:0
	ds_read_b128 v[76:79], v151 offset:2048
	ds_read_b128 v[96:99], v163 offset:16384
	s_waitcnt lgkmcnt(8)
	v_mfma_f32_16x16x32_bf16 v[8:11], v[64:67], v[120:123], v[8:11]
	v_mfma_f32_16x16x32_bf16 v[40:43], v[68:71], v[120:123], v[40:43]
	ds_read_b128 v[100:103], v163 offset:18432
	s_waitcnt lgkmcnt(8)
	v_mfma_f32_16x16x32_bf16 v[12:15], v[64:67], v[124:127], v[12:15]
	v_mfma_f32_16x16x32_bf16 v[44:47], v[68:71], v[124:127], v[44:47]
	ds_read_b128 v[104:107], v163 offset:20480
	s_waitcnt lgkmcnt(8)
	v_mfma_f32_16x16x32_bf16 v[16:19], v[64:67], v[80:83], v[16:19]
	v_mfma_f32_16x16x32_bf16 v[48:51], v[68:71], v[80:83], v[48:51]
	ds_read_b128 v[108:111], v163 offset:22528
	s_waitcnt lgkmcnt(8)
	v_mfma_f32_16x16x32_bf16 v[20:23], v[64:67], v[84:87], v[20:23]
	v_mfma_f32_16x16x32_bf16 v[52:55], v[68:71], v[84:87], v[52:55]
	ds_read_b128 v[112:115], v163 offset:24576
	s_waitcnt lgkmcnt(8)
	v_mfma_f32_16x16x32_bf16 v[24:27], v[64:67], v[88:91], v[24:27]
	v_mfma_f32_16x16x32_bf16 v[56:59], v[68:71], v[88:91], v[56:59]
	ds_read_b128 v[116:119], v163 offset:26624
	s_waitcnt lgkmcnt(8)
	v_mfma_f32_16x16x32_bf16 v[28:31], v[64:67], v[92:95], v[28:31]
	v_mfma_f32_16x16x32_bf16 v[60:63], v[68:71], v[92:95], v[60:63]
	ds_read_b128 v[120:123], v163 offset:28672
	s_waitcnt lgkmcnt(6)
	v_mfma_f32_16x16x32_bf16 v[0:3], v[72:75], v[96:99], v[0:3]
	v_mfma_f32_16x16x32_bf16 v[32:35], v[76:79], v[96:99], v[32:35]
	ds_read_b128 v[124:127], v163 offset:30720
	s_waitcnt vmcnt(0) lgkmcnt(0)
	s_barrier
	s_add_u32 m0, s38, 0
	s_nop 0
	global_load_lds_dwordx4 v164, s[98:99]
	s_waitcnt lgkmcnt(6)
	v_mfma_f32_16x16x32_bf16 v[4:7], v[72:75], v[100:103], v[4:7]
	v_mfma_f32_16x16x32_bf16 v[36:39], v[76:79], v[100:103], v[36:39]
	ds_read_b128 v[64:67], v150 offset:32768
	ds_read_b128 v[68:71], v150 offset:34816
	ds_read_b128 v[80:83], v162 offset:49152
	s_add_u32 m0, s38, 4096
	s_nop 0
	global_load_lds_dwordx4 v165, s[98:99]
	s_waitcnt lgkmcnt(8)
	v_mfma_f32_16x16x32_bf16 v[8:11], v[72:75], v[104:107], v[8:11]
	v_mfma_f32_16x16x32_bf16 v[40:43], v[76:79], v[104:107], v[40:43]
	ds_read_b128 v[84:87], v162 offset:51200
	s_add_u32 m0, s38, 8192
	s_nop 0
	global_load_lds_dwordx4 v166, s[98:99]
	s_waitcnt lgkmcnt(8)
	v_mfma_f32_16x16x32_bf16 v[12:15], v[72:75], v[108:111], v[12:15]
	v_mfma_f32_16x16x32_bf16 v[44:47], v[76:79], v[108:111], v[44:47]
	ds_read_b128 v[88:91], v162 offset:53248
	s_add_u32 m0, s38, 12288
	s_nop 0
	global_load_lds_dwordx4 v167, s[98:99]
	s_add_u32 s98, s98, 128
	s_addc_u32 s99, s99, 0
	s_waitcnt lgkmcnt(8)
	v_mfma_f32_16x16x32_bf16 v[16:19], v[72:75], v[112:115], v[16:19]
	v_mfma_f32_16x16x32_bf16 v[48:51], v[76:79], v[112:115], v[48:51]
	ds_read_b128 v[92:95], v162 offset:55296
	s_add_u32 m0, s38, 16384
	s_nop 0
	global_load_lds_dwordx4 v164, s[100:101]
	s_waitcnt lgkmcnt(8)
	v_mfma_f32_16x16x32_bf16 v[20:23], v[72:75], v[116:119], v[20:23]
	v_mfma_f32_16x16x32_bf16 v[52:55], v[76:79], v[116:119], v[52:55]
	ds_read_b128 v[96:99], v162 offset:57344
	s_add_u32 m0, s38, 20480
	s_nop 0
	global_load_lds_dwordx4 v165, s[100:101]
	s_waitcnt lgkmcnt(8)
	v_mfma_f32_16x16x32_bf16 v[24:27], v[72:75], v[120:123], v[24:27]
	v_mfma_f32_16x16x32_bf16 v[56:59], v[76:79], v[120:123], v[56:59]
	ds_read_b128 v[100:103], v162 offset:59392
	s_add_u32 m0, s38, 24576
	s_nop 0
	global_load_lds_dwordx4 v166, s[100:101]
	s_waitcnt lgkmcnt(8)
	v_mfma_f32_16x16x32_bf16 v[28:31], v[72:75], v[124:127], v[28:31]
	v_mfma_f32_16x16x32_bf16 v[60:63], v[76:79], v[124:127], v[60:63]
	ds_read_b128 v[104:107], v162 offset:61440
	s_add_u32 m0, s38, 28672
	s_nop 0
	global_load_lds_dwordx4 v167, s[100:101]
	s_add_u32 s100, s100, 128
	s_addc_u32 s101, s101, 0
	s_waitcnt lgkmcnt(6)
	v_mfma_f32_16x16x32_bf16 v[0:3], v[64:67], v[80:83], v[0:3]
	v_mfma_f32_16x16x32_bf16 v[32:35], v[68:71], v[80:83], v[32:35]
	ds_read_b128 v[108:111], v162 offset:63488
	s_waitcnt lgkmcnt(6)
	v_mfma_f32_16x16x32_bf16 v[4:7], v[64:67], v[84:87], v[4:7]
	v_mfma_f32_16x16x32_bf16 v[36:39], v[68:71], v[84:87], v[36:39]
	ds_read_b128 v[72:75], v151 offset:32768
	ds_read_b128 v[76:79], v151 offset:34816
	ds_read_b128 v[112:115], v163 offset:49152
	s_waitcnt lgkmcnt(8)
	v_mfma_f32_16x16x32_bf16 v[8:11], v[64:67], v[88:91], v[8:11]
	v_mfma_f32_16x16x32_bf16 v[40:43], v[68:71], v[88:91], v[40:43]
	ds_read_b128 v[116:119], v163 offset:51200
	s_waitcnt lgkmcnt(8)
	v_mfma_f32_16x16x32_bf16 v[12:15], v[64:67], v[92:95], v[12:15]
	v_mfma_f32_16x16x32_bf16 v[44:47], v[68:71], v[92:95], v[44:47]
	ds_read_b128 v[120:123], v163 offset:53248
	s_waitcnt lgkmcnt(8)
	v_mfma_f32_16x16x32_bf16 v[16:19], v[64:67], v[96:99], v[16:19]
	v_mfma_f32_16x16x32_bf16 v[48:51], v[68:71], v[96:99], v[48:51]
	ds_read_b128 v[124:127], v163 offset:55296
	s_waitcnt lgkmcnt(8)
	v_mfma_f32_16x16x32_bf16 v[20:23], v[64:67], v[100:103], v[20:23]
	v_mfma_f32_16x16x32_bf16 v[52:55], v[68:71], v[100:103], v[52:55]
	ds_read_b128 v[80:83], v163 offset:57344
	s_waitcnt lgkmcnt(8)
	v_mfma_f32_16x16x32_bf16 v[24:27], v[64:67], v[104:107], v[24:27]
	v_mfma_f32_16x16x32_bf16 v[56:59], v[68:71], v[104:107], v[56:59]
	ds_read_b128 v[84:87], v163 offset:59392
	s_waitcnt lgkmcnt(8)
	v_mfma_f32_16x16x32_bf16 v[28:31], v[64:67], v[108:111], v[28:31]
	v_mfma_f32_16x16x32_bf16 v[60:63], v[68:71], v[108:111], v[60:63]
	ds_read_b128 v[88:91], v163 offset:61440
	s_waitcnt lgkmcnt(6)
	v_mfma_f32_16x16x32_bf16 v[0:3], v[72:75], v[112:115], v[0:3]
	v_mfma_f32_16x16x32_bf16 v[32:35], v[76:79], v[112:115], v[32:35]
	ds_read_b128 v[92:95], v163 offset:63488
	s_waitcnt vmcnt(0) lgkmcnt(0)
	s_barrier
	s_add_u32 m0, s38, 32768
	s_nop 0
	global_load_lds_dwordx4 v164, s[98:99]
	s_waitcnt lgkmcnt(6)
	v_mfma_f32_16x16x32_bf16 v[4:7], v[72:75], v[116:119], v[4:7]
	v_mfma_f32_16x16x32_bf16 v[36:39], v[76:79], v[116:119], v[36:39]
	ds_read_b128 v[64:67], v150 offset:0
	ds_read_b128 v[68:71], v150 offset:2048
	ds_read_b128 v[96:99], v162 offset:16384
	s_add_u32 m0, s38, 36864
	s_nop 0
	global_load_lds_dwordx4 v165, s[98:99]
	s_waitcnt lgkmcnt(8)
	v_mfma_f32_16x16x32_bf16 v[8:11], v[72:75], v[120:123], v[8:11]
	v_mfma_f32_16x16x32_bf16 v[40:43], v[76:79], v[120:123], v[40:43]
	ds_read_b128 v[100:103], v162 offset:18432
	s_add_u32 m0, s38, 40960
	s_nop 0
	global_load_lds_dwordx4 v166, s[98:99]
	s_waitcnt lgkmcnt(8)
	v_mfma_f32_16x16x32_bf16 v[12:15], v[72:75], v[124:127], v[12:15]
	v_mfma_f32_16x16x32_bf16 v[44:47], v[76:79], v[124:127], v[44:47]
	ds_read_b128 v[104:107], v162 offset:20480
	s_add_u32 m0, s38, 45056
	s_nop 0
	global_load_lds_dwordx4 v167, s[98:99]
	s_add_u32 s98, s98, 128
	s_addc_u32 s99, s99, 0
	s_waitcnt lgkmcnt(8)
	v_mfma_f32_16x16x32_bf16 v[16:19], v[72:75], v[80:83], v[16:19]
	v_mfma_f32_16x16x32_bf16 v[48:51], v[76:79], v[80:83], v[48:51]
	ds_read_b128 v[108:111], v162 offset:22528
	s_add_u32 m0, s38, 49152
	s_nop 0
	global_load_lds_dwordx4 v164, s[100:101]
	s_waitcnt lgkmcnt(8)
	v_mfma_f32_16x16x32_bf16 v[20:23], v[72:75], v[84:87], v[20:23]
	v_mfma_f32_16x16x32_bf16 v[52:55], v[76:79], v[84:87], v[52:55]
	ds_read_b128 v[112:115], v162 offset:24576
	s_add_u32 m0, s38, 53248
	s_nop 0
	global_load_lds_dwordx4 v165, s[100:101]
	s_waitcnt lgkmcnt(8)
	v_mfma_f32_16x16x32_bf16 v[24:27], v[72:75], v[88:91], v[24:27]
	v_mfma_f32_16x16x32_bf16 v[56:59], v[76:79], v[88:91], v[56:59]
	ds_read_b128 v[116:119], v162 offset:26624
	s_add_u32 m0, s38, 57344
	s_nop 0
	global_load_lds_dwordx4 v166, s[100:101]
	s_waitcnt lgkmcnt(8)
	v_mfma_f32_16x16x32_bf16 v[28:31], v[72:75], v[92:95], v[28:31]
	v_mfma_f32_16x16x32_bf16 v[60:63], v[76:79], v[92:95], v[60:63]
	ds_read_b128 v[120:123], v162 offset:28672
	s_add_u32 m0, s38, 61440
	s_nop 0
	global_load_lds_dwordx4 v167, s[100:101]
	s_add_u32 s100, s100, 128
	s_addc_u32 s101, s101, 0
	s_waitcnt lgkmcnt(6)
	v_mfma_f32_16x16x32_bf16 v[0:3], v[64:67], v[96:99], v[0:3]
	v_mfma_f32_16x16x32_bf16 v[32:35], v[68:71], v[96:99], v[32:35]
	ds_read_b128 v[124:127], v162 offset:30720
	s_waitcnt lgkmcnt(6)
	v_mfma_f32_16x16x32_bf16 v[4:7], v[64:67], v[100:103], v[4:7]
	v_mfma_f32_16x16x32_bf16 v[36:39], v[68:71], v[100:103], v[36:39]
	ds_read_b128 v[72:75], v151 offset:0
	ds_read_b128 v[76:79], v151 offset:2048
	ds_read_b128 v[80:83], v163 offset:16384
	s_waitcnt lgkmcnt(8)
	v_mfma_f32_16x16x32_bf16 v[8:11], v[64:67], v[104:107], v[8:11]
	v_mfma_f32_16x16x32_bf16 v[40:43], v[68:71], v[104:107], v[40:43]
	ds_read_b128 v[84:87], v163 offset:18432
	s_waitcnt lgkmcnt(8)
	v_mfma_f32_16x16x32_bf16 v[12:15], v[64:67], v[108:111], v[12:15]
	v_mfma_f32_16x16x32_bf16 v[44:47], v[68:71], v[108:111], v[44:47]
	ds_read_b128 v[88:91], v163 offset:20480
	s_waitcnt lgkmcnt(8)
	v_mfma_f32_16x16x32_bf16 v[16:19], v[64:67], v[112:115], v[16:19]
	v_mfma_f32_16x16x32_bf16 v[48:51], v[68:71], v[112:115], v[48:51]
	ds_read_b128 v[92:95], v163 offset:22528
	s_waitcnt lgkmcnt(8)
	v_mfma_f32_16x16x32_bf16 v[20:23], v[64:67], v[116:119], v[20:23]
	v_mfma_f32_16x16x32_bf16 v[52:55], v[68:71], v[116:119], v[52:55]
	ds_read_b128 v[96:99], v163 offset:24576
	s_waitcnt lgkmcnt(8)
	v_mfma_f32_16x16x32_bf16 v[24:27], v[64:67], v[120:123], v[24:27]
	v_mfma_f32_16x16x32_bf16 v[56:59], v[68:71], v[120:123], v[56:59]
	ds_read_b128 v[100:103], v163 offset:26624
	s_waitcnt lgkmcnt(8)
	v_mfma_f32_16x16x32_bf16 v[28:31], v[64:67], v[124:127], v[28:31]
	v_mfma_f32_16x16x32_bf16 v[60:63], v[68:71], v[124:127], v[60:63]
	ds_read_b128 v[104:107], v163 offset:28672
	s_waitcnt lgkmcnt(6)
	v_mfma_f32_16x16x32_bf16 v[0:3], v[72:75], v[80:83], v[0:3]
	v_mfma_f32_16x16x32_bf16 v[32:35], v[76:79], v[80:83], v[32:35]
	ds_read_b128 v[108:111], v163 offset:30720
	s_waitcnt vmcnt(0) lgkmcnt(0)
	s_barrier
	s_add_u32 m0, s38, 0
	s_nop 0
	global_load_lds_dwordx4 v164, s[98:99]
	s_waitcnt lgkmcnt(6)
	v_mfma_f32_16x16x32_bf16 v[4:7], v[72:75], v[84:87], v[4:7]
	v_mfma_f32_16x16x32_bf16 v[36:39], v[76:79], v[84:87], v[36:39]
	ds_read_b128 v[64:67], v150 offset:32768
	ds_read_b128 v[68:71], v150 offset:34816
	ds_read_b128 v[112:115], v162 offset:49152
	s_add_u32 m0, s38, 4096
	s_nop 0
	global_load_lds_dwordx4 v165, s[98:99]
	s_waitcnt lgkmcnt(8)
	v_mfma_f32_16x16x32_bf16 v[8:11], v[72:75], v[88:91], v[8:11]
	v_mfma_f32_16x16x32_bf16 v[40:43], v[76:79], v[88:91], v[40:43]
	ds_read_b128 v[116:119], v162 offset:51200
	s_add_u32 m0, s38, 8192
	s_nop 0
	global_load_lds_dwordx4 v166, s[98:99]
	s_waitcnt lgkmcnt(8)
	v_mfma_f32_16x16x32_bf16 v[12:15], v[72:75], v[92:95], v[12:15]
	v_mfma_f32_16x16x32_bf16 v[44:47], v[76:79], v[92:95], v[44:47]
	ds_read_b128 v[120:123], v162 offset:53248
	s_add_u32 m0, s38, 12288
	s_nop 0
	global_load_lds_dwordx4 v167, s[98:99]
	s_add_u32 s98, s98, 128
	s_addc_u32 s99, s99, 0
	s_waitcnt lgkmcnt(8)
	v_mfma_f32_16x16x32_bf16 v[16:19], v[72:75], v[96:99], v[16:19]
	v_mfma_f32_16x16x32_bf16 v[48:51], v[76:79], v[96:99], v[48:51]
	ds_read_b128 v[124:127], v162 offset:55296
	s_add_u32 m0, s38, 16384
	s_nop 0
	global_load_lds_dwordx4 v164, s[100:101]
	s_waitcnt lgkmcnt(8)
	v_mfma_f32_16x16x32_bf16 v[20:23], v[72:75], v[100:103], v[20:23]
	v_mfma_f32_16x16x32_bf16 v[52:55], v[76:79], v[100:103], v[52:55]
	ds_read_b128 v[80:83], v162 offset:57344
	s_add_u32 m0, s38, 20480
	s_nop 0
	global_load_lds_dwordx4 v165, s[100:101]
	s_waitcnt lgkmcnt(8)
	v_mfma_f32_16x16x32_bf16 v[24:27], v[72:75], v[104:107], v[24:27]
	v_mfma_f32_16x16x32_bf16 v[56:59], v[76:79], v[104:107], v[56:59]
	ds_read_b128 v[84:87], v162 offset:59392
	s_add_u32 m0, s38, 24576
	s_nop 0
	global_load_lds_dwordx4 v166, s[100:101]
	s_waitcnt lgkmcnt(8)
	v_mfma_f32_16x16x32_bf16 v[28:31], v[72:75], v[108:111], v[28:31]
	v_mfma_f32_16x16x32_bf16 v[60:63], v[76:79], v[108:111], v[60:63]
	ds_read_b128 v[88:91], v162 offset:61440
	s_add_u32 m0, s38, 28672
	s_nop 0
	global_load_lds_dwordx4 v167, s[100:101]
	s_add_u32 s100, s100, 128
	s_addc_u32 s101, s101, 0
	s_waitcnt lgkmcnt(6)
	v_mfma_f32_16x16x32_bf16 v[0:3], v[64:67], v[112:115], v[0:3]
	v_mfma_f32_16x16x32_bf16 v[32:35], v[68:71], v[112:115], v[32:35]
	ds_read_b128 v[92:95], v162 offset:63488
	s_waitcnt lgkmcnt(6)
	v_mfma_f32_16x16x32_bf16 v[4:7], v[64:67], v[116:119], v[4:7]
	v_mfma_f32_16x16x32_bf16 v[36:39], v[68:71], v[116:119], v[36:39]
	ds_read_b128 v[72:75], v151 offset:32768
	ds_read_b128 v[76:79], v151 offset:34816
	ds_read_b128 v[96:99], v163 offset:49152
	s_waitcnt lgkmcnt(8)
	v_mfma_f32_16x16x32_bf16 v[8:11], v[64:67], v[120:123], v[8:11]
	v_mfma_f32_16x16x32_bf16 v[40:43], v[68:71], v[120:123], v[40:43]
	ds_read_b128 v[100:103], v163 offset:51200
	s_waitcnt lgkmcnt(8)
	v_mfma_f32_16x16x32_bf16 v[12:15], v[64:67], v[124:127], v[12:15]
	v_mfma_f32_16x16x32_bf16 v[44:47], v[68:71], v[124:127], v[44:47]
	ds_read_b128 v[104:107], v163 offset:53248
	s_waitcnt lgkmcnt(8)
	v_mfma_f32_16x16x32_bf16 v[16:19], v[64:67], v[80:83], v[16:19]
	v_mfma_f32_16x16x32_bf16 v[48:51], v[68:71], v[80:83], v[48:51]
	ds_read_b128 v[108:111], v163 offset:55296
	s_waitcnt lgkmcnt(8)
	v_mfma_f32_16x16x32_bf16 v[20:23], v[64:67], v[84:87], v[20:23]
	v_mfma_f32_16x16x32_bf16 v[52:55], v[68:71], v[84:87], v[52:55]
	ds_read_b128 v[112:115], v163 offset:57344
	s_waitcnt lgkmcnt(8)
	v_mfma_f32_16x16x32_bf16 v[24:27], v[64:67], v[88:91], v[24:27]
	v_mfma_f32_16x16x32_bf16 v[56:59], v[68:71], v[88:91], v[56:59]
	ds_read_b128 v[116:119], v163 offset:59392
	s_waitcnt lgkmcnt(8)
	v_mfma_f32_16x16x32_bf16 v[28:31], v[64:67], v[92:95], v[28:31]
	v_mfma_f32_16x16x32_bf16 v[60:63], v[68:71], v[92:95], v[60:63]
	ds_read_b128 v[120:123], v163 offset:61440
	s_waitcnt lgkmcnt(6)
	v_mfma_f32_16x16x32_bf16 v[0:3], v[72:75], v[96:99], v[0:3]
	v_mfma_f32_16x16x32_bf16 v[32:35], v[76:79], v[96:99], v[32:35]
	ds_read_b128 v[124:127], v163 offset:63488
	s_waitcnt vmcnt(0) lgkmcnt(0)
	s_barrier
	s_add_u32 m0, s38, 32768
	s_nop 0
	global_load_lds_dwordx4 v164, s[98:99]
	s_waitcnt lgkmcnt(6)
	v_mfma_f32_16x16x32_bf16 v[4:7], v[72:75], v[100:103], v[4:7]
	v_mfma_f32_16x16x32_bf16 v[36:39], v[76:79], v[100:103], v[36:39]
	ds_read_b128 v[64:67], v150 offset:0
	ds_read_b128 v[68:71], v150 offset:2048
	ds_read_b128 v[80:83], v162 offset:16384
	s_add_u32 m0, s38, 36864
	s_nop 0
	global_load_lds_dwordx4 v165, s[98:99]
	s_waitcnt lgkmcnt(8)
	v_mfma_f32_16x16x32_bf16 v[8:11], v[72:75], v[104:107], v[8:11]
	v_mfma_f32_16x16x32_bf16 v[40:43], v[76:79], v[104:107], v[40:43]
	ds_read_b128 v[84:87], v162 offset:18432
	s_add_u32 m0, s38, 40960
	s_nop 0
	global_load_lds_dwordx4 v166, s[98:99]
	s_waitcnt lgkmcnt(8)
	v_mfma_f32_16x16x32_bf16 v[12:15], v[72:75], v[108:111], v[12:15]
	v_mfma_f32_16x16x32_bf16 v[44:47], v[76:79], v[108:111], v[44:47]
	ds_read_b128 v[88:91], v162 offset:20480
	s_add_u32 m0, s38, 45056
	s_nop 0
	global_load_lds_dwordx4 v167, s[98:99]
	s_add_u32 s98, s98, 128
	s_addc_u32 s99, s99, 0
	s_waitcnt lgkmcnt(8)
	v_mfma_f32_16x16x32_bf16 v[16:19], v[72:75], v[112:115], v[16:19]
	v_mfma_f32_16x16x32_bf16 v[48:51], v[76:79], v[112:115], v[48:51]
	ds_read_b128 v[92:95], v162 offset:22528
	s_add_u32 m0, s38, 49152
	s_nop 0
	global_load_lds_dwordx4 v164, s[100:101]
	s_waitcnt lgkmcnt(8)
	v_mfma_f32_16x16x32_bf16 v[20:23], v[72:75], v[116:119], v[20:23]
	v_mfma_f32_16x16x32_bf16 v[52:55], v[76:79], v[116:119], v[52:55]
	ds_read_b128 v[96:99], v162 offset:24576
	s_add_u32 m0, s38, 53248
	s_nop 0
	global_load_lds_dwordx4 v165, s[100:101]
	s_waitcnt lgkmcnt(8)
	v_mfma_f32_16x16x32_bf16 v[24:27], v[72:75], v[120:123], v[24:27]
	v_mfma_f32_16x16x32_bf16 v[56:59], v[76:79], v[120:123], v[56:59]
	ds_read_b128 v[100:103], v162 offset:26624
	s_add_u32 m0, s38, 57344
	s_nop 0
	global_load_lds_dwordx4 v166, s[100:101]
	s_waitcnt lgkmcnt(8)
	v_mfma_f32_16x16x32_bf16 v[28:31], v[72:75], v[124:127], v[28:31]
	v_mfma_f32_16x16x32_bf16 v[60:63], v[76:79], v[124:127], v[60:63]
	ds_read_b128 v[104:107], v162 offset:28672
	s_add_u32 m0, s38, 61440
	s_nop 0
	global_load_lds_dwordx4 v167, s[100:101]
	s_add_u32 s100, s100, 128
	s_addc_u32 s101, s101, 0
	s_waitcnt lgkmcnt(6)
	v_mfma_f32_16x16x32_bf16 v[0:3], v[64:67], v[80:83], v[0:3]
	v_mfma_f32_16x16x32_bf16 v[32:35], v[68:71], v[80:83], v[32:35]
	ds_read_b128 v[108:111], v162 offset:30720
	s_waitcnt lgkmcnt(6)
	v_mfma_f32_16x16x32_bf16 v[4:7], v[64:67], v[84:87], v[4:7]
	v_mfma_f32_16x16x32_bf16 v[36:39], v[68:71], v[84:87], v[36:39]
	ds_read_b128 v[72:75], v151 offset:0
	ds_read_b128 v[76:79], v151 offset:2048
	ds_read_b128 v[112:115], v163 offset:16384
	s_waitcnt lgkmcnt(8)
	v_mfma_f32_16x16x32_bf16 v[8:11], v[64:67], v[88:91], v[8:11]
	v_mfma_f32_16x16x32_bf16 v[40:43], v[68:71], v[88:91], v[40:43]
	ds_read_b128 v[116:119], v163 offset:18432
	s_waitcnt lgkmcnt(8)
	v_mfma_f32_16x16x32_bf16 v[12:15], v[64:67], v[92:95], v[12:15]
	v_mfma_f32_16x16x32_bf16 v[44:47], v[68:71], v[92:95], v[44:47]
	ds_read_b128 v[120:123], v163 offset:20480
	s_waitcnt lgkmcnt(8)
	v_mfma_f32_16x16x32_bf16 v[16:19], v[64:67], v[96:99], v[16:19]
	v_mfma_f32_16x16x32_bf16 v[48:51], v[68:71], v[96:99], v[48:51]
	ds_read_b128 v[124:127], v163 offset:22528
	s_waitcnt lgkmcnt(8)
	v_mfma_f32_16x16x32_bf16 v[20:23], v[64:67], v[100:103], v[20:23]
	v_mfma_f32_16x16x32_bf16 v[52:55], v[68:71], v[100:103], v[52:55]
	ds_read_b128 v[80:83], v163 offset:24576
	s_waitcnt lgkmcnt(8)
	v_mfma_f32_16x16x32_bf16 v[24:27], v[64:67], v[104:107], v[24:27]
	v_mfma_f32_16x16x32_bf16 v[56:59], v[68:71], v[104:107], v[56:59]
	ds_read_b128 v[84:87], v163 offset:26624
	s_waitcnt lgkmcnt(8)
	v_mfma_f32_16x16x32_bf16 v[28:31], v[64:67], v[108:111], v[28:31]
	v_mfma_f32_16x16x32_bf16 v[60:63], v[68:71], v[108:111], v[60:63]
	ds_read_b128 v[88:91], v163 offset:28672
	s_waitcnt lgkmcnt(6)
	v_mfma_f32_16x16x32_bf16 v[0:3], v[72:75], v[112:115], v[0:3]
	v_mfma_f32_16x16x32_bf16 v[32:35], v[76:79], v[112:115], v[32:35]
	ds_read_b128 v[92:95], v163 offset:30720
	s_waitcnt vmcnt(0) lgkmcnt(0)
	s_barrier
	s_add_u32 m0, s38, 0
	s_nop 0
	global_load_lds_dwordx4 v164, s[98:99]
	s_waitcnt lgkmcnt(6)
	v_mfma_f32_16x16x32_bf16 v[4:7], v[72:75], v[116:119], v[4:7]
	v_mfma_f32_16x16x32_bf16 v[36:39], v[76:79], v[116:119], v[36:39]
	ds_read_b128 v[64:67], v150 offset:32768
	ds_read_b128 v[68:71], v150 offset:34816
	ds_read_b128 v[96:99], v162 offset:49152
	s_add_u32 m0, s38, 4096
	s_nop 0
	global_load_lds_dwordx4 v165, s[98:99]
	s_waitcnt lgkmcnt(8)
	v_mfma_f32_16x16x32_bf16 v[8:11], v[72:75], v[120:123], v[8:11]
	v_mfma_f32_16x16x32_bf16 v[40:43], v[76:79], v[120:123], v[40:43]
	ds_read_b128 v[100:103], v162 offset:51200
	s_add_u32 m0, s38, 8192
	s_nop 0
	global_load_lds_dwordx4 v166, s[98:99]
	s_waitcnt lgkmcnt(8)
	v_mfma_f32_16x16x32_bf16 v[12:15], v[72:75], v[124:127], v[12:15]
	v_mfma_f32_16x16x32_bf16 v[44:47], v[76:79], v[124:127], v[44:47]
	ds_read_b128 v[104:107], v162 offset:53248
	s_add_u32 m0, s38, 12288
	s_nop 0
	global_load_lds_dwordx4 v167, s[98:99]
	s_add_u32 s98, s98, 128
	s_addc_u32 s99, s99, 0
	s_waitcnt lgkmcnt(8)
	v_mfma_f32_16x16x32_bf16 v[16:19], v[72:75], v[80:83], v[16:19]
	v_mfma_f32_16x16x32_bf16 v[48:51], v[76:79], v[80:83], v[48:51]
	ds_read_b128 v[108:111], v162 offset:55296
	s_add_u32 m0, s38, 16384
	s_nop 0
	global_load_lds_dwordx4 v164, s[100:101]
	s_waitcnt lgkmcnt(8)
	v_mfma_f32_16x16x32_bf16 v[20:23], v[72:75], v[84:87], v[20:23]
	v_mfma_f32_16x16x32_bf16 v[52:55], v[76:79], v[84:87], v[52:55]
	ds_read_b128 v[112:115], v162 offset:57344
	s_add_u32 m0, s38, 20480
	s_nop 0
	global_load_lds_dwordx4 v165, s[100:101]
	s_waitcnt lgkmcnt(8)
	v_mfma_f32_16x16x32_bf16 v[24:27], v[72:75], v[88:91], v[24:27]
	v_mfma_f32_16x16x32_bf16 v[56:59], v[76:79], v[88:91], v[56:59]
	ds_read_b128 v[116:119], v162 offset:59392
	s_add_u32 m0, s38, 24576
	s_nop 0
	global_load_lds_dwordx4 v166, s[100:101]
	s_waitcnt lgkmcnt(8)
	v_mfma_f32_16x16x32_bf16 v[28:31], v[72:75], v[92:95], v[28:31]
	v_mfma_f32_16x16x32_bf16 v[60:63], v[76:79], v[92:95], v[60:63]
	ds_read_b128 v[120:123], v162 offset:61440
	s_add_u32 m0, s38, 28672
	s_nop 0
	global_load_lds_dwordx4 v167, s[100:101]
	s_add_u32 s100, s100, 128
	s_addc_u32 s101, s101, 0
	s_waitcnt lgkmcnt(6)
	v_mfma_f32_16x16x32_bf16 v[0:3], v[64:67], v[96:99], v[0:3]
	v_mfma_f32_16x16x32_bf16 v[32:35], v[68:71], v[96:99], v[32:35]
	ds_read_b128 v[124:127], v162 offset:63488
	s_waitcnt lgkmcnt(6)
	v_mfma_f32_16x16x32_bf16 v[4:7], v[64:67], v[100:103], v[4:7]
	v_mfma_f32_16x16x32_bf16 v[36:39], v[68:71], v[100:103], v[36:39]
	ds_read_b128 v[72:75], v151 offset:32768
	ds_read_b128 v[76:79], v151 offset:34816
	ds_read_b128 v[80:83], v163 offset:49152
	s_waitcnt lgkmcnt(8)
	v_mfma_f32_16x16x32_bf16 v[8:11], v[64:67], v[104:107], v[8:11]
	v_mfma_f32_16x16x32_bf16 v[40:43], v[68:71], v[104:107], v[40:43]
	ds_read_b128 v[84:87], v163 offset:51200
	s_waitcnt lgkmcnt(8)
	v_mfma_f32_16x16x32_bf16 v[12:15], v[64:67], v[108:111], v[12:15]
	v_mfma_f32_16x16x32_bf16 v[44:47], v[68:71], v[108:111], v[44:47]
	ds_read_b128 v[88:91], v163 offset:53248
	s_waitcnt lgkmcnt(8)
	v_mfma_f32_16x16x32_bf16 v[16:19], v[64:67], v[112:115], v[16:19]
	v_mfma_f32_16x16x32_bf16 v[48:51], v[68:71], v[112:115], v[48:51]
	ds_read_b128 v[92:95], v163 offset:55296
	s_waitcnt lgkmcnt(8)
	v_mfma_f32_16x16x32_bf16 v[20:23], v[64:67], v[116:119], v[20:23]
	v_mfma_f32_16x16x32_bf16 v[52:55], v[68:71], v[116:119], v[52:55]
	ds_read_b128 v[96:99], v163 offset:57344
	s_waitcnt lgkmcnt(8)
	v_mfma_f32_16x16x32_bf16 v[24:27], v[64:67], v[120:123], v[24:27]
	v_mfma_f32_16x16x32_bf16 v[56:59], v[68:71], v[120:123], v[56:59]
	ds_read_b128 v[100:103], v163 offset:59392
	s_waitcnt lgkmcnt(8)
	v_mfma_f32_16x16x32_bf16 v[28:31], v[64:67], v[124:127], v[28:31]
	v_mfma_f32_16x16x32_bf16 v[60:63], v[68:71], v[124:127], v[60:63]
	ds_read_b128 v[104:107], v163 offset:61440
	s_waitcnt lgkmcnt(6)
	v_mfma_f32_16x16x32_bf16 v[0:3], v[72:75], v[80:83], v[0:3]
	v_mfma_f32_16x16x32_bf16 v[32:35], v[76:79], v[80:83], v[32:35]
	ds_read_b128 v[108:111], v163 offset:63488
	s_waitcnt vmcnt(0) lgkmcnt(0)
	s_barrier
	s_add_u32 m0, s38, 32768
	s_nop 0
	global_load_lds_dwordx4 v164, s[98:99]
	s_waitcnt lgkmcnt(6)
	v_mfma_f32_16x16x32_bf16 v[4:7], v[72:75], v[84:87], v[4:7]
	v_mfma_f32_16x16x32_bf16 v[36:39], v[76:79], v[84:87], v[36:39]
	ds_read_b128 v[64:67], v150 offset:0
	ds_read_b128 v[68:71], v150 offset:2048
	ds_read_b128 v[112:115], v162 offset:16384
	s_add_u32 m0, s38, 36864
	s_nop 0
	global_load_lds_dwordx4 v165, s[98:99]
	s_waitcnt lgkmcnt(8)
	v_mfma_f32_16x16x32_bf16 v[8:11], v[72:75], v[88:91], v[8:11]
	v_mfma_f32_16x16x32_bf16 v[40:43], v[76:79], v[88:91], v[40:43]
	ds_read_b128 v[116:119], v162 offset:18432
	s_add_u32 m0, s38, 40960
	s_nop 0
	global_load_lds_dwordx4 v166, s[98:99]
	s_waitcnt lgkmcnt(8)
	v_mfma_f32_16x16x32_bf16 v[12:15], v[72:75], v[92:95], v[12:15]
	v_mfma_f32_16x16x32_bf16 v[44:47], v[76:79], v[92:95], v[44:47]
	ds_read_b128 v[120:123], v162 offset:20480
	s_add_u32 m0, s38, 45056
	s_nop 0
	global_load_lds_dwordx4 v167, s[98:99]
	s_add_u32 s98, s98, 128
	s_addc_u32 s99, s99, 0
	s_waitcnt lgkmcnt(8)
	v_mfma_f32_16x16x32_bf16 v[16:19], v[72:75], v[96:99], v[16:19]
	v_mfma_f32_16x16x32_bf16 v[48:51], v[76:79], v[96:99], v[48:51]
	ds_read_b128 v[124:127], v162 offset:22528
	s_add_u32 m0, s38, 49152
	s_nop 0
	global_load_lds_dwordx4 v164, s[100:101]
	s_waitcnt lgkmcnt(8)
	v_mfma_f32_16x16x32_bf16 v[20:23], v[72:75], v[100:103], v[20:23]
	v_mfma_f32_16x16x32_bf16 v[52:55], v[76:79], v[100:103], v[52:55]
	ds_read_b128 v[80:83], v162 offset:24576
	s_add_u32 m0, s38, 53248
	s_nop 0
	global_load_lds_dwordx4 v165, s[100:101]
	s_waitcnt lgkmcnt(8)
	v_mfma_f32_16x16x32_bf16 v[24:27], v[72:75], v[104:107], v[24:27]
	v_mfma_f32_16x16x32_bf16 v[56:59], v[76:79], v[104:107], v[56:59]
	ds_read_b128 v[84:87], v162 offset:26624
	s_add_u32 m0, s38, 57344
	s_nop 0
	global_load_lds_dwordx4 v166, s[100:101]
	s_waitcnt lgkmcnt(8)
	v_mfma_f32_16x16x32_bf16 v[28:31], v[72:75], v[108:111], v[28:31]
	v_mfma_f32_16x16x32_bf16 v[60:63], v[76:79], v[108:111], v[60:63]
	ds_read_b128 v[88:91], v162 offset:28672
	s_add_u32 m0, s38, 61440
	s_nop 0
	global_load_lds_dwordx4 v167, s[100:101]
	s_add_u32 s100, s100, 128
	s_addc_u32 s101, s101, 0
	s_waitcnt lgkmcnt(6)
	v_mfma_f32_16x16x32_bf16 v[0:3], v[64:67], v[112:115], v[0:3]
	v_mfma_f32_16x16x32_bf16 v[32:35], v[68:71], v[112:115], v[32:35]
	ds_read_b128 v[92:95], v162 offset:30720
	s_waitcnt lgkmcnt(6)
	v_mfma_f32_16x16x32_bf16 v[4:7], v[64:67], v[116:119], v[4:7]
	v_mfma_f32_16x16x32_bf16 v[36:39], v[68:71], v[116:119], v[36:39]
	ds_read_b128 v[72:75], v151 offset:0
	ds_read_b128 v[76:79], v151 offset:2048
	ds_read_b128 v[96:99], v163 offset:16384
	s_waitcnt lgkmcnt(8)
	v_mfma_f32_16x16x32_bf16 v[8:11], v[64:67], v[120:123], v[8:11]
	v_mfma_f32_16x16x32_bf16 v[40:43], v[68:71], v[120:123], v[40:43]
	ds_read_b128 v[100:103], v163 offset:18432
	s_waitcnt lgkmcnt(8)
	v_mfma_f32_16x16x32_bf16 v[12:15], v[64:67], v[124:127], v[12:15]
	v_mfma_f32_16x16x32_bf16 v[44:47], v[68:71], v[124:127], v[44:47]
	ds_read_b128 v[104:107], v163 offset:20480
	s_waitcnt lgkmcnt(8)
	v_mfma_f32_16x16x32_bf16 v[16:19], v[64:67], v[80:83], v[16:19]
	v_mfma_f32_16x16x32_bf16 v[48:51], v[68:71], v[80:83], v[48:51]
	ds_read_b128 v[108:111], v163 offset:22528
	s_waitcnt lgkmcnt(8)
	v_mfma_f32_16x16x32_bf16 v[20:23], v[64:67], v[84:87], v[20:23]
	v_mfma_f32_16x16x32_bf16 v[52:55], v[68:71], v[84:87], v[52:55]
	ds_read_b128 v[112:115], v163 offset:24576
	s_waitcnt lgkmcnt(8)
	v_mfma_f32_16x16x32_bf16 v[24:27], v[64:67], v[88:91], v[24:27]
	v_mfma_f32_16x16x32_bf16 v[56:59], v[68:71], v[88:91], v[56:59]
	ds_read_b128 v[116:119], v163 offset:26624
	s_waitcnt lgkmcnt(8)
	v_mfma_f32_16x16x32_bf16 v[28:31], v[64:67], v[92:95], v[28:31]
	v_mfma_f32_16x16x32_bf16 v[60:63], v[68:71], v[92:95], v[60:63]
	ds_read_b128 v[120:123], v163 offset:28672
	s_waitcnt lgkmcnt(6)
	v_mfma_f32_16x16x32_bf16 v[0:3], v[72:75], v[96:99], v[0:3]
	v_mfma_f32_16x16x32_bf16 v[32:35], v[76:79], v[96:99], v[32:35]
	ds_read_b128 v[124:127], v163 offset:30720
	s_waitcnt vmcnt(0) lgkmcnt(0)
	s_barrier
	s_add_u32 m0, s38, 0
	s_nop 0
	global_load_lds_dwordx4 v164, s[98:99]
	s_add_u32 m0, s38, 4096
	s_nop 0
	global_load_lds_dwordx4 v165, s[98:99]
	s_waitcnt lgkmcnt(6)
	v_mfma_f32_16x16x32_bf16 v[4:7], v[72:75], v[100:103], v[4:7]
	v_mfma_f32_16x16x32_bf16 v[36:39], v[76:79], v[100:103], v[36:39]
	ds_read_b128 v[64:67], v150 offset:32768
	ds_read_b128 v[68:71], v150 offset:34816
	ds_read_b128 v[80:83], v162 offset:49152
	s_add_u32 m0, s38, 8192
	s_nop 0
	global_load_lds_dwordx4 v166, s[98:99]
	s_add_u32 m0, s38, 12288
	s_nop 0
	global_load_lds_dwordx4 v167, s[98:99]
	s_add_u32 s98, s98, 128
	s_addc_u32 s99, s99, 0
	s_waitcnt lgkmcnt(8)
	v_mfma_f32_16x16x32_bf16 v[8:11], v[72:75], v[104:107], v[8:11]
	v_mfma_f32_16x16x32_bf16 v[40:43], v[76:79], v[104:107], v[40:43]
	ds_read_b128 v[84:87], v162 offset:51200
	s_add_u32 m0, s38, 16384
	s_nop 0
	global_load_lds_dwordx4 v164, s[100:101]
	s_add_u32 m0, s38, 20480
	s_nop 0
	global_load_lds_dwordx4 v165, s[100:101]
	s_waitcnt lgkmcnt(8)
	v_mfma_f32_16x16x32_bf16 v[12:15], v[72:75], v[108:111], v[12:15]
	v_mfma_f32_16x16x32_bf16 v[44:47], v[76:79], v[108:111], v[44:47]
	ds_read_b128 v[88:91], v162 offset:53248
	s_add_u32 m0, s38, 24576
	s_nop 0
	global_load_lds_dwordx4 v166, s[100:101]
	s_add_u32 m0, s38, 28672
	s_nop 0
	global_load_lds_dwordx4 v167, s[100:101]
	s_add_u32 s100, s100, 128
	s_addc_u32 s101, s101, 0
	s_waitcnt lgkmcnt(8)
	v_mfma_f32_16x16x32_bf16 v[16:19], v[72:75], v[112:115], v[16:19]
	v_mfma_f32_16x16x32_bf16 v[48:51], v[76:79], v[112:115], v[48:51]
	ds_read_b128 v[92:95], v162 offset:55296
	global_load_dwordx4 v[172:175], v168, s[14:15] nt
	s_waitcnt lgkmcnt(8)
	v_mfma_f32_16x16x32_bf16 v[20:23], v[72:75], v[116:119], v[20:23]
	v_mfma_f32_16x16x32_bf16 v[52:55], v[76:79], v[116:119], v[52:55]
	ds_read_b128 v[96:99], v162 offset:57344
	global_load_dwordx4 v[176:179], v168, s[14:15] offset:16 nt
	s_add_u32 s14, s14, 0x4000
	s_addc_u32 s15, s15, 0
	s_waitcnt lgkmcnt(8)
	v_mfma_f32_16x16x32_bf16 v[24:27], v[72:75], v[120:123], v[24:27]
	v_mfma_f32_16x16x32_bf16 v[56:59], v[76:79], v[120:123], v[56:59]
	ds_read_b128 v[100:103], v162 offset:59392
	global_load_dwordx4 v[180:183], v168, s[14:15] nt
	s_waitcnt lgkmcnt(8)
	v_mfma_f32_16x16x32_bf16 v[28:31], v[72:75], v[124:127], v[28:31]
	v_mfma_f32_16x16x32_bf16 v[60:63], v[76:79], v[124:127], v[60:63]
	ds_read_b128 v[104:107], v162 offset:61440
	global_load_dwordx4 v[184:187], v168, s[14:15] offset:16 nt
	s_add_u32 s14, s14, 0x4000
	s_addc_u32 s15, s15, 0
	s_waitcnt lgkmcnt(6)
	v_mfma_f32_16x16x32_bf16 v[0:3], v[64:67], v[80:83], v[0:3]
	v_mfma_f32_16x16x32_bf16 v[32:35], v[68:71], v[80:83], v[32:35]
	ds_read_b128 v[108:111], v162 offset:63488
	global_load_dwordx4 v[188:191], v168, s[14:15] nt
	s_waitcnt lgkmcnt(6)
	v_mfma_f32_16x16x32_bf16 v[4:7], v[64:67], v[84:87], v[4:7]
	v_mfma_f32_16x16x32_bf16 v[36:39], v[68:71], v[84:87], v[36:39]
	ds_read_b128 v[72:75], v151 offset:32768
	ds_read_b128 v[76:79], v151 offset:34816
	ds_read_b128 v[112:115], v163 offset:49152
	global_load_dwordx4 v[192:195], v168, s[14:15] offset:16 nt
	s_add_u32 s14, s14, 0x4000
	s_addc_u32 s15, s15, 0
	s_waitcnt lgkmcnt(8)
	v_mfma_f32_16x16x32_bf16 v[8:11], v[64:67], v[88:91], v[8:11]
	v_mfma_f32_16x16x32_bf16 v[40:43], v[68:71], v[88:91], v[40:43]
	ds_read_b128 v[116:119], v163 offset:51200
	global_load_dwordx4 v[196:199], v168, s[14:15] nt
	s_waitcnt lgkmcnt(8)
	v_mfma_f32_16x16x32_bf16 v[12:15], v[64:67], v[92:95], v[12:15]
	v_mfma_f32_16x16x32_bf16 v[44:47], v[68:71], v[92:95], v[44:47]
	ds_read_b128 v[120:123], v163 offset:53248
	global_load_dwordx4 v[200:203], v168, s[14:15] offset:16 nt
	s_add_u32 s14, s14, 0x4000
	s_addc_u32 s15, s15, 0
	s_waitcnt lgkmcnt(8)
	v_mfma_f32_16x16x32_bf16 v[16:19], v[64:67], v[96:99], v[16:19]
	v_mfma_f32_16x16x32_bf16 v[48:51], v[68:71], v[96:99], v[48:51]
	ds_read_b128 v[124:127], v163 offset:55296
	s_waitcnt lgkmcnt(8)
	v_mfma_f32_16x16x32_bf16 v[20:23], v[64:67], v[100:103], v[20:23]
	v_mfma_f32_16x16x32_bf16 v[52:55], v[68:71], v[100:103], v[52:55]
	ds_read_b128 v[80:83], v163 offset:57344
	s_waitcnt lgkmcnt(8)
	v_mfma_f32_16x16x32_bf16 v[24:27], v[64:67], v[104:107], v[24:27]
	v_mfma_f32_16x16x32_bf16 v[56:59], v[68:71], v[104:107], v[56:59]
	ds_read_b128 v[84:87], v163 offset:59392
	s_waitcnt lgkmcnt(8)
	v_mfma_f32_16x16x32_bf16 v[28:31], v[64:67], v[108:111], v[28:31]
	v_mfma_f32_16x16x32_bf16 v[60:63], v[68:71], v[108:111], v[60:63]
	ds_read_b128 v[88:91], v163 offset:61440
	s_waitcnt lgkmcnt(6)
	v_mfma_f32_16x16x32_bf16 v[0:3], v[72:75], v[112:115], v[0:3]
	v_mfma_f32_16x16x32_bf16 v[32:35], v[76:79], v[112:115], v[32:35]
	ds_read_b128 v[92:95], v163 offset:63488
	s_waitcnt vmcnt(8) lgkmcnt(0)
	s_barrier
	s_add_u32 m0, s38, 32768
	s_nop 0
	global_load_lds_dwordx4 v164, s[98:99]
	s_waitcnt lgkmcnt(6)
	v_mfma_f32_16x16x32_bf16 v[4:7], v[72:75], v[116:119], v[4:7]
	v_mfma_f32_16x16x32_bf16 v[36:39], v[76:79], v[116:119], v[36:39]
	ds_read_b128 v[64:67], v150 offset:0
	ds_read_b128 v[68:71], v150 offset:2048
	ds_read_b128 v[96:99], v162 offset:16384
	s_add_u32 m0, s38, 36864
	s_nop 0
	global_load_lds_dwordx4 v165, s[98:99]
	s_waitcnt lgkmcnt(8)
	v_mfma_f32_16x16x32_bf16 v[8:11], v[72:75], v[120:123], v[8:11]
	v_mfma_f32_16x16x32_bf16 v[40:43], v[76:79], v[120:123], v[40:43]
	ds_read_b128 v[100:103], v162 offset:18432
	s_add_u32 m0, s38, 40960
	s_nop 0
	global_load_lds_dwordx4 v166, s[98:99]
	s_waitcnt lgkmcnt(8)
	v_mfma_f32_16x16x32_bf16 v[12:15], v[72:75], v[124:127], v[12:15]
	v_mfma_f32_16x16x32_bf16 v[44:47], v[76:79], v[124:127], v[44:47]
	ds_read_b128 v[104:107], v162 offset:20480
	s_add_u32 m0, s38, 45056
	s_nop 0
	global_load_lds_dwordx4 v167, s[98:99]
	s_add_u32 s98, s98, 128
	s_addc_u32 s99, s99, 0
	s_waitcnt lgkmcnt(8)
	v_mfma_f32_16x16x32_bf16 v[16:19], v[72:75], v[80:83], v[16:19]
	v_mfma_f32_16x16x32_bf16 v[48:51], v[76:79], v[80:83], v[48:51]
	ds_read_b128 v[108:111], v162 offset:22528
	s_add_u32 m0, s38, 49152
	s_nop 0
	global_load_lds_dwordx4 v164, s[100:101]
	s_waitcnt lgkmcnt(8)
	v_mfma_f32_16x16x32_bf16 v[20:23], v[72:75], v[84:87], v[20:23]
	v_mfma_f32_16x16x32_bf16 v[52:55], v[76:79], v[84:87], v[52:55]
	ds_read_b128 v[112:115], v162 offset:24576
	s_add_u32 m0, s38, 53248
	s_nop 0
	global_load_lds_dwordx4 v165, s[100:101]
	s_waitcnt lgkmcnt(8)
	v_mfma_f32_16x16x32_bf16 v[24:27], v[72:75], v[88:91], v[24:27]
	v_mfma_f32_16x16x32_bf16 v[56:59], v[76:79], v[88:91], v[56:59]
	ds_read_b128 v[116:119], v162 offset:26624
	s_add_u32 m0, s38, 57344
	s_nop 0
	global_load_lds_dwordx4 v166, s[100:101]
	s_waitcnt lgkmcnt(8)
	v_mfma_f32_16x16x32_bf16 v[28:31], v[72:75], v[92:95], v[28:31]
	v_mfma_f32_16x16x32_bf16 v[60:63], v[76:79], v[92:95], v[60:63]
	ds_read_b128 v[120:123], v162 offset:28672
	s_add_u32 m0, s38, 61440
	s_nop 0
	global_load_lds_dwordx4 v167, s[100:101]
	s_add_u32 s100, s100, 128
	s_addc_u32 s101, s101, 0
	s_waitcnt lgkmcnt(6)
	v_mfma_f32_16x16x32_bf16 v[0:3], v[64:67], v[96:99], v[0:3]
	v_mfma_f32_16x16x32_bf16 v[32:35], v[68:71], v[96:99], v[32:35]
	ds_read_b128 v[124:127], v162 offset:30720
	s_waitcnt lgkmcnt(6)
	v_mfma_f32_16x16x32_bf16 v[4:7], v[64:67], v[100:103], v[4:7]
	v_mfma_f32_16x16x32_bf16 v[36:39], v[68:71], v[100:103], v[36:39]
	ds_read_b128 v[72:75], v151 offset:0
	ds_read_b128 v[76:79], v151 offset:2048
	ds_read_b128 v[80:83], v163 offset:16384
	s_waitcnt lgkmcnt(8)
	v_mfma_f32_16x16x32_bf16 v[8:11], v[64:67], v[104:107], v[8:11]
	v_mfma_f32_16x16x32_bf16 v[40:43], v[68:71], v[104:107], v[40:43]
	ds_read_b128 v[84:87], v163 offset:18432
	s_waitcnt lgkmcnt(8)
	v_mfma_f32_16x16x32_bf16 v[12:15], v[64:67], v[108:111], v[12:15]
	v_mfma_f32_16x16x32_bf16 v[44:47], v[68:71], v[108:111], v[44:47]
	ds_read_b128 v[88:91], v163 offset:20480
	s_waitcnt lgkmcnt(8)
	v_mfma_f32_16x16x32_bf16 v[16:19], v[64:67], v[112:115], v[16:19]
	v_mfma_f32_16x16x32_bf16 v[48:51], v[68:71], v[112:115], v[48:51]
	ds_read_b128 v[92:95], v163 offset:22528
	s_waitcnt lgkmcnt(8)
	v_mfma_f32_16x16x32_bf16 v[20:23], v[64:67], v[116:119], v[20:23]
	v_mfma_f32_16x16x32_bf16 v[52:55], v[68:71], v[116:119], v[52:55]
	ds_read_b128 v[96:99], v163 offset:24576
	s_waitcnt lgkmcnt(8)
	v_mfma_f32_16x16x32_bf16 v[24:27], v[64:67], v[120:123], v[24:27]
	v_mfma_f32_16x16x32_bf16 v[56:59], v[68:71], v[120:123], v[56:59]
	ds_read_b128 v[100:103], v163 offset:26624
	s_waitcnt lgkmcnt(8)
	v_mfma_f32_16x16x32_bf16 v[28:31], v[64:67], v[124:127], v[28:31]
	v_mfma_f32_16x16x32_bf16 v[60:63], v[68:71], v[124:127], v[60:63]
	ds_read_b128 v[104:107], v163 offset:28672
	s_waitcnt lgkmcnt(6)
	v_mfma_f32_16x16x32_bf16 v[0:3], v[72:75], v[80:83], v[0:3]
	v_mfma_f32_16x16x32_bf16 v[32:35], v[76:79], v[80:83], v[32:35]
	ds_read_b128 v[108:111], v163 offset:30720
	s_waitcnt vmcnt(0) lgkmcnt(0)
	s_barrier
	s_add_u32 m0, s38, 0
	s_nop 0
	global_load_lds_dwordx4 v164, s[98:99]
	s_waitcnt lgkmcnt(6)
	v_mfma_f32_16x16x32_bf16 v[4:7], v[72:75], v[84:87], v[4:7]
	v_mfma_f32_16x16x32_bf16 v[36:39], v[76:79], v[84:87], v[36:39]
	ds_read_b128 v[64:67], v150 offset:32768
	ds_read_b128 v[68:71], v150 offset:34816
	ds_read_b128 v[112:115], v162 offset:49152
	s_add_u32 m0, s38, 4096
	s_nop 0
	global_load_lds_dwordx4 v165, s[98:99]
	s_waitcnt lgkmcnt(8)
	v_mfma_f32_16x16x32_bf16 v[8:11], v[72:75], v[88:91], v[8:11]
	v_mfma_f32_16x16x32_bf16 v[40:43], v[76:79], v[88:91], v[40:43]
	ds_read_b128 v[116:119], v162 offset:51200
	s_add_u32 m0, s38, 8192
	s_nop 0
	global_load_lds_dwordx4 v166, s[98:99]
	s_waitcnt lgkmcnt(8)
	v_mfma_f32_16x16x32_bf16 v[12:15], v[72:75], v[92:95], v[12:15]
	v_mfma_f32_16x16x32_bf16 v[44:47], v[76:79], v[92:95], v[44:47]
	ds_read_b128 v[120:123], v162 offset:53248
	s_add_u32 m0, s38, 12288
	s_nop 0
	global_load_lds_dwordx4 v167, s[98:99]
	s_add_u32 s98, s98, 128
	s_addc_u32 s99, s99, 0
	s_waitcnt lgkmcnt(8)
	v_mfma_f32_16x16x32_bf16 v[16:19], v[72:75], v[96:99], v[16:19]
	v_mfma_f32_16x16x32_bf16 v[48:51], v[76:79], v[96:99], v[48:51]
	ds_read_b128 v[124:127], v162 offset:55296
	s_add_u32 m0, s38, 16384
	s_nop 0
	global_load_lds_dwordx4 v164, s[100:101]
	s_waitcnt lgkmcnt(8)
	v_mfma_f32_16x16x32_bf16 v[20:23], v[72:75], v[100:103], v[20:23]
	v_mfma_f32_16x16x32_bf16 v[52:55], v[76:79], v[100:103], v[52:55]
	ds_read_b128 v[80:83], v162 offset:57344
	s_add_u32 m0, s38, 20480
	s_nop 0
	global_load_lds_dwordx4 v165, s[100:101]
	s_waitcnt lgkmcnt(8)
	v_mfma_f32_16x16x32_bf16 v[24:27], v[72:75], v[104:107], v[24:27]
	v_mfma_f32_16x16x32_bf16 v[56:59], v[76:79], v[104:107], v[56:59]
	ds_read_b128 v[84:87], v162 offset:59392
	s_add_u32 m0, s38, 24576
	s_nop 0
	global_load_lds_dwordx4 v166, s[100:101]
	s_waitcnt lgkmcnt(8)
	v_mfma_f32_16x16x32_bf16 v[28:31], v[72:75], v[108:111], v[28:31]
	v_mfma_f32_16x16x32_bf16 v[60:63], v[76:79], v[108:111], v[60:63]
	ds_read_b128 v[88:91], v162 offset:61440
	s_add_u32 m0, s38, 28672
	s_nop 0
	global_load_lds_dwordx4 v167, s[100:101]
	s_add_u32 s100, s100, 128
	s_addc_u32 s101, s101, 0
	s_waitcnt lgkmcnt(6)
	v_mfma_f32_16x16x32_bf16 v[0:3], v[64:67], v[112:115], v[0:3]
	v_mfma_f32_16x16x32_bf16 v[32:35], v[68:71], v[112:115], v[32:35]
	ds_read_b128 v[92:95], v162 offset:63488
	s_waitcnt lgkmcnt(6)
	v_mfma_f32_16x16x32_bf16 v[4:7], v[64:67], v[116:119], v[4:7]
	v_mfma_f32_16x16x32_bf16 v[36:39], v[68:71], v[116:119], v[36:39]
	ds_read_b128 v[72:75], v151 offset:32768
	ds_read_b128 v[76:79], v151 offset:34816
	ds_read_b128 v[96:99], v163 offset:49152
	s_waitcnt lgkmcnt(8)
	v_mfma_f32_16x16x32_bf16 v[8:11], v[64:67], v[120:123], v[8:11]
	v_mfma_f32_16x16x32_bf16 v[40:43], v[68:71], v[120:123], v[40:43]
	ds_read_b128 v[100:103], v163 offset:51200
	s_waitcnt lgkmcnt(8)
	v_mfma_f32_16x16x32_bf16 v[12:15], v[64:67], v[124:127], v[12:15]
	v_mfma_f32_16x16x32_bf16 v[44:47], v[68:71], v[124:127], v[44:47]
	ds_read_b128 v[104:107], v163 offset:53248
	s_waitcnt lgkmcnt(8)
	v_mfma_f32_16x16x32_bf16 v[16:19], v[64:67], v[80:83], v[16:19]
	v_mfma_f32_16x16x32_bf16 v[48:51], v[68:71], v[80:83], v[48:51]
	ds_read_b128 v[108:111], v163 offset:55296
	s_waitcnt lgkmcnt(8)
	v_mfma_f32_16x16x32_bf16 v[20:23], v[64:67], v[84:87], v[20:23]
	v_mfma_f32_16x16x32_bf16 v[52:55], v[68:71], v[84:87], v[52:55]
	ds_read_b128 v[112:115], v163 offset:57344
	s_waitcnt lgkmcnt(8)
	v_mfma_f32_16x16x32_bf16 v[24:27], v[64:67], v[88:91], v[24:27]
	v_mfma_f32_16x16x32_bf16 v[56:59], v[68:71], v[88:91], v[56:59]
	ds_read_b128 v[116:119], v163 offset:59392
	s_waitcnt lgkmcnt(8)
	v_mfma_f32_16x16x32_bf16 v[28:31], v[64:67], v[92:95], v[28:31]
	v_mfma_f32_16x16x32_bf16 v[60:63], v[68:71], v[92:95], v[60:63]
	ds_read_b128 v[120:123], v163 offset:61440
	s_waitcnt lgkmcnt(6)
	v_mfma_f32_16x16x32_bf16 v[0:3], v[72:75], v[96:99], v[0:3]
	v_mfma_f32_16x16x32_bf16 v[32:35], v[76:79], v[96:99], v[32:35]
	ds_read_b128 v[124:127], v163 offset:63488
	s_waitcnt vmcnt(0) lgkmcnt(0)
	s_barrier
	s_add_u32 m0, s38, 32768
	s_nop 0
	global_load_lds_dwordx4 v164, s[98:99]
	s_waitcnt lgkmcnt(6)
	v_mfma_f32_16x16x32_bf16 v[4:7], v[72:75], v[100:103], v[4:7]
	v_mfma_f32_16x16x32_bf16 v[36:39], v[76:79], v[100:103], v[36:39]
	ds_read_b128 v[64:67], v150 offset:0
	ds_read_b128 v[68:71], v150 offset:2048
	ds_read_b128 v[80:83], v162 offset:16384
	s_add_u32 m0, s38, 36864
	s_nop 0
	global_load_lds_dwordx4 v165, s[98:99]
	s_waitcnt lgkmcnt(8)
	v_mfma_f32_16x16x32_bf16 v[8:11], v[72:75], v[104:107], v[8:11]
	v_mfma_f32_16x16x32_bf16 v[40:43], v[76:79], v[104:107], v[40:43]
	ds_read_b128 v[84:87], v162 offset:18432
	s_add_u32 m0, s38, 40960
	s_nop 0
	global_load_lds_dwordx4 v166, s[98:99]
	s_waitcnt lgkmcnt(8)
	v_mfma_f32_16x16x32_bf16 v[12:15], v[72:75], v[108:111], v[12:15]
	v_mfma_f32_16x16x32_bf16 v[44:47], v[76:79], v[108:111], v[44:47]
	ds_read_b128 v[88:91], v162 offset:20480
	s_add_u32 m0, s38, 45056
	s_nop 0
	global_load_lds_dwordx4 v167, s[98:99]
	s_add_u32 s98, s98, 128
	s_addc_u32 s99, s99, 0
	s_waitcnt lgkmcnt(8)
	v_mfma_f32_16x16x32_bf16 v[16:19], v[72:75], v[112:115], v[16:19]
	v_mfma_f32_16x16x32_bf16 v[48:51], v[76:79], v[112:115], v[48:51]
	ds_read_b128 v[92:95], v162 offset:22528
	s_add_u32 m0, s38, 49152
	s_nop 0
	global_load_lds_dwordx4 v164, s[100:101]
	s_waitcnt lgkmcnt(8)
	v_mfma_f32_16x16x32_bf16 v[20:23], v[72:75], v[116:119], v[20:23]
	v_mfma_f32_16x16x32_bf16 v[52:55], v[76:79], v[116:119], v[52:55]
	ds_read_b128 v[96:99], v162 offset:24576
	s_add_u32 m0, s38, 53248
	s_nop 0
	global_load_lds_dwordx4 v165, s[100:101]
	s_waitcnt lgkmcnt(8)
	v_mfma_f32_16x16x32_bf16 v[24:27], v[72:75], v[120:123], v[24:27]
	v_mfma_f32_16x16x32_bf16 v[56:59], v[76:79], v[120:123], v[56:59]
	ds_read_b128 v[100:103], v162 offset:26624
	s_add_u32 m0, s38, 57344
	s_nop 0
	global_load_lds_dwordx4 v166, s[100:101]
	s_waitcnt lgkmcnt(8)
	v_mfma_f32_16x16x32_bf16 v[28:31], v[72:75], v[124:127], v[28:31]
	v_mfma_f32_16x16x32_bf16 v[60:63], v[76:79], v[124:127], v[60:63]
	ds_read_b128 v[104:107], v162 offset:28672
	s_add_u32 m0, s38, 61440
	s_nop 0
	global_load_lds_dwordx4 v167, s[100:101]
	s_add_u32 s100, s100, 128
	s_addc_u32 s101, s101, 0
	s_waitcnt lgkmcnt(6)
	v_mfma_f32_16x16x32_bf16 v[0:3], v[64:67], v[80:83], v[0:3]
	v_mfma_f32_16x16x32_bf16 v[32:35], v[68:71], v[80:83], v[32:35]
	ds_read_b128 v[108:111], v162 offset:30720
	s_waitcnt lgkmcnt(6)
	v_mfma_f32_16x16x32_bf16 v[4:7], v[64:67], v[84:87], v[4:7]
	v_mfma_f32_16x16x32_bf16 v[36:39], v[68:71], v[84:87], v[36:39]
	ds_read_b128 v[72:75], v151 offset:0
	ds_read_b128 v[76:79], v151 offset:2048
	ds_read_b128 v[112:115], v163 offset:16384
	s_waitcnt lgkmcnt(8)
	v_mfma_f32_16x16x32_bf16 v[8:11], v[64:67], v[88:91], v[8:11]
	v_mfma_f32_16x16x32_bf16 v[40:43], v[68:71], v[88:91], v[40:43]
	ds_read_b128 v[116:119], v163 offset:18432
	s_waitcnt lgkmcnt(8)
	v_mfma_f32_16x16x32_bf16 v[12:15], v[64:67], v[92:95], v[12:15]
	v_mfma_f32_16x16x32_bf16 v[44:47], v[68:71], v[92:95], v[44:47]
	ds_read_b128 v[120:123], v163 offset:20480
	s_waitcnt lgkmcnt(8)
	v_mfma_f32_16x16x32_bf16 v[16:19], v[64:67], v[96:99], v[16:19]
	v_mfma_f32_16x16x32_bf16 v[48:51], v[68:71], v[96:99], v[48:51]
	ds_read_b128 v[124:127], v163 offset:22528
	s_waitcnt lgkmcnt(8)
	v_mfma_f32_16x16x32_bf16 v[20:23], v[64:67], v[100:103], v[20:23]
	v_mfma_f32_16x16x32_bf16 v[52:55], v[68:71], v[100:103], v[52:55]
	ds_read_b128 v[80:83], v163 offset:24576
	s_waitcnt lgkmcnt(8)
	v_mfma_f32_16x16x32_bf16 v[24:27], v[64:67], v[104:107], v[24:27]
	v_mfma_f32_16x16x32_bf16 v[56:59], v[68:71], v[104:107], v[56:59]
	ds_read_b128 v[84:87], v163 offset:26624
	s_waitcnt lgkmcnt(8)
	v_mfma_f32_16x16x32_bf16 v[28:31], v[64:67], v[108:111], v[28:31]
	v_mfma_f32_16x16x32_bf16 v[60:63], v[68:71], v[108:111], v[60:63]
	ds_read_b128 v[88:91], v163 offset:28672
	s_waitcnt lgkmcnt(6)
	v_mfma_f32_16x16x32_bf16 v[0:3], v[72:75], v[112:115], v[0:3]
	v_mfma_f32_16x16x32_bf16 v[32:35], v[76:79], v[112:115], v[32:35]
	ds_read_b128 v[92:95], v163 offset:30720
	s_waitcnt vmcnt(0) lgkmcnt(0)
	s_barrier
	s_add_u32 m0, s38, 0
	s_nop 0
	global_load_lds_dwordx4 v164, s[98:99]
	s_waitcnt lgkmcnt(6)
	v_mfma_f32_16x16x32_bf16 v[4:7], v[72:75], v[116:119], v[4:7]
	v_mfma_f32_16x16x32_bf16 v[36:39], v[76:79], v[116:119], v[36:39]
	ds_read_b128 v[64:67], v150 offset:32768
	ds_read_b128 v[68:71], v150 offset:34816
	ds_read_b128 v[96:99], v162 offset:49152
	s_add_u32 m0, s38, 4096
	s_nop 0
	global_load_lds_dwordx4 v165, s[98:99]
	s_waitcnt lgkmcnt(8)
	v_mfma_f32_16x16x32_bf16 v[8:11], v[72:75], v[120:123], v[8:11]
	v_mfma_f32_16x16x32_bf16 v[40:43], v[76:79], v[120:123], v[40:43]
	ds_read_b128 v[100:103], v162 offset:51200
	s_add_u32 m0, s38, 8192
	s_nop 0
	global_load_lds_dwordx4 v166, s[98:99]
	s_waitcnt lgkmcnt(8)
	v_mfma_f32_16x16x32_bf16 v[12:15], v[72:75], v[124:127], v[12:15]
	v_mfma_f32_16x16x32_bf16 v[44:47], v[76:79], v[124:127], v[44:47]
	ds_read_b128 v[104:107], v162 offset:53248
	s_add_u32 m0, s38, 12288
	s_nop 0
	global_load_lds_dwordx4 v167, s[98:99]
	s_add_u32 s98, s98, 128
	s_addc_u32 s99, s99, 0
	s_waitcnt lgkmcnt(8)
	v_mfma_f32_16x16x32_bf16 v[16:19], v[72:75], v[80:83], v[16:19]
	v_mfma_f32_16x16x32_bf16 v[48:51], v[76:79], v[80:83], v[48:51]
	ds_read_b128 v[108:111], v162 offset:55296
	s_add_u32 m0, s38, 16384
	s_nop 0
	global_load_lds_dwordx4 v164, s[100:101]
	s_waitcnt lgkmcnt(8)
	v_mfma_f32_16x16x32_bf16 v[20:23], v[72:75], v[84:87], v[20:23]
	v_mfma_f32_16x16x32_bf16 v[52:55], v[76:79], v[84:87], v[52:55]
	ds_read_b128 v[112:115], v162 offset:57344
	s_add_u32 m0, s38, 20480
	s_nop 0
	global_load_lds_dwordx4 v165, s[100:101]
	s_waitcnt lgkmcnt(8)
	v_mfma_f32_16x16x32_bf16 v[24:27], v[72:75], v[88:91], v[24:27]
	v_mfma_f32_16x16x32_bf16 v[56:59], v[76:79], v[88:91], v[56:59]
	ds_read_b128 v[116:119], v162 offset:59392
	s_add_u32 m0, s38, 24576
	s_nop 0
	global_load_lds_dwordx4 v166, s[100:101]
	s_waitcnt lgkmcnt(8)
	v_mfma_f32_16x16x32_bf16 v[28:31], v[72:75], v[92:95], v[28:31]
	v_mfma_f32_16x16x32_bf16 v[60:63], v[76:79], v[92:95], v[60:63]
	ds_read_b128 v[120:123], v162 offset:61440
	s_add_u32 m0, s38, 28672
	s_nop 0
	global_load_lds_dwordx4 v167, s[100:101]
	s_add_u32 s100, s100, 128
	s_addc_u32 s101, s101, 0
	s_waitcnt lgkmcnt(6)
	v_mfma_f32_16x16x32_bf16 v[0:3], v[64:67], v[96:99], v[0:3]
	v_mfma_f32_16x16x32_bf16 v[32:35], v[68:71], v[96:99], v[32:35]
	ds_read_b128 v[124:127], v162 offset:63488
	s_waitcnt lgkmcnt(6)
	v_mfma_f32_16x16x32_bf16 v[4:7], v[64:67], v[100:103], v[4:7]
	v_mfma_f32_16x16x32_bf16 v[36:39], v[68:71], v[100:103], v[36:39]
	ds_read_b128 v[72:75], v151 offset:32768
	ds_read_b128 v[76:79], v151 offset:34816
	ds_read_b128 v[80:83], v163 offset:49152
	s_waitcnt lgkmcnt(8)
	v_mfma_f32_16x16x32_bf16 v[8:11], v[64:67], v[104:107], v[8:11]
	v_mfma_f32_16x16x32_bf16 v[40:43], v[68:71], v[104:107], v[40:43]
	ds_read_b128 v[84:87], v163 offset:51200
	s_waitcnt lgkmcnt(8)
	v_mfma_f32_16x16x32_bf16 v[12:15], v[64:67], v[108:111], v[12:15]
	v_mfma_f32_16x16x32_bf16 v[44:47], v[68:71], v[108:111], v[44:47]
	ds_read_b128 v[88:91], v163 offset:53248
	s_waitcnt lgkmcnt(8)
	v_mfma_f32_16x16x32_bf16 v[16:19], v[64:67], v[112:115], v[16:19]
	v_mfma_f32_16x16x32_bf16 v[48:51], v[68:71], v[112:115], v[48:51]
	ds_read_b128 v[92:95], v163 offset:55296
	s_waitcnt lgkmcnt(8)
	v_mfma_f32_16x16x32_bf16 v[20:23], v[64:67], v[116:119], v[20:23]
	v_mfma_f32_16x16x32_bf16 v[52:55], v[68:71], v[116:119], v[52:55]
	ds_read_b128 v[96:99], v163 offset:57344
	s_waitcnt lgkmcnt(8)
	v_mfma_f32_16x16x32_bf16 v[24:27], v[64:67], v[120:123], v[24:27]
	v_mfma_f32_16x16x32_bf16 v[56:59], v[68:71], v[120:123], v[56:59]
	ds_read_b128 v[100:103], v163 offset:59392
	s_waitcnt lgkmcnt(8)
	v_mfma_f32_16x16x32_bf16 v[28:31], v[64:67], v[124:127], v[28:31]
	v_mfma_f32_16x16x32_bf16 v[60:63], v[68:71], v[124:127], v[60:63]
	ds_read_b128 v[104:107], v163 offset:61440
	s_waitcnt lgkmcnt(6)
	v_mfma_f32_16x16x32_bf16 v[0:3], v[72:75], v[80:83], v[0:3]
	v_mfma_f32_16x16x32_bf16 v[32:35], v[76:79], v[80:83], v[32:35]
	ds_read_b128 v[108:111], v163 offset:63488
	s_waitcnt vmcnt(0) lgkmcnt(0)
	s_barrier
	s_add_u32 m0, s38, 32768
	s_nop 0
	global_load_lds_dwordx4 v164, s[98:99]
	s_waitcnt lgkmcnt(6)
	v_mfma_f32_16x16x32_bf16 v[4:7], v[72:75], v[84:87], v[4:7]
	v_mfma_f32_16x16x32_bf16 v[36:39], v[76:79], v[84:87], v[36:39]
	ds_read_b128 v[64:67], v150 offset:0
	ds_read_b128 v[68:71], v150 offset:2048
	ds_read_b128 v[112:115], v162 offset:16384
	s_add_u32 m0, s38, 36864
	s_nop 0
	global_load_lds_dwordx4 v165, s[98:99]
	s_waitcnt lgkmcnt(8)
	v_mfma_f32_16x16x32_bf16 v[8:11], v[72:75], v[88:91], v[8:11]
	v_mfma_f32_16x16x32_bf16 v[40:43], v[76:79], v[88:91], v[40:43]
	ds_read_b128 v[116:119], v162 offset:18432
	s_add_u32 m0, s38, 40960
	s_nop 0
	global_load_lds_dwordx4 v166, s[98:99]
	s_waitcnt lgkmcnt(8)
	v_mfma_f32_16x16x32_bf16 v[12:15], v[72:75], v[92:95], v[12:15]
	v_mfma_f32_16x16x32_bf16 v[44:47], v[76:79], v[92:95], v[44:47]
	ds_read_b128 v[120:123], v162 offset:20480
	s_add_u32 m0, s38, 45056
	s_nop 0
	global_load_lds_dwordx4 v167, s[98:99]
	s_add_u32 s98, s98, 128
	s_addc_u32 s99, s99, 0
	s_waitcnt lgkmcnt(8)
	v_mfma_f32_16x16x32_bf16 v[16:19], v[72:75], v[96:99], v[16:19]
	v_mfma_f32_16x16x32_bf16 v[48:51], v[76:79], v[96:99], v[48:51]
	ds_read_b128 v[124:127], v162 offset:22528
	s_add_u32 m0, s38, 49152
	s_nop 0
	global_load_lds_dwordx4 v164, s[100:101]
	s_waitcnt lgkmcnt(8)
	v_mfma_f32_16x16x32_bf16 v[20:23], v[72:75], v[100:103], v[20:23]
	v_mfma_f32_16x16x32_bf16 v[52:55], v[76:79], v[100:103], v[52:55]
	ds_read_b128 v[80:83], v162 offset:24576
	s_add_u32 m0, s38, 53248
	s_nop 0
	global_load_lds_dwordx4 v165, s[100:101]
	s_waitcnt lgkmcnt(8)
	v_mfma_f32_16x16x32_bf16 v[24:27], v[72:75], v[104:107], v[24:27]
	v_mfma_f32_16x16x32_bf16 v[56:59], v[76:79], v[104:107], v[56:59]
	ds_read_b128 v[84:87], v162 offset:26624
	s_add_u32 m0, s38, 57344
	s_nop 0
	global_load_lds_dwordx4 v166, s[100:101]
	s_waitcnt lgkmcnt(8)
	v_mfma_f32_16x16x32_bf16 v[28:31], v[72:75], v[108:111], v[28:31]
	v_mfma_f32_16x16x32_bf16 v[60:63], v[76:79], v[108:111], v[60:63]
	ds_read_b128 v[88:91], v162 offset:28672
	s_add_u32 m0, s38, 61440
	s_nop 0
	global_load_lds_dwordx4 v167, s[100:101]
	s_add_u32 s100, s100, 128
	s_addc_u32 s101, s101, 0
	s_waitcnt lgkmcnt(6)
	v_mfma_f32_16x16x32_bf16 v[0:3], v[64:67], v[112:115], v[0:3]
	v_mfma_f32_16x16x32_bf16 v[32:35], v[68:71], v[112:115], v[32:35]
	ds_read_b128 v[92:95], v162 offset:30720
	s_waitcnt lgkmcnt(6)
	v_mfma_f32_16x16x32_bf16 v[4:7], v[64:67], v[116:119], v[4:7]
	v_mfma_f32_16x16x32_bf16 v[36:39], v[68:71], v[116:119], v[36:39]
	ds_read_b128 v[72:75], v151 offset:0
	ds_read_b128 v[76:79], v151 offset:2048
	ds_read_b128 v[96:99], v163 offset:16384
	s_waitcnt lgkmcnt(8)
	v_mfma_f32_16x16x32_bf16 v[8:11], v[64:67], v[120:123], v[8:11]
	v_mfma_f32_16x16x32_bf16 v[40:43], v[68:71], v[120:123], v[40:43]
	ds_read_b128 v[100:103], v163 offset:18432
	s_waitcnt lgkmcnt(8)
	v_mfma_f32_16x16x32_bf16 v[12:15], v[64:67], v[124:127], v[12:15]
	v_mfma_f32_16x16x32_bf16 v[44:47], v[68:71], v[124:127], v[44:47]
	ds_read_b128 v[104:107], v163 offset:20480
	s_waitcnt lgkmcnt(8)
	v_mfma_f32_16x16x32_bf16 v[16:19], v[64:67], v[80:83], v[16:19]
	v_mfma_f32_16x16x32_bf16 v[48:51], v[68:71], v[80:83], v[48:51]
	ds_read_b128 v[108:111], v163 offset:22528
	s_waitcnt lgkmcnt(8)
	v_mfma_f32_16x16x32_bf16 v[20:23], v[64:67], v[84:87], v[20:23]
	v_mfma_f32_16x16x32_bf16 v[52:55], v[68:71], v[84:87], v[52:55]
	ds_read_b128 v[112:115], v163 offset:24576
	s_waitcnt lgkmcnt(8)
	v_mfma_f32_16x16x32_bf16 v[24:27], v[64:67], v[88:91], v[24:27]
	v_mfma_f32_16x16x32_bf16 v[56:59], v[68:71], v[88:91], v[56:59]
	ds_read_b128 v[116:119], v163 offset:26624
	s_waitcnt lgkmcnt(8)
	v_mfma_f32_16x16x32_bf16 v[28:31], v[64:67], v[92:95], v[28:31]
	v_mfma_f32_16x16x32_bf16 v[60:63], v[68:71], v[92:95], v[60:63]
	ds_read_b128 v[120:123], v163 offset:28672
	s_waitcnt lgkmcnt(6)
	v_mfma_f32_16x16x32_bf16 v[0:3], v[72:75], v[96:99], v[0:3]
	v_mfma_f32_16x16x32_bf16 v[32:35], v[76:79], v[96:99], v[32:35]
	ds_read_b128 v[124:127], v163 offset:30720
	s_waitcnt vmcnt(0) lgkmcnt(0)
	s_barrier
	s_add_u32 m0, s38, 0
	s_nop 0
	global_load_lds_dwordx4 v164, s[98:99]
	s_waitcnt lgkmcnt(6)
	v_mfma_f32_16x16x32_bf16 v[4:7], v[72:75], v[100:103], v[4:7]
	v_mfma_f32_16x16x32_bf16 v[36:39], v[76:79], v[100:103], v[36:39]
	ds_read_b128 v[64:67], v150 offset:32768
	ds_read_b128 v[68:71], v150 offset:34816
	ds_read_b128 v[80:83], v162 offset:49152
	s_add_u32 m0, s38, 4096
	s_nop 0
	global_load_lds_dwordx4 v165, s[98:99]
	s_waitcnt lgkmcnt(8)
	v_mfma_f32_16x16x32_bf16 v[8:11], v[72:75], v[104:107], v[8:11]
	v_mfma_f32_16x16x32_bf16 v[40:43], v[76:79], v[104:107], v[40:43]
	ds_read_b128 v[84:87], v162 offset:51200
	s_add_u32 m0, s38, 8192
	s_nop 0
	global_load_lds_dwordx4 v166, s[98:99]
	s_waitcnt lgkmcnt(8)
	v_mfma_f32_16x16x32_bf16 v[12:15], v[72:75], v[108:111], v[12:15]
	v_mfma_f32_16x16x32_bf16 v[44:47], v[76:79], v[108:111], v[44:47]
	ds_read_b128 v[88:91], v162 offset:53248
	s_add_u32 m0, s38, 12288
	s_nop 0
	global_load_lds_dwordx4 v167, s[98:99]
	s_add_u32 s98, s98, 128
	s_addc_u32 s99, s99, 0
	s_waitcnt lgkmcnt(8)
	v_mfma_f32_16x16x32_bf16 v[16:19], v[72:75], v[112:115], v[16:19]
	v_mfma_f32_16x16x32_bf16 v[48:51], v[76:79], v[112:115], v[48:51]
	ds_read_b128 v[92:95], v162 offset:55296
	s_add_u32 m0, s38, 16384
	s_nop 0
	global_load_lds_dwordx4 v164, s[100:101]
	s_waitcnt lgkmcnt(8)
	v_mfma_f32_16x16x32_bf16 v[20:23], v[72:75], v[116:119], v[20:23]
	v_mfma_f32_16x16x32_bf16 v[52:55], v[76:79], v[116:119], v[52:55]
	ds_read_b128 v[96:99], v162 offset:57344
	s_add_u32 m0, s38, 20480
	s_nop 0
	global_load_lds_dwordx4 v165, s[100:101]
	s_waitcnt lgkmcnt(8)
	v_mfma_f32_16x16x32_bf16 v[24:27], v[72:75], v[120:123], v[24:27]
	v_mfma_f32_16x16x32_bf16 v[56:59], v[76:79], v[120:123], v[56:59]
	ds_read_b128 v[100:103], v162 offset:59392
	s_add_u32 m0, s38, 24576
	s_nop 0
	global_load_lds_dwordx4 v166, s[100:101]
	s_waitcnt lgkmcnt(8)
	v_mfma_f32_16x16x32_bf16 v[28:31], v[72:75], v[124:127], v[28:31]
	v_mfma_f32_16x16x32_bf16 v[60:63], v[76:79], v[124:127], v[60:63]
	ds_read_b128 v[104:107], v162 offset:61440
	s_add_u32 m0, s38, 28672
	s_nop 0
	global_load_lds_dwordx4 v167, s[100:101]
	s_add_u32 s100, s100, 128
	s_addc_u32 s101, s101, 0
	s_waitcnt lgkmcnt(6)
	v_mfma_f32_16x16x32_bf16 v[0:3], v[64:67], v[80:83], v[0:3]
	v_mfma_f32_16x16x32_bf16 v[32:35], v[68:71], v[80:83], v[32:35]
	ds_read_b128 v[108:111], v162 offset:63488
	s_waitcnt lgkmcnt(6)
	v_mfma_f32_16x16x32_bf16 v[4:7], v[64:67], v[84:87], v[4:7]
	v_mfma_f32_16x16x32_bf16 v[36:39], v[68:71], v[84:87], v[36:39]
	ds_read_b128 v[72:75], v151 offset:32768
	ds_read_b128 v[76:79], v151 offset:34816
	ds_read_b128 v[112:115], v163 offset:49152
	s_waitcnt lgkmcnt(8)
	v_mfma_f32_16x16x32_bf16 v[8:11], v[64:67], v[88:91], v[8:11]
	v_mfma_f32_16x16x32_bf16 v[40:43], v[68:71], v[88:91], v[40:43]
	ds_read_b128 v[116:119], v163 offset:51200
	s_waitcnt lgkmcnt(8)
	v_mfma_f32_16x16x32_bf16 v[12:15], v[64:67], v[92:95], v[12:15]
	v_mfma_f32_16x16x32_bf16 v[44:47], v[68:71], v[92:95], v[44:47]
	ds_read_b128 v[120:123], v163 offset:53248
	s_waitcnt lgkmcnt(8)
	v_mfma_f32_16x16x32_bf16 v[16:19], v[64:67], v[96:99], v[16:19]
	v_mfma_f32_16x16x32_bf16 v[48:51], v[68:71], v[96:99], v[48:51]
	ds_read_b128 v[124:127], v163 offset:55296
	s_waitcnt lgkmcnt(8)
	v_mfma_f32_16x16x32_bf16 v[20:23], v[64:67], v[100:103], v[20:23]
	v_mfma_f32_16x16x32_bf16 v[52:55], v[68:71], v[100:103], v[52:55]
	ds_read_b128 v[80:83], v163 offset:57344
	s_waitcnt lgkmcnt(8)
	v_mfma_f32_16x16x32_bf16 v[24:27], v[64:67], v[104:107], v[24:27]
	v_mfma_f32_16x16x32_bf16 v[56:59], v[68:71], v[104:107], v[56:59]
	ds_read_b128 v[84:87], v163 offset:59392
	s_waitcnt lgkmcnt(8)
	v_mfma_f32_16x16x32_bf16 v[28:31], v[64:67], v[108:111], v[28:31]
	v_mfma_f32_16x16x32_bf16 v[60:63], v[68:71], v[108:111], v[60:63]
	ds_read_b128 v[88:91], v163 offset:61440
	s_waitcnt lgkmcnt(6)
	v_mfma_f32_16x16x32_bf16 v[0:3], v[72:75], v[112:115], v[0:3]
	v_mfma_f32_16x16x32_bf16 v[32:35], v[76:79], v[112:115], v[32:35]
	ds_read_b128 v[92:95], v163 offset:63488
	s_waitcnt vmcnt(0) lgkmcnt(0)
	s_barrier
	s_add_u32 m0, s38, 32768
	s_nop 0
	global_load_lds_dwordx4 v164, s[98:99]
	s_waitcnt lgkmcnt(6)
	v_mfma_f32_16x16x32_bf16 v[4:7], v[72:75], v[116:119], v[4:7]
	v_mfma_f32_16x16x32_bf16 v[36:39], v[76:79], v[116:119], v[36:39]
	ds_read_b128 v[64:67], v150 offset:0
	ds_read_b128 v[68:71], v150 offset:2048
	ds_read_b128 v[96:99], v162 offset:16384
	s_add_u32 m0, s38, 36864
	s_nop 0
	global_load_lds_dwordx4 v165, s[98:99]
	s_waitcnt lgkmcnt(8)
	v_mfma_f32_16x16x32_bf16 v[8:11], v[72:75], v[120:123], v[8:11]
	v_mfma_f32_16x16x32_bf16 v[40:43], v[76:79], v[120:123], v[40:43]
	ds_read_b128 v[100:103], v162 offset:18432
	s_add_u32 m0, s38, 40960
	s_nop 0
	global_load_lds_dwordx4 v166, s[98:99]
	s_waitcnt lgkmcnt(8)
	v_mfma_f32_16x16x32_bf16 v[12:15], v[72:75], v[124:127], v[12:15]
	v_mfma_f32_16x16x32_bf16 v[44:47], v[76:79], v[124:127], v[44:47]
	ds_read_b128 v[104:107], v162 offset:20480
	s_add_u32 m0, s38, 45056
	s_nop 0
	global_load_lds_dwordx4 v167, s[98:99]
	s_add_u32 s98, s98, 128
	s_addc_u32 s99, s99, 0
	s_waitcnt lgkmcnt(8)
	v_mfma_f32_16x16x32_bf16 v[16:19], v[72:75], v[80:83], v[16:19]
	v_mfma_f32_16x16x32_bf16 v[48:51], v[76:79], v[80:83], v[48:51]
	ds_read_b128 v[108:111], v162 offset:22528
	s_add_u32 m0, s38, 49152
	s_nop 0
	global_load_lds_dwordx4 v164, s[100:101]
	s_waitcnt lgkmcnt(8)
	v_mfma_f32_16x16x32_bf16 v[20:23], v[72:75], v[84:87], v[20:23]
	v_mfma_f32_16x16x32_bf16 v[52:55], v[76:79], v[84:87], v[52:55]
	ds_read_b128 v[112:115], v162 offset:24576
	s_add_u32 m0, s38, 53248
	s_nop 0
	global_load_lds_dwordx4 v165, s[100:101]
	s_waitcnt lgkmcnt(8)
	v_mfma_f32_16x16x32_bf16 v[24:27], v[72:75], v[88:91], v[24:27]
	v_mfma_f32_16x16x32_bf16 v[56:59], v[76:79], v[88:91], v[56:59]
	ds_read_b128 v[116:119], v162 offset:26624
	s_add_u32 m0, s38, 57344
	s_nop 0
	global_load_lds_dwordx4 v166, s[100:101]
	s_waitcnt lgkmcnt(8)
	v_mfma_f32_16x16x32_bf16 v[28:31], v[72:75], v[92:95], v[28:31]
	v_mfma_f32_16x16x32_bf16 v[60:63], v[76:79], v[92:95], v[60:63]
	ds_read_b128 v[120:123], v162 offset:28672
	s_add_u32 m0, s38, 61440
	s_nop 0
	global_load_lds_dwordx4 v167, s[100:101]
	s_add_u32 s100, s100, 128
	s_addc_u32 s101, s101, 0
	s_waitcnt lgkmcnt(6)
	v_mfma_f32_16x16x32_bf16 v[0:3], v[64:67], v[96:99], v[0:3]
	v_mfma_f32_16x16x32_bf16 v[32:35], v[68:71], v[96:99], v[32:35]
	ds_read_b128 v[124:127], v162 offset:30720
	s_waitcnt lgkmcnt(6)
	v_mfma_f32_16x16x32_bf16 v[4:7], v[64:67], v[100:103], v[4:7]
	v_mfma_f32_16x16x32_bf16 v[36:39], v[68:71], v[100:103], v[36:39]
	ds_read_b128 v[72:75], v151 offset:0
	ds_read_b128 v[76:79], v151 offset:2048
	ds_read_b128 v[80:83], v163 offset:16384
	s_waitcnt lgkmcnt(8)
	v_mfma_f32_16x16x32_bf16 v[8:11], v[64:67], v[104:107], v[8:11]
	v_mfma_f32_16x16x32_bf16 v[40:43], v[68:71], v[104:107], v[40:43]
	ds_read_b128 v[84:87], v163 offset:18432
	s_waitcnt lgkmcnt(8)
	v_mfma_f32_16x16x32_bf16 v[12:15], v[64:67], v[108:111], v[12:15]
	v_mfma_f32_16x16x32_bf16 v[44:47], v[68:71], v[108:111], v[44:47]
	ds_read_b128 v[88:91], v163 offset:20480
	s_waitcnt lgkmcnt(8)
	v_mfma_f32_16x16x32_bf16 v[16:19], v[64:67], v[112:115], v[16:19]
	v_mfma_f32_16x16x32_bf16 v[48:51], v[68:71], v[112:115], v[48:51]
	ds_read_b128 v[92:95], v163 offset:22528
	s_waitcnt lgkmcnt(8)
	v_mfma_f32_16x16x32_bf16 v[20:23], v[64:67], v[116:119], v[20:23]
	v_mfma_f32_16x16x32_bf16 v[52:55], v[68:71], v[116:119], v[52:55]
	ds_read_b128 v[96:99], v163 offset:24576
	s_waitcnt lgkmcnt(8)
	v_mfma_f32_16x16x32_bf16 v[24:27], v[64:67], v[120:123], v[24:27]
	v_mfma_f32_16x16x32_bf16 v[56:59], v[68:71], v[120:123], v[56:59]
	ds_read_b128 v[100:103], v163 offset:26624
	s_waitcnt lgkmcnt(8)
	v_mfma_f32_16x16x32_bf16 v[28:31], v[64:67], v[124:127], v[28:31]
	v_mfma_f32_16x16x32_bf16 v[60:63], v[68:71], v[124:127], v[60:63]
	ds_read_b128 v[104:107], v163 offset:28672
	s_waitcnt lgkmcnt(6)
	v_mfma_f32_16x16x32_bf16 v[0:3], v[72:75], v[80:83], v[0:3]
	v_mfma_f32_16x16x32_bf16 v[32:35], v[76:79], v[80:83], v[32:35]
	ds_read_b128 v[108:111], v163 offset:30720
	s_waitcnt vmcnt(0) lgkmcnt(0)
	s_barrier
	s_add_u32 m0, s38, 0
	s_nop 0
	global_load_lds_dwordx4 v164, s[98:99]
	s_waitcnt lgkmcnt(6)
	v_mfma_f32_16x16x32_bf16 v[4:7], v[72:75], v[84:87], v[4:7]
	v_mfma_f32_16x16x32_bf16 v[36:39], v[76:79], v[84:87], v[36:39]
	ds_read_b128 v[64:67], v150 offset:32768
	ds_read_b128 v[68:71], v150 offset:34816
	ds_read_b128 v[112:115], v162 offset:49152
	s_add_u32 m0, s38, 4096
	s_nop 0
	global_load_lds_dwordx4 v165, s[98:99]
	s_waitcnt lgkmcnt(8)
	v_mfma_f32_16x16x32_bf16 v[8:11], v[72:75], v[88:91], v[8:11]
	v_mfma_f32_16x16x32_bf16 v[40:43], v[76:79], v[88:91], v[40:43]
	ds_read_b128 v[116:119], v162 offset:51200
	s_add_u32 m0, s38, 8192
	s_nop 0
	global_load_lds_dwordx4 v166, s[98:99]
	s_waitcnt lgkmcnt(8)
	v_mfma_f32_16x16x32_bf16 v[12:15], v[72:75], v[92:95], v[12:15]
	v_mfma_f32_16x16x32_bf16 v[44:47], v[76:79], v[92:95], v[44:47]
	ds_read_b128 v[120:123], v162 offset:53248
	s_add_u32 m0, s38, 12288
	s_nop 0
	global_load_lds_dwordx4 v167, s[98:99]
	s_add_u32 s98, s98, 128
	s_addc_u32 s99, s99, 0
	s_waitcnt lgkmcnt(8)
	v_mfma_f32_16x16x32_bf16 v[16:19], v[72:75], v[96:99], v[16:19]
	v_mfma_f32_16x16x32_bf16 v[48:51], v[76:79], v[96:99], v[48:51]
	ds_read_b128 v[124:127], v162 offset:55296
	s_add_u32 m0, s38, 16384
	s_nop 0
	global_load_lds_dwordx4 v164, s[100:101]
	s_waitcnt lgkmcnt(8)
	v_mfma_f32_16x16x32_bf16 v[20:23], v[72:75], v[100:103], v[20:23]
	v_mfma_f32_16x16x32_bf16 v[52:55], v[76:79], v[100:103], v[52:55]
	ds_read_b128 v[80:83], v162 offset:57344
	s_add_u32 m0, s38, 20480
	s_nop 0
	global_load_lds_dwordx4 v165, s[100:101]
	s_waitcnt lgkmcnt(8)
	v_mfma_f32_16x16x32_bf16 v[24:27], v[72:75], v[104:107], v[24:27]
	v_mfma_f32_16x16x32_bf16 v[56:59], v[76:79], v[104:107], v[56:59]
	ds_read_b128 v[84:87], v162 offset:59392
	s_add_u32 m0, s38, 24576
	s_nop 0
	global_load_lds_dwordx4 v166, s[100:101]
	s_waitcnt lgkmcnt(8)
	v_mfma_f32_16x16x32_bf16 v[28:31], v[72:75], v[108:111], v[28:31]
	v_mfma_f32_16x16x32_bf16 v[60:63], v[76:79], v[108:111], v[60:63]
	ds_read_b128 v[88:91], v162 offset:61440
	s_add_u32 m0, s38, 28672
	s_nop 0
	global_load_lds_dwordx4 v167, s[100:101]
	s_add_u32 s100, s100, 128
	s_addc_u32 s101, s101, 0
	s_waitcnt lgkmcnt(6)
	v_mfma_f32_16x16x32_bf16 v[0:3], v[64:67], v[112:115], v[0:3]
	v_mfma_f32_16x16x32_bf16 v[32:35], v[68:71], v[112:115], v[32:35]
	ds_read_b128 v[92:95], v162 offset:63488
	s_waitcnt lgkmcnt(6)
	v_mfma_f32_16x16x32_bf16 v[4:7], v[64:67], v[116:119], v[4:7]
	v_mfma_f32_16x16x32_bf16 v[36:39], v[68:71], v[116:119], v[36:39]
	ds_read_b128 v[72:75], v151 offset:32768
	ds_read_b128 v[76:79], v151 offset:34816
	ds_read_b128 v[96:99], v163 offset:49152
	s_waitcnt lgkmcnt(8)
	v_mfma_f32_16x16x32_bf16 v[8:11], v[64:67], v[120:123], v[8:11]
	v_mfma_f32_16x16x32_bf16 v[40:43], v[68:71], v[120:123], v[40:43]
	ds_read_b128 v[100:103], v163 offset:51200
	s_waitcnt lgkmcnt(8)
	v_mfma_f32_16x16x32_bf16 v[12:15], v[64:67], v[124:127], v[12:15]
	v_mfma_f32_16x16x32_bf16 v[44:47], v[68:71], v[124:127], v[44:47]
	ds_read_b128 v[104:107], v163 offset:53248
	s_waitcnt lgkmcnt(8)
	v_mfma_f32_16x16x32_bf16 v[16:19], v[64:67], v[80:83], v[16:19]
	v_mfma_f32_16x16x32_bf16 v[48:51], v[68:71], v[80:83], v[48:51]
	ds_read_b128 v[108:111], v163 offset:55296
	s_waitcnt lgkmcnt(8)
	v_mfma_f32_16x16x32_bf16 v[20:23], v[64:67], v[84:87], v[20:23]
	v_mfma_f32_16x16x32_bf16 v[52:55], v[68:71], v[84:87], v[52:55]
	ds_read_b128 v[112:115], v163 offset:57344
	s_waitcnt lgkmcnt(8)
	v_mfma_f32_16x16x32_bf16 v[24:27], v[64:67], v[88:91], v[24:27]
	v_mfma_f32_16x16x32_bf16 v[56:59], v[68:71], v[88:91], v[56:59]
	ds_read_b128 v[116:119], v163 offset:59392
	s_waitcnt lgkmcnt(8)
	v_mfma_f32_16x16x32_bf16 v[28:31], v[64:67], v[92:95], v[28:31]
	v_mfma_f32_16x16x32_bf16 v[60:63], v[68:71], v[92:95], v[60:63]
	ds_read_b128 v[120:123], v163 offset:61440
	s_waitcnt lgkmcnt(6)
	v_mfma_f32_16x16x32_bf16 v[0:3], v[72:75], v[96:99], v[0:3]
	v_mfma_f32_16x16x32_bf16 v[32:35], v[76:79], v[96:99], v[32:35]
	ds_read_b128 v[124:127], v163 offset:63488
	s_waitcnt vmcnt(0) lgkmcnt(0)
	s_barrier
	s_add_u32 m0, s38, 32768
	s_nop 0
	global_load_lds_dwordx4 v164, s[98:99]
	s_waitcnt lgkmcnt(6)
	v_mfma_f32_16x16x32_bf16 v[4:7], v[72:75], v[100:103], v[4:7]
	v_mfma_f32_16x16x32_bf16 v[36:39], v[76:79], v[100:103], v[36:39]
	ds_read_b128 v[64:67], v150 offset:0
	ds_read_b128 v[68:71], v150 offset:2048
	ds_read_b128 v[80:83], v162 offset:16384
	s_add_u32 m0, s38, 36864
	s_nop 0
	global_load_lds_dwordx4 v165, s[98:99]
	s_waitcnt lgkmcnt(8)
	v_mfma_f32_16x16x32_bf16 v[8:11], v[72:75], v[104:107], v[8:11]
	v_mfma_f32_16x16x32_bf16 v[40:43], v[76:79], v[104:107], v[40:43]
	ds_read_b128 v[84:87], v162 offset:18432
	s_add_u32 m0, s38, 40960
	s_nop 0
	global_load_lds_dwordx4 v166, s[98:99]
	s_waitcnt lgkmcnt(8)
	v_mfma_f32_16x16x32_bf16 v[12:15], v[72:75], v[108:111], v[12:15]
	v_mfma_f32_16x16x32_bf16 v[44:47], v[76:79], v[108:111], v[44:47]
	ds_read_b128 v[88:91], v162 offset:20480
	s_add_u32 m0, s38, 45056
	s_nop 0
	global_load_lds_dwordx4 v167, s[98:99]
	s_add_u32 s98, s98, 128
	s_addc_u32 s99, s99, 0
	s_waitcnt lgkmcnt(8)
	v_mfma_f32_16x16x32_bf16 v[16:19], v[72:75], v[112:115], v[16:19]
	v_mfma_f32_16x16x32_bf16 v[48:51], v[76:79], v[112:115], v[48:51]
	ds_read_b128 v[92:95], v162 offset:22528
	s_add_u32 m0, s38, 49152
	s_nop 0
	global_load_lds_dwordx4 v164, s[100:101]
	s_waitcnt lgkmcnt(8)
	v_mfma_f32_16x16x32_bf16 v[20:23], v[72:75], v[116:119], v[20:23]
	v_mfma_f32_16x16x32_bf16 v[52:55], v[76:79], v[116:119], v[52:55]
	ds_read_b128 v[96:99], v162 offset:24576
	s_add_u32 m0, s38, 53248
	s_nop 0
	global_load_lds_dwordx4 v165, s[100:101]
	s_waitcnt lgkmcnt(8)
	v_mfma_f32_16x16x32_bf16 v[24:27], v[72:75], v[120:123], v[24:27]
	v_mfma_f32_16x16x32_bf16 v[56:59], v[76:79], v[120:123], v[56:59]
	ds_read_b128 v[100:103], v162 offset:26624
	s_add_u32 m0, s38, 57344
	s_nop 0
	global_load_lds_dwordx4 v166, s[100:101]
	s_waitcnt lgkmcnt(8)
	v_mfma_f32_16x16x32_bf16 v[28:31], v[72:75], v[124:127], v[28:31]
	v_mfma_f32_16x16x32_bf16 v[60:63], v[76:79], v[124:127], v[60:63]
	ds_read_b128 v[104:107], v162 offset:28672
	s_add_u32 m0, s38, 61440
	s_nop 0
	global_load_lds_dwordx4 v167, s[100:101]
	s_add_u32 s100, s100, 128
	s_addc_u32 s101, s101, 0
	s_waitcnt lgkmcnt(6)
	v_mfma_f32_16x16x32_bf16 v[0:3], v[64:67], v[80:83], v[0:3]
	v_mfma_f32_16x16x32_bf16 v[32:35], v[68:71], v[80:83], v[32:35]
	ds_read_b128 v[108:111], v162 offset:30720
	s_waitcnt lgkmcnt(6)
	v_mfma_f32_16x16x32_bf16 v[4:7], v[64:67], v[84:87], v[4:7]
	v_mfma_f32_16x16x32_bf16 v[36:39], v[68:71], v[84:87], v[36:39]
	ds_read_b128 v[72:75], v151 offset:0
	ds_read_b128 v[76:79], v151 offset:2048
	ds_read_b128 v[112:115], v163 offset:16384
	s_waitcnt lgkmcnt(8)
	v_mfma_f32_16x16x32_bf16 v[8:11], v[64:67], v[88:91], v[8:11]
	v_mfma_f32_16x16x32_bf16 v[40:43], v[68:71], v[88:91], v[40:43]
	ds_read_b128 v[116:119], v163 offset:18432
	s_waitcnt lgkmcnt(8)
	v_mfma_f32_16x16x32_bf16 v[12:15], v[64:67], v[92:95], v[12:15]
	v_mfma_f32_16x16x32_bf16 v[44:47], v[68:71], v[92:95], v[44:47]
	ds_read_b128 v[120:123], v163 offset:20480
	s_waitcnt lgkmcnt(8)
	v_mfma_f32_16x16x32_bf16 v[16:19], v[64:67], v[96:99], v[16:19]
	v_mfma_f32_16x16x32_bf16 v[48:51], v[68:71], v[96:99], v[48:51]
	ds_read_b128 v[124:127], v163 offset:22528
	s_waitcnt lgkmcnt(8)
	v_mfma_f32_16x16x32_bf16 v[20:23], v[64:67], v[100:103], v[20:23]
	v_mfma_f32_16x16x32_bf16 v[52:55], v[68:71], v[100:103], v[52:55]
	ds_read_b128 v[80:83], v163 offset:24576
	s_waitcnt lgkmcnt(8)
	v_mfma_f32_16x16x32_bf16 v[24:27], v[64:67], v[104:107], v[24:27]
	v_mfma_f32_16x16x32_bf16 v[56:59], v[68:71], v[104:107], v[56:59]
	ds_read_b128 v[84:87], v163 offset:26624
	s_waitcnt lgkmcnt(8)
	v_mfma_f32_16x16x32_bf16 v[28:31], v[64:67], v[108:111], v[28:31]
	v_mfma_f32_16x16x32_bf16 v[60:63], v[68:71], v[108:111], v[60:63]
	ds_read_b128 v[88:91], v163 offset:28672
	s_waitcnt lgkmcnt(6)
	v_mfma_f32_16x16x32_bf16 v[0:3], v[72:75], v[112:115], v[0:3]
	v_mfma_f32_16x16x32_bf16 v[32:35], v[76:79], v[112:115], v[32:35]
	ds_read_b128 v[92:95], v163 offset:30720
	s_waitcnt vmcnt(0) lgkmcnt(0)
	s_barrier
	s_waitcnt lgkmcnt(6)
	v_mfma_f32_16x16x32_bf16 v[4:7], v[72:75], v[116:119], v[4:7]
	v_mfma_f32_16x16x32_bf16 v[36:39], v[76:79], v[116:119], v[36:39]
	ds_read_b128 v[64:67], v150 offset:32768
	ds_read_b128 v[68:71], v150 offset:34816
	ds_read_b128 v[96:99], v162 offset:49152
	s_waitcnt lgkmcnt(8)
	v_mfma_f32_16x16x32_bf16 v[8:11], v[72:75], v[120:123], v[8:11]
	v_mfma_f32_16x16x32_bf16 v[40:43], v[76:79], v[120:123], v[40:43]
	ds_read_b128 v[100:103], v162 offset:51200
	s_waitcnt lgkmcnt(8)
	v_mfma_f32_16x16x32_bf16 v[12:15], v[72:75], v[124:127], v[12:15]
	v_mfma_f32_16x16x32_bf16 v[44:47], v[76:79], v[124:127], v[44:47]
	ds_read_b128 v[104:107], v162 offset:53248
	s_waitcnt lgkmcnt(8)
	v_mfma_f32_16x16x32_bf16 v[16:19], v[72:75], v[80:83], v[16:19]
	v_mfma_f32_16x16x32_bf16 v[48:51], v[76:79], v[80:83], v[48:51]
	ds_read_b128 v[108:111], v162 offset:55296
	s_waitcnt lgkmcnt(8)
	v_mfma_f32_16x16x32_bf16 v[20:23], v[72:75], v[84:87], v[20:23]
	v_mfma_f32_16x16x32_bf16 v[52:55], v[76:79], v[84:87], v[52:55]
	ds_read_b128 v[112:115], v162 offset:57344
	s_waitcnt lgkmcnt(8)
	v_mfma_f32_16x16x32_bf16 v[24:27], v[72:75], v[88:91], v[24:27]
	v_mfma_f32_16x16x32_bf16 v[56:59], v[76:79], v[88:91], v[56:59]
	ds_read_b128 v[116:119], v162 offset:59392
	s_waitcnt lgkmcnt(8)
	v_mfma_f32_16x16x32_bf16 v[28:31], v[72:75], v[92:95], v[28:31]
	v_mfma_f32_16x16x32_bf16 v[60:63], v[76:79], v[92:95], v[60:63]
	ds_read_b128 v[120:123], v162 offset:61440
	s_waitcnt lgkmcnt(6)
	v_mfma_f32_16x16x32_bf16 v[0:3], v[64:67], v[96:99], v[0:3]
	v_mfma_f32_16x16x32_bf16 v[32:35], v[68:71], v[96:99], v[32:35]
	ds_read_b128 v[124:127], v162 offset:63488
	s_waitcnt lgkmcnt(6)
	v_mfma_f32_16x16x32_bf16 v[4:7], v[64:67], v[100:103], v[4:7]
	v_mfma_f32_16x16x32_bf16 v[36:39], v[68:71], v[100:103], v[36:39]
	ds_read_b128 v[72:75], v151 offset:32768
	ds_read_b128 v[76:79], v151 offset:34816
	ds_read_b128 v[80:83], v163 offset:49152
	s_waitcnt lgkmcnt(8)
	v_mfma_f32_16x16x32_bf16 v[8:11], v[64:67], v[104:107], v[8:11]
	v_mfma_f32_16x16x32_bf16 v[40:43], v[68:71], v[104:107], v[40:43]
	ds_read_b128 v[84:87], v163 offset:51200
	s_waitcnt lgkmcnt(8)
	v_mfma_f32_16x16x32_bf16 v[12:15], v[64:67], v[108:111], v[12:15]
	v_mfma_f32_16x16x32_bf16 v[44:47], v[68:71], v[108:111], v[44:47]
	ds_read_b128 v[88:91], v163 offset:53248
	s_waitcnt lgkmcnt(8)
	v_mfma_f32_16x16x32_bf16 v[16:19], v[64:67], v[112:115], v[16:19]
	v_mfma_f32_16x16x32_bf16 v[48:51], v[68:71], v[112:115], v[48:51]
	ds_read_b128 v[92:95], v163 offset:55296
	s_waitcnt lgkmcnt(8)
	v_mfma_f32_16x16x32_bf16 v[20:23], v[64:67], v[116:119], v[20:23]
	v_mfma_f32_16x16x32_bf16 v[52:55], v[68:71], v[116:119], v[52:55]
	ds_read_b128 v[96:99], v163 offset:57344
	s_waitcnt lgkmcnt(8)
	v_mfma_f32_16x16x32_bf16 v[24:27], v[64:67], v[120:123], v[24:27]
	v_mfma_f32_16x16x32_bf16 v[56:59], v[68:71], v[120:123], v[56:59]
	ds_read_b128 v[100:103], v163 offset:59392
	s_waitcnt lgkmcnt(8)
	v_mfma_f32_16x16x32_bf16 v[28:31], v[64:67], v[124:127], v[28:31]
	v_mfma_f32_16x16x32_bf16 v[60:63], v[68:71], v[124:127], v[60:63]
	ds_read_b128 v[104:107], v163 offset:61440
	s_waitcnt lgkmcnt(6)
	v_mfma_f32_16x16x32_bf16 v[0:3], v[72:75], v[80:83], v[0:3]
	v_mfma_f32_16x16x32_bf16 v[32:35], v[76:79], v[80:83], v[32:35]
	ds_read_b128 v[108:111], v163 offset:63488
	s_waitcnt lgkmcnt(6)
	v_mfma_f32_16x16x32_bf16 v[4:7], v[72:75], v[84:87], v[4:7]
	v_mfma_f32_16x16x32_bf16 v[36:39], v[76:79], v[84:87], v[36:39]
	s_waitcnt lgkmcnt(5)
	v_mfma_f32_16x16x32_bf16 v[8:11], v[72:75], v[88:91], v[8:11]
	v_mfma_f32_16x16x32_bf16 v[40:43], v[76:79], v[88:91], v[40:43]
	s_waitcnt lgkmcnt(4)
	v_mfma_f32_16x16x32_bf16 v[12:15], v[72:75], v[92:95], v[12:15]
	v_mfma_f32_16x16x32_bf16 v[44:47], v[76:79], v[92:95], v[44:47]
	s_waitcnt lgkmcnt(3)
	v_mfma_f32_16x16x32_bf16 v[16:19], v[72:75], v[96:99], v[16:19]
	v_mfma_f32_16x16x32_bf16 v[48:51], v[76:79], v[96:99], v[48:51]
	s_waitcnt lgkmcnt(2)
	v_mfma_f32_16x16x32_bf16 v[20:23], v[72:75], v[100:103], v[20:23]
	v_mfma_f32_16x16x32_bf16 v[52:55], v[76:79], v[100:103], v[52:55]
	s_waitcnt lgkmcnt(1)
	v_mfma_f32_16x16x32_bf16 v[24:27], v[72:75], v[104:107], v[24:27]
	v_mfma_f32_16x16x32_bf16 v[56:59], v[76:79], v[104:107], v[56:59]
	s_waitcnt lgkmcnt(0)
	v_mfma_f32_16x16x32_bf16 v[28:31], v[72:75], v[108:111], v[28:31]
	v_mfma_f32_16x16x32_bf16 v[60:63], v[76:79], v[108:111], v[60:63]
	global_load_dwordx4 v[64:67], v168, s[14:15] nt
	global_load_dwordx4 v[68:71], v168, s[14:15] offset:16 nt
	s_add_u32 s14, s14, 0x4000
	s_addc_u32 s15, s15, 0
	global_load_dwordx4 v[72:75], v168, s[14:15] nt
	global_load_dwordx4 v[76:79], v168, s[14:15] offset:16 nt
	s_add_u32 s14, s14, 0x4000
	s_addc_u32 s15, s15, 0
	global_load_dwordx4 v[80:83], v168, s[14:15] nt
	global_load_dwordx4 v[84:87], v168, s[14:15] offset:16 nt
	s_add_u32 s14, s14, 0x4000
	s_addc_u32 s15, s15, 0
	global_load_dwordx4 v[88:91], v168, s[14:15] nt
	global_load_dwordx4 v[92:95], v168, s[14:15] offset:16 nt
	s_add_u32 s14, s14, 0x4000
	s_addc_u32 s15, s15, 0
	s_nop 7
	s_waitcnt lgkmcnt(0)
	s_barrier
	ds_write_b32 v169, v0 offset:0
	ds_write_b32 v169, v1 offset:512
	ds_write_b32 v169, v2 offset:1024
	ds_write_b32 v169, v3 offset:1536
	ds_write_b32 v169, v4 offset:64
	ds_write_b32 v169, v5 offset:576
	ds_write_b32 v169, v6 offset:1088
	ds_write_b32 v169, v7 offset:1600
	ds_write_b32 v169, v8 offset:128
	ds_write_b32 v169, v9 offset:640
	ds_write_b32 v169, v10 offset:1152
	ds_write_b32 v169, v11 offset:1664
	ds_write_b32 v169, v12 offset:192
	ds_write_b32 v169, v13 offset:704
	ds_write_b32 v169, v14 offset:1216
	ds_write_b32 v169, v15 offset:1728
	ds_write_b32 v169, v16 offset:256
	ds_write_b32 v169, v17 offset:768
	ds_write_b32 v169, v18 offset:1280
	ds_write_b32 v169, v19 offset:1792
	ds_write_b32 v169, v20 offset:320
	ds_write_b32 v169, v21 offset:832
	ds_write_b32 v169, v22 offset:1344
	ds_write_b32 v169, v23 offset:1856
	ds_write_b32 v170, v24 offset:0
	ds_write_b32 v170, v25 offset:512
	ds_write_b32 v170, v26 offset:1024
	ds_write_b32 v170, v27 offset:1536
	ds_write_b32 v171, v28 offset:0
	ds_write_b32 v171, v29 offset:512
	ds_write_b32 v171, v30 offset:1024
	ds_write_b32 v171, v31 offset:1536
	s_waitcnt lgkmcnt(0)
	ds_read_b128 v[0:3], v220
	ds_read_b128 v[4:7], v220 offset:16
	ds_read_b128 v[8:11], v222
	ds_read_b128 v[12:15], v222 offset:16
	ds_read_b128 v[16:19], v224
	ds_read_b128 v[20:23], v224 offset:16
	ds_read_b128 v[24:27], v226
	ds_read_b128 v[28:31], v226 offset:16
	s_waitcnt lgkmcnt(6)
	v_pk_fma_f32 v[0:1], v[142:143], v[0:1], v[172:173]
	v_pk_fma_f32 v[2:3], v[144:145], v[2:3], v[174:175]
	v_pk_fma_f32 v[4:5], v[146:147], v[4:5], v[176:177]
	v_pk_fma_f32 v[6:7], v[160:161], v[6:7], v[178:179]
	global_store_dwordx4 v168, v[0:3], s[18:19]
	global_store_dwordx4 v168, v[4:7], s[18:19] offset:16
	s_add_u32 s18, s18, 0x4000
	s_addc_u32 s19, s19, 0
	s_waitcnt lgkmcnt(4)
	v_pk_fma_f32 v[8:9], v[142:143], v[8:9], v[180:181]
	v_pk_fma_f32 v[10:11], v[144:145], v[10:11], v[182:183]
	v_pk_fma_f32 v[12:13], v[146:147], v[12:13], v[184:185]
	v_pk_fma_f32 v[14:15], v[160:161], v[14:15], v[186:187]
	global_store_dwordx4 v168, v[8:11], s[18:19]
	global_store_dwordx4 v168, v[12:15], s[18:19] offset:16
	s_add_u32 s18, s18, 0x4000
	s_addc_u32 s19, s19, 0
	s_waitcnt lgkmcnt(2)
	v_pk_fma_f32 v[16:17], v[142:143], v[16:17], v[188:189]
	v_pk_fma_f32 v[18:19], v[144:145], v[18:19], v[190:191]
	v_pk_fma_f32 v[20:21], v[146:147], v[20:21], v[192:193]
	v_pk_fma_f32 v[22:23], v[160:161], v[22:23], v[194:195]
	global_store_dwordx4 v168, v[16:19], s[18:19]
	global_store_dwordx4 v168, v[20:23], s[18:19] offset:16
	s_add_u32 s18, s18, 0x4000
	s_addc_u32 s19, s19, 0
	s_waitcnt lgkmcnt(0)
	v_pk_fma_f32 v[24:25], v[142:143], v[24:25], v[196:197]
	v_pk_fma_f32 v[26:27], v[144:145], v[26:27], v[198:199]
	v_pk_fma_f32 v[28:29], v[146:147], v[28:29], v[200:201]
	v_pk_fma_f32 v[30:31], v[160:161], v[30:31], v[202:203]
	global_store_dwordx4 v168, v[24:27], s[18:19]
	global_store_dwordx4 v168, v[28:31], s[18:19] offset:16
	s_add_u32 s18, s18, 0x4000
	s_addc_u32 s19, s19, 0
	ds_write_b32 v169, v32 offset:0
	ds_write_b32 v169, v33 offset:512
	ds_write_b32 v169, v34 offset:1024
	ds_write_b32 v169, v35 offset:1536
	ds_write_b32 v169, v36 offset:64
	ds_write_b32 v169, v37 offset:576
	ds_write_b32 v169, v38 offset:1088
	ds_write_b32 v169, v39 offset:1600
	ds_write_b32 v169, v40 offset:128
	ds_write_b32 v169, v41 offset:640
	ds_write_b32 v169, v42 offset:1152
	ds_write_b32 v169, v43 offset:1664
	ds_write_b32 v169, v44 offset:192
	ds_write_b32 v169, v45 offset:704
	ds_write_b32 v169, v46 offset:1216
	ds_write_b32 v169, v47 offset:1728
	ds_write_b32 v169, v48 offset:256
	ds_write_b32 v169, v49 offset:768
	ds_write_b32 v169, v50 offset:1280
	ds_write_b32 v169, v51 offset:1792
	ds_write_b32 v169, v52 offset:320
	ds_write_b32 v169, v53 offset:832
	ds_write_b32 v169, v54 offset:1344
	ds_write_b32 v169, v55 offset:1856
	ds_write_b32 v170, v56 offset:0
	ds_write_b32 v170, v57 offset:512
	ds_write_b32 v170, v58 offset:1024
	ds_write_b32 v170, v59 offset:1536
	ds_write_b32 v171, v60 offset:0
	ds_write_b32 v171, v61 offset:512
	ds_write_b32 v171, v62 offset:1024
	ds_write_b32 v171, v63 offset:1536
	s_waitcnt lgkmcnt(0)
	ds_read_b128 v[32:35], v220
	ds_read_b128 v[36:39], v220 offset:16
	ds_read_b128 v[40:43], v222
	ds_read_b128 v[44:47], v222 offset:16
	ds_read_b128 v[48:51], v224
	ds_read_b128 v[52:55], v224 offset:16
	ds_read_b128 v[56:59], v226
	ds_read_b128 v[60:63], v226 offset:16
	s_waitcnt vmcnt(14) lgkmcnt(6)
	v_pk_fma_f32 v[32:33], v[142:143], v[32:33], v[64:65]
	v_pk_fma_f32 v[34:35], v[144:145], v[34:35], v[66:67]
	v_pk_fma_f32 v[36:37], v[146:147], v[36:37], v[68:69]
	v_pk_fma_f32 v[38:39], v[160:161], v[38:39], v[70:71]
	global_store_dwordx4 v168, v[32:35], s[18:19]
	global_store_dwordx4 v168, v[36:39], s[18:19] offset:16
	s_add_u32 s18, s18, 0x4000
	s_addc_u32 s19, s19, 0
	s_waitcnt vmcnt(14) lgkmcnt(4)
	v_pk_fma_f32 v[40:41], v[142:143], v[40:41], v[72:73]
	v_pk_fma_f32 v[42:43], v[144:145], v[42:43], v[74:75]
	v_pk_fma_f32 v[44:45], v[146:147], v[44:45], v[76:77]
	v_pk_fma_f32 v[46:47], v[160:161], v[46:47], v[78:79]
	global_store_dwordx4 v168, v[40:43], s[18:19]
	global_store_dwordx4 v168, v[44:47], s[18:19] offset:16
	s_add_u32 s18, s18, 0x4000
	s_addc_u32 s19, s19, 0
	s_waitcnt vmcnt(14) lgkmcnt(2)
	v_pk_fma_f32 v[48:49], v[142:143], v[48:49], v[80:81]
	v_pk_fma_f32 v[50:51], v[144:145], v[50:51], v[82:83]
	v_pk_fma_f32 v[52:53], v[146:147], v[52:53], v[84:85]
	v_pk_fma_f32 v[54:55], v[160:161], v[54:55], v[86:87]
	global_store_dwordx4 v168, v[48:51], s[18:19]
	global_store_dwordx4 v168, v[52:55], s[18:19] offset:16
	s_add_u32 s18, s18, 0x4000
	s_addc_u32 s19, s19, 0
	s_waitcnt vmcnt(14) lgkmcnt(0)
	v_pk_fma_f32 v[56:57], v[142:143], v[56:57], v[88:89]
	v_pk_fma_f32 v[58:59], v[144:145], v[58:59], v[90:91]
	v_pk_fma_f32 v[60:61], v[146:147], v[60:61], v[92:93]
	v_pk_fma_f32 v[62:63], v[160:161], v[62:63], v[94:95]
	global_store_dwordx4 v168, v[56:59], s[18:19]
	global_store_dwordx4 v168, v[60:63], s[18:19] offset:16
	s_add_u32 s18, s18, 0x4000
	s_addc_u32 s19, s19, 0
	s_add_i32 s52, s52, s3
	s_cmpk_lt_i32 s52, 0x400
	s_cbranch_scc1 .Lmy_op0_tile

.LBB0_684:
	s_or_b64 exec, exec, s[0:1]
	s_and_b64 vcc, exec, s[54:55]
	s_waitcnt lgkmcnt(0)
	s_barrier
	s_cbranch_vccnz .LBB0_689
	v_lshrrev_b32_e32 v141, 4, v129
	v_and_b32_e32 v0, 15, v141
	v_bfe_u32 v1, v141, 4, 2
	v_bfe_u32 v2, v141, 1, 3
	v_xor_b32_e32 v2, v1, v2
	v_lshlrev_b32_e32 v2, 4, v2
	v_lshl_or_b32 v162, v0, 7, v2
	v_xor_b32_e32 v163, 64, v162
	v_lshrrev_b32_e32 v2, 6, v141
	v_lshl_add_u32 v150, v2, 12, v162
	v_lshl_add_u32 v151, v2, 12, v163
	v_bfe_u32 v3, v141, 4, 3
	v_and_b32_e32 v4, 7, v141
	v_xor_b32_e32 v3, v3, v4
	v_lshlrev_b32_e32 v3, 4, v3
	v_lshrrev_b32_e32 v4, 3, v141
	v_lshl_or_b32 v164, v4, 12, v3
	v_add_u32_e32 v165, 131072, v164
	v_add_u32_e32 v166, 262144, v164
	v_add_u32_e32 v167, 393216, v164
	v_lshlrev_b32_e32 v148, 5, v0
	v_lshlrev_b32_e32 v5, 17, v2
	v_lshl_add_u32 v5, v1, 12, v5
	v_add_u32_e32 v168, v5, v148
	v_lshlrev_b32_e32 v5, 13, v2
	v_lshl_add_u32 v6, v1, 3, v0
	v_lshl_add_u32 v7, v1, 11, v5
	v_lshl_add_u32 v169, v6, 2, v7
	v_add_u32_e32 v8, 0x60, v6
	v_and_b32_e32 v8, 0x7f, v8
	v_lshl_add_u32 v170, v8, 2, v7
	v_add_u32_e32 v8, 0x70, v6
	v_and_b32_e32 v8, 0x7f, v8
	v_lshl_add_u32 v171, v8, 2, v7
	v_lshlrev_b32_e32 v8, 3, v0
	v_lshl_add_u32 v10, v1, 9, v5
	v_add_u32_e32 v9, 0, v8
	v_and_b32_e32 v9, 0x7f, v9
	v_lshl_add_u32 v220, v9, 2, v10
	v_add_u32_e32 v9, 8, v8
	v_and_b32_e32 v9, 0x7f, v9
	v_lshl_add_u32 v222, v9, 2, v10
	v_add_u32_e32 v222, 2048, v222
	v_add_u32_e32 v9, 16, v8
	v_and_b32_e32 v9, 0x7f, v9
	v_lshl_add_u32 v224, v9, 2, v10
	v_add_u32_e32 v224, 4096, v224
	v_add_u32_e32 v9, 24, v8
	v_and_b32_e32 v9, 0x7f, v9
	v_lshl_add_u32 v226, v9, 2, v10
	v_add_u32_e32 v226, 6144, v226
	v_readfirstlane_b32 s38, v129
	s_mov_b32 s52, s2
.Lmy_op1_tile:
	s_and_b32 s10, s52, 7
	s_lshr_b32 s11, s52, 9
	s_lshl_b32 s11, s11, 3
	s_add_i32 s10, s10, s11
	s_bfe_u32 s11, s52, 0x30003
	s_lshl_b32 s12, s10, 3
	s_or_b32 s12, s12, s11
	s_bfe_u32 s13, s52, 0x30006
	s_lshl_b32 s10, s12, 19
	s_add_u32 s98, s50, s10
	s_addc_u32 s99, s51, 0
	s_add_u32 s98, s98, 0x5a00000
	s_addc_u32 s99, s99, 0
	s_lshl_b32 s11, s13, 19
	s_add_u32 s100, s50, s11
	s_addc_u32 s101, s51, 0
	s_add_u32 s100, s100, 0xc00000
	s_addc_u32 s101, s101, 0
	s_lshr_b32 s11, s12, 5
	s_mul_i32 s11, s11, 0x3000
	s_lshl_b32 s20, s13, 9
	s_add_i32 s11, s11, s20
	s_add_i32 s11, s11, 0x1122000
	s_add_u32 s4, s50, s11
	s_addc_u32 s5, s51, 0
	s_add_i32 s10, s10, s20
	s_add_u32 s6, s48, s10
	s_addc_u32 s7, s49, 0
	s_add_u32 s8, s48, s10
	s_addc_u32 s9, s49, 0
	s_mov_b32 s14, s6
	s_mov_b32 s15, s7
	s_mov_b32 s18, s8
	s_mov_b32 s19, s9
	global_load_dwordx4 v[172:175], v148, s[4:5]
	global_load_dwordx4 v[176:179], v148, s[4:5] offset:16
	s_add_u32 s4, s4, 0xc000
	s_addc_u32 s5, s5, 0
	global_load_dwordx4 v[180:183], v148, s[4:5]
	global_load_dwordx4 v[184:187], v148, s[4:5] offset:16
	s_add_u32 s4, s4, 0xc000
	s_addc_u32 s5, s5, 0
	global_load_dwordx4 v[188:191], v148, s[4:5]
	global_load_dwordx4 v[192:195], v148, s[4:5] offset:16
	s_add_u32 s4, s4, 0xc000
	s_addc_u32 s5, s5, 0
	global_load_dwordx4 v[196:199], v148, s[4:5]
	global_load_dwordx4 v[200:203], v148, s[4:5] offset:16
	s_add_u32 s4, s4, 0xc000
	s_addc_u32 s5, s5, 0
	global_load_dwordx4 v[204:207], v148, s[4:5]
	global_load_dwordx4 v[208:211], v148, s[4:5] offset:16
	s_add_u32 s4, s4, 0xc000
	s_addc_u32 s5, s5, 0
	global_load_dwordx4 v[212:215], v148, s[4:5]
	global_load_dwordx4 v[216:219], v148, s[4:5] offset:16
	s_add_u32 s4, s4, 0xc000
	s_addc_u32 s5, s5, 0
	global_load_dwordx4 v[230:233], v148, s[4:5]
	global_load_dwordx4 v[234:237], v148, s[4:5] offset:16
	s_add_u32 s4, s4, 0xc000
	s_addc_u32 s5, s5, 0
	global_load_dwordx4 v[238:241], v148, s[4:5]
	global_load_dwordx4 v[242:245], v148, s[4:5] offset:16
	s_barrier
	s_add_u32 m0, s38, 0
	v_mov_b32_e32 v0, 0
	v_mov_b32_e32 v1, 0
	global_load_lds_dwordx4 v164, s[98:99]
	s_add_u32 m0, s38, 4096
	v_mov_b32_e32 v2, 0
	v_mov_b32_e32 v3, 0
	global_load_lds_dwordx4 v165, s[98:99]
	s_add_u32 m0, s38, 8192
	v_mov_b32_e32 v4, 0
	v_mov_b32_e32 v5, 0
	global_load_lds_dwordx4 v166, s[98:99]
	s_add_u32 m0, s38, 12288
	v_mov_b32_e32 v6, 0
	v_mov_b32_e32 v7, 0
	global_load_lds_dwordx4 v167, s[98:99]
	s_add_u32 s98, s98, 128
	s_addc_u32 s99, s99, 0
	s_add_u32 m0, s38, 16384
	v_mov_b32_e32 v8, 0
	v_mov_b32_e32 v9, 0
	global_load_lds_dwordx4 v164, s[100:101]
	s_add_u32 m0, s38, 20480
	v_mov_b32_e32 v10, 0
	v_mov_b32_e32 v11, 0
	global_load_lds_dwordx4 v165, s[100:101]
	s_add_u32 m0, s38, 24576
	v_mov_b32_e32 v12, 0
	v_mov_b32_e32 v13, 0
	global_load_lds_dwordx4 v166, s[100:101]
	s_add_u32 m0, s38, 28672
	v_mov_b32_e32 v14, 0
	v_mov_b32_e32 v15, 0
	global_load_lds_dwordx4 v167, s[100:101]
	s_add_u32 s100, s100, 128
	s_addc_u32 s101, s101, 0
	s_add_u32 m0, s38, 32768
	v_mov_b32_e32 v16, 0
	v_mov_b32_e32 v17, 0
	global_load_lds_dwordx4 v164, s[98:99]
	s_add_u32 m0, s38, 36864
	v_mov_b32_e32 v18, 0
	v_mov_b32_e32 v19, 0
	global_load_lds_dwordx4 v165, s[98:99]
	s_add_u32 m0, s38, 40960
	v_mov_b32_e32 v20, 0
	v_mov_b32_e32 v21, 0
	global_load_lds_dwordx4 v166, s[98:99]
	s_add_u32 m0, s38, 45056
	v_mov_b32_e32 v22, 0
	v_mov_b32_e32 v23, 0
	global_load_lds_dwordx4 v167, s[98:99]
	s_add_u32 s98, s98, 128
	s_addc_u32 s99, s99, 0
	s_add_u32 m0, s38, 49152
	v_mov_b32_e32 v24, 0
	v_mov_b32_e32 v25, 0
	global_load_lds_dwordx4 v164, s[100:101]
	s_add_u32 m0, s38, 53248
	v_mov_b32_e32 v26, 0
	v_mov_b32_e32 v27, 0
	global_load_lds_dwordx4 v165, s[100:101]
	s_add_u32 m0, s38, 57344
	v_mov_b32_e32 v28, 0
	v_mov_b32_e32 v29, 0
	global_load_lds_dwordx4 v166, s[100:101]
	s_add_u32 m0, s38, 61440
	v_mov_b32_e32 v30, 0
	v_mov_b32_e32 v31, 0
	global_load_lds_dwordx4 v167, s[100:101]
	s_add_u32 s100, s100, 128
	s_addc_u32 s101, s101, 0
	v_mov_b32_e32 v32, 0
	v_mov_b32_e32 v33, 0
	v_mov_b32_e32 v34, 0
	v_mov_b32_e32 v35, 0
	v_mov_b32_e32 v36, 0
	v_mov_b32_e32 v37, 0
	v_mov_b32_e32 v38, 0
	v_mov_b32_e32 v39, 0
	v_mov_b32_e32 v40, 0
	v_mov_b32_e32 v41, 0
	v_mov_b32_e32 v42, 0
	v_mov_b32_e32 v43, 0
	v_mov_b32_e32 v44, 0
	v_mov_b32_e32 v45, 0
	v_mov_b32_e32 v46, 0
	v_mov_b32_e32 v47, 0
	v_mov_b32_e32 v48, 0
	v_mov_b32_e32 v49, 0
	v_mov_b32_e32 v50, 0
	v_mov_b32_e32 v51, 0
	v_mov_b32_e32 v52, 0
	v_mov_b32_e32 v53, 0
	v_mov_b32_e32 v54, 0
	v_mov_b32_e32 v55, 0
	v_mov_b32_e32 v56, 0
	v_mov_b32_e32 v57, 0
	v_mov_b32_e32 v58, 0
	v_mov_b32_e32 v59, 0
	v_mov_b32_e32 v60, 0
	v_mov_b32_e32 v61, 0
	v_mov_b32_e32 v62, 0
	v_mov_b32_e32 v63, 0
	s_waitcnt vmcnt(8)
	s_barrier
	ds_read_b128 v[64:67], v150 offset:0
	ds_read_b128 v[68:71], v150 offset:2048
	ds_read_b128 v[80:83], v162 offset:16384
	ds_read_b128 v[84:87], v162 offset:18432
	ds_read_b128 v[88:91], v162 offset:20480
	ds_read_b128 v[92:95], v162 offset:22528
	ds_read_b128 v[96:99], v162 offset:24576
	ds_read_b128 v[100:103], v162 offset:26624
	ds_read_b128 v[104:107], v162 offset:28672
	v_add_f32_e32 v142, 0, v172
	v_add_f32_e32 v143, 0, v173
	v_add_f32_e32 v144, 0, v174
	v_add_f32_e32 v145, 0, v175
	s_waitcnt lgkmcnt(6)
	v_mfma_f32_16x16x32_bf16 v[0:3], v[64:67], v[80:83], v[0:3]
	v_mfma_f32_16x16x32_bf16 v[32:35], v[68:71], v[80:83], v[32:35]
	ds_read_b128 v[108:111], v162 offset:30720
	v_add_f32_e32 v146, 0, v176
	v_add_f32_e32 v147, 0, v177
	v_add_f32_e32 v160, 0, v178
	v_add_f32_e32 v161, 0, v179
	s_waitcnt lgkmcnt(6)
	v_mfma_f32_16x16x32_bf16 v[4:7], v[64:67], v[84:87], v[4:7]
	v_mfma_f32_16x16x32_bf16 v[36:39], v[68:71], v[84:87], v[36:39]
	ds_read_b128 v[72:75], v151 offset:0
	ds_read_b128 v[76:79], v151 offset:2048
	ds_read_b128 v[112:115], v163 offset:16384
	v_add_f32_e32 v142, v142, v180
	v_add_f32_e32 v143, v143, v181
	v_add_f32_e32 v144, v144, v182
	v_add_f32_e32 v145, v145, v183
	s_waitcnt lgkmcnt(8)
	v_mfma_f32_16x16x32_bf16 v[8:11], v[64:67], v[88:91], v[8:11]
	v_mfma_f32_16x16x32_bf16 v[40:43], v[68:71], v[88:91], v[40:43]
	ds_read_b128 v[116:119], v163 offset:18432
	v_add_f32_e32 v146, v146, v184
	v_add_f32_e32 v147, v147, v185
	v_add_f32_e32 v160, v160, v186
	v_add_f32_e32 v161, v161, v187
	s_waitcnt lgkmcnt(8)
	v_mfma_f32_16x16x32_bf16 v[12:15], v[64:67], v[92:95], v[12:15]
	v_mfma_f32_16x16x32_bf16 v[44:47], v[68:71], v[92:95], v[44:47]
	ds_read_b128 v[120:123], v163 offset:20480
	v_add_f32_e32 v142, v142, v188
	v_add_f32_e32 v143, v143, v189
	v_add_f32_e32 v144, v144, v190
	v_add_f32_e32 v145, v145, v191
	s_waitcnt lgkmcnt(8)
	v_mfma_f32_16x16x32_bf16 v[16:19], v[64:67], v[96:99], v[16:19]
	v_mfma_f32_16x16x32_bf16 v[48:51], v[68:71], v[96:99], v[48:51]
	ds_read_b128 v[124:127], v163 offset:22528
	v_add_f32_e32 v146, v146, v192
	v_add_f32_e32 v147, v147, v193
	v_add_f32_e32 v160, v160, v194
	v_add_f32_e32 v161, v161, v195
	s_waitcnt lgkmcnt(8)
	v_mfma_f32_16x16x32_bf16 v[20:23], v[64:67], v[100:103], v[20:23]
	v_mfma_f32_16x16x32_bf16 v[52:55], v[68:71], v[100:103], v[52:55]
	ds_read_b128 v[80:83], v163 offset:24576
	v_add_f32_e32 v142, v142, v196
	v_add_f32_e32 v143, v143, v197
	v_add_f32_e32 v144, v144, v198
	v_add_f32_e32 v145, v145, v199
	s_waitcnt lgkmcnt(8)
	v_mfma_f32_16x16x32_bf16 v[24:27], v[64:67], v[104:107], v[24:27]
	v_mfma_f32_16x16x32_bf16 v[56:59], v[68:71], v[104:107], v[56:59]
	ds_read_b128 v[84:87], v163 offset:26624
	v_add_f32_e32 v146, v146, v200
	v_add_f32_e32 v147, v147, v201
	v_add_f32_e32 v160, v160, v202
	v_add_f32_e32 v161, v161, v203
	s_waitcnt lgkmcnt(8)
	v_mfma_f32_16x16x32_bf16 v[28:31], v[64:67], v[108:111], v[28:31]
	v_mfma_f32_16x16x32_bf16 v[60:63], v[68:71], v[108:111], v[60:63]
	ds_read_b128 v[88:91], v163 offset:28672
	v_add_f32_e32 v142, v142, v204
	v_add_f32_e32 v143, v143, v205
	v_add_f32_e32 v144, v144, v206
	v_add_f32_e32 v145, v145, v207
	s_waitcnt lgkmcnt(6)
	v_mfma_f32_16x16x32_bf16 v[0:3], v[72:75], v[112:115], v[0:3]
	v_mfma_f32_16x16x32_bf16 v[32:35], v[76:79], v[112:115], v[32:35]
	ds_read_b128 v[92:95], v163 offset:30720
	s_waitcnt vmcnt(0) lgkmcnt(0)
	s_barrier
	s_add_u32 m0, s38, 0
	s_nop 0
	global_load_lds_dwordx4 v164, s[98:99]
	v_add_f32_e32 v146, v146, v208
	v_add_f32_e32 v147, v147, v209
	v_add_f32_e32 v160, v160, v210
	v_add_f32_e32 v161, v161, v211
	s_waitcnt lgkmcnt(6)
	v_mfma_f32_16x16x32_bf16 v[4:7], v[72:75], v[116:119], v[4:7]
	v_mfma_f32_16x16x32_bf16 v[36:39], v[76:79], v[116:119], v[36:39]
	ds_read_b128 v[64:67], v150 offset:32768
	ds_read_b128 v[68:71], v150 offset:34816
	ds_read_b128 v[96:99], v162 offset:49152
	s_add_u32 m0, s38, 4096
	s_nop 0
	global_load_lds_dwordx4 v165, s[98:99]
	v_add_f32_e32 v142, v142, v212
	v_add_f32_e32 v143, v143, v213
	v_add_f32_e32 v144, v144, v214
	v_add_f32_e32 v145, v145, v215
	s_waitcnt lgkmcnt(8)
	v_mfma_f32_16x16x32_bf16 v[8:11], v[72:75], v[120:123], v[8:11]
	v_mfma_f32_16x16x32_bf16 v[40:43], v[76:79], v[120:123], v[40:43]
	ds_read_b128 v[100:103], v162 offset:51200
	s_add_u32 m0, s38, 8192
	s_nop 0
	global_load_lds_dwordx4 v166, s[98:99]
	v_add_f32_e32 v146, v146, v216
	v_add_f32_e32 v147, v147, v217
	v_add_f32_e32 v160, v160, v218
	v_add_f32_e32 v161, v161, v219
	s_waitcnt lgkmcnt(8)
	v_mfma_f32_16x16x32_bf16 v[12:15], v[72:75], v[124:127], v[12:15]
	v_mfma_f32_16x16x32_bf16 v[44:47], v[76:79], v[124:127], v[44:47]
	ds_read_b128 v[104:107], v162 offset:53248
	s_add_u32 m0, s38, 12288
	s_nop 0
	global_load_lds_dwordx4 v167, s[98:99]
	s_add_u32 s98, s98, 128
	s_addc_u32 s99, s99, 0
	v_add_f32_e32 v142, v142, v230
	v_add_f32_e32 v143, v143, v231
	v_add_f32_e32 v144, v144, v232
	v_add_f32_e32 v145, v145, v233
	s_waitcnt lgkmcnt(8)
	v_mfma_f32_16x16x32_bf16 v[16:19], v[72:75], v[80:83], v[16:19]
	v_mfma_f32_16x16x32_bf16 v[48:51], v[76:79], v[80:83], v[48:51]
	ds_read_b128 v[108:111], v162 offset:55296
	s_add_u32 m0, s38, 16384
	s_nop 0
	global_load_lds_dwordx4 v164, s[100:101]
	v_add_f32_e32 v146, v146, v234
	v_add_f32_e32 v147, v147, v235
	v_add_f32_e32 v160, v160, v236
	v_add_f32_e32 v161, v161, v237
	s_waitcnt lgkmcnt(8)
	v_mfma_f32_16x16x32_bf16 v[20:23], v[72:75], v[84:87], v[20:23]
	v_mfma_f32_16x16x32_bf16 v[52:55], v[76:79], v[84:87], v[52:55]
	ds_read_b128 v[112:115], v162 offset:57344
	s_add_u32 m0, s38, 20480
	s_nop 0
	global_load_lds_dwordx4 v165, s[100:101]
	v_add_f32_e32 v142, v142, v238
	v_add_f32_e32 v143, v143, v239
	v_add_f32_e32 v144, v144, v240
	v_add_f32_e32 v145, v145, v241
	s_waitcnt lgkmcnt(8)
	v_mfma_f32_16x16x32_bf16 v[24:27], v[72:75], v[88:91], v[24:27]
	v_mfma_f32_16x16x32_bf16 v[56:59], v[76:79], v[88:91], v[56:59]
	ds_read_b128 v[116:119], v162 offset:59392
	s_add_u32 m0, s38, 24576
	s_nop 0
	global_load_lds_dwordx4 v166, s[100:101]
	v_add_f32_e32 v146, v146, v242
	v_add_f32_e32 v147, v147, v243
	v_add_f32_e32 v160, v160, v244
	v_add_f32_e32 v161, v161, v245
	s_waitcnt lgkmcnt(8)
	v_mfma_f32_16x16x32_bf16 v[28:31], v[72:75], v[92:95], v[28:31]
	v_mfma_f32_16x16x32_bf16 v[60:63], v[76:79], v[92:95], v[60:63]
	ds_read_b128 v[120:123], v162 offset:61440
	s_add_u32 m0, s38, 28672
	s_nop 0
	global_load_lds_dwordx4 v167, s[100:101]
	s_add_u32 s100, s100, 128
	s_addc_u32 s101, s101, 0
	s_waitcnt lgkmcnt(6)
	v_mfma_f32_16x16x32_bf16 v[0:3], v[64:67], v[96:99], v[0:3]
	v_mfma_f32_16x16x32_bf16 v[32:35], v[68:71], v[96:99], v[32:35]
	ds_read_b128 v[124:127], v162 offset:63488
	s_waitcnt lgkmcnt(6)
	v_mfma_f32_16x16x32_bf16 v[4:7], v[64:67], v[100:103], v[4:7]
	v_mfma_f32_16x16x32_bf16 v[36:39], v[68:71], v[100:103], v[36:39]
	ds_read_b128 v[72:75], v151 offset:32768
	ds_read_b128 v[76:79], v151 offset:34816
	ds_read_b128 v[80:83], v163 offset:49152
	s_waitcnt lgkmcnt(8)
	v_mfma_f32_16x16x32_bf16 v[8:11], v[64:67], v[104:107], v[8:11]
	v_mfma_f32_16x16x32_bf16 v[40:43], v[68:71], v[104:107], v[40:43]
	ds_read_b128 v[84:87], v163 offset:51200
	s_waitcnt lgkmcnt(8)
	v_mfma_f32_16x16x32_bf16 v[12:15], v[64:67], v[108:111], v[12:15]
	v_mfma_f32_16x16x32_bf16 v[44:47], v[68:71], v[108:111], v[44:47]
	ds_read_b128 v[88:91], v163 offset:53248
	s_waitcnt lgkmcnt(8)
	v_mfma_f32_16x16x32_bf16 v[16:19], v[64:67], v[112:115], v[16:19]
	v_mfma_f32_16x16x32_bf16 v[48:51], v[68:71], v[112:115], v[48:51]
	ds_read_b128 v[92:95], v163 offset:55296
	s_waitcnt lgkmcnt(8)
	v_mfma_f32_16x16x32_bf16 v[20:23], v[64:67], v[116:119], v[20:23]
	v_mfma_f32_16x16x32_bf16 v[52:55], v[68:71], v[116:119], v[52:55]
	ds_read_b128 v[96:99], v163 offset:57344
	s_waitcnt lgkmcnt(8)
	v_mfma_f32_16x16x32_bf16 v[24:27], v[64:67], v[120:123], v[24:27]
	v_mfma_f32_16x16x32_bf16 v[56:59], v[68:71], v[120:123], v[56:59]
	ds_read_b128 v[100:103], v163 offset:59392
	s_waitcnt lgkmcnt(8)
	v_mfma_f32_16x16x32_bf16 v[28:31], v[64:67], v[124:127], v[28:31]
	v_mfma_f32_16x16x32_bf16 v[60:63], v[68:71], v[124:127], v[60:63]
	ds_read_b128 v[104:107], v163 offset:61440
	s_waitcnt lgkmcnt(6)
	v_mfma_f32_16x16x32_bf16 v[0:3], v[72:75], v[80:83], v[0:3]
	v_mfma_f32_16x16x32_bf16 v[32:35], v[76:79], v[80:83], v[32:35]
	ds_read_b128 v[108:111], v163 offset:63488
	s_waitcnt vmcnt(0) lgkmcnt(0)
	s_barrier
	s_add_u32 m0, s38, 32768
	s_nop 0
	global_load_lds_dwordx4 v164, s[98:99]
	s_waitcnt lgkmcnt(6)
	v_mfma_f32_16x16x32_bf16 v[4:7], v[72:75], v[84:87], v[4:7]
	v_mfma_f32_16x16x32_bf16 v[36:39], v[76:79], v[84:87], v[36:39]
	ds_read_b128 v[64:67], v150 offset:0
	ds_read_b128 v[68:71], v150 offset:2048
	ds_read_b128 v[112:115], v162 offset:16384
	s_add_u32 m0, s38, 36864
	s_nop 0
	global_load_lds_dwordx4 v165, s[98:99]
	s_waitcnt lgkmcnt(8)
	v_mfma_f32_16x16x32_bf16 v[8:11], v[72:75], v[88:91], v[8:11]
	v_mfma_f32_16x16x32_bf16 v[40:43], v[76:79], v[88:91], v[40:43]
	ds_read_b128 v[116:119], v162 offset:18432
	s_add_u32 m0, s38, 40960
	s_nop 0
	global_load_lds_dwordx4 v166, s[98:99]
	s_waitcnt lgkmcnt(8)
	v_mfma_f32_16x16x32_bf16 v[12:15], v[72:75], v[92:95], v[12:15]
	v_mfma_f32_16x16x32_bf16 v[44:47], v[76:79], v[92:95], v[44:47]
	ds_read_b128 v[120:123], v162 offset:20480
	s_add_u32 m0, s38, 45056
	s_nop 0
	global_load_lds_dwordx4 v167, s[98:99]
	s_add_u32 s98, s98, 128
	s_addc_u32 s99, s99, 0
	s_waitcnt lgkmcnt(8)
	v_mfma_f32_16x16x32_bf16 v[16:19], v[72:75], v[96:99], v[16:19]
	v_mfma_f32_16x16x32_bf16 v[48:51], v[76:79], v[96:99], v[48:51]
	ds_read_b128 v[124:127], v162 offset:22528
	s_add_u32 m0, s38, 49152
	s_nop 0
	global_load_lds_dwordx4 v164, s[100:101]
	s_waitcnt lgkmcnt(8)
	v_mfma_f32_16x16x32_bf16 v[20:23], v[72:75], v[100:103], v[20:23]
	v_mfma_f32_16x16x32_bf16 v[52:55], v[76:79], v[100:103], v[52:55]
	ds_read_b128 v[80:83], v162 offset:24576
	s_add_u32 m0, s38, 53248
	s_nop 0
	global_load_lds_dwordx4 v165, s[100:101]
	s_waitcnt lgkmcnt(8)
	v_mfma_f32_16x16x32_bf16 v[24:27], v[72:75], v[104:107], v[24:27]
	v_mfma_f32_16x16x32_bf16 v[56:59], v[76:79], v[104:107], v[56:59]
	ds_read_b128 v[84:87], v162 offset:26624
	s_add_u32 m0, s38, 57344
	s_nop 0
	global_load_lds_dwordx4 v166, s[100:101]
	s_waitcnt lgkmcnt(8)
	v_mfma_f32_16x16x32_bf16 v[28:31], v[72:75], v[108:111], v[28:31]
	v_mfma_f32_16x16x32_bf16 v[60:63], v[76:79], v[108:111], v[60:63]
	ds_read_b128 v[88:91], v162 offset:28672
	s_add_u32 m0, s38, 61440
	s_nop 0
	global_load_lds_dwordx4 v167, s[100:101]
	s_add_u32 s100, s100, 128
	s_addc_u32 s101, s101, 0
	s_waitcnt lgkmcnt(6)
	v_mfma_f32_16x16x32_bf16 v[0:3], v[64:67], v[112:115], v[0:3]
	v_mfma_f32_16x16x32_bf16 v[32:35], v[68:71], v[112:115], v[32:35]
	ds_read_b128 v[92:95], v162 offset:30720
	s_waitcnt lgkmcnt(6)
	v_mfma_f32_16x16x32_bf16 v[4:7], v[64:67], v[116:119], v[4:7]
	v_mfma_f32_16x16x32_bf16 v[36:39], v[68:71], v[116:119], v[36:39]
	ds_read_b128 v[72:75], v151 offset:0
	ds_read_b128 v[76:79], v151 offset:2048
	ds_read_b128 v[96:99], v163 offset:16384
	s_waitcnt lgkmcnt(8)
	v_mfma_f32_16x16x32_bf16 v[8:11], v[64:67], v[120:123], v[8:11]
	v_mfma_f32_16x16x32_bf16 v[40:43], v[68:71], v[120:123], v[40:43]
	ds_read_b128 v[100:103], v163 offset:18432
	s_waitcnt lgkmcnt(8)
	v_mfma_f32_16x16x32_bf16 v[12:15], v[64:67], v[124:127], v[12:15]
	v_mfma_f32_16x16x32_bf16 v[44:47], v[68:71], v[124:127], v[44:47]
	ds_read_b128 v[104:107], v163 offset:20480
	s_waitcnt lgkmcnt(8)
	v_mfma_f32_16x16x32_bf16 v[16:19], v[64:67], v[80:83], v[16:19]
	v_mfma_f32_16x16x32_bf16 v[48:51], v[68:71], v[80:83], v[48:51]
	ds_read_b128 v[108:111], v163 offset:22528
	s_waitcnt lgkmcnt(8)
	v_mfma_f32_16x16x32_bf16 v[20:23], v[64:67], v[84:87], v[20:23]
	v_mfma_f32_16x16x32_bf16 v[52:55], v[68:71], v[84:87], v[52:55]
	ds_read_b128 v[112:115], v163 offset:24576
	s_waitcnt lgkmcnt(8)
	v_mfma_f32_16x16x32_bf16 v[24:27], v[64:67], v[88:91], v[24:27]
	v_mfma_f32_16x16x32_bf16 v[56:59], v[68:71], v[88:91], v[56:59]
	ds_read_b128 v[116:119], v163 offset:26624
	s_waitcnt lgkmcnt(8)
	v_mfma_f32_16x16x32_bf16 v[28:31], v[64:67], v[92:95], v[28:31]
	v_mfma_f32_16x16x32_bf16 v[60:63], v[68:71], v[92:95], v[60:63]
	ds_read_b128 v[120:123], v163 offset:28672
	s_waitcnt lgkmcnt(6)
	v_mfma_f32_16x16x32_bf16 v[0:3], v[72:75], v[96:99], v[0:3]
	v_mfma_f32_16x16x32_bf16 v[32:35], v[76:79], v[96:99], v[32:35]
	ds_read_b128 v[124:127], v163 offset:30720
	s_waitcnt vmcnt(0) lgkmcnt(0)
	s_barrier
	s_add_u32 m0, s38, 0
	s_nop 0
	global_load_lds_dwordx4 v164, s[98:99]
	s_waitcnt lgkmcnt(6)
	v_mfma_f32_16x16x32_bf16 v[4:7], v[72:75], v[100:103], v[4:7]
	v_mfma_f32_16x16x32_bf16 v[36:39], v[76:79], v[100:103], v[36:39]
	ds_read_b128 v[64:67], v150 offset:32768
	ds_read_b128 v[68:71], v150 offset:34816
	ds_read_b128 v[80:83], v162 offset:49152
	s_add_u32 m0, s38, 4096
	s_nop 0
	global_load_lds_dwordx4 v165, s[98:99]
	s_waitcnt lgkmcnt(8)
	v_mfma_f32_16x16x32_bf16 v[8:11], v[72:75], v[104:107], v[8:11]
	v_mfma_f32_16x16x32_bf16 v[40:43], v[76:79], v[104:107], v[40:43]
	ds_read_b128 v[84:87], v162 offset:51200
	s_add_u32 m0, s38, 8192
	s_nop 0
	global_load_lds_dwordx4 v166, s[98:99]
	s_waitcnt lgkmcnt(8)
	v_mfma_f32_16x16x32_bf16 v[12:15], v[72:75], v[108:111], v[12:15]
	v_mfma_f32_16x16x32_bf16 v[44:47], v[76:79], v[108:111], v[44:47]
	ds_read_b128 v[88:91], v162 offset:53248
	s_add_u32 m0, s38, 12288
	s_nop 0
	global_load_lds_dwordx4 v167, s[98:99]
	s_add_u32 s98, s98, 128
	s_addc_u32 s99, s99, 0
	s_waitcnt lgkmcnt(8)
	v_mfma_f32_16x16x32_bf16 v[16:19], v[72:75], v[112:115], v[16:19]
	v_mfma_f32_16x16x32_bf16 v[48:51], v[76:79], v[112:115], v[48:51]
	ds_read_b128 v[92:95], v162 offset:55296
	s_add_u32 m0, s38, 16384
	s_nop 0
	global_load_lds_dwordx4 v164, s[100:101]
	s_waitcnt lgkmcnt(8)
	v_mfma_f32_16x16x32_bf16 v[20:23], v[72:75], v[116:119], v[20:23]
	v_mfma_f32_16x16x32_bf16 v[52:55], v[76:79], v[116:119], v[52:55]
	ds_read_b128 v[96:99], v162 offset:57344
	s_add_u32 m0, s38, 20480
	s_nop 0
	global_load_lds_dwordx4 v165, s[100:101]
	s_waitcnt lgkmcnt(8)
	v_mfma_f32_16x16x32_bf16 v[24:27], v[72:75], v[120:123], v[24:27]
	v_mfma_f32_16x16x32_bf16 v[56:59], v[76:79], v[120:123], v[56:59]
	ds_read_b128 v[100:103], v162 offset:59392
	s_add_u32 m0, s38, 24576
	s_nop 0
	global_load_lds_dwordx4 v166, s[100:101]
	s_waitcnt lgkmcnt(8)
	v_mfma_f32_16x16x32_bf16 v[28:31], v[72:75], v[124:127], v[28:31]
	v_mfma_f32_16x16x32_bf16 v[60:63], v[76:79], v[124:127], v[60:63]
	ds_read_b128 v[104:107], v162 offset:61440
	s_add_u32 m0, s38, 28672
	s_nop 0
	global_load_lds_dwordx4 v167, s[100:101]
	s_add_u32 s100, s100, 128
	s_addc_u32 s101, s101, 0
	s_waitcnt lgkmcnt(6)
	v_mfma_f32_16x16x32_bf16 v[0:3], v[64:67], v[80:83], v[0:3]
	v_mfma_f32_16x16x32_bf16 v[32:35], v[68:71], v[80:83], v[32:35]
	ds_read_b128 v[108:111], v162 offset:63488
	s_waitcnt lgkmcnt(6)
	v_mfma_f32_16x16x32_bf16 v[4:7], v[64:67], v[84:87], v[4:7]
	v_mfma_f32_16x16x32_bf16 v[36:39], v[68:71], v[84:87], v[36:39]
	ds_read_b128 v[72:75], v151 offset:32768
	ds_read_b128 v[76:79], v151 offset:34816
	ds_read_b128 v[112:115], v163 offset:49152
	s_waitcnt lgkmcnt(8)
	v_mfma_f32_16x16x32_bf16 v[8:11], v[64:67], v[88:91], v[8:11]
	v_mfma_f32_16x16x32_bf16 v[40:43], v[68:71], v[88:91], v[40:43]
	ds_read_b128 v[116:119], v163 offset:51200
	s_waitcnt lgkmcnt(8)
	v_mfma_f32_16x16x32_bf16 v[12:15], v[64:67], v[92:95], v[12:15]
	v_mfma_f32_16x16x32_bf16 v[44:47], v[68:71], v[92:95], v[44:47]
	ds_read_b128 v[120:123], v163 offset:53248
	s_waitcnt lgkmcnt(8)
	v_mfma_f32_16x16x32_bf16 v[16:19], v[64:67], v[96:99], v[16:19]
	v_mfma_f32_16x16x32_bf16 v[48:51], v[68:71], v[96:99], v[48:51]
	ds_read_b128 v[124:127], v163 offset:55296
	s_waitcnt lgkmcnt(8)
	v_mfma_f32_16x16x32_bf16 v[20:23], v[64:67], v[100:103], v[20:23]
	v_mfma_f32_16x16x32_bf16 v[52:55], v[68:71], v[100:103], v[52:55]
	ds_read_b128 v[80:83], v163 offset:57344
	s_waitcnt lgkmcnt(8)
	v_mfma_f32_16x16x32_bf16 v[24:27], v[64:67], v[104:107], v[24:27]
	v_mfma_f32_16x16x32_bf16 v[56:59], v[68:71], v[104:107], v[56:59]
	ds_read_b128 v[84:87], v163 offset:59392
	s_waitcnt lgkmcnt(8)
	v_mfma_f32_16x16x32_bf16 v[28:31], v[64:67], v[108:111], v[28:31]
	v_mfma_f32_16x16x32_bf16 v[60:63], v[68:71], v[108:111], v[60:63]
	ds_read_b128 v[88:91], v163 offset:61440
	s_waitcnt lgkmcnt(6)
	v_mfma_f32_16x16x32_bf16 v[0:3], v[72:75], v[112:115], v[0:3]
	v_mfma_f32_16x16x32_bf16 v[32:35], v[76:79], v[112:115], v[32:35]
	ds_read_b128 v[92:95], v163 offset:63488
	s_waitcnt vmcnt(0) lgkmcnt(0)
	s_barrier
	s_add_u32 m0, s38, 32768
	s_nop 0
	global_load_lds_dwordx4 v164, s[98:99]
	s_waitcnt lgkmcnt(6)
	v_mfma_f32_16x16x32_bf16 v[4:7], v[72:75], v[116:119], v[4:7]
	v_mfma_f32_16x16x32_bf16 v[36:39], v[76:79], v[116:119], v[36:39]
	ds_read_b128 v[64:67], v150 offset:0
	ds_read_b128 v[68:71], v150 offset:2048
	ds_read_b128 v[96:99], v162 offset:16384
	s_add_u32 m0, s38, 36864
	s_nop 0
	global_load_lds_dwordx4 v165, s[98:99]
	s_waitcnt lgkmcnt(8)
	v_mfma_f32_16x16x32_bf16 v[8:11], v[72:75], v[120:123], v[8:11]
	v_mfma_f32_16x16x32_bf16 v[40:43], v[76:79], v[120:123], v[40:43]
	ds_read_b128 v[100:103], v162 offset:18432
	s_add_u32 m0, s38, 40960
	s_nop 0
	global_load_lds_dwordx4 v166, s[98:99]
	s_waitcnt lgkmcnt(8)
	v_mfma_f32_16x16x32_bf16 v[12:15], v[72:75], v[124:127], v[12:15]
	v_mfma_f32_16x16x32_bf16 v[44:47], v[76:79], v[124:127], v[44:47]
	ds_read_b128 v[104:107], v162 offset:20480
	s_add_u32 m0, s38, 45056
	s_nop 0
	global_load_lds_dwordx4 v167, s[98:99]
	s_add_u32 s98, s98, 128
	s_addc_u32 s99, s99, 0
	s_waitcnt lgkmcnt(8)
	v_mfma_f32_16x16x32_bf16 v[16:19], v[72:75], v[80:83], v[16:19]
	v_mfma_f32_16x16x32_bf16 v[48:51], v[76:79], v[80:83], v[48:51]
	ds_read_b128 v[108:111], v162 offset:22528
	s_add_u32 m0, s38, 49152
	s_nop 0
	global_load_lds_dwordx4 v164, s[100:101]
	s_waitcnt lgkmcnt(8)
	v_mfma_f32_16x16x32_bf16 v[20:23], v[72:75], v[84:87], v[20:23]
	v_mfma_f32_16x16x32_bf16 v[52:55], v[76:79], v[84:87], v[52:55]
	ds_read_b128 v[112:115], v162 offset:24576
	s_add_u32 m0, s38, 53248
	s_nop 0
	global_load_lds_dwordx4 v165, s[100:101]
	s_waitcnt lgkmcnt(8)
	v_mfma_f32_16x16x32_bf16 v[24:27], v[72:75], v[88:91], v[24:27]
	v_mfma_f32_16x16x32_bf16 v[56:59], v[76:79], v[88:91], v[56:59]
	ds_read_b128 v[116:119], v162 offset:26624
	s_add_u32 m0, s38, 57344
	s_nop 0
	global_load_lds_dwordx4 v166, s[100:101]
	s_waitcnt lgkmcnt(8)
	v_mfma_f32_16x16x32_bf16 v[28:31], v[72:75], v[92:95], v[28:31]
	v_mfma_f32_16x16x32_bf16 v[60:63], v[76:79], v[92:95], v[60:63]
	ds_read_b128 v[120:123], v162 offset:28672
	s_add_u32 m0, s38, 61440
	s_nop 0
	global_load_lds_dwordx4 v167, s[100:101]
	s_add_u32 s100, s100, 128
	s_addc_u32 s101, s101, 0
	s_waitcnt lgkmcnt(6)
	v_mfma_f32_16x16x32_bf16 v[0:3], v[64:67], v[96:99], v[0:3]
	v_mfma_f32_16x16x32_bf16 v[32:35], v[68:71], v[96:99], v[32:35]
	ds_read_b128 v[124:127], v162 offset:30720
	s_waitcnt lgkmcnt(6)
	v_mfma_f32_16x16x32_bf16 v[4:7], v[64:67], v[100:103], v[4:7]
	v_mfma_f32_16x16x32_bf16 v[36:39], v[68:71], v[100:103], v[36:39]
	ds_read_b128 v[72:75], v151 offset:0
	ds_read_b128 v[76:79], v151 offset:2048
	ds_read_b128 v[80:83], v163 offset:16384
	s_waitcnt lgkmcnt(8)
	v_mfma_f32_16x16x32_bf16 v[8:11], v[64:67], v[104:107], v[8:11]
	v_mfma_f32_16x16x32_bf16 v[40:43], v[68:71], v[104:107], v[40:43]
	ds_read_b128 v[84:87], v163 offset:18432
	s_waitcnt lgkmcnt(8)
	v_mfma_f32_16x16x32_bf16 v[12:15], v[64:67], v[108:111], v[12:15]
	v_mfma_f32_16x16x32_bf16 v[44:47], v[68:71], v[108:111], v[44:47]
	ds_read_b128 v[88:91], v163 offset:20480
	s_waitcnt lgkmcnt(8)
	v_mfma_f32_16x16x32_bf16 v[16:19], v[64:67], v[112:115], v[16:19]
	v_mfma_f32_16x16x32_bf16 v[48:51], v[68:71], v[112:115], v[48:51]
	ds_read_b128 v[92:95], v163 offset:22528
	s_waitcnt lgkmcnt(8)
	v_mfma_f32_16x16x32_bf16 v[20:23], v[64:67], v[116:119], v[20:23]
	v_mfma_f32_16x16x32_bf16 v[52:55], v[68:71], v[116:119], v[52:55]
	ds_read_b128 v[96:99], v163 offset:24576
	s_waitcnt lgkmcnt(8)
	v_mfma_f32_16x16x32_bf16 v[24:27], v[64:67], v[120:123], v[24:27]
	v_mfma_f32_16x16x32_bf16 v[56:59], v[68:71], v[120:123], v[56:59]
	ds_read_b128 v[100:103], v163 offset:26624
	s_waitcnt lgkmcnt(8)
	v_mfma_f32_16x16x32_bf16 v[28:31], v[64:67], v[124:127], v[28:31]
	v_mfma_f32_16x16x32_bf16 v[60:63], v[68:71], v[124:127], v[60:63]
	ds_read_b128 v[104:107], v163 offset:28672
	s_waitcnt lgkmcnt(6)
	v_mfma_f32_16x16x32_bf16 v[0:3], v[72:75], v[80:83], v[0:3]
	v_mfma_f32_16x16x32_bf16 v[32:35], v[76:79], v[80:83], v[32:35]
	ds_read_b128 v[108:111], v163 offset:30720
	s_waitcnt vmcnt(0) lgkmcnt(0)
	s_barrier
	s_add_u32 m0, s38, 0
	s_nop 0
	global_load_lds_dwordx4 v164, s[98:99]
	s_waitcnt lgkmcnt(6)
	v_mfma_f32_16x16x32_bf16 v[4:7], v[72:75], v[84:87], v[4:7]
	v_mfma_f32_16x16x32_bf16 v[36:39], v[76:79], v[84:87], v[36:39]
	ds_read_b128 v[64:67], v150 offset:32768
	ds_read_b128 v[68:71], v150 offset:34816
	ds_read_b128 v[112:115], v162 offset:49152
	s_add_u32 m0, s38, 4096
	s_nop 0
	global_load_lds_dwordx4 v165, s[98:99]
	s_waitcnt lgkmcnt(8)
	v_mfma_f32_16x16x32_bf16 v[8:11], v[72:75], v[88:91], v[8:11]
	v_mfma_f32_16x16x32_bf16 v[40:43], v[76:79], v[88:91], v[40:43]
	ds_read_b128 v[116:119], v162 offset:51200
	s_add_u32 m0, s38, 8192
	s_nop 0
	global_load_lds_dwordx4 v166, s[98:99]
	s_waitcnt lgkmcnt(8)
	v_mfma_f32_16x16x32_bf16 v[12:15], v[72:75], v[92:95], v[12:15]
	v_mfma_f32_16x16x32_bf16 v[44:47], v[76:79], v[92:95], v[44:47]
	ds_read_b128 v[120:123], v162 offset:53248
	s_add_u32 m0, s38, 12288
	s_nop 0
	global_load_lds_dwordx4 v167, s[98:99]
	s_add_u32 s98, s98, 128
	s_addc_u32 s99, s99, 0
	s_waitcnt lgkmcnt(8)
	v_mfma_f32_16x16x32_bf16 v[16:19], v[72:75], v[96:99], v[16:19]
	v_mfma_f32_16x16x32_bf16 v[48:51], v[76:79], v[96:99], v[48:51]
	ds_read_b128 v[124:127], v162 offset:55296
	s_add_u32 m0, s38, 16384
	s_nop 0
	global_load_lds_dwordx4 v164, s[100:101]
	s_waitcnt lgkmcnt(8)
	v_mfma_f32_16x16x32_bf16 v[20:23], v[72:75], v[100:103], v[20:23]
	v_mfma_f32_16x16x32_bf16 v[52:55], v[76:79], v[100:103], v[52:55]
	ds_read_b128 v[80:83], v162 offset:57344
	s_add_u32 m0, s38, 20480
	s_nop 0
	global_load_lds_dwordx4 v165, s[100:101]
	s_waitcnt lgkmcnt(8)
	v_mfma_f32_16x16x32_bf16 v[24:27], v[72:75], v[104:107], v[24:27]
	v_mfma_f32_16x16x32_bf16 v[56:59], v[76:79], v[104:107], v[56:59]
	ds_read_b128 v[84:87], v162 offset:59392
	s_add_u32 m0, s38, 24576
	s_nop 0
	global_load_lds_dwordx4 v166, s[100:101]
	s_waitcnt lgkmcnt(8)
	v_mfma_f32_16x16x32_bf16 v[28:31], v[72:75], v[108:111], v[28:31]
	v_mfma_f32_16x16x32_bf16 v[60:63], v[76:79], v[108:111], v[60:63]
	ds_read_b128 v[88:91], v162 offset:61440
	s_add_u32 m0, s38, 28672
	s_nop 0
	global_load_lds_dwordx4 v167, s[100:101]
	s_add_u32 s100, s100, 128
	s_addc_u32 s101, s101, 0
	s_waitcnt lgkmcnt(6)
	v_mfma_f32_16x16x32_bf16 v[0:3], v[64:67], v[112:115], v[0:3]
	v_mfma_f32_16x16x32_bf16 v[32:35], v[68:71], v[112:115], v[32:35]
	ds_read_b128 v[92:95], v162 offset:63488
	s_waitcnt lgkmcnt(6)
	v_mfma_f32_16x16x32_bf16 v[4:7], v[64:67], v[116:119], v[4:7]
	v_mfma_f32_16x16x32_bf16 v[36:39], v[68:71], v[116:119], v[36:39]
	ds_read_b128 v[72:75], v151 offset:32768
	ds_read_b128 v[76:79], v151 offset:34816
	ds_read_b128 v[96:99], v163 offset:49152
	s_waitcnt lgkmcnt(8)
	v_mfma_f32_16x16x32_bf16 v[8:11], v[64:67], v[120:123], v[8:11]
	v_mfma_f32_16x16x32_bf16 v[40:43], v[68:71], v[120:123], v[40:43]
	ds_read_b128 v[100:103], v163 offset:51200
	s_waitcnt lgkmcnt(8)
	v_mfma_f32_16x16x32_bf16 v[12:15], v[64:67], v[124:127], v[12:15]
	v_mfma_f32_16x16x32_bf16 v[44:47], v[68:71], v[124:127], v[44:47]
	ds_read_b128 v[104:107], v163 offset:53248
	s_waitcnt lgkmcnt(8)
	v_mfma_f32_16x16x32_bf16 v[16:19], v[64:67], v[80:83], v[16:19]
	v_mfma_f32_16x16x32_bf16 v[48:51], v[68:71], v[80:83], v[48:51]
	ds_read_b128 v[108:111], v163 offset:55296
	s_waitcnt lgkmcnt(8)
	v_mfma_f32_16x16x32_bf16 v[20:23], v[64:67], v[84:87], v[20:23]
	v_mfma_f32_16x16x32_bf16 v[52:55], v[68:71], v[84:87], v[52:55]
	ds_read_b128 v[112:115], v163 offset:57344
	s_waitcnt lgkmcnt(8)
	v_mfma_f32_16x16x32_bf16 v[24:27], v[64:67], v[88:91], v[24:27]
	v_mfma_f32_16x16x32_bf16 v[56:59], v[68:71], v[88:91], v[56:59]
	ds_read_b128 v[116:119], v163 offset:59392
	s_waitcnt lgkmcnt(8)
	v_mfma_f32_16x16x32_bf16 v[28:31], v[64:67], v[92:95], v[28:31]
	v_mfma_f32_16x16x32_bf16 v[60:63], v[68:71], v[92:95], v[60:63]
	ds_read_b128 v[120:123], v163 offset:61440
	s_waitcnt lgkmcnt(6)
	v_mfma_f32_16x16x32_bf16 v[0:3], v[72:75], v[96:99], v[0:3]
	v_mfma_f32_16x16x32_bf16 v[32:35], v[76:79], v[96:99], v[32:35]
	ds_read_b128 v[124:127], v163 offset:63488
	s_waitcnt vmcnt(0) lgkmcnt(0)
	s_barrier
	s_add_u32 m0, s38, 32768
	s_nop 0
	global_load_lds_dwordx4 v164, s[98:99]
	s_waitcnt lgkmcnt(6)
	v_mfma_f32_16x16x32_bf16 v[4:7], v[72:75], v[100:103], v[4:7]
	v_mfma_f32_16x16x32_bf16 v[36:39], v[76:79], v[100:103], v[36:39]
	ds_read_b128 v[64:67], v150 offset:0
	ds_read_b128 v[68:71], v150 offset:2048
	ds_read_b128 v[80:83], v162 offset:16384
	s_add_u32 m0, s38, 36864
	s_nop 0
	global_load_lds_dwordx4 v165, s[98:99]
	s_waitcnt lgkmcnt(8)
	v_mfma_f32_16x16x32_bf16 v[8:11], v[72:75], v[104:107], v[8:11]
	v_mfma_f32_16x16x32_bf16 v[40:43], v[76:79], v[104:107], v[40:43]
	ds_read_b128 v[84:87], v162 offset:18432
	s_add_u32 m0, s38, 40960
	s_nop 0
	global_load_lds_dwordx4 v166, s[98:99]
	s_waitcnt lgkmcnt(8)
	v_mfma_f32_16x16x32_bf16 v[12:15], v[72:75], v[108:111], v[12:15]
	v_mfma_f32_16x16x32_bf16 v[44:47], v[76:79], v[108:111], v[44:47]
	ds_read_b128 v[88:91], v162 offset:20480
	s_add_u32 m0, s38, 45056
	s_nop 0
	global_load_lds_dwordx4 v167, s[98:99]
	s_add_u32 s98, s98, 128
	s_addc_u32 s99, s99, 0
	s_waitcnt lgkmcnt(8)
	v_mfma_f32_16x16x32_bf16 v[16:19], v[72:75], v[112:115], v[16:19]
	v_mfma_f32_16x16x32_bf16 v[48:51], v[76:79], v[112:115], v[48:51]
	ds_read_b128 v[92:95], v162 offset:22528
	s_add_u32 m0, s38, 49152
	s_nop 0
	global_load_lds_dwordx4 v164, s[100:101]
	s_waitcnt lgkmcnt(8)
	v_mfma_f32_16x16x32_bf16 v[20:23], v[72:75], v[116:119], v[20:23]
	v_mfma_f32_16x16x32_bf16 v[52:55], v[76:79], v[116:119], v[52:55]
	ds_read_b128 v[96:99], v162 offset:24576
	s_add_u32 m0, s38, 53248
	s_nop 0
	global_load_lds_dwordx4 v165, s[100:101]
	s_waitcnt lgkmcnt(8)
	v_mfma_f32_16x16x32_bf16 v[24:27], v[72:75], v[120:123], v[24:27]
	v_mfma_f32_16x16x32_bf16 v[56:59], v[76:79], v[120:123], v[56:59]
	ds_read_b128 v[100:103], v162 offset:26624
	s_add_u32 m0, s38, 57344
	s_nop 0
	global_load_lds_dwordx4 v166, s[100:101]
	s_waitcnt lgkmcnt(8)
	v_mfma_f32_16x16x32_bf16 v[28:31], v[72:75], v[124:127], v[28:31]
	v_mfma_f32_16x16x32_bf16 v[60:63], v[76:79], v[124:127], v[60:63]
	ds_read_b128 v[104:107], v162 offset:28672
	s_add_u32 m0, s38, 61440
	s_nop 0
	global_load_lds_dwordx4 v167, s[100:101]
	s_add_u32 s100, s100, 128
	s_addc_u32 s101, s101, 0
	s_waitcnt lgkmcnt(6)
	v_mfma_f32_16x16x32_bf16 v[0:3], v[64:67], v[80:83], v[0:3]
	v_mfma_f32_16x16x32_bf16 v[32:35], v[68:71], v[80:83], v[32:35]
	ds_read_b128 v[108:111], v162 offset:30720
	s_waitcnt lgkmcnt(6)
	v_mfma_f32_16x16x32_bf16 v[4:7], v[64:67], v[84:87], v[4:7]
	v_mfma_f32_16x16x32_bf16 v[36:39], v[68:71], v[84:87], v[36:39]
	ds_read_b128 v[72:75], v151 offset:0
	ds_read_b128 v[76:79], v151 offset:2048
	ds_read_b128 v[112:115], v163 offset:16384
	s_waitcnt lgkmcnt(8)
	v_mfma_f32_16x16x32_bf16 v[8:11], v[64:67], v[88:91], v[8:11]
	v_mfma_f32_16x16x32_bf16 v[40:43], v[68:71], v[88:91], v[40:43]
	ds_read_b128 v[116:119], v163 offset:18432
	s_waitcnt lgkmcnt(8)
	v_mfma_f32_16x16x32_bf16 v[12:15], v[64:67], v[92:95], v[12:15]
	v_mfma_f32_16x16x32_bf16 v[44:47], v[68:71], v[92:95], v[44:47]
	ds_read_b128 v[120:123], v163 offset:20480
	s_waitcnt lgkmcnt(8)
	v_mfma_f32_16x16x32_bf16 v[16:19], v[64:67], v[96:99], v[16:19]
	v_mfma_f32_16x16x32_bf16 v[48:51], v[68:71], v[96:99], v[48:51]
	ds_read_b128 v[124:127], v163 offset:22528
	s_waitcnt lgkmcnt(8)
	v_mfma_f32_16x16x32_bf16 v[20:23], v[64:67], v[100:103], v[20:23]
	v_mfma_f32_16x16x32_bf16 v[52:55], v[68:71], v[100:103], v[52:55]
	ds_read_b128 v[80:83], v163 offset:24576
	s_waitcnt lgkmcnt(8)
	v_mfma_f32_16x16x32_bf16 v[24:27], v[64:67], v[104:107], v[24:27]
	v_mfma_f32_16x16x32_bf16 v[56:59], v[68:71], v[104:107], v[56:59]
	ds_read_b128 v[84:87], v163 offset:26624
	s_waitcnt lgkmcnt(8)
	v_mfma_f32_16x16x32_bf16 v[28:31], v[64:67], v[108:111], v[28:31]
	v_mfma_f32_16x16x32_bf16 v[60:63], v[68:71], v[108:111], v[60:63]
	ds_read_b128 v[88:91], v163 offset:28672
	s_waitcnt lgkmcnt(6)
	v_mfma_f32_16x16x32_bf16 v[0:3], v[72:75], v[112:115], v[0:3]
	v_mfma_f32_16x16x32_bf16 v[32:35], v[76:79], v[112:115], v[32:35]
	ds_read_b128 v[92:95], v163 offset:30720
	s_waitcnt vmcnt(0) lgkmcnt(0)
	s_barrier
	s_add_u32 m0, s38, 0
	s_nop 0
	global_load_lds_dwordx4 v164, s[98:99]
	s_waitcnt lgkmcnt(6)
	v_mfma_f32_16x16x32_bf16 v[4:7], v[72:75], v[116:119], v[4:7]
	v_mfma_f32_16x16x32_bf16 v[36:39], v[76:79], v[116:119], v[36:39]
	ds_read_b128 v[64:67], v150 offset:32768
	ds_read_b128 v[68:71], v150 offset:34816
	ds_read_b128 v[96:99], v162 offset:49152
	s_add_u32 m0, s38, 4096
	s_nop 0
	global_load_lds_dwordx4 v165, s[98:99]
	s_waitcnt lgkmcnt(8)
	v_mfma_f32_16x16x32_bf16 v[8:11], v[72:75], v[120:123], v[8:11]
	v_mfma_f32_16x16x32_bf16 v[40:43], v[76:79], v[120:123], v[40:43]
	ds_read_b128 v[100:103], v162 offset:51200
	s_add_u32 m0, s38, 8192
	s_nop 0
	global_load_lds_dwordx4 v166, s[98:99]
	s_waitcnt lgkmcnt(8)
	v_mfma_f32_16x16x32_bf16 v[12:15], v[72:75], v[124:127], v[12:15]
	v_mfma_f32_16x16x32_bf16 v[44:47], v[76:79], v[124:127], v[44:47]
	ds_read_b128 v[104:107], v162 offset:53248
	s_add_u32 m0, s38, 12288
	s_nop 0
	global_load_lds_dwordx4 v167, s[98:99]
	s_add_u32 s98, s98, 128
	s_addc_u32 s99, s99, 0
	s_waitcnt lgkmcnt(8)
	v_mfma_f32_16x16x32_bf16 v[16:19], v[72:75], v[80:83], v[16:19]
	v_mfma_f32_16x16x32_bf16 v[48:51], v[76:79], v[80:83], v[48:51]
	ds_read_b128 v[108:111], v162 offset:55296
	s_add_u32 m0, s38, 16384
	s_nop 0
	global_load_lds_dwordx4 v164, s[100:101]
	s_waitcnt lgkmcnt(8)
	v_mfma_f32_16x16x32_bf16 v[20:23], v[72:75], v[84:87], v[20:23]
	v_mfma_f32_16x16x32_bf16 v[52:55], v[76:79], v[84:87], v[52:55]
	ds_read_b128 v[112:115], v162 offset:57344
	s_add_u32 m0, s38, 20480
	s_nop 0
	global_load_lds_dwordx4 v165, s[100:101]
	s_waitcnt lgkmcnt(8)
	v_mfma_f32_16x16x32_bf16 v[24:27], v[72:75], v[88:91], v[24:27]
	v_mfma_f32_16x16x32_bf16 v[56:59], v[76:79], v[88:91], v[56:59]
	ds_read_b128 v[116:119], v162 offset:59392
	s_add_u32 m0, s38, 24576
	s_nop 0
	global_load_lds_dwordx4 v166, s[100:101]
	s_waitcnt lgkmcnt(8)
	v_mfma_f32_16x16x32_bf16 v[28:31], v[72:75], v[92:95], v[28:31]
	v_mfma_f32_16x16x32_bf16 v[60:63], v[76:79], v[92:95], v[60:63]
	ds_read_b128 v[120:123], v162 offset:61440
	s_add_u32 m0, s38, 28672
	s_nop 0
	global_load_lds_dwordx4 v167, s[100:101]
	s_add_u32 s100, s100, 128
	s_addc_u32 s101, s101, 0
	s_waitcnt lgkmcnt(6)
	v_mfma_f32_16x16x32_bf16 v[0:3], v[64:67], v[96:99], v[0:3]
	v_mfma_f32_16x16x32_bf16 v[32:35], v[68:71], v[96:99], v[32:35]
	ds_read_b128 v[124:127], v162 offset:63488
	s_waitcnt lgkmcnt(6)
	v_mfma_f32_16x16x32_bf16 v[4:7], v[64:67], v[100:103], v[4:7]
	v_mfma_f32_16x16x32_bf16 v[36:39], v[68:71], v[100:103], v[36:39]
	ds_read_b128 v[72:75], v151 offset:32768
	ds_read_b128 v[76:79], v151 offset:34816
	ds_read_b128 v[80:83], v163 offset:49152
	s_waitcnt lgkmcnt(8)
	v_mfma_f32_16x16x32_bf16 v[8:11], v[64:67], v[104:107], v[8:11]
	v_mfma_f32_16x16x32_bf16 v[40:43], v[68:71], v[104:107], v[40:43]
	ds_read_b128 v[84:87], v163 offset:51200
	s_waitcnt lgkmcnt(8)
	v_mfma_f32_16x16x32_bf16 v[12:15], v[64:67], v[108:111], v[12:15]
	v_mfma_f32_16x16x32_bf16 v[44:47], v[68:71], v[108:111], v[44:47]
	ds_read_b128 v[88:91], v163 offset:53248
	s_waitcnt lgkmcnt(8)
	v_mfma_f32_16x16x32_bf16 v[16:19], v[64:67], v[112:115], v[16:19]
	v_mfma_f32_16x16x32_bf16 v[48:51], v[68:71], v[112:115], v[48:51]
	ds_read_b128 v[92:95], v163 offset:55296
	s_waitcnt lgkmcnt(8)
	v_mfma_f32_16x16x32_bf16 v[20:23], v[64:67], v[116:119], v[20:23]
	v_mfma_f32_16x16x32_bf16 v[52:55], v[68:71], v[116:119], v[52:55]
	ds_read_b128 v[96:99], v163 offset:57344
	s_waitcnt lgkmcnt(8)
	v_mfma_f32_16x16x32_bf16 v[24:27], v[64:67], v[120:123], v[24:27]
	v_mfma_f32_16x16x32_bf16 v[56:59], v[68:71], v[120:123], v[56:59]
	ds_read_b128 v[100:103], v163 offset:59392
	s_waitcnt lgkmcnt(8)
	v_mfma_f32_16x16x32_bf16 v[28:31], v[64:67], v[124:127], v[28:31]
	v_mfma_f32_16x16x32_bf16 v[60:63], v[68:71], v[124:127], v[60:63]
	ds_read_b128 v[104:107], v163 offset:61440
	s_waitcnt lgkmcnt(6)
	v_mfma_f32_16x16x32_bf16 v[0:3], v[72:75], v[80:83], v[0:3]
	v_mfma_f32_16x16x32_bf16 v[32:35], v[76:79], v[80:83], v[32:35]
	ds_read_b128 v[108:111], v163 offset:63488
	s_waitcnt vmcnt(0) lgkmcnt(0)
	s_barrier
	s_add_u32 m0, s38, 32768
	s_nop 0
	global_load_lds_dwordx4 v164, s[98:99]
	s_waitcnt lgkmcnt(6)
	v_mfma_f32_16x16x32_bf16 v[4:7], v[72:75], v[84:87], v[4:7]
	v_mfma_f32_16x16x32_bf16 v[36:39], v[76:79], v[84:87], v[36:39]
	ds_read_b128 v[64:67], v150 offset:0
	ds_read_b128 v[68:71], v150 offset:2048
	ds_read_b128 v[112:115], v162 offset:16384
	s_add_u32 m0, s38, 36864
	s_nop 0
	global_load_lds_dwordx4 v165, s[98:99]
	s_waitcnt lgkmcnt(8)
	v_mfma_f32_16x16x32_bf16 v[8:11], v[72:75], v[88:91], v[8:11]
	v_mfma_f32_16x16x32_bf16 v[40:43], v[76:79], v[88:91], v[40:43]
	ds_read_b128 v[116:119], v162 offset:18432
	s_add_u32 m0, s38, 40960
	s_nop 0
	global_load_lds_dwordx4 v166, s[98:99]
	s_waitcnt lgkmcnt(8)
	v_mfma_f32_16x16x32_bf16 v[12:15], v[72:75], v[92:95], v[12:15]
	v_mfma_f32_16x16x32_bf16 v[44:47], v[76:79], v[92:95], v[44:47]
	ds_read_b128 v[120:123], v162 offset:20480
	s_add_u32 m0, s38, 45056
	s_nop 0
	global_load_lds_dwordx4 v167, s[98:99]
	s_add_u32 s98, s98, 128
	s_addc_u32 s99, s99, 0
	s_waitcnt lgkmcnt(8)
	v_mfma_f32_16x16x32_bf16 v[16:19], v[72:75], v[96:99], v[16:19]
	v_mfma_f32_16x16x32_bf16 v[48:51], v[76:79], v[96:99], v[48:51]
	ds_read_b128 v[124:127], v162 offset:22528
	s_add_u32 m0, s38, 49152
	s_nop 0
	global_load_lds_dwordx4 v164, s[100:101]
	s_waitcnt lgkmcnt(8)
	v_mfma_f32_16x16x32_bf16 v[20:23], v[72:75], v[100:103], v[20:23]
	v_mfma_f32_16x16x32_bf16 v[52:55], v[76:79], v[100:103], v[52:55]
	ds_read_b128 v[80:83], v162 offset:24576
	s_add_u32 m0, s38, 53248
	s_nop 0
	global_load_lds_dwordx4 v165, s[100:101]
	s_waitcnt lgkmcnt(8)
	v_mfma_f32_16x16x32_bf16 v[24:27], v[72:75], v[104:107], v[24:27]
	v_mfma_f32_16x16x32_bf16 v[56:59], v[76:79], v[104:107], v[56:59]
	ds_read_b128 v[84:87], v162 offset:26624
	s_add_u32 m0, s38, 57344
	s_nop 0
	global_load_lds_dwordx4 v166, s[100:101]
	s_waitcnt lgkmcnt(8)
	v_mfma_f32_16x16x32_bf16 v[28:31], v[72:75], v[108:111], v[28:31]
	v_mfma_f32_16x16x32_bf16 v[60:63], v[76:79], v[108:111], v[60:63]
	ds_read_b128 v[88:91], v162 offset:28672
	s_add_u32 m0, s38, 61440
	s_nop 0
	global_load_lds_dwordx4 v167, s[100:101]
	s_add_u32 s100, s100, 128
	s_addc_u32 s101, s101, 0
	s_waitcnt lgkmcnt(6)
	v_mfma_f32_16x16x32_bf16 v[0:3], v[64:67], v[112:115], v[0:3]
	v_mfma_f32_16x16x32_bf16 v[32:35], v[68:71], v[112:115], v[32:35]
	ds_read_b128 v[92:95], v162 offset:30720
	s_waitcnt lgkmcnt(6)
	v_mfma_f32_16x16x32_bf16 v[4:7], v[64:67], v[116:119], v[4:7]
	v_mfma_f32_16x16x32_bf16 v[36:39], v[68:71], v[116:119], v[36:39]
	ds_read_b128 v[72:75], v151 offset:0
	ds_read_b128 v[76:79], v151 offset:2048
	ds_read_b128 v[96:99], v163 offset:16384
	s_waitcnt lgkmcnt(8)
	v_mfma_f32_16x16x32_bf16 v[8:11], v[64:67], v[120:123], v[8:11]
	v_mfma_f32_16x16x32_bf16 v[40:43], v[68:71], v[120:123], v[40:43]
	ds_read_b128 v[100:103], v163 offset:18432
	s_waitcnt lgkmcnt(8)
	v_mfma_f32_16x16x32_bf16 v[12:15], v[64:67], v[124:127], v[12:15]
	v_mfma_f32_16x16x32_bf16 v[44:47], v[68:71], v[124:127], v[44:47]
	ds_read_b128 v[104:107], v163 offset:20480
	s_waitcnt lgkmcnt(8)
	v_mfma_f32_16x16x32_bf16 v[16:19], v[64:67], v[80:83], v[16:19]
	v_mfma_f32_16x16x32_bf16 v[48:51], v[68:71], v[80:83], v[48:51]
	ds_read_b128 v[108:111], v163 offset:22528
	s_waitcnt lgkmcnt(8)
	v_mfma_f32_16x16x32_bf16 v[20:23], v[64:67], v[84:87], v[20:23]
	v_mfma_f32_16x16x32_bf16 v[52:55], v[68:71], v[84:87], v[52:55]
	ds_read_b128 v[112:115], v163 offset:24576
	s_waitcnt lgkmcnt(8)
	v_mfma_f32_16x16x32_bf16 v[24:27], v[64:67], v[88:91], v[24:27]
	v_mfma_f32_16x16x32_bf16 v[56:59], v[68:71], v[88:91], v[56:59]
	ds_read_b128 v[116:119], v163 offset:26624
	s_waitcnt lgkmcnt(8)
	v_mfma_f32_16x16x32_bf16 v[28:31], v[64:67], v[92:95], v[28:31]
	v_mfma_f32_16x16x32_bf16 v[60:63], v[68:71], v[92:95], v[60:63]
	ds_read_b128 v[120:123], v163 offset:28672
	s_waitcnt lgkmcnt(6)
	v_mfma_f32_16x16x32_bf16 v[0:3], v[72:75], v[96:99], v[0:3]
	v_mfma_f32_16x16x32_bf16 v[32:35], v[76:79], v[96:99], v[32:35]
	ds_read_b128 v[124:127], v163 offset:30720
	s_waitcnt vmcnt(0) lgkmcnt(0)
	s_barrier
	s_add_u32 m0, s38, 0
	s_nop 0
	global_load_lds_dwordx4 v164, s[98:99]
	s_waitcnt lgkmcnt(6)
	v_mfma_f32_16x16x32_bf16 v[4:7], v[72:75], v[100:103], v[4:7]
	v_mfma_f32_16x16x32_bf16 v[36:39], v[76:79], v[100:103], v[36:39]
	ds_read_b128 v[64:67], v150 offset:32768
	ds_read_b128 v[68:71], v150 offset:34816
	ds_read_b128 v[80:83], v162 offset:49152
	s_add_u32 m0, s38, 4096
	s_nop 0
	global_load_lds_dwordx4 v165, s[98:99]
	s_waitcnt lgkmcnt(8)
	v_mfma_f32_16x16x32_bf16 v[8:11], v[72:75], v[104:107], v[8:11]
	v_mfma_f32_16x16x32_bf16 v[40:43], v[76:79], v[104:107], v[40:43]
	ds_read_b128 v[84:87], v162 offset:51200
	s_add_u32 m0, s38, 8192
	s_nop 0
	global_load_lds_dwordx4 v166, s[98:99]
	s_waitcnt lgkmcnt(8)
	v_mfma_f32_16x16x32_bf16 v[12:15], v[72:75], v[108:111], v[12:15]
	v_mfma_f32_16x16x32_bf16 v[44:47], v[76:79], v[108:111], v[44:47]
	ds_read_b128 v[88:91], v162 offset:53248
	s_add_u32 m0, s38, 12288
	s_nop 0
	global_load_lds_dwordx4 v167, s[98:99]
	s_add_u32 s98, s98, 128
	s_addc_u32 s99, s99, 0
	s_waitcnt lgkmcnt(8)
	v_mfma_f32_16x16x32_bf16 v[16:19], v[72:75], v[112:115], v[16:19]
	v_mfma_f32_16x16x32_bf16 v[48:51], v[76:79], v[112:115], v[48:51]
	ds_read_b128 v[92:95], v162 offset:55296
	s_add_u32 m0, s38, 16384
	s_nop 0
	global_load_lds_dwordx4 v164, s[100:101]
	s_waitcnt lgkmcnt(8)
	v_mfma_f32_16x16x32_bf16 v[20:23], v[72:75], v[116:119], v[20:23]
	v_mfma_f32_16x16x32_bf16 v[52:55], v[76:79], v[116:119], v[52:55]
	ds_read_b128 v[96:99], v162 offset:57344
	s_add_u32 m0, s38, 20480
	s_nop 0
	global_load_lds_dwordx4 v165, s[100:101]
	s_waitcnt lgkmcnt(8)
	v_mfma_f32_16x16x32_bf16 v[24:27], v[72:75], v[120:123], v[24:27]
	v_mfma_f32_16x16x32_bf16 v[56:59], v[76:79], v[120:123], v[56:59]
	ds_read_b128 v[100:103], v162 offset:59392
	s_add_u32 m0, s38, 24576
	s_nop 0
	global_load_lds_dwordx4 v166, s[100:101]
	s_waitcnt lgkmcnt(8)
	v_mfma_f32_16x16x32_bf16 v[28:31], v[72:75], v[124:127], v[28:31]
	v_mfma_f32_16x16x32_bf16 v[60:63], v[76:79], v[124:127], v[60:63]
	ds_read_b128 v[104:107], v162 offset:61440
	s_add_u32 m0, s38, 28672
	s_nop 0
	global_load_lds_dwordx4 v167, s[100:101]
	s_add_u32 s100, s100, 128
	s_addc_u32 s101, s101, 0
	s_waitcnt lgkmcnt(6)
	v_mfma_f32_16x16x32_bf16 v[0:3], v[64:67], v[80:83], v[0:3]
	v_mfma_f32_16x16x32_bf16 v[32:35], v[68:71], v[80:83], v[32:35]
	ds_read_b128 v[108:111], v162 offset:63488
	s_waitcnt lgkmcnt(6)
	v_mfma_f32_16x16x32_bf16 v[4:7], v[64:67], v[84:87], v[4:7]
	v_mfma_f32_16x16x32_bf16 v[36:39], v[68:71], v[84:87], v[36:39]
	ds_read_b128 v[72:75], v151 offset:32768
	ds_read_b128 v[76:79], v151 offset:34816
	ds_read_b128 v[112:115], v163 offset:49152
	s_waitcnt lgkmcnt(8)
	v_mfma_f32_16x16x32_bf16 v[8:11], v[64:67], v[88:91], v[8:11]
	v_mfma_f32_16x16x32_bf16 v[40:43], v[68:71], v[88:91], v[40:43]
	ds_read_b128 v[116:119], v163 offset:51200
	s_waitcnt lgkmcnt(8)
	v_mfma_f32_16x16x32_bf16 v[12:15], v[64:67], v[92:95], v[12:15]
	v_mfma_f32_16x16x32_bf16 v[44:47], v[68:71], v[92:95], v[44:47]
	ds_read_b128 v[120:123], v163 offset:53248
	s_waitcnt lgkmcnt(8)
	v_mfma_f32_16x16x32_bf16 v[16:19], v[64:67], v[96:99], v[16:19]
	v_mfma_f32_16x16x32_bf16 v[48:51], v[68:71], v[96:99], v[48:51]
	ds_read_b128 v[124:127], v163 offset:55296
	s_waitcnt lgkmcnt(8)
	v_mfma_f32_16x16x32_bf16 v[20:23], v[64:67], v[100:103], v[20:23]
	v_mfma_f32_16x16x32_bf16 v[52:55], v[68:71], v[100:103], v[52:55]
	ds_read_b128 v[80:83], v163 offset:57344
	s_waitcnt lgkmcnt(8)
	v_mfma_f32_16x16x32_bf16 v[24:27], v[64:67], v[104:107], v[24:27]
	v_mfma_f32_16x16x32_bf16 v[56:59], v[68:71], v[104:107], v[56:59]
	ds_read_b128 v[84:87], v163 offset:59392
	s_waitcnt lgkmcnt(8)
	v_mfma_f32_16x16x32_bf16 v[28:31], v[64:67], v[108:111], v[28:31]
	v_mfma_f32_16x16x32_bf16 v[60:63], v[68:71], v[108:111], v[60:63]
	ds_read_b128 v[88:91], v163 offset:61440
	s_waitcnt lgkmcnt(6)
	v_mfma_f32_16x16x32_bf16 v[0:3], v[72:75], v[112:115], v[0:3]
	v_mfma_f32_16x16x32_bf16 v[32:35], v[76:79], v[112:115], v[32:35]
	ds_read_b128 v[92:95], v163 offset:63488
	s_waitcnt vmcnt(0) lgkmcnt(0)
	s_barrier
	s_add_u32 m0, s38, 32768
	s_nop 0
	global_load_lds_dwordx4 v164, s[98:99]
	s_waitcnt lgkmcnt(6)
	v_mfma_f32_16x16x32_bf16 v[4:7], v[72:75], v[116:119], v[4:7]
	v_mfma_f32_16x16x32_bf16 v[36:39], v[76:79], v[116:119], v[36:39]
	ds_read_b128 v[64:67], v150 offset:0
	ds_read_b128 v[68:71], v150 offset:2048
	ds_read_b128 v[96:99], v162 offset:16384
	s_add_u32 m0, s38, 36864
	s_nop 0
	global_load_lds_dwordx4 v165, s[98:99]
	s_waitcnt lgkmcnt(8)
	v_mfma_f32_16x16x32_bf16 v[8:11], v[72:75], v[120:123], v[8:11]
	v_mfma_f32_16x16x32_bf16 v[40:43], v[76:79], v[120:123], v[40:43]
	ds_read_b128 v[100:103], v162 offset:18432
	s_add_u32 m0, s38, 40960
	s_nop 0
	global_load_lds_dwordx4 v166, s[98:99]
	s_waitcnt lgkmcnt(8)
	v_mfma_f32_16x16x32_bf16 v[12:15], v[72:75], v[124:127], v[12:15]
	v_mfma_f32_16x16x32_bf16 v[44:47], v[76:79], v[124:127], v[44:47]
	ds_read_b128 v[104:107], v162 offset:20480
	s_add_u32 m0, s38, 45056
	s_nop 0
	global_load_lds_dwordx4 v167, s[98:99]
	s_add_u32 s98, s98, 128
	s_addc_u32 s99, s99, 0
	s_waitcnt lgkmcnt(8)
	v_mfma_f32_16x16x32_bf16 v[16:19], v[72:75], v[80:83], v[16:19]
	v_mfma_f32_16x16x32_bf16 v[48:51], v[76:79], v[80:83], v[48:51]
	ds_read_b128 v[108:111], v162 offset:22528
	s_add_u32 m0, s38, 49152
	s_nop 0
	global_load_lds_dwordx4 v164, s[100:101]
	s_waitcnt lgkmcnt(8)
	v_mfma_f32_16x16x32_bf16 v[20:23], v[72:75], v[84:87], v[20:23]
	v_mfma_f32_16x16x32_bf16 v[52:55], v[76:79], v[84:87], v[52:55]
	ds_read_b128 v[112:115], v162 offset:24576
	s_add_u32 m0, s38, 53248
	s_nop 0
	global_load_lds_dwordx4 v165, s[100:101]
	s_waitcnt lgkmcnt(8)
	v_mfma_f32_16x16x32_bf16 v[24:27], v[72:75], v[88:91], v[24:27]
	v_mfma_f32_16x16x32_bf16 v[56:59], v[76:79], v[88:91], v[56:59]
	ds_read_b128 v[116:119], v162 offset:26624
	s_add_u32 m0, s38, 57344
	s_nop 0
	global_load_lds_dwordx4 v166, s[100:101]
	s_waitcnt lgkmcnt(8)
	v_mfma_f32_16x16x32_bf16 v[28:31], v[72:75], v[92:95], v[28:31]
	v_mfma_f32_16x16x32_bf16 v[60:63], v[76:79], v[92:95], v[60:63]
	ds_read_b128 v[120:123], v162 offset:28672
	s_add_u32 m0, s38, 61440
	s_nop 0
	global_load_lds_dwordx4 v167, s[100:101]
	s_add_u32 s100, s100, 128
	s_addc_u32 s101, s101, 0
	s_waitcnt lgkmcnt(6)
	v_mfma_f32_16x16x32_bf16 v[0:3], v[64:67], v[96:99], v[0:3]
	v_mfma_f32_16x16x32_bf16 v[32:35], v[68:71], v[96:99], v[32:35]
	ds_read_b128 v[124:127], v162 offset:30720
	s_waitcnt lgkmcnt(6)
	v_mfma_f32_16x16x32_bf16 v[4:7], v[64:67], v[100:103], v[4:7]
	v_mfma_f32_16x16x32_bf16 v[36:39], v[68:71], v[100:103], v[36:39]
	ds_read_b128 v[72:75], v151 offset:0
	ds_read_b128 v[76:79], v151 offset:2048
	ds_read_b128 v[80:83], v163 offset:16384
	s_waitcnt lgkmcnt(8)
	v_mfma_f32_16x16x32_bf16 v[8:11], v[64:67], v[104:107], v[8:11]
	v_mfma_f32_16x16x32_bf16 v[40:43], v[68:71], v[104:107], v[40:43]
	ds_read_b128 v[84:87], v163 offset:18432
	s_waitcnt lgkmcnt(8)
	v_mfma_f32_16x16x32_bf16 v[12:15], v[64:67], v[108:111], v[12:15]
	v_mfma_f32_16x16x32_bf16 v[44:47], v[68:71], v[108:111], v[44:47]
	ds_read_b128 v[88:91], v163 offset:20480
	s_waitcnt lgkmcnt(8)
	v_mfma_f32_16x16x32_bf16 v[16:19], v[64:67], v[112:115], v[16:19]
	v_mfma_f32_16x16x32_bf16 v[48:51], v[68:71], v[112:115], v[48:51]
	ds_read_b128 v[92:95], v163 offset:22528
	s_waitcnt lgkmcnt(8)
	v_mfma_f32_16x16x32_bf16 v[20:23], v[64:67], v[116:119], v[20:23]
	v_mfma_f32_16x16x32_bf16 v[52:55], v[68:71], v[116:119], v[52:55]
	ds_read_b128 v[96:99], v163 offset:24576
	s_waitcnt lgkmcnt(8)
	v_mfma_f32_16x16x32_bf16 v[24:27], v[64:67], v[120:123], v[24:27]
	v_mfma_f32_16x16x32_bf16 v[56:59], v[68:71], v[120:123], v[56:59]
	ds_read_b128 v[100:103], v163 offset:26624
	s_waitcnt lgkmcnt(8)
	v_mfma_f32_16x16x32_bf16 v[28:31], v[64:67], v[124:127], v[28:31]
	v_mfma_f32_16x16x32_bf16 v[60:63], v[68:71], v[124:127], v[60:63]
	ds_read_b128 v[104:107], v163 offset:28672
	s_waitcnt lgkmcnt(6)
	v_mfma_f32_16x16x32_bf16 v[0:3], v[72:75], v[80:83], v[0:3]
	v_mfma_f32_16x16x32_bf16 v[32:35], v[76:79], v[80:83], v[32:35]
	ds_read_b128 v[108:111], v163 offset:30720
	s_waitcnt vmcnt(0) lgkmcnt(0)
	s_barrier
	s_add_u32 m0, s38, 0
	s_nop 0
	global_load_lds_dwordx4 v164, s[98:99]
	s_waitcnt lgkmcnt(6)
	v_mfma_f32_16x16x32_bf16 v[4:7], v[72:75], v[84:87], v[4:7]
	v_mfma_f32_16x16x32_bf16 v[36:39], v[76:79], v[84:87], v[36:39]
	ds_read_b128 v[64:67], v150 offset:32768
	ds_read_b128 v[68:71], v150 offset:34816
	ds_read_b128 v[112:115], v162 offset:49152
	s_add_u32 m0, s38, 4096
	s_nop 0
	global_load_lds_dwordx4 v165, s[98:99]
	s_waitcnt lgkmcnt(8)
	v_mfma_f32_16x16x32_bf16 v[8:11], v[72:75], v[88:91], v[8:11]
	v_mfma_f32_16x16x32_bf16 v[40:43], v[76:79], v[88:91], v[40:43]
	ds_read_b128 v[116:119], v162 offset:51200
	s_add_u32 m0, s38, 8192
	s_nop 0
	global_load_lds_dwordx4 v166, s[98:99]
	s_waitcnt lgkmcnt(8)
	v_mfma_f32_16x16x32_bf16 v[12:15], v[72:75], v[92:95], v[12:15]
	v_mfma_f32_16x16x32_bf16 v[44:47], v[76:79], v[92:95], v[44:47]
	ds_read_b128 v[120:123], v162 offset:53248
	s_add_u32 m0, s38, 12288
	s_nop 0
	global_load_lds_dwordx4 v167, s[98:99]
	s_add_u32 s98, s98, 128
	s_addc_u32 s99, s99, 0
	s_waitcnt lgkmcnt(8)
	v_mfma_f32_16x16x32_bf16 v[16:19], v[72:75], v[96:99], v[16:19]
	v_mfma_f32_16x16x32_bf16 v[48:51], v[76:79], v[96:99], v[48:51]
	ds_read_b128 v[124:127], v162 offset:55296
	s_add_u32 m0, s38, 16384
	s_nop 0
	global_load_lds_dwordx4 v164, s[100:101]
	s_waitcnt lgkmcnt(8)
	v_mfma_f32_16x16x32_bf16 v[20:23], v[72:75], v[100:103], v[20:23]
	v_mfma_f32_16x16x32_bf16 v[52:55], v[76:79], v[100:103], v[52:55]
	ds_read_b128 v[80:83], v162 offset:57344
	s_add_u32 m0, s38, 20480
	s_nop 0
	global_load_lds_dwordx4 v165, s[100:101]
	s_waitcnt lgkmcnt(8)
	v_mfma_f32_16x16x32_bf16 v[24:27], v[72:75], v[104:107], v[24:27]
	v_mfma_f32_16x16x32_bf16 v[56:59], v[76:79], v[104:107], v[56:59]
	ds_read_b128 v[84:87], v162 offset:59392
	s_add_u32 m0, s38, 24576
	s_nop 0
	global_load_lds_dwordx4 v166, s[100:101]
	s_waitcnt lgkmcnt(8)
	v_mfma_f32_16x16x32_bf16 v[28:31], v[72:75], v[108:111], v[28:31]
	v_mfma_f32_16x16x32_bf16 v[60:63], v[76:79], v[108:111], v[60:63]
	ds_read_b128 v[88:91], v162 offset:61440
	s_add_u32 m0, s38, 28672
	s_nop 0
	global_load_lds_dwordx4 v167, s[100:101]
	s_add_u32 s100, s100, 128
	s_addc_u32 s101, s101, 0
	s_waitcnt lgkmcnt(6)
	v_mfma_f32_16x16x32_bf16 v[0:3], v[64:67], v[112:115], v[0:3]
	v_mfma_f32_16x16x32_bf16 v[32:35], v[68:71], v[112:115], v[32:35]
	ds_read_b128 v[92:95], v162 offset:63488
	s_waitcnt lgkmcnt(6)
	v_mfma_f32_16x16x32_bf16 v[4:7], v[64:67], v[116:119], v[4:7]
	v_mfma_f32_16x16x32_bf16 v[36:39], v[68:71], v[116:119], v[36:39]
	ds_read_b128 v[72:75], v151 offset:32768
	ds_read_b128 v[76:79], v151 offset:34816
	ds_read_b128 v[96:99], v163 offset:49152
	s_waitcnt lgkmcnt(8)
	v_mfma_f32_16x16x32_bf16 v[8:11], v[64:67], v[120:123], v[8:11]
	v_mfma_f32_16x16x32_bf16 v[40:43], v[68:71], v[120:123], v[40:43]
	ds_read_b128 v[100:103], v163 offset:51200
	s_waitcnt lgkmcnt(8)
	v_mfma_f32_16x16x32_bf16 v[12:15], v[64:67], v[124:127], v[12:15]
	v_mfma_f32_16x16x32_bf16 v[44:47], v[68:71], v[124:127], v[44:47]
	ds_read_b128 v[104:107], v163 offset:53248
	s_waitcnt lgkmcnt(8)
	v_mfma_f32_16x16x32_bf16 v[16:19], v[64:67], v[80:83], v[16:19]
	v_mfma_f32_16x16x32_bf16 v[48:51], v[68:71], v[80:83], v[48:51]
	ds_read_b128 v[108:111], v163 offset:55296
	s_waitcnt lgkmcnt(8)
	v_mfma_f32_16x16x32_bf16 v[20:23], v[64:67], v[84:87], v[20:23]
	v_mfma_f32_16x16x32_bf16 v[52:55], v[68:71], v[84:87], v[52:55]
	ds_read_b128 v[112:115], v163 offset:57344
	s_waitcnt lgkmcnt(8)
	v_mfma_f32_16x16x32_bf16 v[24:27], v[64:67], v[88:91], v[24:27]
	v_mfma_f32_16x16x32_bf16 v[56:59], v[68:71], v[88:91], v[56:59]
	ds_read_b128 v[116:119], v163 offset:59392
	s_waitcnt lgkmcnt(8)
	v_mfma_f32_16x16x32_bf16 v[28:31], v[64:67], v[92:95], v[28:31]
	v_mfma_f32_16x16x32_bf16 v[60:63], v[68:71], v[92:95], v[60:63]
	ds_read_b128 v[120:123], v163 offset:61440
	s_waitcnt lgkmcnt(6)
	v_mfma_f32_16x16x32_bf16 v[0:3], v[72:75], v[96:99], v[0:3]
	v_mfma_f32_16x16x32_bf16 v[32:35], v[76:79], v[96:99], v[32:35]
	ds_read_b128 v[124:127], v163 offset:63488
	s_waitcnt vmcnt(0) lgkmcnt(0)
	s_barrier
	s_add_u32 m0, s38, 32768
	s_nop 0
	global_load_lds_dwordx4 v164, s[98:99]
	s_waitcnt lgkmcnt(6)
	v_mfma_f32_16x16x32_bf16 v[4:7], v[72:75], v[100:103], v[4:7]
	v_mfma_f32_16x16x32_bf16 v[36:39], v[76:79], v[100:103], v[36:39]
	ds_read_b128 v[64:67], v150 offset:0
	ds_read_b128 v[68:71], v150 offset:2048
	ds_read_b128 v[80:83], v162 offset:16384
	s_add_u32 m0, s38, 36864
	s_nop 0
	global_load_lds_dwordx4 v165, s[98:99]
	s_waitcnt lgkmcnt(8)
	v_mfma_f32_16x16x32_bf16 v[8:11], v[72:75], v[104:107], v[8:11]
	v_mfma_f32_16x16x32_bf16 v[40:43], v[76:79], v[104:107], v[40:43]
	ds_read_b128 v[84:87], v162 offset:18432
	s_add_u32 m0, s38, 40960
	s_nop 0
	global_load_lds_dwordx4 v166, s[98:99]
	s_waitcnt lgkmcnt(8)
	v_mfma_f32_16x16x32_bf16 v[12:15], v[72:75], v[108:111], v[12:15]
	v_mfma_f32_16x16x32_bf16 v[44:47], v[76:79], v[108:111], v[44:47]
	ds_read_b128 v[88:91], v162 offset:20480
	s_add_u32 m0, s38, 45056
	s_nop 0
	global_load_lds_dwordx4 v167, s[98:99]
	s_add_u32 s98, s98, 128
	s_addc_u32 s99, s99, 0
	s_waitcnt lgkmcnt(8)
	v_mfma_f32_16x16x32_bf16 v[16:19], v[72:75], v[112:115], v[16:19]
	v_mfma_f32_16x16x32_bf16 v[48:51], v[76:79], v[112:115], v[48:51]
	ds_read_b128 v[92:95], v162 offset:22528
	s_add_u32 m0, s38, 49152
	s_nop 0
	global_load_lds_dwordx4 v164, s[100:101]
	s_waitcnt lgkmcnt(8)
	v_mfma_f32_16x16x32_bf16 v[20:23], v[72:75], v[116:119], v[20:23]
	v_mfma_f32_16x16x32_bf16 v[52:55], v[76:79], v[116:119], v[52:55]
	ds_read_b128 v[96:99], v162 offset:24576
	s_add_u32 m0, s38, 53248
	s_nop 0
	global_load_lds_dwordx4 v165, s[100:101]
	s_waitcnt lgkmcnt(8)
	v_mfma_f32_16x16x32_bf16 v[24:27], v[72:75], v[120:123], v[24:27]
	v_mfma_f32_16x16x32_bf16 v[56:59], v[76:79], v[120:123], v[56:59]
	ds_read_b128 v[100:103], v162 offset:26624
	s_add_u32 m0, s38, 57344
	s_nop 0
	global_load_lds_dwordx4 v166, s[100:101]
	s_waitcnt lgkmcnt(8)
	v_mfma_f32_16x16x32_bf16 v[28:31], v[72:75], v[124:127], v[28:31]
	v_mfma_f32_16x16x32_bf16 v[60:63], v[76:79], v[124:127], v[60:63]
	ds_read_b128 v[104:107], v162 offset:28672
	s_add_u32 m0, s38, 61440
	s_nop 0
	global_load_lds_dwordx4 v167, s[100:101]
	s_add_u32 s100, s100, 128
	s_addc_u32 s101, s101, 0
	s_waitcnt lgkmcnt(6)
	v_mfma_f32_16x16x32_bf16 v[0:3], v[64:67], v[80:83], v[0:3]
	v_mfma_f32_16x16x32_bf16 v[32:35], v[68:71], v[80:83], v[32:35]
	ds_read_b128 v[108:111], v162 offset:30720
	s_waitcnt lgkmcnt(6)
	v_mfma_f32_16x16x32_bf16 v[4:7], v[64:67], v[84:87], v[4:7]
	v_mfma_f32_16x16x32_bf16 v[36:39], v[68:71], v[84:87], v[36:39]
	ds_read_b128 v[72:75], v151 offset:0
	ds_read_b128 v[76:79], v151 offset:2048
	ds_read_b128 v[112:115], v163 offset:16384
	s_waitcnt lgkmcnt(8)
	v_mfma_f32_16x16x32_bf16 v[8:11], v[64:67], v[88:91], v[8:11]
	v_mfma_f32_16x16x32_bf16 v[40:43], v[68:71], v[88:91], v[40:43]
	ds_read_b128 v[116:119], v163 offset:18432
	s_waitcnt lgkmcnt(8)
	v_mfma_f32_16x16x32_bf16 v[12:15], v[64:67], v[92:95], v[12:15]
	v_mfma_f32_16x16x32_bf16 v[44:47], v[68:71], v[92:95], v[44:47]
	ds_read_b128 v[120:123], v163 offset:20480
	s_waitcnt lgkmcnt(8)
	v_mfma_f32_16x16x32_bf16 v[16:19], v[64:67], v[96:99], v[16:19]
	v_mfma_f32_16x16x32_bf16 v[48:51], v[68:71], v[96:99], v[48:51]
	ds_read_b128 v[124:127], v163 offset:22528
	s_waitcnt lgkmcnt(8)
	v_mfma_f32_16x16x32_bf16 v[20:23], v[64:67], v[100:103], v[20:23]
	v_mfma_f32_16x16x32_bf16 v[52:55], v[68:71], v[100:103], v[52:55]
	ds_read_b128 v[80:83], v163 offset:24576
	s_waitcnt lgkmcnt(8)
	v_mfma_f32_16x16x32_bf16 v[24:27], v[64:67], v[104:107], v[24:27]
	v_mfma_f32_16x16x32_bf16 v[56:59], v[68:71], v[104:107], v[56:59]
	ds_read_b128 v[84:87], v163 offset:26624
	s_waitcnt lgkmcnt(8)
	v_mfma_f32_16x16x32_bf16 v[28:31], v[64:67], v[108:111], v[28:31]
	v_mfma_f32_16x16x32_bf16 v[60:63], v[68:71], v[108:111], v[60:63]
	ds_read_b128 v[88:91], v163 offset:28672
	s_waitcnt lgkmcnt(6)
	v_mfma_f32_16x16x32_bf16 v[0:3], v[72:75], v[112:115], v[0:3]
	v_mfma_f32_16x16x32_bf16 v[32:35], v[76:79], v[112:115], v[32:35]
	ds_read_b128 v[92:95], v163 offset:30720
	s_waitcnt vmcnt(0) lgkmcnt(0)
	s_barrier
	s_add_u32 m0, s38, 0
	s_nop 0
	global_load_lds_dwordx4 v164, s[98:99]
	s_waitcnt lgkmcnt(6)
	v_mfma_f32_16x16x32_bf16 v[4:7], v[72:75], v[116:119], v[4:7]
	v_mfma_f32_16x16x32_bf16 v[36:39], v[76:79], v[116:119], v[36:39]
	ds_read_b128 v[64:67], v150 offset:32768
	ds_read_b128 v[68:71], v150 offset:34816
	ds_read_b128 v[96:99], v162 offset:49152
	s_add_u32 m0, s38, 4096
	s_nop 0
	global_load_lds_dwordx4 v165, s[98:99]
	s_waitcnt lgkmcnt(8)
	v_mfma_f32_16x16x32_bf16 v[8:11], v[72:75], v[120:123], v[8:11]
	v_mfma_f32_16x16x32_bf16 v[40:43], v[76:79], v[120:123], v[40:43]
	ds_read_b128 v[100:103], v162 offset:51200
	s_add_u32 m0, s38, 8192
	s_nop 0
	global_load_lds_dwordx4 v166, s[98:99]
	s_waitcnt lgkmcnt(8)
	v_mfma_f32_16x16x32_bf16 v[12:15], v[72:75], v[124:127], v[12:15]
	v_mfma_f32_16x16x32_bf16 v[44:47], v[76:79], v[124:127], v[44:47]
	ds_read_b128 v[104:107], v162 offset:53248
	s_add_u32 m0, s38, 12288
	s_nop 0
	global_load_lds_dwordx4 v167, s[98:99]
	s_add_u32 s98, s98, 128
	s_addc_u32 s99, s99, 0
	s_waitcnt lgkmcnt(8)
	v_mfma_f32_16x16x32_bf16 v[16:19], v[72:75], v[80:83], v[16:19]
	v_mfma_f32_16x16x32_bf16 v[48:51], v[76:79], v[80:83], v[48:51]
	ds_read_b128 v[108:111], v162 offset:55296
	s_add_u32 m0, s38, 16384
	s_nop 0
	global_load_lds_dwordx4 v164, s[100:101]
	s_waitcnt lgkmcnt(8)
	v_mfma_f32_16x16x32_bf16 v[20:23], v[72:75], v[84:87], v[20:23]
	v_mfma_f32_16x16x32_bf16 v[52:55], v[76:79], v[84:87], v[52:55]
	ds_read_b128 v[112:115], v162 offset:57344
	s_add_u32 m0, s38, 20480
	s_nop 0
	global_load_lds_dwordx4 v165, s[100:101]
	s_waitcnt lgkmcnt(8)
	v_mfma_f32_16x16x32_bf16 v[24:27], v[72:75], v[88:91], v[24:27]
	v_mfma_f32_16x16x32_bf16 v[56:59], v[76:79], v[88:91], v[56:59]
	ds_read_b128 v[116:119], v162 offset:59392
	s_add_u32 m0, s38, 24576
	s_nop 0
	global_load_lds_dwordx4 v166, s[100:101]
	s_waitcnt lgkmcnt(8)
	v_mfma_f32_16x16x32_bf16 v[28:31], v[72:75], v[92:95], v[28:31]
	v_mfma_f32_16x16x32_bf16 v[60:63], v[76:79], v[92:95], v[60:63]
	ds_read_b128 v[120:123], v162 offset:61440
	s_add_u32 m0, s38, 28672
	s_nop 0
	global_load_lds_dwordx4 v167, s[100:101]
	s_add_u32 s100, s100, 128
	s_addc_u32 s101, s101, 0
	s_waitcnt lgkmcnt(6)
	v_mfma_f32_16x16x32_bf16 v[0:3], v[64:67], v[96:99], v[0:3]
	v_mfma_f32_16x16x32_bf16 v[32:35], v[68:71], v[96:99], v[32:35]
	ds_read_b128 v[124:127], v162 offset:63488
	s_waitcnt lgkmcnt(6)
	v_mfma_f32_16x16x32_bf16 v[4:7], v[64:67], v[100:103], v[4:7]
	v_mfma_f32_16x16x32_bf16 v[36:39], v[68:71], v[100:103], v[36:39]
	ds_read_b128 v[72:75], v151 offset:32768
	ds_read_b128 v[76:79], v151 offset:34816
	ds_read_b128 v[80:83], v163 offset:49152
	s_waitcnt lgkmcnt(8)
	v_mfma_f32_16x16x32_bf16 v[8:11], v[64:67], v[104:107], v[8:11]
	v_mfma_f32_16x16x32_bf16 v[40:43], v[68:71], v[104:107], v[40:43]
	ds_read_b128 v[84:87], v163 offset:51200
	s_waitcnt lgkmcnt(8)
	v_mfma_f32_16x16x32_bf16 v[12:15], v[64:67], v[108:111], v[12:15]
	v_mfma_f32_16x16x32_bf16 v[44:47], v[68:71], v[108:111], v[44:47]
	ds_read_b128 v[88:91], v163 offset:53248
	s_waitcnt lgkmcnt(8)
	v_mfma_f32_16x16x32_bf16 v[16:19], v[64:67], v[112:115], v[16:19]
	v_mfma_f32_16x16x32_bf16 v[48:51], v[68:71], v[112:115], v[48:51]
	ds_read_b128 v[92:95], v163 offset:55296
	s_waitcnt lgkmcnt(8)
	v_mfma_f32_16x16x32_bf16 v[20:23], v[64:67], v[116:119], v[20:23]
	v_mfma_f32_16x16x32_bf16 v[52:55], v[68:71], v[116:119], v[52:55]
	ds_read_b128 v[96:99], v163 offset:57344
	s_waitcnt lgkmcnt(8)
	v_mfma_f32_16x16x32_bf16 v[24:27], v[64:67], v[120:123], v[24:27]
	v_mfma_f32_16x16x32_bf16 v[56:59], v[68:71], v[120:123], v[56:59]
	ds_read_b128 v[100:103], v163 offset:59392
	s_waitcnt lgkmcnt(8)
	v_mfma_f32_16x16x32_bf16 v[28:31], v[64:67], v[124:127], v[28:31]
	v_mfma_f32_16x16x32_bf16 v[60:63], v[68:71], v[124:127], v[60:63]
	ds_read_b128 v[104:107], v163 offset:61440
	s_waitcnt lgkmcnt(6)
	v_mfma_f32_16x16x32_bf16 v[0:3], v[72:75], v[80:83], v[0:3]
	v_mfma_f32_16x16x32_bf16 v[32:35], v[76:79], v[80:83], v[32:35]
	ds_read_b128 v[108:111], v163 offset:63488
	s_waitcnt vmcnt(0) lgkmcnt(0)
	s_barrier
	s_add_u32 m0, s38, 32768
	s_nop 0
	global_load_lds_dwordx4 v164, s[98:99]
	s_waitcnt lgkmcnt(6)
	v_mfma_f32_16x16x32_bf16 v[4:7], v[72:75], v[84:87], v[4:7]
	v_mfma_f32_16x16x32_bf16 v[36:39], v[76:79], v[84:87], v[36:39]
	ds_read_b128 v[64:67], v150 offset:0
	ds_read_b128 v[68:71], v150 offset:2048
	ds_read_b128 v[112:115], v162 offset:16384
	s_add_u32 m0, s38, 36864
	s_nop 0
	global_load_lds_dwordx4 v165, s[98:99]
	s_waitcnt lgkmcnt(8)
	v_mfma_f32_16x16x32_bf16 v[8:11], v[72:75], v[88:91], v[8:11]
	v_mfma_f32_16x16x32_bf16 v[40:43], v[76:79], v[88:91], v[40:43]
	ds_read_b128 v[116:119], v162 offset:18432
	s_add_u32 m0, s38, 40960
	s_nop 0
	global_load_lds_dwordx4 v166, s[98:99]
	s_waitcnt lgkmcnt(8)
	v_mfma_f32_16x16x32_bf16 v[12:15], v[72:75], v[92:95], v[12:15]
	v_mfma_f32_16x16x32_bf16 v[44:47], v[76:79], v[92:95], v[44:47]
	ds_read_b128 v[120:123], v162 offset:20480
	s_add_u32 m0, s38, 45056
	s_nop 0
	global_load_lds_dwordx4 v167, s[98:99]
	s_add_u32 s98, s98, 128
	s_addc_u32 s99, s99, 0
	s_waitcnt lgkmcnt(8)
	v_mfma_f32_16x16x32_bf16 v[16:19], v[72:75], v[96:99], v[16:19]
	v_mfma_f32_16x16x32_bf16 v[48:51], v[76:79], v[96:99], v[48:51]
	ds_read_b128 v[124:127], v162 offset:22528
	s_add_u32 m0, s38, 49152
	s_nop 0
	global_load_lds_dwordx4 v164, s[100:101]
	s_waitcnt lgkmcnt(8)
	v_mfma_f32_16x16x32_bf16 v[20:23], v[72:75], v[100:103], v[20:23]
	v_mfma_f32_16x16x32_bf16 v[52:55], v[76:79], v[100:103], v[52:55]
	ds_read_b128 v[80:83], v162 offset:24576
	s_add_u32 m0, s38, 53248
	s_nop 0
	global_load_lds_dwordx4 v165, s[100:101]
	s_waitcnt lgkmcnt(8)
	v_mfma_f32_16x16x32_bf16 v[24:27], v[72:75], v[104:107], v[24:27]
	v_mfma_f32_16x16x32_bf16 v[56:59], v[76:79], v[104:107], v[56:59]
	ds_read_b128 v[84:87], v162 offset:26624
	s_add_u32 m0, s38, 57344
	s_nop 0
	global_load_lds_dwordx4 v166, s[100:101]
	s_waitcnt lgkmcnt(8)
	v_mfma_f32_16x16x32_bf16 v[28:31], v[72:75], v[108:111], v[28:31]
	v_mfma_f32_16x16x32_bf16 v[60:63], v[76:79], v[108:111], v[60:63]
	ds_read_b128 v[88:91], v162 offset:28672
	s_add_u32 m0, s38, 61440
	s_nop 0
	global_load_lds_dwordx4 v167, s[100:101]
	s_add_u32 s100, s100, 128
	s_addc_u32 s101, s101, 0
	s_waitcnt lgkmcnt(6)
	v_mfma_f32_16x16x32_bf16 v[0:3], v[64:67], v[112:115], v[0:3]
	v_mfma_f32_16x16x32_bf16 v[32:35], v[68:71], v[112:115], v[32:35]
	ds_read_b128 v[92:95], v162 offset:30720
	s_waitcnt lgkmcnt(6)
	v_mfma_f32_16x16x32_bf16 v[4:7], v[64:67], v[116:119], v[4:7]
	v_mfma_f32_16x16x32_bf16 v[36:39], v[68:71], v[116:119], v[36:39]
	ds_read_b128 v[72:75], v151 offset:0
	ds_read_b128 v[76:79], v151 offset:2048
	ds_read_b128 v[96:99], v163 offset:16384
	s_waitcnt lgkmcnt(8)
	v_mfma_f32_16x16x32_bf16 v[8:11], v[64:67], v[120:123], v[8:11]
	v_mfma_f32_16x16x32_bf16 v[40:43], v[68:71], v[120:123], v[40:43]
	ds_read_b128 v[100:103], v163 offset:18432
	s_waitcnt lgkmcnt(8)
	v_mfma_f32_16x16x32_bf16 v[12:15], v[64:67], v[124:127], v[12:15]
	v_mfma_f32_16x16x32_bf16 v[44:47], v[68:71], v[124:127], v[44:47]
	ds_read_b128 v[104:107], v163 offset:20480
	s_waitcnt lgkmcnt(8)
	v_mfma_f32_16x16x32_bf16 v[16:19], v[64:67], v[80:83], v[16:19]
	v_mfma_f32_16x16x32_bf16 v[48:51], v[68:71], v[80:83], v[48:51]
	ds_read_b128 v[108:111], v163 offset:22528
	s_waitcnt lgkmcnt(8)
	v_mfma_f32_16x16x32_bf16 v[20:23], v[64:67], v[84:87], v[20:23]
	v_mfma_f32_16x16x32_bf16 v[52:55], v[68:71], v[84:87], v[52:55]
	ds_read_b128 v[112:115], v163 offset:24576
	s_waitcnt lgkmcnt(8)
	v_mfma_f32_16x16x32_bf16 v[24:27], v[64:67], v[88:91], v[24:27]
	v_mfma_f32_16x16x32_bf16 v[56:59], v[68:71], v[88:91], v[56:59]
	ds_read_b128 v[116:119], v163 offset:26624
	s_waitcnt lgkmcnt(8)
	v_mfma_f32_16x16x32_bf16 v[28:31], v[64:67], v[92:95], v[28:31]
	v_mfma_f32_16x16x32_bf16 v[60:63], v[68:71], v[92:95], v[60:63]
	ds_read_b128 v[120:123], v163 offset:28672
	s_waitcnt lgkmcnt(6)
	v_mfma_f32_16x16x32_bf16 v[0:3], v[72:75], v[96:99], v[0:3]
	v_mfma_f32_16x16x32_bf16 v[32:35], v[76:79], v[96:99], v[32:35]
	ds_read_b128 v[124:127], v163 offset:30720
	s_waitcnt vmcnt(0) lgkmcnt(0)
	s_barrier
	s_add_u32 m0, s38, 0
	s_nop 0
	global_load_lds_dwordx4 v164, s[98:99]
	s_waitcnt lgkmcnt(6)
	v_mfma_f32_16x16x32_bf16 v[4:7], v[72:75], v[100:103], v[4:7]
	v_mfma_f32_16x16x32_bf16 v[36:39], v[76:79], v[100:103], v[36:39]
	ds_read_b128 v[64:67], v150 offset:32768
	ds_read_b128 v[68:71], v150 offset:34816
	ds_read_b128 v[80:83], v162 offset:49152
	s_add_u32 m0, s38, 4096
	s_nop 0
	global_load_lds_dwordx4 v165, s[98:99]
	s_waitcnt lgkmcnt(8)
	v_mfma_f32_16x16x32_bf16 v[8:11], v[72:75], v[104:107], v[8:11]
	v_mfma_f32_16x16x32_bf16 v[40:43], v[76:79], v[104:107], v[40:43]
	ds_read_b128 v[84:87], v162 offset:51200
	s_add_u32 m0, s38, 8192
	s_nop 0
	global_load_lds_dwordx4 v166, s[98:99]
	s_waitcnt lgkmcnt(8)
	v_mfma_f32_16x16x32_bf16 v[12:15], v[72:75], v[108:111], v[12:15]
	v_mfma_f32_16x16x32_bf16 v[44:47], v[76:79], v[108:111], v[44:47]
	ds_read_b128 v[88:91], v162 offset:53248
	s_add_u32 m0, s38, 12288
	s_nop 0
	global_load_lds_dwordx4 v167, s[98:99]
	s_add_u32 s98, s98, 128
	s_addc_u32 s99, s99, 0
	s_waitcnt lgkmcnt(8)
	v_mfma_f32_16x16x32_bf16 v[16:19], v[72:75], v[112:115], v[16:19]
	v_mfma_f32_16x16x32_bf16 v[48:51], v[76:79], v[112:115], v[48:51]
	ds_read_b128 v[92:95], v162 offset:55296
	s_add_u32 m0, s38, 16384
	s_nop 0
	global_load_lds_dwordx4 v164, s[100:101]
	s_waitcnt lgkmcnt(8)
	v_mfma_f32_16x16x32_bf16 v[20:23], v[72:75], v[116:119], v[20:23]
	v_mfma_f32_16x16x32_bf16 v[52:55], v[76:79], v[116:119], v[52:55]
	ds_read_b128 v[96:99], v162 offset:57344
	s_add_u32 m0, s38, 20480
	s_nop 0
	global_load_lds_dwordx4 v165, s[100:101]
	s_waitcnt lgkmcnt(8)
	v_mfma_f32_16x16x32_bf16 v[24:27], v[72:75], v[120:123], v[24:27]
	v_mfma_f32_16x16x32_bf16 v[56:59], v[76:79], v[120:123], v[56:59]
	ds_read_b128 v[100:103], v162 offset:59392
	s_add_u32 m0, s38, 24576
	s_nop 0
	global_load_lds_dwordx4 v166, s[100:101]
	s_waitcnt lgkmcnt(8)
	v_mfma_f32_16x16x32_bf16 v[28:31], v[72:75], v[124:127], v[28:31]
	v_mfma_f32_16x16x32_bf16 v[60:63], v[76:79], v[124:127], v[60:63]
	ds_read_b128 v[104:107], v162 offset:61440
	s_add_u32 m0, s38, 28672
	s_nop 0
	global_load_lds_dwordx4 v167, s[100:101]
	s_add_u32 s100, s100, 128
	s_addc_u32 s101, s101, 0
	s_waitcnt lgkmcnt(6)
	v_mfma_f32_16x16x32_bf16 v[0:3], v[64:67], v[80:83], v[0:3]
	v_mfma_f32_16x16x32_bf16 v[32:35], v[68:71], v[80:83], v[32:35]
	ds_read_b128 v[108:111], v162 offset:63488
	s_waitcnt lgkmcnt(6)
	v_mfma_f32_16x16x32_bf16 v[4:7], v[64:67], v[84:87], v[4:7]
	v_mfma_f32_16x16x32_bf16 v[36:39], v[68:71], v[84:87], v[36:39]
	ds_read_b128 v[72:75], v151 offset:32768
	ds_read_b128 v[76:79], v151 offset:34816
	ds_read_b128 v[112:115], v163 offset:49152
	s_waitcnt lgkmcnt(8)
	v_mfma_f32_16x16x32_bf16 v[8:11], v[64:67], v[88:91], v[8:11]
	v_mfma_f32_16x16x32_bf16 v[40:43], v[68:71], v[88:91], v[40:43]
	ds_read_b128 v[116:119], v163 offset:51200
	s_waitcnt lgkmcnt(8)
	v_mfma_f32_16x16x32_bf16 v[12:15], v[64:67], v[92:95], v[12:15]
	v_mfma_f32_16x16x32_bf16 v[44:47], v[68:71], v[92:95], v[44:47]
	ds_read_b128 v[120:123], v163 offset:53248
	s_waitcnt lgkmcnt(8)
	v_mfma_f32_16x16x32_bf16 v[16:19], v[64:67], v[96:99], v[16:19]
	v_mfma_f32_16x16x32_bf16 v[48:51], v[68:71], v[96:99], v[48:51]
	ds_read_b128 v[124:127], v163 offset:55296
	s_waitcnt lgkmcnt(8)
	v_mfma_f32_16x16x32_bf16 v[20:23], v[64:67], v[100:103], v[20:23]
	v_mfma_f32_16x16x32_bf16 v[52:55], v[68:71], v[100:103], v[52:55]
	ds_read_b128 v[80:83], v163 offset:57344
	s_waitcnt lgkmcnt(8)
	v_mfma_f32_16x16x32_bf16 v[24:27], v[64:67], v[104:107], v[24:27]
	v_mfma_f32_16x16x32_bf16 v[56:59], v[68:71], v[104:107], v[56:59]
	ds_read_b128 v[84:87], v163 offset:59392
	s_waitcnt lgkmcnt(8)
	v_mfma_f32_16x16x32_bf16 v[28:31], v[64:67], v[108:111], v[28:31]
	v_mfma_f32_16x16x32_bf16 v[60:63], v[68:71], v[108:111], v[60:63]
	ds_read_b128 v[88:91], v163 offset:61440
	s_waitcnt lgkmcnt(6)
	v_mfma_f32_16x16x32_bf16 v[0:3], v[72:75], v[112:115], v[0:3]
	v_mfma_f32_16x16x32_bf16 v[32:35], v[76:79], v[112:115], v[32:35]
	ds_read_b128 v[92:95], v163 offset:63488
	s_waitcnt vmcnt(0) lgkmcnt(0)
	s_barrier
	s_add_u32 m0, s38, 32768
	s_nop 0
	global_load_lds_dwordx4 v164, s[98:99]
	s_waitcnt lgkmcnt(6)
	v_mfma_f32_16x16x32_bf16 v[4:7], v[72:75], v[116:119], v[4:7]
	v_mfma_f32_16x16x32_bf16 v[36:39], v[76:79], v[116:119], v[36:39]
	ds_read_b128 v[64:67], v150 offset:0
	ds_read_b128 v[68:71], v150 offset:2048
	ds_read_b128 v[96:99], v162 offset:16384
	s_add_u32 m0, s38, 36864
	s_nop 0
	global_load_lds_dwordx4 v165, s[98:99]
	s_waitcnt lgkmcnt(8)
	v_mfma_f32_16x16x32_bf16 v[8:11], v[72:75], v[120:123], v[8:11]
	v_mfma_f32_16x16x32_bf16 v[40:43], v[76:79], v[120:123], v[40:43]
	ds_read_b128 v[100:103], v162 offset:18432
	s_add_u32 m0, s38, 40960
	s_nop 0
	global_load_lds_dwordx4 v166, s[98:99]
	s_waitcnt lgkmcnt(8)
	v_mfma_f32_16x16x32_bf16 v[12:15], v[72:75], v[124:127], v[12:15]
	v_mfma_f32_16x16x32_bf16 v[44:47], v[76:79], v[124:127], v[44:47]
	ds_read_b128 v[104:107], v162 offset:20480
	s_add_u32 m0, s38, 45056
	s_nop 0
	global_load_lds_dwordx4 v167, s[98:99]
	s_add_u32 s98, s98, 128
	s_addc_u32 s99, s99, 0
	s_waitcnt lgkmcnt(8)
	v_mfma_f32_16x16x32_bf16 v[16:19], v[72:75], v[80:83], v[16:19]
	v_mfma_f32_16x16x32_bf16 v[48:51], v[76:79], v[80:83], v[48:51]
	ds_read_b128 v[108:111], v162 offset:22528
	s_add_u32 m0, s38, 49152
	s_nop 0
	global_load_lds_dwordx4 v164, s[100:101]
	s_waitcnt lgkmcnt(8)
	v_mfma_f32_16x16x32_bf16 v[20:23], v[72:75], v[84:87], v[20:23]
	v_mfma_f32_16x16x32_bf16 v[52:55], v[76:79], v[84:87], v[52:55]
	ds_read_b128 v[112:115], v162 offset:24576
	s_add_u32 m0, s38, 53248
	s_nop 0
	global_load_lds_dwordx4 v165, s[100:101]
	s_waitcnt lgkmcnt(8)
	v_mfma_f32_16x16x32_bf16 v[24:27], v[72:75], v[88:91], v[24:27]
	v_mfma_f32_16x16x32_bf16 v[56:59], v[76:79], v[88:91], v[56:59]
	ds_read_b128 v[116:119], v162 offset:26624
	s_add_u32 m0, s38, 57344
	s_nop 0
	global_load_lds_dwordx4 v166, s[100:101]
	s_waitcnt lgkmcnt(8)
	v_mfma_f32_16x16x32_bf16 v[28:31], v[72:75], v[92:95], v[28:31]
	v_mfma_f32_16x16x32_bf16 v[60:63], v[76:79], v[92:95], v[60:63]
	ds_read_b128 v[120:123], v162 offset:28672
	s_add_u32 m0, s38, 61440
	s_nop 0
	global_load_lds_dwordx4 v167, s[100:101]
	s_add_u32 s100, s100, 128
	s_addc_u32 s101, s101, 0
	s_waitcnt lgkmcnt(6)
	v_mfma_f32_16x16x32_bf16 v[0:3], v[64:67], v[96:99], v[0:3]
	v_mfma_f32_16x16x32_bf16 v[32:35], v[68:71], v[96:99], v[32:35]
	ds_read_b128 v[124:127], v162 offset:30720
	s_waitcnt lgkmcnt(6)
	v_mfma_f32_16x16x32_bf16 v[4:7], v[64:67], v[100:103], v[4:7]
	v_mfma_f32_16x16x32_bf16 v[36:39], v[68:71], v[100:103], v[36:39]
	ds_read_b128 v[72:75], v151 offset:0
	ds_read_b128 v[76:79], v151 offset:2048
	ds_read_b128 v[80:83], v163 offset:16384
	s_waitcnt lgkmcnt(8)
	v_mfma_f32_16x16x32_bf16 v[8:11], v[64:67], v[104:107], v[8:11]
	v_mfma_f32_16x16x32_bf16 v[40:43], v[68:71], v[104:107], v[40:43]
	ds_read_b128 v[84:87], v163 offset:18432
	s_waitcnt lgkmcnt(8)
	v_mfma_f32_16x16x32_bf16 v[12:15], v[64:67], v[108:111], v[12:15]
	v_mfma_f32_16x16x32_bf16 v[44:47], v[68:71], v[108:111], v[44:47]
	ds_read_b128 v[88:91], v163 offset:20480
	s_waitcnt lgkmcnt(8)
	v_mfma_f32_16x16x32_bf16 v[16:19], v[64:67], v[112:115], v[16:19]
	v_mfma_f32_16x16x32_bf16 v[48:51], v[68:71], v[112:115], v[48:51]
	ds_read_b128 v[92:95], v163 offset:22528
	s_waitcnt lgkmcnt(8)
	v_mfma_f32_16x16x32_bf16 v[20:23], v[64:67], v[116:119], v[20:23]
	v_mfma_f32_16x16x32_bf16 v[52:55], v[68:71], v[116:119], v[52:55]
	ds_read_b128 v[96:99], v163 offset:24576
	s_waitcnt lgkmcnt(8)
	v_mfma_f32_16x16x32_bf16 v[24:27], v[64:67], v[120:123], v[24:27]
	v_mfma_f32_16x16x32_bf16 v[56:59], v[68:71], v[120:123], v[56:59]
	ds_read_b128 v[100:103], v163 offset:26624
	s_waitcnt lgkmcnt(8)
	v_mfma_f32_16x16x32_bf16 v[28:31], v[64:67], v[124:127], v[28:31]
	v_mfma_f32_16x16x32_bf16 v[60:63], v[68:71], v[124:127], v[60:63]
	ds_read_b128 v[104:107], v163 offset:28672
	s_waitcnt lgkmcnt(6)
	v_mfma_f32_16x16x32_bf16 v[0:3], v[72:75], v[80:83], v[0:3]
	v_mfma_f32_16x16x32_bf16 v[32:35], v[76:79], v[80:83], v[32:35]
	ds_read_b128 v[108:111], v163 offset:30720
	s_waitcnt vmcnt(0) lgkmcnt(0)
	s_barrier
	s_add_u32 m0, s38, 0
	s_nop 0
	global_load_lds_dwordx4 v164, s[98:99]
	s_waitcnt lgkmcnt(6)
	v_mfma_f32_16x16x32_bf16 v[4:7], v[72:75], v[84:87], v[4:7]
	v_mfma_f32_16x16x32_bf16 v[36:39], v[76:79], v[84:87], v[36:39]
	ds_read_b128 v[64:67], v150 offset:32768
	ds_read_b128 v[68:71], v150 offset:34816
	ds_read_b128 v[112:115], v162 offset:49152
	s_add_u32 m0, s38, 4096
	s_nop 0
	global_load_lds_dwordx4 v165, s[98:99]
	s_waitcnt lgkmcnt(8)
	v_mfma_f32_16x16x32_bf16 v[8:11], v[72:75], v[88:91], v[8:11]
	v_mfma_f32_16x16x32_bf16 v[40:43], v[76:79], v[88:91], v[40:43]
	ds_read_b128 v[116:119], v162 offset:51200
	s_add_u32 m0, s38, 8192
	s_nop 0
	global_load_lds_dwordx4 v166, s[98:99]
	s_waitcnt lgkmcnt(8)
	v_mfma_f32_16x16x32_bf16 v[12:15], v[72:75], v[92:95], v[12:15]
	v_mfma_f32_16x16x32_bf16 v[44:47], v[76:79], v[92:95], v[44:47]
	ds_read_b128 v[120:123], v162 offset:53248
	s_add_u32 m0, s38, 12288
	s_nop 0
	global_load_lds_dwordx4 v167, s[98:99]
	s_add_u32 s98, s98, 128
	s_addc_u32 s99, s99, 0
	s_waitcnt lgkmcnt(8)
	v_mfma_f32_16x16x32_bf16 v[16:19], v[72:75], v[96:99], v[16:19]
	v_mfma_f32_16x16x32_bf16 v[48:51], v[76:79], v[96:99], v[48:51]
	ds_read_b128 v[124:127], v162 offset:55296
	s_add_u32 m0, s38, 16384
	s_nop 0
	global_load_lds_dwordx4 v164, s[100:101]
	s_waitcnt lgkmcnt(8)
	v_mfma_f32_16x16x32_bf16 v[20:23], v[72:75], v[100:103], v[20:23]
	v_mfma_f32_16x16x32_bf16 v[52:55], v[76:79], v[100:103], v[52:55]
	ds_read_b128 v[80:83], v162 offset:57344
	s_add_u32 m0, s38, 20480
	s_nop 0
	global_load_lds_dwordx4 v165, s[100:101]
	s_waitcnt lgkmcnt(8)
	v_mfma_f32_16x16x32_bf16 v[24:27], v[72:75], v[104:107], v[24:27]
	v_mfma_f32_16x16x32_bf16 v[56:59], v[76:79], v[104:107], v[56:59]
	ds_read_b128 v[84:87], v162 offset:59392
	s_add_u32 m0, s38, 24576
	s_nop 0
	global_load_lds_dwordx4 v166, s[100:101]
	s_waitcnt lgkmcnt(8)
	v_mfma_f32_16x16x32_bf16 v[28:31], v[72:75], v[108:111], v[28:31]
	v_mfma_f32_16x16x32_bf16 v[60:63], v[76:79], v[108:111], v[60:63]
	ds_read_b128 v[88:91], v162 offset:61440
	s_add_u32 m0, s38, 28672
	s_nop 0
	global_load_lds_dwordx4 v167, s[100:101]
	s_add_u32 s100, s100, 128
	s_addc_u32 s101, s101, 0
	s_waitcnt lgkmcnt(6)
	v_mfma_f32_16x16x32_bf16 v[0:3], v[64:67], v[112:115], v[0:3]
	v_mfma_f32_16x16x32_bf16 v[32:35], v[68:71], v[112:115], v[32:35]
	ds_read_b128 v[92:95], v162 offset:63488
	s_waitcnt lgkmcnt(6)
	v_mfma_f32_16x16x32_bf16 v[4:7], v[64:67], v[116:119], v[4:7]
	v_mfma_f32_16x16x32_bf16 v[36:39], v[68:71], v[116:119], v[36:39]
	ds_read_b128 v[72:75], v151 offset:32768
	ds_read_b128 v[76:79], v151 offset:34816
	ds_read_b128 v[96:99], v163 offset:49152
	s_waitcnt lgkmcnt(8)
	v_mfma_f32_16x16x32_bf16 v[8:11], v[64:67], v[120:123], v[8:11]
	v_mfma_f32_16x16x32_bf16 v[40:43], v[68:71], v[120:123], v[40:43]
	ds_read_b128 v[100:103], v163 offset:51200
	s_waitcnt lgkmcnt(8)
	v_mfma_f32_16x16x32_bf16 v[12:15], v[64:67], v[124:127], v[12:15]
	v_mfma_f32_16x16x32_bf16 v[44:47], v[68:71], v[124:127], v[44:47]
	ds_read_b128 v[104:107], v163 offset:53248
	s_waitcnt lgkmcnt(8)
	v_mfma_f32_16x16x32_bf16 v[16:19], v[64:67], v[80:83], v[16:19]
	v_mfma_f32_16x16x32_bf16 v[48:51], v[68:71], v[80:83], v[48:51]
	ds_read_b128 v[108:111], v163 offset:55296
	s_waitcnt lgkmcnt(8)
	v_mfma_f32_16x16x32_bf16 v[20:23], v[64:67], v[84:87], v[20:23]
	v_mfma_f32_16x16x32_bf16 v[52:55], v[68:71], v[84:87], v[52:55]
	ds_read_b128 v[112:115], v163 offset:57344
	s_waitcnt lgkmcnt(8)
	v_mfma_f32_16x16x32_bf16 v[24:27], v[64:67], v[88:91], v[24:27]
	v_mfma_f32_16x16x32_bf16 v[56:59], v[68:71], v[88:91], v[56:59]
	ds_read_b128 v[116:119], v163 offset:59392
	s_waitcnt lgkmcnt(8)
	v_mfma_f32_16x16x32_bf16 v[28:31], v[64:67], v[92:95], v[28:31]
	v_mfma_f32_16x16x32_bf16 v[60:63], v[68:71], v[92:95], v[60:63]
	ds_read_b128 v[120:123], v163 offset:61440
	s_waitcnt lgkmcnt(6)
	v_mfma_f32_16x16x32_bf16 v[0:3], v[72:75], v[96:99], v[0:3]
	v_mfma_f32_16x16x32_bf16 v[32:35], v[76:79], v[96:99], v[32:35]
	ds_read_b128 v[124:127], v163 offset:63488
	s_waitcnt vmcnt(0) lgkmcnt(0)
	s_barrier
	s_add_u32 m0, s38, 32768
	s_nop 0
	global_load_lds_dwordx4 v164, s[98:99]
	s_waitcnt lgkmcnt(6)
	v_mfma_f32_16x16x32_bf16 v[4:7], v[72:75], v[100:103], v[4:7]
	v_mfma_f32_16x16x32_bf16 v[36:39], v[76:79], v[100:103], v[36:39]
	ds_read_b128 v[64:67], v150 offset:0
	ds_read_b128 v[68:71], v150 offset:2048
	ds_read_b128 v[80:83], v162 offset:16384
	s_add_u32 m0, s38, 36864
	s_nop 0
	global_load_lds_dwordx4 v165, s[98:99]
	s_waitcnt lgkmcnt(8)
	v_mfma_f32_16x16x32_bf16 v[8:11], v[72:75], v[104:107], v[8:11]
	v_mfma_f32_16x16x32_bf16 v[40:43], v[76:79], v[104:107], v[40:43]
	ds_read_b128 v[84:87], v162 offset:18432
	s_add_u32 m0, s38, 40960
	s_nop 0
	global_load_lds_dwordx4 v166, s[98:99]
	s_waitcnt lgkmcnt(8)
	v_mfma_f32_16x16x32_bf16 v[12:15], v[72:75], v[108:111], v[12:15]
	v_mfma_f32_16x16x32_bf16 v[44:47], v[76:79], v[108:111], v[44:47]
	ds_read_b128 v[88:91], v162 offset:20480
	s_add_u32 m0, s38, 45056
	s_nop 0
	global_load_lds_dwordx4 v167, s[98:99]
	s_add_u32 s98, s98, 128
	s_addc_u32 s99, s99, 0
	s_waitcnt lgkmcnt(8)
	v_mfma_f32_16x16x32_bf16 v[16:19], v[72:75], v[112:115], v[16:19]
	v_mfma_f32_16x16x32_bf16 v[48:51], v[76:79], v[112:115], v[48:51]
	ds_read_b128 v[92:95], v162 offset:22528
	s_add_u32 m0, s38, 49152
	s_nop 0
	global_load_lds_dwordx4 v164, s[100:101]
	s_waitcnt lgkmcnt(8)
	v_mfma_f32_16x16x32_bf16 v[20:23], v[72:75], v[116:119], v[20:23]
	v_mfma_f32_16x16x32_bf16 v[52:55], v[76:79], v[116:119], v[52:55]
	ds_read_b128 v[96:99], v162 offset:24576
	s_add_u32 m0, s38, 53248
	s_nop 0
	global_load_lds_dwordx4 v165, s[100:101]
	s_waitcnt lgkmcnt(8)
	v_mfma_f32_16x16x32_bf16 v[24:27], v[72:75], v[120:123], v[24:27]
	v_mfma_f32_16x16x32_bf16 v[56:59], v[76:79], v[120:123], v[56:59]
	ds_read_b128 v[100:103], v162 offset:26624
	s_add_u32 m0, s38, 57344
	s_nop 0
	global_load_lds_dwordx4 v166, s[100:101]
	s_waitcnt lgkmcnt(8)
	v_mfma_f32_16x16x32_bf16 v[28:31], v[72:75], v[124:127], v[28:31]
	v_mfma_f32_16x16x32_bf16 v[60:63], v[76:79], v[124:127], v[60:63]
	ds_read_b128 v[104:107], v162 offset:28672
	s_add_u32 m0, s38, 61440
	s_nop 0
	global_load_lds_dwordx4 v167, s[100:101]
	s_add_u32 s100, s100, 128
	s_addc_u32 s101, s101, 0
	s_waitcnt lgkmcnt(6)
	v_mfma_f32_16x16x32_bf16 v[0:3], v[64:67], v[80:83], v[0:3]
	v_mfma_f32_16x16x32_bf16 v[32:35], v[68:71], v[80:83], v[32:35]
	ds_read_b128 v[108:111], v162 offset:30720
	s_waitcnt lgkmcnt(6)
	v_mfma_f32_16x16x32_bf16 v[4:7], v[64:67], v[84:87], v[4:7]
	v_mfma_f32_16x16x32_bf16 v[36:39], v[68:71], v[84:87], v[36:39]
	ds_read_b128 v[72:75], v151 offset:0
	ds_read_b128 v[76:79], v151 offset:2048
	ds_read_b128 v[112:115], v163 offset:16384
	s_waitcnt lgkmcnt(8)
	v_mfma_f32_16x16x32_bf16 v[8:11], v[64:67], v[88:91], v[8:11]
	v_mfma_f32_16x16x32_bf16 v[40:43], v[68:71], v[88:91], v[40:43]
	ds_read_b128 v[116:119], v163 offset:18432
	s_waitcnt lgkmcnt(8)
	v_mfma_f32_16x16x32_bf16 v[12:15], v[64:67], v[92:95], v[12:15]
	v_mfma_f32_16x16x32_bf16 v[44:47], v[68:71], v[92:95], v[44:47]
	ds_read_b128 v[120:123], v163 offset:20480
	s_waitcnt lgkmcnt(8)
	v_mfma_f32_16x16x32_bf16 v[16:19], v[64:67], v[96:99], v[16:19]
	v_mfma_f32_16x16x32_bf16 v[48:51], v[68:71], v[96:99], v[48:51]
	ds_read_b128 v[124:127], v163 offset:22528
	s_waitcnt lgkmcnt(8)
	v_mfma_f32_16x16x32_bf16 v[20:23], v[64:67], v[100:103], v[20:23]
	v_mfma_f32_16x16x32_bf16 v[52:55], v[68:71], v[100:103], v[52:55]
	ds_read_b128 v[80:83], v163 offset:24576
	s_waitcnt lgkmcnt(8)
	v_mfma_f32_16x16x32_bf16 v[24:27], v[64:67], v[104:107], v[24:27]
	v_mfma_f32_16x16x32_bf16 v[56:59], v[68:71], v[104:107], v[56:59]
	ds_read_b128 v[84:87], v163 offset:26624
	s_waitcnt lgkmcnt(8)
	v_mfma_f32_16x16x32_bf16 v[28:31], v[64:67], v[108:111], v[28:31]
	v_mfma_f32_16x16x32_bf16 v[60:63], v[68:71], v[108:111], v[60:63]
	ds_read_b128 v[88:91], v163 offset:28672
	s_waitcnt lgkmcnt(6)
	v_mfma_f32_16x16x32_bf16 v[0:3], v[72:75], v[112:115], v[0:3]
	v_mfma_f32_16x16x32_bf16 v[32:35], v[76:79], v[112:115], v[32:35]
	ds_read_b128 v[92:95], v163 offset:30720
	s_waitcnt vmcnt(0) lgkmcnt(0)
	s_barrier
	s_add_u32 m0, s38, 0
	s_nop 0
	global_load_lds_dwordx4 v164, s[98:99]
	s_waitcnt lgkmcnt(6)
	v_mfma_f32_16x16x32_bf16 v[4:7], v[72:75], v[116:119], v[4:7]
	v_mfma_f32_16x16x32_bf16 v[36:39], v[76:79], v[116:119], v[36:39]
	ds_read_b128 v[64:67], v150 offset:32768
	ds_read_b128 v[68:71], v150 offset:34816
	ds_read_b128 v[96:99], v162 offset:49152
	s_add_u32 m0, s38, 4096
	s_nop 0
	global_load_lds_dwordx4 v165, s[98:99]
	s_waitcnt lgkmcnt(8)
	v_mfma_f32_16x16x32_bf16 v[8:11], v[72:75], v[120:123], v[8:11]
	v_mfma_f32_16x16x32_bf16 v[40:43], v[76:79], v[120:123], v[40:43]
	ds_read_b128 v[100:103], v162 offset:51200
	s_add_u32 m0, s38, 8192
	s_nop 0
	global_load_lds_dwordx4 v166, s[98:99]
	s_waitcnt lgkmcnt(8)
	v_mfma_f32_16x16x32_bf16 v[12:15], v[72:75], v[124:127], v[12:15]
	v_mfma_f32_16x16x32_bf16 v[44:47], v[76:79], v[124:127], v[44:47]
	ds_read_b128 v[104:107], v162 offset:53248
	s_add_u32 m0, s38, 12288
	s_nop 0
	global_load_lds_dwordx4 v167, s[98:99]
	s_add_u32 s98, s98, 128
	s_addc_u32 s99, s99, 0
	s_waitcnt lgkmcnt(8)
	v_mfma_f32_16x16x32_bf16 v[16:19], v[72:75], v[80:83], v[16:19]
	v_mfma_f32_16x16x32_bf16 v[48:51], v[76:79], v[80:83], v[48:51]
	ds_read_b128 v[108:111], v162 offset:55296
	s_add_u32 m0, s38, 16384
	s_nop 0
	global_load_lds_dwordx4 v164, s[100:101]
	s_waitcnt lgkmcnt(8)
	v_mfma_f32_16x16x32_bf16 v[20:23], v[72:75], v[84:87], v[20:23]
	v_mfma_f32_16x16x32_bf16 v[52:55], v[76:79], v[84:87], v[52:55]
	ds_read_b128 v[112:115], v162 offset:57344
	s_add_u32 m0, s38, 20480
	s_nop 0
	global_load_lds_dwordx4 v165, s[100:101]
	s_waitcnt lgkmcnt(8)
	v_mfma_f32_16x16x32_bf16 v[24:27], v[72:75], v[88:91], v[24:27]
	v_mfma_f32_16x16x32_bf16 v[56:59], v[76:79], v[88:91], v[56:59]
	ds_read_b128 v[116:119], v162 offset:59392
	s_add_u32 m0, s38, 24576
	s_nop 0
	global_load_lds_dwordx4 v166, s[100:101]
	s_waitcnt lgkmcnt(8)
	v_mfma_f32_16x16x32_bf16 v[28:31], v[72:75], v[92:95], v[28:31]
	v_mfma_f32_16x16x32_bf16 v[60:63], v[76:79], v[92:95], v[60:63]
	ds_read_b128 v[120:123], v162 offset:61440
	s_add_u32 m0, s38, 28672
	s_nop 0
	global_load_lds_dwordx4 v167, s[100:101]
	s_add_u32 s100, s100, 128
	s_addc_u32 s101, s101, 0
	s_waitcnt lgkmcnt(6)
	v_mfma_f32_16x16x32_bf16 v[0:3], v[64:67], v[96:99], v[0:3]
	v_mfma_f32_16x16x32_bf16 v[32:35], v[68:71], v[96:99], v[32:35]
	ds_read_b128 v[124:127], v162 offset:63488
	s_waitcnt lgkmcnt(6)
	v_mfma_f32_16x16x32_bf16 v[4:7], v[64:67], v[100:103], v[4:7]
	v_mfma_f32_16x16x32_bf16 v[36:39], v[68:71], v[100:103], v[36:39]
	ds_read_b128 v[72:75], v151 offset:32768
	ds_read_b128 v[76:79], v151 offset:34816
	ds_read_b128 v[80:83], v163 offset:49152
	s_waitcnt lgkmcnt(8)
	v_mfma_f32_16x16x32_bf16 v[8:11], v[64:67], v[104:107], v[8:11]
	v_mfma_f32_16x16x32_bf16 v[40:43], v[68:71], v[104:107], v[40:43]
	ds_read_b128 v[84:87], v163 offset:51200
	s_waitcnt lgkmcnt(8)
	v_mfma_f32_16x16x32_bf16 v[12:15], v[64:67], v[108:111], v[12:15]
	v_mfma_f32_16x16x32_bf16 v[44:47], v[68:71], v[108:111], v[44:47]
	ds_read_b128 v[88:91], v163 offset:53248
	s_waitcnt lgkmcnt(8)
	v_mfma_f32_16x16x32_bf16 v[16:19], v[64:67], v[112:115], v[16:19]
	v_mfma_f32_16x16x32_bf16 v[48:51], v[68:71], v[112:115], v[48:51]
	ds_read_b128 v[92:95], v163 offset:55296
	s_waitcnt lgkmcnt(8)
	v_mfma_f32_16x16x32_bf16 v[20:23], v[64:67], v[116:119], v[20:23]
	v_mfma_f32_16x16x32_bf16 v[52:55], v[68:71], v[116:119], v[52:55]
	ds_read_b128 v[96:99], v163 offset:57344
	s_waitcnt lgkmcnt(8)
	v_mfma_f32_16x16x32_bf16 v[24:27], v[64:67], v[120:123], v[24:27]
	v_mfma_f32_16x16x32_bf16 v[56:59], v[68:71], v[120:123], v[56:59]
	ds_read_b128 v[100:103], v163 offset:59392
	s_waitcnt lgkmcnt(8)
	v_mfma_f32_16x16x32_bf16 v[28:31], v[64:67], v[124:127], v[28:31]
	v_mfma_f32_16x16x32_bf16 v[60:63], v[68:71], v[124:127], v[60:63]
	ds_read_b128 v[104:107], v163 offset:61440
	s_waitcnt lgkmcnt(6)
	v_mfma_f32_16x16x32_bf16 v[0:3], v[72:75], v[80:83], v[0:3]
	v_mfma_f32_16x16x32_bf16 v[32:35], v[76:79], v[80:83], v[32:35]
	ds_read_b128 v[108:111], v163 offset:63488
	s_waitcnt vmcnt(0) lgkmcnt(0)
	s_barrier
	s_add_u32 m0, s38, 32768
	s_nop 0
	global_load_lds_dwordx4 v164, s[98:99]
	s_waitcnt lgkmcnt(6)
	v_mfma_f32_16x16x32_bf16 v[4:7], v[72:75], v[84:87], v[4:7]
	v_mfma_f32_16x16x32_bf16 v[36:39], v[76:79], v[84:87], v[36:39]
	ds_read_b128 v[64:67], v150 offset:0
	ds_read_b128 v[68:71], v150 offset:2048
	ds_read_b128 v[112:115], v162 offset:16384
	s_add_u32 m0, s38, 36864
	s_nop 0
	global_load_lds_dwordx4 v165, s[98:99]
	s_waitcnt lgkmcnt(8)
	v_mfma_f32_16x16x32_bf16 v[8:11], v[72:75], v[88:91], v[8:11]
	v_mfma_f32_16x16x32_bf16 v[40:43], v[76:79], v[88:91], v[40:43]
	ds_read_b128 v[116:119], v162 offset:18432
	s_add_u32 m0, s38, 40960
	s_nop 0
	global_load_lds_dwordx4 v166, s[98:99]
	s_waitcnt lgkmcnt(8)
	v_mfma_f32_16x16x32_bf16 v[12:15], v[72:75], v[92:95], v[12:15]
	v_mfma_f32_16x16x32_bf16 v[44:47], v[76:79], v[92:95], v[44:47]
	ds_read_b128 v[120:123], v162 offset:20480
	s_add_u32 m0, s38, 45056
	s_nop 0
	global_load_lds_dwordx4 v167, s[98:99]
	s_add_u32 s98, s98, 128
	s_addc_u32 s99, s99, 0
	s_waitcnt lgkmcnt(8)
	v_mfma_f32_16x16x32_bf16 v[16:19], v[72:75], v[96:99], v[16:19]
	v_mfma_f32_16x16x32_bf16 v[48:51], v[76:79], v[96:99], v[48:51]
	ds_read_b128 v[124:127], v162 offset:22528
	s_add_u32 m0, s38, 49152
	s_nop 0
	global_load_lds_dwordx4 v164, s[100:101]
	s_waitcnt lgkmcnt(8)
	v_mfma_f32_16x16x32_bf16 v[20:23], v[72:75], v[100:103], v[20:23]
	v_mfma_f32_16x16x32_bf16 v[52:55], v[76:79], v[100:103], v[52:55]
	ds_read_b128 v[80:83], v162 offset:24576
	s_add_u32 m0, s38, 53248
	s_nop 0
	global_load_lds_dwordx4 v165, s[100:101]
	s_waitcnt lgkmcnt(8)
	v_mfma_f32_16x16x32_bf16 v[24:27], v[72:75], v[104:107], v[24:27]
	v_mfma_f32_16x16x32_bf16 v[56:59], v[76:79], v[104:107], v[56:59]
	ds_read_b128 v[84:87], v162 offset:26624
	s_add_u32 m0, s38, 57344
	s_nop 0
	global_load_lds_dwordx4 v166, s[100:101]
	s_waitcnt lgkmcnt(8)
	v_mfma_f32_16x16x32_bf16 v[28:31], v[72:75], v[108:111], v[28:31]
	v_mfma_f32_16x16x32_bf16 v[60:63], v[76:79], v[108:111], v[60:63]
	ds_read_b128 v[88:91], v162 offset:28672
	s_add_u32 m0, s38, 61440
	s_nop 0
	global_load_lds_dwordx4 v167, s[100:101]
	s_add_u32 s100, s100, 128
	s_addc_u32 s101, s101, 0
	s_waitcnt lgkmcnt(6)
	v_mfma_f32_16x16x32_bf16 v[0:3], v[64:67], v[112:115], v[0:3]
	v_mfma_f32_16x16x32_bf16 v[32:35], v[68:71], v[112:115], v[32:35]
	ds_read_b128 v[92:95], v162 offset:30720
	s_waitcnt lgkmcnt(6)
	v_mfma_f32_16x16x32_bf16 v[4:7], v[64:67], v[116:119], v[4:7]
	v_mfma_f32_16x16x32_bf16 v[36:39], v[68:71], v[116:119], v[36:39]
	ds_read_b128 v[72:75], v151 offset:0
	ds_read_b128 v[76:79], v151 offset:2048
	ds_read_b128 v[96:99], v163 offset:16384
	s_waitcnt lgkmcnt(8)
	v_mfma_f32_16x16x32_bf16 v[8:11], v[64:67], v[120:123], v[8:11]
	v_mfma_f32_16x16x32_bf16 v[40:43], v[68:71], v[120:123], v[40:43]
	ds_read_b128 v[100:103], v163 offset:18432
	s_waitcnt lgkmcnt(8)
	v_mfma_f32_16x16x32_bf16 v[12:15], v[64:67], v[124:127], v[12:15]
	v_mfma_f32_16x16x32_bf16 v[44:47], v[68:71], v[124:127], v[44:47]
	ds_read_b128 v[104:107], v163 offset:20480
	s_waitcnt lgkmcnt(8)
	v_mfma_f32_16x16x32_bf16 v[16:19], v[64:67], v[80:83], v[16:19]
	v_mfma_f32_16x16x32_bf16 v[48:51], v[68:71], v[80:83], v[48:51]
	ds_read_b128 v[108:111], v163 offset:22528
	s_waitcnt lgkmcnt(8)
	v_mfma_f32_16x16x32_bf16 v[20:23], v[64:67], v[84:87], v[20:23]
	v_mfma_f32_16x16x32_bf16 v[52:55], v[68:71], v[84:87], v[52:55]
	ds_read_b128 v[112:115], v163 offset:24576
	s_waitcnt lgkmcnt(8)
	v_mfma_f32_16x16x32_bf16 v[24:27], v[64:67], v[88:91], v[24:27]
	v_mfma_f32_16x16x32_bf16 v[56:59], v[68:71], v[88:91], v[56:59]
	ds_read_b128 v[116:119], v163 offset:26624
	s_waitcnt lgkmcnt(8)
	v_mfma_f32_16x16x32_bf16 v[28:31], v[64:67], v[92:95], v[28:31]
	v_mfma_f32_16x16x32_bf16 v[60:63], v[68:71], v[92:95], v[60:63]
	ds_read_b128 v[120:123], v163 offset:28672
	s_waitcnt lgkmcnt(6)
	v_mfma_f32_16x16x32_bf16 v[0:3], v[72:75], v[96:99], v[0:3]
	v_mfma_f32_16x16x32_bf16 v[32:35], v[76:79], v[96:99], v[32:35]
	ds_read_b128 v[124:127], v163 offset:30720
	s_waitcnt vmcnt(0) lgkmcnt(0)
	s_barrier
	s_add_u32 m0, s38, 0
	s_nop 0
	global_load_lds_dwordx4 v164, s[98:99]
	s_add_u32 m0, s38, 4096
	s_nop 0
	global_load_lds_dwordx4 v165, s[98:99]
	s_waitcnt lgkmcnt(6)
	v_mfma_f32_16x16x32_bf16 v[4:7], v[72:75], v[100:103], v[4:7]
	v_mfma_f32_16x16x32_bf16 v[36:39], v[76:79], v[100:103], v[36:39]
	ds_read_b128 v[64:67], v150 offset:32768
	ds_read_b128 v[68:71], v150 offset:34816
	ds_read_b128 v[80:83], v162 offset:49152
	s_add_u32 m0, s38, 8192
	s_nop 0
	global_load_lds_dwordx4 v166, s[98:99]
	s_add_u32 m0, s38, 12288
	s_nop 0
	global_load_lds_dwordx4 v167, s[98:99]
	s_add_u32 s98, s98, 128
	s_addc_u32 s99, s99, 0
	s_waitcnt lgkmcnt(8)
	v_mfma_f32_16x16x32_bf16 v[8:11], v[72:75], v[104:107], v[8:11]
	v_mfma_f32_16x16x32_bf16 v[40:43], v[76:79], v[104:107], v[40:43]
	ds_read_b128 v[84:87], v162 offset:51200
	s_add_u32 m0, s38, 16384
	s_nop 0
	global_load_lds_dwordx4 v164, s[100:101]
	s_add_u32 m0, s38, 20480
	s_nop 0
	global_load_lds_dwordx4 v165, s[100:101]
	s_waitcnt lgkmcnt(8)
	v_mfma_f32_16x16x32_bf16 v[12:15], v[72:75], v[108:111], v[12:15]
	v_mfma_f32_16x16x32_bf16 v[44:47], v[76:79], v[108:111], v[44:47]
	ds_read_b128 v[88:91], v162 offset:53248
	s_add_u32 m0, s38, 24576
	s_nop 0
	global_load_lds_dwordx4 v166, s[100:101]
	s_add_u32 m0, s38, 28672
	s_nop 0
	global_load_lds_dwordx4 v167, s[100:101]
	s_add_u32 s100, s100, 128
	s_addc_u32 s101, s101, 0
	s_waitcnt lgkmcnt(8)
	v_mfma_f32_16x16x32_bf16 v[16:19], v[72:75], v[112:115], v[16:19]
	v_mfma_f32_16x16x32_bf16 v[48:51], v[76:79], v[112:115], v[48:51]
	ds_read_b128 v[92:95], v162 offset:55296
	global_load_dwordx4 v[172:175], v168, s[14:15] nt
	s_waitcnt lgkmcnt(8)
	v_mfma_f32_16x16x32_bf16 v[20:23], v[72:75], v[116:119], v[20:23]
	v_mfma_f32_16x16x32_bf16 v[52:55], v[76:79], v[116:119], v[52:55]
	ds_read_b128 v[96:99], v162 offset:57344
	global_load_dwordx4 v[176:179], v168, s[14:15] offset:16 nt
	s_add_u32 s14, s14, 0x4000
	s_addc_u32 s15, s15, 0
	s_waitcnt lgkmcnt(8)
	v_mfma_f32_16x16x32_bf16 v[24:27], v[72:75], v[120:123], v[24:27]
	v_mfma_f32_16x16x32_bf16 v[56:59], v[76:79], v[120:123], v[56:59]
	ds_read_b128 v[100:103], v162 offset:59392
	global_load_dwordx4 v[180:183], v168, s[14:15] nt
	s_waitcnt lgkmcnt(8)
	v_mfma_f32_16x16x32_bf16 v[28:31], v[72:75], v[124:127], v[28:31]
	v_mfma_f32_16x16x32_bf16 v[60:63], v[76:79], v[124:127], v[60:63]
	ds_read_b128 v[104:107], v162 offset:61440
	global_load_dwordx4 v[184:187], v168, s[14:15] offset:16 nt
	s_add_u32 s14, s14, 0x4000
	s_addc_u32 s15, s15, 0
	s_waitcnt lgkmcnt(6)
	v_mfma_f32_16x16x32_bf16 v[0:3], v[64:67], v[80:83], v[0:3]
	v_mfma_f32_16x16x32_bf16 v[32:35], v[68:71], v[80:83], v[32:35]
	ds_read_b128 v[108:111], v162 offset:63488
	global_load_dwordx4 v[188:191], v168, s[14:15] nt
	s_waitcnt lgkmcnt(6)
	v_mfma_f32_16x16x32_bf16 v[4:7], v[64:67], v[84:87], v[4:7]
	v_mfma_f32_16x16x32_bf16 v[36:39], v[68:71], v[84:87], v[36:39]
	ds_read_b128 v[72:75], v151 offset:32768
	ds_read_b128 v[76:79], v151 offset:34816
	ds_read_b128 v[112:115], v163 offset:49152
	global_load_dwordx4 v[192:195], v168, s[14:15] offset:16 nt
	s_add_u32 s14, s14, 0x4000
	s_addc_u32 s15, s15, 0
	s_waitcnt lgkmcnt(8)
	v_mfma_f32_16x16x32_bf16 v[8:11], v[64:67], v[88:91], v[8:11]
	v_mfma_f32_16x16x32_bf16 v[40:43], v[68:71], v[88:91], v[40:43]
	ds_read_b128 v[116:119], v163 offset:51200
	global_load_dwordx4 v[196:199], v168, s[14:15] nt
	s_waitcnt lgkmcnt(8)
	v_mfma_f32_16x16x32_bf16 v[12:15], v[64:67], v[92:95], v[12:15]
	v_mfma_f32_16x16x32_bf16 v[44:47], v[68:71], v[92:95], v[44:47]
	ds_read_b128 v[120:123], v163 offset:53248
	global_load_dwordx4 v[200:203], v168, s[14:15] offset:16 nt
	s_add_u32 s14, s14, 0x4000
	s_addc_u32 s15, s15, 0
	s_waitcnt lgkmcnt(8)
	v_mfma_f32_16x16x32_bf16 v[16:19], v[64:67], v[96:99], v[16:19]
	v_mfma_f32_16x16x32_bf16 v[48:51], v[68:71], v[96:99], v[48:51]
	ds_read_b128 v[124:127], v163 offset:55296
	s_waitcnt lgkmcnt(8)
	v_mfma_f32_16x16x32_bf16 v[20:23], v[64:67], v[100:103], v[20:23]
	v_mfma_f32_16x16x32_bf16 v[52:55], v[68:71], v[100:103], v[52:55]
	ds_read_b128 v[80:83], v163 offset:57344
	s_waitcnt lgkmcnt(8)
	v_mfma_f32_16x16x32_bf16 v[24:27], v[64:67], v[104:107], v[24:27]
	v_mfma_f32_16x16x32_bf16 v[56:59], v[68:71], v[104:107], v[56:59]
	ds_read_b128 v[84:87], v163 offset:59392
	s_waitcnt lgkmcnt(8)
	v_mfma_f32_16x16x32_bf16 v[28:31], v[64:67], v[108:111], v[28:31]
	v_mfma_f32_16x16x32_bf16 v[60:63], v[68:71], v[108:111], v[60:63]
	ds_read_b128 v[88:91], v163 offset:61440
	s_waitcnt lgkmcnt(6)
	v_mfma_f32_16x16x32_bf16 v[0:3], v[72:75], v[112:115], v[0:3]
	v_mfma_f32_16x16x32_bf16 v[32:35], v[76:79], v[112:115], v[32:35]
	ds_read_b128 v[92:95], v163 offset:63488
	s_waitcnt vmcnt(8) lgkmcnt(0)
	s_barrier
	s_add_u32 m0, s38, 32768
	s_nop 0
	global_load_lds_dwordx4 v164, s[98:99]
	s_waitcnt lgkmcnt(6)
	v_mfma_f32_16x16x32_bf16 v[4:7], v[72:75], v[116:119], v[4:7]
	v_mfma_f32_16x16x32_bf16 v[36:39], v[76:79], v[116:119], v[36:39]
	ds_read_b128 v[64:67], v150 offset:0
	ds_read_b128 v[68:71], v150 offset:2048
	ds_read_b128 v[96:99], v162 offset:16384
	s_add_u32 m0, s38, 36864
	s_nop 0
	global_load_lds_dwordx4 v165, s[98:99]
	s_waitcnt lgkmcnt(8)
	v_mfma_f32_16x16x32_bf16 v[8:11], v[72:75], v[120:123], v[8:11]
	v_mfma_f32_16x16x32_bf16 v[40:43], v[76:79], v[120:123], v[40:43]
	ds_read_b128 v[100:103], v162 offset:18432
	s_add_u32 m0, s38, 40960
	s_nop 0
	global_load_lds_dwordx4 v166, s[98:99]
	s_waitcnt lgkmcnt(8)
	v_mfma_f32_16x16x32_bf16 v[12:15], v[72:75], v[124:127], v[12:15]
	v_mfma_f32_16x16x32_bf16 v[44:47], v[76:79], v[124:127], v[44:47]
	ds_read_b128 v[104:107], v162 offset:20480
	s_add_u32 m0, s38, 45056
	s_nop 0
	global_load_lds_dwordx4 v167, s[98:99]
	s_add_u32 s98, s98, 128
	s_addc_u32 s99, s99, 0
	s_waitcnt lgkmcnt(8)
	v_mfma_f32_16x16x32_bf16 v[16:19], v[72:75], v[80:83], v[16:19]
	v_mfma_f32_16x16x32_bf16 v[48:51], v[76:79], v[80:83], v[48:51]
	ds_read_b128 v[108:111], v162 offset:22528
	s_add_u32 m0, s38, 49152
	s_nop 0
	global_load_lds_dwordx4 v164, s[100:101]
	s_waitcnt lgkmcnt(8)
	v_mfma_f32_16x16x32_bf16 v[20:23], v[72:75], v[84:87], v[20:23]
	v_mfma_f32_16x16x32_bf16 v[52:55], v[76:79], v[84:87], v[52:55]
	ds_read_b128 v[112:115], v162 offset:24576
	s_add_u32 m0, s38, 53248
	s_nop 0
	global_load_lds_dwordx4 v165, s[100:101]
	s_waitcnt lgkmcnt(8)
	v_mfma_f32_16x16x32_bf16 v[24:27], v[72:75], v[88:91], v[24:27]
	v_mfma_f32_16x16x32_bf16 v[56:59], v[76:79], v[88:91], v[56:59]
	ds_read_b128 v[116:119], v162 offset:26624
	s_add_u32 m0, s38, 57344
	s_nop 0
	global_load_lds_dwordx4 v166, s[100:101]
	s_waitcnt lgkmcnt(8)
	v_mfma_f32_16x16x32_bf16 v[28:31], v[72:75], v[92:95], v[28:31]
	v_mfma_f32_16x16x32_bf16 v[60:63], v[76:79], v[92:95], v[60:63]
	ds_read_b128 v[120:123], v162 offset:28672
	s_add_u32 m0, s38, 61440
	s_nop 0
	global_load_lds_dwordx4 v167, s[100:101]
	s_add_u32 s100, s100, 128
	s_addc_u32 s101, s101, 0
	s_waitcnt lgkmcnt(6)
	v_mfma_f32_16x16x32_bf16 v[0:3], v[64:67], v[96:99], v[0:3]
	v_mfma_f32_16x16x32_bf16 v[32:35], v[68:71], v[96:99], v[32:35]
	ds_read_b128 v[124:127], v162 offset:30720
	s_waitcnt lgkmcnt(6)
	v_mfma_f32_16x16x32_bf16 v[4:7], v[64:67], v[100:103], v[4:7]
	v_mfma_f32_16x16x32_bf16 v[36:39], v[68:71], v[100:103], v[36:39]
	ds_read_b128 v[72:75], v151 offset:0
	ds_read_b128 v[76:79], v151 offset:2048
	ds_read_b128 v[80:83], v163 offset:16384
	s_waitcnt lgkmcnt(8)
	v_mfma_f32_16x16x32_bf16 v[8:11], v[64:67], v[104:107], v[8:11]
	v_mfma_f32_16x16x32_bf16 v[40:43], v[68:71], v[104:107], v[40:43]
	ds_read_b128 v[84:87], v163 offset:18432
	s_waitcnt lgkmcnt(8)
	v_mfma_f32_16x16x32_bf16 v[12:15], v[64:67], v[108:111], v[12:15]
	v_mfma_f32_16x16x32_bf16 v[44:47], v[68:71], v[108:111], v[44:47]
	ds_read_b128 v[88:91], v163 offset:20480
	s_waitcnt lgkmcnt(8)
	v_mfma_f32_16x16x32_bf16 v[16:19], v[64:67], v[112:115], v[16:19]
	v_mfma_f32_16x16x32_bf16 v[48:51], v[68:71], v[112:115], v[48:51]
	ds_read_b128 v[92:95], v163 offset:22528
	s_waitcnt lgkmcnt(8)
	v_mfma_f32_16x16x32_bf16 v[20:23], v[64:67], v[116:119], v[20:23]
	v_mfma_f32_16x16x32_bf16 v[52:55], v[68:71], v[116:119], v[52:55]
	ds_read_b128 v[96:99], v163 offset:24576
	s_waitcnt lgkmcnt(8)
	v_mfma_f32_16x16x32_bf16 v[24:27], v[64:67], v[120:123], v[24:27]
	v_mfma_f32_16x16x32_bf16 v[56:59], v[68:71], v[120:123], v[56:59]
	ds_read_b128 v[100:103], v163 offset:26624
	s_waitcnt lgkmcnt(8)
	v_mfma_f32_16x16x32_bf16 v[28:31], v[64:67], v[124:127], v[28:31]
	v_mfma_f32_16x16x32_bf16 v[60:63], v[68:71], v[124:127], v[60:63]
	ds_read_b128 v[104:107], v163 offset:28672
	s_waitcnt lgkmcnt(6)
	v_mfma_f32_16x16x32_bf16 v[0:3], v[72:75], v[80:83], v[0:3]
	v_mfma_f32_16x16x32_bf16 v[32:35], v[76:79], v[80:83], v[32:35]
	ds_read_b128 v[108:111], v163 offset:30720
	s_waitcnt vmcnt(0) lgkmcnt(0)
	s_barrier
	s_add_u32 m0, s38, 0
	s_nop 0
	global_load_lds_dwordx4 v164, s[98:99]
	s_waitcnt lgkmcnt(6)
	v_mfma_f32_16x16x32_bf16 v[4:7], v[72:75], v[84:87], v[4:7]
	v_mfma_f32_16x16x32_bf16 v[36:39], v[76:79], v[84:87], v[36:39]
	ds_read_b128 v[64:67], v150 offset:32768
	ds_read_b128 v[68:71], v150 offset:34816
	ds_read_b128 v[112:115], v162 offset:49152
	s_add_u32 m0, s38, 4096
	s_nop 0
	global_load_lds_dwordx4 v165, s[98:99]
	s_waitcnt lgkmcnt(8)
	v_mfma_f32_16x16x32_bf16 v[8:11], v[72:75], v[88:91], v[8:11]
	v_mfma_f32_16x16x32_bf16 v[40:43], v[76:79], v[88:91], v[40:43]
	ds_read_b128 v[116:119], v162 offset:51200
	s_add_u32 m0, s38, 8192
	s_nop 0
	global_load_lds_dwordx4 v166, s[98:99]
	s_waitcnt lgkmcnt(8)
	v_mfma_f32_16x16x32_bf16 v[12:15], v[72:75], v[92:95], v[12:15]
	v_mfma_f32_16x16x32_bf16 v[44:47], v[76:79], v[92:95], v[44:47]
	ds_read_b128 v[120:123], v162 offset:53248
	s_add_u32 m0, s38, 12288
	s_nop 0
	global_load_lds_dwordx4 v167, s[98:99]
	s_add_u32 s98, s98, 128
	s_addc_u32 s99, s99, 0
	s_waitcnt lgkmcnt(8)
	v_mfma_f32_16x16x32_bf16 v[16:19], v[72:75], v[96:99], v[16:19]
	v_mfma_f32_16x16x32_bf16 v[48:51], v[76:79], v[96:99], v[48:51]
	ds_read_b128 v[124:127], v162 offset:55296
	s_add_u32 m0, s38, 16384
	s_nop 0
	global_load_lds_dwordx4 v164, s[100:101]
	s_waitcnt lgkmcnt(8)
	v_mfma_f32_16x16x32_bf16 v[20:23], v[72:75], v[100:103], v[20:23]
	v_mfma_f32_16x16x32_bf16 v[52:55], v[76:79], v[100:103], v[52:55]
	ds_read_b128 v[80:83], v162 offset:57344
	s_add_u32 m0, s38, 20480
	s_nop 0
	global_load_lds_dwordx4 v165, s[100:101]
	s_waitcnt lgkmcnt(8)
	v_mfma_f32_16x16x32_bf16 v[24:27], v[72:75], v[104:107], v[24:27]
	v_mfma_f32_16x16x32_bf16 v[56:59], v[76:79], v[104:107], v[56:59]
	ds_read_b128 v[84:87], v162 offset:59392
	s_add_u32 m0, s38, 24576
	s_nop 0
	global_load_lds_dwordx4 v166, s[100:101]
	s_waitcnt lgkmcnt(8)
	v_mfma_f32_16x16x32_bf16 v[28:31], v[72:75], v[108:111], v[28:31]
	v_mfma_f32_16x16x32_bf16 v[60:63], v[76:79], v[108:111], v[60:63]
	ds_read_b128 v[88:91], v162 offset:61440
	s_add_u32 m0, s38, 28672
	s_nop 0
	global_load_lds_dwordx4 v167, s[100:101]
	s_add_u32 s100, s100, 128
	s_addc_u32 s101, s101, 0
	s_waitcnt lgkmcnt(6)
	v_mfma_f32_16x16x32_bf16 v[0:3], v[64:67], v[112:115], v[0:3]
	v_mfma_f32_16x16x32_bf16 v[32:35], v[68:71], v[112:115], v[32:35]
	ds_read_b128 v[92:95], v162 offset:63488
	s_waitcnt lgkmcnt(6)
	v_mfma_f32_16x16x32_bf16 v[4:7], v[64:67], v[116:119], v[4:7]
	v_mfma_f32_16x16x32_bf16 v[36:39], v[68:71], v[116:119], v[36:39]
	ds_read_b128 v[72:75], v151 offset:32768
	ds_read_b128 v[76:79], v151 offset:34816
	ds_read_b128 v[96:99], v163 offset:49152
	s_waitcnt lgkmcnt(8)
	v_mfma_f32_16x16x32_bf16 v[8:11], v[64:67], v[120:123], v[8:11]
	v_mfma_f32_16x16x32_bf16 v[40:43], v[68:71], v[120:123], v[40:43]
	ds_read_b128 v[100:103], v163 offset:51200
	s_waitcnt lgkmcnt(8)
	v_mfma_f32_16x16x32_bf16 v[12:15], v[64:67], v[124:127], v[12:15]
	v_mfma_f32_16x16x32_bf16 v[44:47], v[68:71], v[124:127], v[44:47]
	ds_read_b128 v[104:107], v163 offset:53248
	s_waitcnt lgkmcnt(8)
	v_mfma_f32_16x16x32_bf16 v[16:19], v[64:67], v[80:83], v[16:19]
	v_mfma_f32_16x16x32_bf16 v[48:51], v[68:71], v[80:83], v[48:51]
	ds_read_b128 v[108:111], v163 offset:55296
	s_waitcnt lgkmcnt(8)
	v_mfma_f32_16x16x32_bf16 v[20:23], v[64:67], v[84:87], v[20:23]
	v_mfma_f32_16x16x32_bf16 v[52:55], v[68:71], v[84:87], v[52:55]
	ds_read_b128 v[112:115], v163 offset:57344
	s_waitcnt lgkmcnt(8)
	v_mfma_f32_16x16x32_bf16 v[24:27], v[64:67], v[88:91], v[24:27]
	v_mfma_f32_16x16x32_bf16 v[56:59], v[68:71], v[88:91], v[56:59]
	ds_read_b128 v[116:119], v163 offset:59392
	s_waitcnt lgkmcnt(8)
	v_mfma_f32_16x16x32_bf16 v[28:31], v[64:67], v[92:95], v[28:31]
	v_mfma_f32_16x16x32_bf16 v[60:63], v[68:71], v[92:95], v[60:63]
	ds_read_b128 v[120:123], v163 offset:61440
	s_waitcnt lgkmcnt(6)
	v_mfma_f32_16x16x32_bf16 v[0:3], v[72:75], v[96:99], v[0:3]
	v_mfma_f32_16x16x32_bf16 v[32:35], v[76:79], v[96:99], v[32:35]
	ds_read_b128 v[124:127], v163 offset:63488
	s_waitcnt vmcnt(0) lgkmcnt(0)
	s_barrier
	s_add_u32 m0, s38, 32768
	s_nop 0
	global_load_lds_dwordx4 v164, s[98:99]
	s_waitcnt lgkmcnt(6)
	v_mfma_f32_16x16x32_bf16 v[4:7], v[72:75], v[100:103], v[4:7]
	v_mfma_f32_16x16x32_bf16 v[36:39], v[76:79], v[100:103], v[36:39]
	ds_read_b128 v[64:67], v150 offset:0
	ds_read_b128 v[68:71], v150 offset:2048
	ds_read_b128 v[80:83], v162 offset:16384
	s_add_u32 m0, s38, 36864
	s_nop 0
	global_load_lds_dwordx4 v165, s[98:99]
	s_waitcnt lgkmcnt(8)
	v_mfma_f32_16x16x32_bf16 v[8:11], v[72:75], v[104:107], v[8:11]
	v_mfma_f32_16x16x32_bf16 v[40:43], v[76:79], v[104:107], v[40:43]
	ds_read_b128 v[84:87], v162 offset:18432
	s_add_u32 m0, s38, 40960
	s_nop 0
	global_load_lds_dwordx4 v166, s[98:99]
	s_waitcnt lgkmcnt(8)
	v_mfma_f32_16x16x32_bf16 v[12:15], v[72:75], v[108:111], v[12:15]
	v_mfma_f32_16x16x32_bf16 v[44:47], v[76:79], v[108:111], v[44:47]
	ds_read_b128 v[88:91], v162 offset:20480
	s_add_u32 m0, s38, 45056
	s_nop 0
	global_load_lds_dwordx4 v167, s[98:99]
	s_add_u32 s98, s98, 128
	s_addc_u32 s99, s99, 0
	s_waitcnt lgkmcnt(8)
	v_mfma_f32_16x16x32_bf16 v[16:19], v[72:75], v[112:115], v[16:19]
	v_mfma_f32_16x16x32_bf16 v[48:51], v[76:79], v[112:115], v[48:51]
	ds_read_b128 v[92:95], v162 offset:22528
	s_add_u32 m0, s38, 49152
	s_nop 0
	global_load_lds_dwordx4 v164, s[100:101]
	s_waitcnt lgkmcnt(8)
	v_mfma_f32_16x16x32_bf16 v[20:23], v[72:75], v[116:119], v[20:23]
	v_mfma_f32_16x16x32_bf16 v[52:55], v[76:79], v[116:119], v[52:55]
	ds_read_b128 v[96:99], v162 offset:24576
	s_add_u32 m0, s38, 53248
	s_nop 0
	global_load_lds_dwordx4 v165, s[100:101]
	s_waitcnt lgkmcnt(8)
	v_mfma_f32_16x16x32_bf16 v[24:27], v[72:75], v[120:123], v[24:27]
	v_mfma_f32_16x16x32_bf16 v[56:59], v[76:79], v[120:123], v[56:59]
	ds_read_b128 v[100:103], v162 offset:26624
	s_add_u32 m0, s38, 57344
	s_nop 0
	global_load_lds_dwordx4 v166, s[100:101]
	s_waitcnt lgkmcnt(8)
	v_mfma_f32_16x16x32_bf16 v[28:31], v[72:75], v[124:127], v[28:31]
	v_mfma_f32_16x16x32_bf16 v[60:63], v[76:79], v[124:127], v[60:63]
	ds_read_b128 v[104:107], v162 offset:28672
	s_add_u32 m0, s38, 61440
	s_nop 0
	global_load_lds_dwordx4 v167, s[100:101]
	s_add_u32 s100, s100, 128
	s_addc_u32 s101, s101, 0
	s_waitcnt lgkmcnt(6)
	v_mfma_f32_16x16x32_bf16 v[0:3], v[64:67], v[80:83], v[0:3]
	v_mfma_f32_16x16x32_bf16 v[32:35], v[68:71], v[80:83], v[32:35]
	ds_read_b128 v[108:111], v162 offset:30720
	s_waitcnt lgkmcnt(6)
	v_mfma_f32_16x16x32_bf16 v[4:7], v[64:67], v[84:87], v[4:7]
	v_mfma_f32_16x16x32_bf16 v[36:39], v[68:71], v[84:87], v[36:39]
	ds_read_b128 v[72:75], v151 offset:0
	ds_read_b128 v[76:79], v151 offset:2048
	ds_read_b128 v[112:115], v163 offset:16384
	s_waitcnt lgkmcnt(8)
	v_mfma_f32_16x16x32_bf16 v[8:11], v[64:67], v[88:91], v[8:11]
	v_mfma_f32_16x16x32_bf16 v[40:43], v[68:71], v[88:91], v[40:43]
	ds_read_b128 v[116:119], v163 offset:18432
	s_waitcnt lgkmcnt(8)
	v_mfma_f32_16x16x32_bf16 v[12:15], v[64:67], v[92:95], v[12:15]
	v_mfma_f32_16x16x32_bf16 v[44:47], v[68:71], v[92:95], v[44:47]
	ds_read_b128 v[120:123], v163 offset:20480
	s_waitcnt lgkmcnt(8)
	v_mfma_f32_16x16x32_bf16 v[16:19], v[64:67], v[96:99], v[16:19]
	v_mfma_f32_16x16x32_bf16 v[48:51], v[68:71], v[96:99], v[48:51]
	ds_read_b128 v[124:127], v163 offset:22528
	s_waitcnt lgkmcnt(8)
	v_mfma_f32_16x16x32_bf16 v[20:23], v[64:67], v[100:103], v[20:23]
	v_mfma_f32_16x16x32_bf16 v[52:55], v[68:71], v[100:103], v[52:55]
	ds_read_b128 v[80:83], v163 offset:24576
	s_waitcnt lgkmcnt(8)
	v_mfma_f32_16x16x32_bf16 v[24:27], v[64:67], v[104:107], v[24:27]
	v_mfma_f32_16x16x32_bf16 v[56:59], v[68:71], v[104:107], v[56:59]
	ds_read_b128 v[84:87], v163 offset:26624
	s_waitcnt lgkmcnt(8)
	v_mfma_f32_16x16x32_bf16 v[28:31], v[64:67], v[108:111], v[28:31]
	v_mfma_f32_16x16x32_bf16 v[60:63], v[68:71], v[108:111], v[60:63]
	ds_read_b128 v[88:91], v163 offset:28672
	s_waitcnt lgkmcnt(6)
	v_mfma_f32_16x16x32_bf16 v[0:3], v[72:75], v[112:115], v[0:3]
	v_mfma_f32_16x16x32_bf16 v[32:35], v[76:79], v[112:115], v[32:35]
	ds_read_b128 v[92:95], v163 offset:30720
	s_waitcnt vmcnt(0) lgkmcnt(0)
	s_barrier
	s_add_u32 m0, s38, 0
	s_nop 0
	global_load_lds_dwordx4 v164, s[98:99]
	s_waitcnt lgkmcnt(6)
	v_mfma_f32_16x16x32_bf16 v[4:7], v[72:75], v[116:119], v[4:7]
	v_mfma_f32_16x16x32_bf16 v[36:39], v[76:79], v[116:119], v[36:39]
	ds_read_b128 v[64:67], v150 offset:32768
	ds_read_b128 v[68:71], v150 offset:34816
	ds_read_b128 v[96:99], v162 offset:49152
	s_add_u32 m0, s38, 4096
	s_nop 0
	global_load_lds_dwordx4 v165, s[98:99]
	s_waitcnt lgkmcnt(8)
	v_mfma_f32_16x16x32_bf16 v[8:11], v[72:75], v[120:123], v[8:11]
	v_mfma_f32_16x16x32_bf16 v[40:43], v[76:79], v[120:123], v[40:43]
	ds_read_b128 v[100:103], v162 offset:51200
	s_add_u32 m0, s38, 8192
	s_nop 0
	global_load_lds_dwordx4 v166, s[98:99]
	s_waitcnt lgkmcnt(8)
	v_mfma_f32_16x16x32_bf16 v[12:15], v[72:75], v[124:127], v[12:15]
	v_mfma_f32_16x16x32_bf16 v[44:47], v[76:79], v[124:127], v[44:47]
	ds_read_b128 v[104:107], v162 offset:53248
	s_add_u32 m0, s38, 12288
	s_nop 0
	global_load_lds_dwordx4 v167, s[98:99]
	s_add_u32 s98, s98, 128
	s_addc_u32 s99, s99, 0
	s_waitcnt lgkmcnt(8)
	v_mfma_f32_16x16x32_bf16 v[16:19], v[72:75], v[80:83], v[16:19]
	v_mfma_f32_16x16x32_bf16 v[48:51], v[76:79], v[80:83], v[48:51]
	ds_read_b128 v[108:111], v162 offset:55296
	s_add_u32 m0, s38, 16384
	s_nop 0
	global_load_lds_dwordx4 v164, s[100:101]
	s_waitcnt lgkmcnt(8)
	v_mfma_f32_16x16x32_bf16 v[20:23], v[72:75], v[84:87], v[20:23]
	v_mfma_f32_16x16x32_bf16 v[52:55], v[76:79], v[84:87], v[52:55]
	ds_read_b128 v[112:115], v162 offset:57344
	s_add_u32 m0, s38, 20480
	s_nop 0
	global_load_lds_dwordx4 v165, s[100:101]
	s_waitcnt lgkmcnt(8)
	v_mfma_f32_16x16x32_bf16 v[24:27], v[72:75], v[88:91], v[24:27]
	v_mfma_f32_16x16x32_bf16 v[56:59], v[76:79], v[88:91], v[56:59]
	ds_read_b128 v[116:119], v162 offset:59392
	s_add_u32 m0, s38, 24576
	s_nop 0
	global_load_lds_dwordx4 v166, s[100:101]
	s_waitcnt lgkmcnt(8)
	v_mfma_f32_16x16x32_bf16 v[28:31], v[72:75], v[92:95], v[28:31]
	v_mfma_f32_16x16x32_bf16 v[60:63], v[76:79], v[92:95], v[60:63]
	ds_read_b128 v[120:123], v162 offset:61440
	s_add_u32 m0, s38, 28672
	s_nop 0
	global_load_lds_dwordx4 v167, s[100:101]
	s_add_u32 s100, s100, 128
	s_addc_u32 s101, s101, 0
	s_waitcnt lgkmcnt(6)
	v_mfma_f32_16x16x32_bf16 v[0:3], v[64:67], v[96:99], v[0:3]
	v_mfma_f32_16x16x32_bf16 v[32:35], v[68:71], v[96:99], v[32:35]
	ds_read_b128 v[124:127], v162 offset:63488
	s_waitcnt lgkmcnt(6)
	v_mfma_f32_16x16x32_bf16 v[4:7], v[64:67], v[100:103], v[4:7]
	v_mfma_f32_16x16x32_bf16 v[36:39], v[68:71], v[100:103], v[36:39]
	ds_read_b128 v[72:75], v151 offset:32768
	ds_read_b128 v[76:79], v151 offset:34816
	ds_read_b128 v[80:83], v163 offset:49152
	s_waitcnt lgkmcnt(8)
	v_mfma_f32_16x16x32_bf16 v[8:11], v[64:67], v[104:107], v[8:11]
	v_mfma_f32_16x16x32_bf16 v[40:43], v[68:71], v[104:107], v[40:43]
	ds_read_b128 v[84:87], v163 offset:51200
	s_waitcnt lgkmcnt(8)
	v_mfma_f32_16x16x32_bf16 v[12:15], v[64:67], v[108:111], v[12:15]
	v_mfma_f32_16x16x32_bf16 v[44:47], v[68:71], v[108:111], v[44:47]
	ds_read_b128 v[88:91], v163 offset:53248
	s_waitcnt lgkmcnt(8)
	v_mfma_f32_16x16x32_bf16 v[16:19], v[64:67], v[112:115], v[16:19]
	v_mfma_f32_16x16x32_bf16 v[48:51], v[68:71], v[112:115], v[48:51]
	ds_read_b128 v[92:95], v163 offset:55296
	s_waitcnt lgkmcnt(8)
	v_mfma_f32_16x16x32_bf16 v[20:23], v[64:67], v[116:119], v[20:23]
	v_mfma_f32_16x16x32_bf16 v[52:55], v[68:71], v[116:119], v[52:55]
	ds_read_b128 v[96:99], v163 offset:57344
	s_waitcnt lgkmcnt(8)
	v_mfma_f32_16x16x32_bf16 v[24:27], v[64:67], v[120:123], v[24:27]
	v_mfma_f32_16x16x32_bf16 v[56:59], v[68:71], v[120:123], v[56:59]
	ds_read_b128 v[100:103], v163 offset:59392
	s_waitcnt lgkmcnt(8)
	v_mfma_f32_16x16x32_bf16 v[28:31], v[64:67], v[124:127], v[28:31]
	v_mfma_f32_16x16x32_bf16 v[60:63], v[68:71], v[124:127], v[60:63]
	ds_read_b128 v[104:107], v163 offset:61440
	s_waitcnt lgkmcnt(6)
	v_mfma_f32_16x16x32_bf16 v[0:3], v[72:75], v[80:83], v[0:3]
	v_mfma_f32_16x16x32_bf16 v[32:35], v[76:79], v[80:83], v[32:35]
	ds_read_b128 v[108:111], v163 offset:63488
	s_waitcnt vmcnt(0) lgkmcnt(0)
	s_barrier
	s_add_u32 m0, s38, 32768
	s_nop 0
	global_load_lds_dwordx4 v164, s[98:99]
	s_waitcnt lgkmcnt(6)
	v_mfma_f32_16x16x32_bf16 v[4:7], v[72:75], v[84:87], v[4:7]
	v_mfma_f32_16x16x32_bf16 v[36:39], v[76:79], v[84:87], v[36:39]
	ds_read_b128 v[64:67], v150 offset:0
	ds_read_b128 v[68:71], v150 offset:2048
	ds_read_b128 v[112:115], v162 offset:16384
	s_add_u32 m0, s38, 36864
	s_nop 0
	global_load_lds_dwordx4 v165, s[98:99]
	s_waitcnt lgkmcnt(8)
	v_mfma_f32_16x16x32_bf16 v[8:11], v[72:75], v[88:91], v[8:11]
	v_mfma_f32_16x16x32_bf16 v[40:43], v[76:79], v[88:91], v[40:43]
	ds_read_b128 v[116:119], v162 offset:18432
	s_add_u32 m0, s38, 40960
	s_nop 0
	global_load_lds_dwordx4 v166, s[98:99]
	s_waitcnt lgkmcnt(8)
	v_mfma_f32_16x16x32_bf16 v[12:15], v[72:75], v[92:95], v[12:15]
	v_mfma_f32_16x16x32_bf16 v[44:47], v[76:79], v[92:95], v[44:47]
	ds_read_b128 v[120:123], v162 offset:20480
	s_add_u32 m0, s38, 45056
	s_nop 0
	global_load_lds_dwordx4 v167, s[98:99]
	s_add_u32 s98, s98, 128
	s_addc_u32 s99, s99, 0
	s_waitcnt lgkmcnt(8)
	v_mfma_f32_16x16x32_bf16 v[16:19], v[72:75], v[96:99], v[16:19]
	v_mfma_f32_16x16x32_bf16 v[48:51], v[76:79], v[96:99], v[48:51]
	ds_read_b128 v[124:127], v162 offset:22528
	s_add_u32 m0, s38, 49152
	s_nop 0
	global_load_lds_dwordx4 v164, s[100:101]
	s_waitcnt lgkmcnt(8)
	v_mfma_f32_16x16x32_bf16 v[20:23], v[72:75], v[100:103], v[20:23]
	v_mfma_f32_16x16x32_bf16 v[52:55], v[76:79], v[100:103], v[52:55]
	ds_read_b128 v[80:83], v162 offset:24576
	s_add_u32 m0, s38, 53248
	s_nop 0
	global_load_lds_dwordx4 v165, s[100:101]
	s_waitcnt lgkmcnt(8)
	v_mfma_f32_16x16x32_bf16 v[24:27], v[72:75], v[104:107], v[24:27]
	v_mfma_f32_16x16x32_bf16 v[56:59], v[76:79], v[104:107], v[56:59]
	ds_read_b128 v[84:87], v162 offset:26624
	s_add_u32 m0, s38, 57344
	s_nop 0
	global_load_lds_dwordx4 v166, s[100:101]
	s_waitcnt lgkmcnt(8)
	v_mfma_f32_16x16x32_bf16 v[28:31], v[72:75], v[108:111], v[28:31]
	v_mfma_f32_16x16x32_bf16 v[60:63], v[76:79], v[108:111], v[60:63]
	ds_read_b128 v[88:91], v162 offset:28672
	s_add_u32 m0, s38, 61440
	s_nop 0
	global_load_lds_dwordx4 v167, s[100:101]
	s_add_u32 s100, s100, 128
	s_addc_u32 s101, s101, 0
	s_waitcnt lgkmcnt(6)
	v_mfma_f32_16x16x32_bf16 v[0:3], v[64:67], v[112:115], v[0:3]
	v_mfma_f32_16x16x32_bf16 v[32:35], v[68:71], v[112:115], v[32:35]
	ds_read_b128 v[92:95], v162 offset:30720
	s_waitcnt lgkmcnt(6)
	v_mfma_f32_16x16x32_bf16 v[4:7], v[64:67], v[116:119], v[4:7]
	v_mfma_f32_16x16x32_bf16 v[36:39], v[68:71], v[116:119], v[36:39]
	ds_read_b128 v[72:75], v151 offset:0
	ds_read_b128 v[76:79], v151 offset:2048
	ds_read_b128 v[96:99], v163 offset:16384
	s_waitcnt lgkmcnt(8)
	v_mfma_f32_16x16x32_bf16 v[8:11], v[64:67], v[120:123], v[8:11]
	v_mfma_f32_16x16x32_bf16 v[40:43], v[68:71], v[120:123], v[40:43]
	ds_read_b128 v[100:103], v163 offset:18432
	s_waitcnt lgkmcnt(8)
	v_mfma_f32_16x16x32_bf16 v[12:15], v[64:67], v[124:127], v[12:15]
	v_mfma_f32_16x16x32_bf16 v[44:47], v[68:71], v[124:127], v[44:47]
	ds_read_b128 v[104:107], v163 offset:20480
	s_waitcnt lgkmcnt(8)
	v_mfma_f32_16x16x32_bf16 v[16:19], v[64:67], v[80:83], v[16:19]
	v_mfma_f32_16x16x32_bf16 v[48:51], v[68:71], v[80:83], v[48:51]
	ds_read_b128 v[108:111], v163 offset:22528
	s_waitcnt lgkmcnt(8)
	v_mfma_f32_16x16x32_bf16 v[20:23], v[64:67], v[84:87], v[20:23]
	v_mfma_f32_16x16x32_bf16 v[52:55], v[68:71], v[84:87], v[52:55]
	ds_read_b128 v[112:115], v163 offset:24576
	s_waitcnt lgkmcnt(8)
	v_mfma_f32_16x16x32_bf16 v[24:27], v[64:67], v[88:91], v[24:27]
	v_mfma_f32_16x16x32_bf16 v[56:59], v[68:71], v[88:91], v[56:59]
	ds_read_b128 v[116:119], v163 offset:26624
	s_waitcnt lgkmcnt(8)
	v_mfma_f32_16x16x32_bf16 v[28:31], v[64:67], v[92:95], v[28:31]
	v_mfma_f32_16x16x32_bf16 v[60:63], v[68:71], v[92:95], v[60:63]
	ds_read_b128 v[120:123], v163 offset:28672
	s_waitcnt lgkmcnt(6)
	v_mfma_f32_16x16x32_bf16 v[0:3], v[72:75], v[96:99], v[0:3]
	v_mfma_f32_16x16x32_bf16 v[32:35], v[76:79], v[96:99], v[32:35]
	ds_read_b128 v[124:127], v163 offset:30720
	s_waitcnt vmcnt(0) lgkmcnt(0)
	s_barrier
	s_add_u32 m0, s38, 0
	s_nop 0
	global_load_lds_dwordx4 v164, s[98:99]
	s_waitcnt lgkmcnt(6)
	v_mfma_f32_16x16x32_bf16 v[4:7], v[72:75], v[100:103], v[4:7]
	v_mfma_f32_16x16x32_bf16 v[36:39], v[76:79], v[100:103], v[36:39]
	ds_read_b128 v[64:67], v150 offset:32768
	ds_read_b128 v[68:71], v150 offset:34816
	ds_read_b128 v[80:83], v162 offset:49152
	s_add_u32 m0, s38, 4096
	s_nop 0
	global_load_lds_dwordx4 v165, s[98:99]
	s_waitcnt lgkmcnt(8)
	v_mfma_f32_16x16x32_bf16 v[8:11], v[72:75], v[104:107], v[8:11]
	v_mfma_f32_16x16x32_bf16 v[40:43], v[76:79], v[104:107], v[40:43]
	ds_read_b128 v[84:87], v162 offset:51200
	s_add_u32 m0, s38, 8192
	s_nop 0
	global_load_lds_dwordx4 v166, s[98:99]
	s_waitcnt lgkmcnt(8)
	v_mfma_f32_16x16x32_bf16 v[12:15], v[72:75], v[108:111], v[12:15]
	v_mfma_f32_16x16x32_bf16 v[44:47], v[76:79], v[108:111], v[44:47]
	ds_read_b128 v[88:91], v162 offset:53248
	s_add_u32 m0, s38, 12288
	s_nop 0
	global_load_lds_dwordx4 v167, s[98:99]
	s_add_u32 s98, s98, 128
	s_addc_u32 s99, s99, 0
	s_waitcnt lgkmcnt(8)
	v_mfma_f32_16x16x32_bf16 v[16:19], v[72:75], v[112:115], v[16:19]
	v_mfma_f32_16x16x32_bf16 v[48:51], v[76:79], v[112:115], v[48:51]
	ds_read_b128 v[92:95], v162 offset:55296
	s_add_u32 m0, s38, 16384
	s_nop 0
	global_load_lds_dwordx4 v164, s[100:101]
	s_waitcnt lgkmcnt(8)
	v_mfma_f32_16x16x32_bf16 v[20:23], v[72:75], v[116:119], v[20:23]
	v_mfma_f32_16x16x32_bf16 v[52:55], v[76:79], v[116:119], v[52:55]
	ds_read_b128 v[96:99], v162 offset:57344
	s_add_u32 m0, s38, 20480
	s_nop 0
	global_load_lds_dwordx4 v165, s[100:101]
	s_waitcnt lgkmcnt(8)
	v_mfma_f32_16x16x32_bf16 v[24:27], v[72:75], v[120:123], v[24:27]
	v_mfma_f32_16x16x32_bf16 v[56:59], v[76:79], v[120:123], v[56:59]
	ds_read_b128 v[100:103], v162 offset:59392
	s_add_u32 m0, s38, 24576
	s_nop 0
	global_load_lds_dwordx4 v166, s[100:101]
	s_waitcnt lgkmcnt(8)
	v_mfma_f32_16x16x32_bf16 v[28:31], v[72:75], v[124:127], v[28:31]
	v_mfma_f32_16x16x32_bf16 v[60:63], v[76:79], v[124:127], v[60:63]
	ds_read_b128 v[104:107], v162 offset:61440
	s_add_u32 m0, s38, 28672
	s_nop 0
	global_load_lds_dwordx4 v167, s[100:101]
	s_add_u32 s100, s100, 128
	s_addc_u32 s101, s101, 0
	s_waitcnt lgkmcnt(6)
	v_mfma_f32_16x16x32_bf16 v[0:3], v[64:67], v[80:83], v[0:3]
	v_mfma_f32_16x16x32_bf16 v[32:35], v[68:71], v[80:83], v[32:35]
	ds_read_b128 v[108:111], v162 offset:63488
	s_waitcnt lgkmcnt(6)
	v_mfma_f32_16x16x32_bf16 v[4:7], v[64:67], v[84:87], v[4:7]
	v_mfma_f32_16x16x32_bf16 v[36:39], v[68:71], v[84:87], v[36:39]
	ds_read_b128 v[72:75], v151 offset:32768
	ds_read_b128 v[76:79], v151 offset:34816
	ds_read_b128 v[112:115], v163 offset:49152
	s_waitcnt lgkmcnt(8)
	v_mfma_f32_16x16x32_bf16 v[8:11], v[64:67], v[88:91], v[8:11]
	v_mfma_f32_16x16x32_bf16 v[40:43], v[68:71], v[88:91], v[40:43]
	ds_read_b128 v[116:119], v163 offset:51200
	s_waitcnt lgkmcnt(8)
	v_mfma_f32_16x16x32_bf16 v[12:15], v[64:67], v[92:95], v[12:15]
	v_mfma_f32_16x16x32_bf16 v[44:47], v[68:71], v[92:95], v[44:47]
	ds_read_b128 v[120:123], v163 offset:53248
	s_waitcnt lgkmcnt(8)
	v_mfma_f32_16x16x32_bf16 v[16:19], v[64:67], v[96:99], v[16:19]
	v_mfma_f32_16x16x32_bf16 v[48:51], v[68:71], v[96:99], v[48:51]
	ds_read_b128 v[124:127], v163 offset:55296
	s_waitcnt lgkmcnt(8)
	v_mfma_f32_16x16x32_bf16 v[20:23], v[64:67], v[100:103], v[20:23]
	v_mfma_f32_16x16x32_bf16 v[52:55], v[68:71], v[100:103], v[52:55]
	ds_read_b128 v[80:83], v163 offset:57344
	s_waitcnt lgkmcnt(8)
	v_mfma_f32_16x16x32_bf16 v[24:27], v[64:67], v[104:107], v[24:27]
	v_mfma_f32_16x16x32_bf16 v[56:59], v[68:71], v[104:107], v[56:59]
	ds_read_b128 v[84:87], v163 offset:59392
	s_waitcnt lgkmcnt(8)
	v_mfma_f32_16x16x32_bf16 v[28:31], v[64:67], v[108:111], v[28:31]
	v_mfma_f32_16x16x32_bf16 v[60:63], v[68:71], v[108:111], v[60:63]
	ds_read_b128 v[88:91], v163 offset:61440
	s_waitcnt lgkmcnt(6)
	v_mfma_f32_16x16x32_bf16 v[0:3], v[72:75], v[112:115], v[0:3]
	v_mfma_f32_16x16x32_bf16 v[32:35], v[76:79], v[112:115], v[32:35]
	ds_read_b128 v[92:95], v163 offset:63488
	s_waitcnt vmcnt(0) lgkmcnt(0)
	s_barrier
	s_add_u32 m0, s38, 32768
	s_nop 0
	global_load_lds_dwordx4 v164, s[98:99]
	s_waitcnt lgkmcnt(6)
	v_mfma_f32_16x16x32_bf16 v[4:7], v[72:75], v[116:119], v[4:7]
	v_mfma_f32_16x16x32_bf16 v[36:39], v[76:79], v[116:119], v[36:39]
	ds_read_b128 v[64:67], v150 offset:0
	ds_read_b128 v[68:71], v150 offset:2048
	ds_read_b128 v[96:99], v162 offset:16384
	s_add_u32 m0, s38, 36864
	s_nop 0
	global_load_lds_dwordx4 v165, s[98:99]
	s_waitcnt lgkmcnt(8)
	v_mfma_f32_16x16x32_bf16 v[8:11], v[72:75], v[120:123], v[8:11]
	v_mfma_f32_16x16x32_bf16 v[40:43], v[76:79], v[120:123], v[40:43]
	ds_read_b128 v[100:103], v162 offset:18432
	s_add_u32 m0, s38, 40960
	s_nop 0
	global_load_lds_dwordx4 v166, s[98:99]
	s_waitcnt lgkmcnt(8)
	v_mfma_f32_16x16x32_bf16 v[12:15], v[72:75], v[124:127], v[12:15]
	v_mfma_f32_16x16x32_bf16 v[44:47], v[76:79], v[124:127], v[44:47]
	ds_read_b128 v[104:107], v162 offset:20480
	s_add_u32 m0, s38, 45056
	s_nop 0
	global_load_lds_dwordx4 v167, s[98:99]
	s_add_u32 s98, s98, 128
	s_addc_u32 s99, s99, 0
	s_waitcnt lgkmcnt(8)
	v_mfma_f32_16x16x32_bf16 v[16:19], v[72:75], v[80:83], v[16:19]
	v_mfma_f32_16x16x32_bf16 v[48:51], v[76:79], v[80:83], v[48:51]
	ds_read_b128 v[108:111], v162 offset:22528
	s_add_u32 m0, s38, 49152
	s_nop 0
	global_load_lds_dwordx4 v164, s[100:101]
	s_waitcnt lgkmcnt(8)
	v_mfma_f32_16x16x32_bf16 v[20:23], v[72:75], v[84:87], v[20:23]
	v_mfma_f32_16x16x32_bf16 v[52:55], v[76:79], v[84:87], v[52:55]
	ds_read_b128 v[112:115], v162 offset:24576
	s_add_u32 m0, s38, 53248
	s_nop 0
	global_load_lds_dwordx4 v165, s[100:101]
	s_waitcnt lgkmcnt(8)
	v_mfma_f32_16x16x32_bf16 v[24:27], v[72:75], v[88:91], v[24:27]
	v_mfma_f32_16x16x32_bf16 v[56:59], v[76:79], v[88:91], v[56:59]
	ds_read_b128 v[116:119], v162 offset:26624
	s_add_u32 m0, s38, 57344
	s_nop 0
	global_load_lds_dwordx4 v166, s[100:101]
	s_waitcnt lgkmcnt(8)
	v_mfma_f32_16x16x32_bf16 v[28:31], v[72:75], v[92:95], v[28:31]
	v_mfma_f32_16x16x32_bf16 v[60:63], v[76:79], v[92:95], v[60:63]
	ds_read_b128 v[120:123], v162 offset:28672
	s_add_u32 m0, s38, 61440
	s_nop 0
	global_load_lds_dwordx4 v167, s[100:101]
	s_add_u32 s100, s100, 128
	s_addc_u32 s101, s101, 0
	s_waitcnt lgkmcnt(6)
	v_mfma_f32_16x16x32_bf16 v[0:3], v[64:67], v[96:99], v[0:3]
	v_mfma_f32_16x16x32_bf16 v[32:35], v[68:71], v[96:99], v[32:35]
	ds_read_b128 v[124:127], v162 offset:30720
	s_waitcnt lgkmcnt(6)
	v_mfma_f32_16x16x32_bf16 v[4:7], v[64:67], v[100:103], v[4:7]
	v_mfma_f32_16x16x32_bf16 v[36:39], v[68:71], v[100:103], v[36:39]
	ds_read_b128 v[72:75], v151 offset:0
	ds_read_b128 v[76:79], v151 offset:2048
	ds_read_b128 v[80:83], v163 offset:16384
	s_waitcnt lgkmcnt(8)
	v_mfma_f32_16x16x32_bf16 v[8:11], v[64:67], v[104:107], v[8:11]
	v_mfma_f32_16x16x32_bf16 v[40:43], v[68:71], v[104:107], v[40:43]
	ds_read_b128 v[84:87], v163 offset:18432
	s_waitcnt lgkmcnt(8)
	v_mfma_f32_16x16x32_bf16 v[12:15], v[64:67], v[108:111], v[12:15]
	v_mfma_f32_16x16x32_bf16 v[44:47], v[68:71], v[108:111], v[44:47]
	ds_read_b128 v[88:91], v163 offset:20480
	s_waitcnt lgkmcnt(8)
	v_mfma_f32_16x16x32_bf16 v[16:19], v[64:67], v[112:115], v[16:19]
	v_mfma_f32_16x16x32_bf16 v[48:51], v[68:71], v[112:115], v[48:51]
	ds_read_b128 v[92:95], v163 offset:22528
	s_waitcnt lgkmcnt(8)
	v_mfma_f32_16x16x32_bf16 v[20:23], v[64:67], v[116:119], v[20:23]
	v_mfma_f32_16x16x32_bf16 v[52:55], v[68:71], v[116:119], v[52:55]
	ds_read_b128 v[96:99], v163 offset:24576
	s_waitcnt lgkmcnt(8)
	v_mfma_f32_16x16x32_bf16 v[24:27], v[64:67], v[120:123], v[24:27]
	v_mfma_f32_16x16x32_bf16 v[56:59], v[68:71], v[120:123], v[56:59]
	ds_read_b128 v[100:103], v163 offset:26624
	s_waitcnt lgkmcnt(8)
	v_mfma_f32_16x16x32_bf16 v[28:31], v[64:67], v[124:127], v[28:31]
	v_mfma_f32_16x16x32_bf16 v[60:63], v[68:71], v[124:127], v[60:63]
	ds_read_b128 v[104:107], v163 offset:28672
	s_waitcnt lgkmcnt(6)
	v_mfma_f32_16x16x32_bf16 v[0:3], v[72:75], v[80:83], v[0:3]
	v_mfma_f32_16x16x32_bf16 v[32:35], v[76:79], v[80:83], v[32:35]
	ds_read_b128 v[108:111], v163 offset:30720
	s_waitcnt vmcnt(0) lgkmcnt(0)
	s_barrier
	s_add_u32 m0, s38, 0
	s_nop 0
	global_load_lds_dwordx4 v164, s[98:99]
	s_waitcnt lgkmcnt(6)
	v_mfma_f32_16x16x32_bf16 v[4:7], v[72:75], v[84:87], v[4:7]
	v_mfma_f32_16x16x32_bf16 v[36:39], v[76:79], v[84:87], v[36:39]
	ds_read_b128 v[64:67], v150 offset:32768
	ds_read_b128 v[68:71], v150 offset:34816
	ds_read_b128 v[112:115], v162 offset:49152
	s_add_u32 m0, s38, 4096
	s_nop 0
	global_load_lds_dwordx4 v165, s[98:99]
	s_waitcnt lgkmcnt(8)
	v_mfma_f32_16x16x32_bf16 v[8:11], v[72:75], v[88:91], v[8:11]
	v_mfma_f32_16x16x32_bf16 v[40:43], v[76:79], v[88:91], v[40:43]
	ds_read_b128 v[116:119], v162 offset:51200
	s_add_u32 m0, s38, 8192
	s_nop 0
	global_load_lds_dwordx4 v166, s[98:99]
	s_waitcnt lgkmcnt(8)
	v_mfma_f32_16x16x32_bf16 v[12:15], v[72:75], v[92:95], v[12:15]
	v_mfma_f32_16x16x32_bf16 v[44:47], v[76:79], v[92:95], v[44:47]
	ds_read_b128 v[120:123], v162 offset:53248
	s_add_u32 m0, s38, 12288
	s_nop 0
	global_load_lds_dwordx4 v167, s[98:99]
	s_add_u32 s98, s98, 128
	s_addc_u32 s99, s99, 0
	s_waitcnt lgkmcnt(8)
	v_mfma_f32_16x16x32_bf16 v[16:19], v[72:75], v[96:99], v[16:19]
	v_mfma_f32_16x16x32_bf16 v[48:51], v[76:79], v[96:99], v[48:51]
	ds_read_b128 v[124:127], v162 offset:55296
	s_add_u32 m0, s38, 16384
	s_nop 0
	global_load_lds_dwordx4 v164, s[100:101]
	s_waitcnt lgkmcnt(8)
	v_mfma_f32_16x16x32_bf16 v[20:23], v[72:75], v[100:103], v[20:23]
	v_mfma_f32_16x16x32_bf16 v[52:55], v[76:79], v[100:103], v[52:55]
	ds_read_b128 v[80:83], v162 offset:57344
	s_add_u32 m0, s38, 20480
	s_nop 0
	global_load_lds_dwordx4 v165, s[100:101]
	s_waitcnt lgkmcnt(8)
	v_mfma_f32_16x16x32_bf16 v[24:27], v[72:75], v[104:107], v[24:27]
	v_mfma_f32_16x16x32_bf16 v[56:59], v[76:79], v[104:107], v[56:59]
	ds_read_b128 v[84:87], v162 offset:59392
	s_add_u32 m0, s38, 24576
	s_nop 0
	global_load_lds_dwordx4 v166, s[100:101]
	s_waitcnt lgkmcnt(8)
	v_mfma_f32_16x16x32_bf16 v[28:31], v[72:75], v[108:111], v[28:31]
	v_mfma_f32_16x16x32_bf16 v[60:63], v[76:79], v[108:111], v[60:63]
	ds_read_b128 v[88:91], v162 offset:61440
	s_add_u32 m0, s38, 28672
	s_nop 0
	global_load_lds_dwordx4 v167, s[100:101]
	s_add_u32 s100, s100, 128
	s_addc_u32 s101, s101, 0
	s_waitcnt lgkmcnt(6)
	v_mfma_f32_16x16x32_bf16 v[0:3], v[64:67], v[112:115], v[0:3]
	v_mfma_f32_16x16x32_bf16 v[32:35], v[68:71], v[112:115], v[32:35]
	ds_read_b128 v[92:95], v162 offset:63488
	s_waitcnt lgkmcnt(6)
	v_mfma_f32_16x16x32_bf16 v[4:7], v[64:67], v[116:119], v[4:7]
	v_mfma_f32_16x16x32_bf16 v[36:39], v[68:71], v[116:119], v[36:39]
	ds_read_b128 v[72:75], v151 offset:32768
	ds_read_b128 v[76:79], v151 offset:34816
	ds_read_b128 v[96:99], v163 offset:49152
	s_waitcnt lgkmcnt(8)
	v_mfma_f32_16x16x32_bf16 v[8:11], v[64:67], v[120:123], v[8:11]
	v_mfma_f32_16x16x32_bf16 v[40:43], v[68:71], v[120:123], v[40:43]
	ds_read_b128 v[100:103], v163 offset:51200
	s_waitcnt lgkmcnt(8)
	v_mfma_f32_16x16x32_bf16 v[12:15], v[64:67], v[124:127], v[12:15]
	v_mfma_f32_16x16x32_bf16 v[44:47], v[68:71], v[124:127], v[44:47]
	ds_read_b128 v[104:107], v163 offset:53248
	s_waitcnt lgkmcnt(8)
	v_mfma_f32_16x16x32_bf16 v[16:19], v[64:67], v[80:83], v[16:19]
	v_mfma_f32_16x16x32_bf16 v[48:51], v[68:71], v[80:83], v[48:51]
	ds_read_b128 v[108:111], v163 offset:55296
	s_waitcnt lgkmcnt(8)
	v_mfma_f32_16x16x32_bf16 v[20:23], v[64:67], v[84:87], v[20:23]
	v_mfma_f32_16x16x32_bf16 v[52:55], v[68:71], v[84:87], v[52:55]
	ds_read_b128 v[112:115], v163 offset:57344
	s_waitcnt lgkmcnt(8)
	v_mfma_f32_16x16x32_bf16 v[24:27], v[64:67], v[88:91], v[24:27]
	v_mfma_f32_16x16x32_bf16 v[56:59], v[68:71], v[88:91], v[56:59]
	ds_read_b128 v[116:119], v163 offset:59392
	s_waitcnt lgkmcnt(8)
	v_mfma_f32_16x16x32_bf16 v[28:31], v[64:67], v[92:95], v[28:31]
	v_mfma_f32_16x16x32_bf16 v[60:63], v[68:71], v[92:95], v[60:63]
	ds_read_b128 v[120:123], v163 offset:61440
	s_waitcnt lgkmcnt(6)
	v_mfma_f32_16x16x32_bf16 v[0:3], v[72:75], v[96:99], v[0:3]
	v_mfma_f32_16x16x32_bf16 v[32:35], v[76:79], v[96:99], v[32:35]
	ds_read_b128 v[124:127], v163 offset:63488
	s_waitcnt vmcnt(0) lgkmcnt(0)
	s_barrier
	s_add_u32 m0, s38, 32768
	s_nop 0
	global_load_lds_dwordx4 v164, s[98:99]
	s_waitcnt lgkmcnt(6)
	v_mfma_f32_16x16x32_bf16 v[4:7], v[72:75], v[100:103], v[4:7]
	v_mfma_f32_16x16x32_bf16 v[36:39], v[76:79], v[100:103], v[36:39]
	ds_read_b128 v[64:67], v150 offset:0
	ds_read_b128 v[68:71], v150 offset:2048
	ds_read_b128 v[80:83], v162 offset:16384
	s_add_u32 m0, s38, 36864
	s_nop 0
	global_load_lds_dwordx4 v165, s[98:99]
	s_waitcnt lgkmcnt(8)
	v_mfma_f32_16x16x32_bf16 v[8:11], v[72:75], v[104:107], v[8:11]
	v_mfma_f32_16x16x32_bf16 v[40:43], v[76:79], v[104:107], v[40:43]
	ds_read_b128 v[84:87], v162 offset:18432
	s_add_u32 m0, s38, 40960
	s_nop 0
	global_load_lds_dwordx4 v166, s[98:99]
	s_waitcnt lgkmcnt(8)
	v_mfma_f32_16x16x32_bf16 v[12:15], v[72:75], v[108:111], v[12:15]
	v_mfma_f32_16x16x32_bf16 v[44:47], v[76:79], v[108:111], v[44:47]
	ds_read_b128 v[88:91], v162 offset:20480
	s_add_u32 m0, s38, 45056
	s_nop 0
	global_load_lds_dwordx4 v167, s[98:99]
	s_add_u32 s98, s98, 128
	s_addc_u32 s99, s99, 0
	s_waitcnt lgkmcnt(8)
	v_mfma_f32_16x16x32_bf16 v[16:19], v[72:75], v[112:115], v[16:19]
	v_mfma_f32_16x16x32_bf16 v[48:51], v[76:79], v[112:115], v[48:51]
	ds_read_b128 v[92:95], v162 offset:22528
	s_add_u32 m0, s38, 49152
	s_nop 0
	global_load_lds_dwordx4 v164, s[100:101]
	s_waitcnt lgkmcnt(8)
	v_mfma_f32_16x16x32_bf16 v[20:23], v[72:75], v[116:119], v[20:23]
	v_mfma_f32_16x16x32_bf16 v[52:55], v[76:79], v[116:119], v[52:55]
	ds_read_b128 v[96:99], v162 offset:24576
	s_add_u32 m0, s38, 53248
	s_nop 0
	global_load_lds_dwordx4 v165, s[100:101]
	s_waitcnt lgkmcnt(8)
	v_mfma_f32_16x16x32_bf16 v[24:27], v[72:75], v[120:123], v[24:27]
	v_mfma_f32_16x16x32_bf16 v[56:59], v[76:79], v[120:123], v[56:59]
	ds_read_b128 v[100:103], v162 offset:26624
	s_add_u32 m0, s38, 57344
	s_nop 0
	global_load_lds_dwordx4 v166, s[100:101]
	s_waitcnt lgkmcnt(8)
	v_mfma_f32_16x16x32_bf16 v[28:31], v[72:75], v[124:127], v[28:31]
	v_mfma_f32_16x16x32_bf16 v[60:63], v[76:79], v[124:127], v[60:63]
	ds_read_b128 v[104:107], v162 offset:28672
	s_add_u32 m0, s38, 61440
	s_nop 0
	global_load_lds_dwordx4 v167, s[100:101]
	s_add_u32 s100, s100, 128
	s_addc_u32 s101, s101, 0
	s_waitcnt lgkmcnt(6)
	v_mfma_f32_16x16x32_bf16 v[0:3], v[64:67], v[80:83], v[0:3]
	v_mfma_f32_16x16x32_bf16 v[32:35], v[68:71], v[80:83], v[32:35]
	ds_read_b128 v[108:111], v162 offset:30720
	s_waitcnt lgkmcnt(6)
	v_mfma_f32_16x16x32_bf16 v[4:7], v[64:67], v[84:87], v[4:7]
	v_mfma_f32_16x16x32_bf16 v[36:39], v[68:71], v[84:87], v[36:39]
	ds_read_b128 v[72:75], v151 offset:0
	ds_read_b128 v[76:79], v151 offset:2048
	ds_read_b128 v[112:115], v163 offset:16384
	s_waitcnt lgkmcnt(8)
	v_mfma_f32_16x16x32_bf16 v[8:11], v[64:67], v[88:91], v[8:11]
	v_mfma_f32_16x16x32_bf16 v[40:43], v[68:71], v[88:91], v[40:43]
	ds_read_b128 v[116:119], v163 offset:18432
	s_waitcnt lgkmcnt(8)
	v_mfma_f32_16x16x32_bf16 v[12:15], v[64:67], v[92:95], v[12:15]
	v_mfma_f32_16x16x32_bf16 v[44:47], v[68:71], v[92:95], v[44:47]
	ds_read_b128 v[120:123], v163 offset:20480
	s_waitcnt lgkmcnt(8)
	v_mfma_f32_16x16x32_bf16 v[16:19], v[64:67], v[96:99], v[16:19]
	v_mfma_f32_16x16x32_bf16 v[48:51], v[68:71], v[96:99], v[48:51]
	ds_read_b128 v[124:127], v163 offset:22528
	s_waitcnt lgkmcnt(8)
	v_mfma_f32_16x16x32_bf16 v[20:23], v[64:67], v[100:103], v[20:23]
	v_mfma_f32_16x16x32_bf16 v[52:55], v[68:71], v[100:103], v[52:55]
	ds_read_b128 v[80:83], v163 offset:24576
	s_waitcnt lgkmcnt(8)
	v_mfma_f32_16x16x32_bf16 v[24:27], v[64:67], v[104:107], v[24:27]
	v_mfma_f32_16x16x32_bf16 v[56:59], v[68:71], v[104:107], v[56:59]
	ds_read_b128 v[84:87], v163 offset:26624
	s_waitcnt lgkmcnt(8)
	v_mfma_f32_16x16x32_bf16 v[28:31], v[64:67], v[108:111], v[28:31]
	v_mfma_f32_16x16x32_bf16 v[60:63], v[68:71], v[108:111], v[60:63]
	ds_read_b128 v[88:91], v163 offset:28672
	s_waitcnt lgkmcnt(6)
	v_mfma_f32_16x16x32_bf16 v[0:3], v[72:75], v[112:115], v[0:3]
	v_mfma_f32_16x16x32_bf16 v[32:35], v[76:79], v[112:115], v[32:35]
	ds_read_b128 v[92:95], v163 offset:30720
	s_waitcnt vmcnt(0) lgkmcnt(0)
	s_barrier
	s_waitcnt lgkmcnt(6)
	v_mfma_f32_16x16x32_bf16 v[4:7], v[72:75], v[116:119], v[4:7]
	v_mfma_f32_16x16x32_bf16 v[36:39], v[76:79], v[116:119], v[36:39]
	ds_read_b128 v[64:67], v150 offset:32768
	ds_read_b128 v[68:71], v150 offset:34816
	ds_read_b128 v[96:99], v162 offset:49152
	s_waitcnt lgkmcnt(8)
	v_mfma_f32_16x16x32_bf16 v[8:11], v[72:75], v[120:123], v[8:11]
	v_mfma_f32_16x16x32_bf16 v[40:43], v[76:79], v[120:123], v[40:43]
	ds_read_b128 v[100:103], v162 offset:51200
	s_waitcnt lgkmcnt(8)
	v_mfma_f32_16x16x32_bf16 v[12:15], v[72:75], v[124:127], v[12:15]
	v_mfma_f32_16x16x32_bf16 v[44:47], v[76:79], v[124:127], v[44:47]
	ds_read_b128 v[104:107], v162 offset:53248
	s_waitcnt lgkmcnt(8)
	v_mfma_f32_16x16x32_bf16 v[16:19], v[72:75], v[80:83], v[16:19]
	v_mfma_f32_16x16x32_bf16 v[48:51], v[76:79], v[80:83], v[48:51]
	ds_read_b128 v[108:111], v162 offset:55296
	s_waitcnt lgkmcnt(8)
	v_mfma_f32_16x16x32_bf16 v[20:23], v[72:75], v[84:87], v[20:23]
	v_mfma_f32_16x16x32_bf16 v[52:55], v[76:79], v[84:87], v[52:55]
	ds_read_b128 v[112:115], v162 offset:57344
	s_waitcnt lgkmcnt(8)
	v_mfma_f32_16x16x32_bf16 v[24:27], v[72:75], v[88:91], v[24:27]
	v_mfma_f32_16x16x32_bf16 v[56:59], v[76:79], v[88:91], v[56:59]
	ds_read_b128 v[116:119], v162 offset:59392
	s_waitcnt lgkmcnt(8)
	v_mfma_f32_16x16x32_bf16 v[28:31], v[72:75], v[92:95], v[28:31]
	v_mfma_f32_16x16x32_bf16 v[60:63], v[76:79], v[92:95], v[60:63]
	ds_read_b128 v[120:123], v162 offset:61440
	s_waitcnt lgkmcnt(6)
	v_mfma_f32_16x16x32_bf16 v[0:3], v[64:67], v[96:99], v[0:3]
	v_mfma_f32_16x16x32_bf16 v[32:35], v[68:71], v[96:99], v[32:35]
	ds_read_b128 v[124:127], v162 offset:63488
	s_waitcnt lgkmcnt(6)
	v_mfma_f32_16x16x32_bf16 v[4:7], v[64:67], v[100:103], v[4:7]
	v_mfma_f32_16x16x32_bf16 v[36:39], v[68:71], v[100:103], v[36:39]
	ds_read_b128 v[72:75], v151 offset:32768
	ds_read_b128 v[76:79], v151 offset:34816
	ds_read_b128 v[80:83], v163 offset:49152
	s_waitcnt lgkmcnt(8)
	v_mfma_f32_16x16x32_bf16 v[8:11], v[64:67], v[104:107], v[8:11]
	v_mfma_f32_16x16x32_bf16 v[40:43], v[68:71], v[104:107], v[40:43]
	ds_read_b128 v[84:87], v163 offset:51200
	s_waitcnt lgkmcnt(8)
	v_mfma_f32_16x16x32_bf16 v[12:15], v[64:67], v[108:111], v[12:15]
	v_mfma_f32_16x16x32_bf16 v[44:47], v[68:71], v[108:111], v[44:47]
	ds_read_b128 v[88:91], v163 offset:53248
	s_waitcnt lgkmcnt(8)
	v_mfma_f32_16x16x32_bf16 v[16:19], v[64:67], v[112:115], v[16:19]
	v_mfma_f32_16x16x32_bf16 v[48:51], v[68:71], v[112:115], v[48:51]
	ds_read_b128 v[92:95], v163 offset:55296
	s_waitcnt lgkmcnt(8)
	v_mfma_f32_16x16x32_bf16 v[20:23], v[64:67], v[116:119], v[20:23]
	v_mfma_f32_16x16x32_bf16 v[52:55], v[68:71], v[116:119], v[52:55]
	ds_read_b128 v[96:99], v163 offset:57344
	s_waitcnt lgkmcnt(8)
	v_mfma_f32_16x16x32_bf16 v[24:27], v[64:67], v[120:123], v[24:27]
	v_mfma_f32_16x16x32_bf16 v[56:59], v[68:71], v[120:123], v[56:59]
	ds_read_b128 v[100:103], v163 offset:59392
	s_waitcnt lgkmcnt(8)
	v_mfma_f32_16x16x32_bf16 v[28:31], v[64:67], v[124:127], v[28:31]
	v_mfma_f32_16x16x32_bf16 v[60:63], v[68:71], v[124:127], v[60:63]
	ds_read_b128 v[104:107], v163 offset:61440
	s_waitcnt lgkmcnt(6)
	v_mfma_f32_16x16x32_bf16 v[0:3], v[72:75], v[80:83], v[0:3]
	v_mfma_f32_16x16x32_bf16 v[32:35], v[76:79], v[80:83], v[32:35]
	ds_read_b128 v[108:111], v163 offset:63488
	s_waitcnt lgkmcnt(6)
	v_mfma_f32_16x16x32_bf16 v[4:7], v[72:75], v[84:87], v[4:7]
	v_mfma_f32_16x16x32_bf16 v[36:39], v[76:79], v[84:87], v[36:39]
	s_waitcnt lgkmcnt(5)
	v_mfma_f32_16x16x32_bf16 v[8:11], v[72:75], v[88:91], v[8:11]
	v_mfma_f32_16x16x32_bf16 v[40:43], v[76:79], v[88:91], v[40:43]
	s_waitcnt lgkmcnt(4)
	v_mfma_f32_16x16x32_bf16 v[12:15], v[72:75], v[92:95], v[12:15]
	v_mfma_f32_16x16x32_bf16 v[44:47], v[76:79], v[92:95], v[44:47]
	s_waitcnt lgkmcnt(3)
	v_mfma_f32_16x16x32_bf16 v[16:19], v[72:75], v[96:99], v[16:19]
	v_mfma_f32_16x16x32_bf16 v[48:51], v[76:79], v[96:99], v[48:51]
	s_waitcnt lgkmcnt(2)
	v_mfma_f32_16x16x32_bf16 v[20:23], v[72:75], v[100:103], v[20:23]
	v_mfma_f32_16x16x32_bf16 v[52:55], v[76:79], v[100:103], v[52:55]
	s_waitcnt lgkmcnt(1)
	v_mfma_f32_16x16x32_bf16 v[24:27], v[72:75], v[104:107], v[24:27]
	v_mfma_f32_16x16x32_bf16 v[56:59], v[76:79], v[104:107], v[56:59]
	s_waitcnt lgkmcnt(0)
	v_mfma_f32_16x16x32_bf16 v[28:31], v[72:75], v[108:111], v[28:31]
	v_mfma_f32_16x16x32_bf16 v[60:63], v[76:79], v[108:111], v[60:63]
	global_load_dwordx4 v[64:67], v168, s[14:15] nt
	global_load_dwordx4 v[68:71], v168, s[14:15] offset:16 nt
	s_add_u32 s14, s14, 0x4000
	s_addc_u32 s15, s15, 0
	global_load_dwordx4 v[72:75], v168, s[14:15] nt
	global_load_dwordx4 v[76:79], v168, s[14:15] offset:16 nt
	s_add_u32 s14, s14, 0x4000
	s_addc_u32 s15, s15, 0
	global_load_dwordx4 v[80:83], v168, s[14:15] nt
	global_load_dwordx4 v[84:87], v168, s[14:15] offset:16 nt
	s_add_u32 s14, s14, 0x4000
	s_addc_u32 s15, s15, 0
	global_load_dwordx4 v[88:91], v168, s[14:15] nt
	global_load_dwordx4 v[92:95], v168, s[14:15] offset:16 nt
	s_add_u32 s14, s14, 0x4000
	s_addc_u32 s15, s15, 0
	s_nop 7
	s_waitcnt lgkmcnt(0)
	s_barrier
	ds_write_b32 v169, v0 offset:0
	ds_write_b32 v169, v1 offset:512
	ds_write_b32 v169, v2 offset:1024
	ds_write_b32 v169, v3 offset:1536
	ds_write_b32 v169, v4 offset:64
	ds_write_b32 v169, v5 offset:576
	ds_write_b32 v169, v6 offset:1088
	ds_write_b32 v169, v7 offset:1600
	ds_write_b32 v169, v8 offset:128
	ds_write_b32 v169, v9 offset:640
	ds_write_b32 v169, v10 offset:1152
	ds_write_b32 v169, v11 offset:1664
	ds_write_b32 v169, v12 offset:192
	ds_write_b32 v169, v13 offset:704
	ds_write_b32 v169, v14 offset:1216
	ds_write_b32 v169, v15 offset:1728
	ds_write_b32 v169, v16 offset:256
	ds_write_b32 v169, v17 offset:768
	ds_write_b32 v169, v18 offset:1280
	ds_write_b32 v169, v19 offset:1792
	ds_write_b32 v169, v20 offset:320
	ds_write_b32 v169, v21 offset:832
	ds_write_b32 v169, v22 offset:1344
	ds_write_b32 v169, v23 offset:1856
	ds_write_b32 v170, v24 offset:0
	ds_write_b32 v170, v25 offset:512
	ds_write_b32 v170, v26 offset:1024
	ds_write_b32 v170, v27 offset:1536
	ds_write_b32 v171, v28 offset:0
	ds_write_b32 v171, v29 offset:512
	ds_write_b32 v171, v30 offset:1024
	ds_write_b32 v171, v31 offset:1536
	s_waitcnt lgkmcnt(0)
	ds_read_b128 v[0:3], v220
	ds_read_b128 v[4:7], v220 offset:16
	ds_read_b128 v[8:11], v222
	ds_read_b128 v[12:15], v222 offset:16
	ds_read_b128 v[16:19], v224
	ds_read_b128 v[20:23], v224 offset:16
	ds_read_b128 v[24:27], v226
	ds_read_b128 v[28:31], v226 offset:16
	s_waitcnt lgkmcnt(6)
	v_pk_fma_f32 v[0:1], v[142:143], v[0:1], v[172:173]
	v_pk_fma_f32 v[2:3], v[144:145], v[2:3], v[174:175]
	v_pk_fma_f32 v[4:5], v[146:147], v[4:5], v[176:177]
	v_pk_fma_f32 v[6:7], v[160:161], v[6:7], v[178:179]
	global_store_dwordx4 v168, v[0:3], s[18:19]
	global_store_dwordx4 v168, v[4:7], s[18:19] offset:16
	s_add_u32 s18, s18, 0x4000
	s_addc_u32 s19, s19, 0
	s_waitcnt lgkmcnt(4)
	v_pk_fma_f32 v[8:9], v[142:143], v[8:9], v[180:181]
	v_pk_fma_f32 v[10:11], v[144:145], v[10:11], v[182:183]
	v_pk_fma_f32 v[12:13], v[146:147], v[12:13], v[184:185]
	v_pk_fma_f32 v[14:15], v[160:161], v[14:15], v[186:187]
	global_store_dwordx4 v168, v[8:11], s[18:19]
	global_store_dwordx4 v168, v[12:15], s[18:19] offset:16
	s_add_u32 s18, s18, 0x4000
	s_addc_u32 s19, s19, 0
	s_waitcnt lgkmcnt(2)
	v_pk_fma_f32 v[16:17], v[142:143], v[16:17], v[188:189]
	v_pk_fma_f32 v[18:19], v[144:145], v[18:19], v[190:191]
	v_pk_fma_f32 v[20:21], v[146:147], v[20:21], v[192:193]
	v_pk_fma_f32 v[22:23], v[160:161], v[22:23], v[194:195]
	global_store_dwordx4 v168, v[16:19], s[18:19]
	global_store_dwordx4 v168, v[20:23], s[18:19] offset:16
	s_add_u32 s18, s18, 0x4000
	s_addc_u32 s19, s19, 0
	s_waitcnt lgkmcnt(0)
	v_pk_fma_f32 v[24:25], v[142:143], v[24:25], v[196:197]
	v_pk_fma_f32 v[26:27], v[144:145], v[26:27], v[198:199]
	v_pk_fma_f32 v[28:29], v[146:147], v[28:29], v[200:201]
	v_pk_fma_f32 v[30:31], v[160:161], v[30:31], v[202:203]
	global_store_dwordx4 v168, v[24:27], s[18:19]
	global_store_dwordx4 v168, v[28:31], s[18:19] offset:16
	s_add_u32 s18, s18, 0x4000
	s_addc_u32 s19, s19, 0
	ds_write_b32 v169, v32 offset:0
	ds_write_b32 v169, v33 offset:512
	ds_write_b32 v169, v34 offset:1024
	ds_write_b32 v169, v35 offset:1536
	ds_write_b32 v169, v36 offset:64
	ds_write_b32 v169, v37 offset:576
	ds_write_b32 v169, v38 offset:1088
	ds_write_b32 v169, v39 offset:1600
	ds_write_b32 v169, v40 offset:128
	ds_write_b32 v169, v41 offset:640
	ds_write_b32 v169, v42 offset:1152
	ds_write_b32 v169, v43 offset:1664
	ds_write_b32 v169, v44 offset:192
	ds_write_b32 v169, v45 offset:704
	ds_write_b32 v169, v46 offset:1216
	ds_write_b32 v169, v47 offset:1728
	ds_write_b32 v169, v48 offset:256
	ds_write_b32 v169, v49 offset:768
	ds_write_b32 v169, v50 offset:1280
	ds_write_b32 v169, v51 offset:1792
	ds_write_b32 v169, v52 offset:320
	ds_write_b32 v169, v53 offset:832
	ds_write_b32 v169, v54 offset:1344
	ds_write_b32 v169, v55 offset:1856
	ds_write_b32 v170, v56 offset:0
	ds_write_b32 v170, v57 offset:512
	ds_write_b32 v170, v58 offset:1024
	ds_write_b32 v170, v59 offset:1536
	ds_write_b32 v171, v60 offset:0
	ds_write_b32 v171, v61 offset:512
	ds_write_b32 v171, v62 offset:1024
	ds_write_b32 v171, v63 offset:1536
	s_waitcnt lgkmcnt(0)
	ds_read_b128 v[32:35], v220
	ds_read_b128 v[36:39], v220 offset:16
	ds_read_b128 v[40:43], v222
	ds_read_b128 v[44:47], v222 offset:16
	ds_read_b128 v[48:51], v224
	ds_read_b128 v[52:55], v224 offset:16
	ds_read_b128 v[56:59], v226
	ds_read_b128 v[60:63], v226 offset:16
	s_waitcnt vmcnt(14) lgkmcnt(6)
	v_pk_fma_f32 v[32:33], v[142:143], v[32:33], v[64:65]
	v_pk_fma_f32 v[34:35], v[144:145], v[34:35], v[66:67]
	v_pk_fma_f32 v[36:37], v[146:147], v[36:37], v[68:69]
	v_pk_fma_f32 v[38:39], v[160:161], v[38:39], v[70:71]
	global_store_dwordx4 v168, v[32:35], s[18:19]
	global_store_dwordx4 v168, v[36:39], s[18:19] offset:16
	s_add_u32 s18, s18, 0x4000
	s_addc_u32 s19, s19, 0
	s_waitcnt vmcnt(14) lgkmcnt(4)
	v_pk_fma_f32 v[40:41], v[142:143], v[40:41], v[72:73]
	v_pk_fma_f32 v[42:43], v[144:145], v[42:43], v[74:75]
	v_pk_fma_f32 v[44:45], v[146:147], v[44:45], v[76:77]
	v_pk_fma_f32 v[46:47], v[160:161], v[46:47], v[78:79]
	global_store_dwordx4 v168, v[40:43], s[18:19]
	global_store_dwordx4 v168, v[44:47], s[18:19] offset:16
	s_add_u32 s18, s18, 0x4000
	s_addc_u32 s19, s19, 0
	s_waitcnt vmcnt(14) lgkmcnt(2)
	v_pk_fma_f32 v[48:49], v[142:143], v[48:49], v[80:81]
	v_pk_fma_f32 v[50:51], v[144:145], v[50:51], v[82:83]
	v_pk_fma_f32 v[52:53], v[146:147], v[52:53], v[84:85]
	v_pk_fma_f32 v[54:55], v[160:161], v[54:55], v[86:87]
	global_store_dwordx4 v168, v[48:51], s[18:19]
	global_store_dwordx4 v168, v[52:55], s[18:19] offset:16
	s_add_u32 s18, s18, 0x4000
	s_addc_u32 s19, s19, 0
	s_waitcnt vmcnt(14) lgkmcnt(0)
	v_pk_fma_f32 v[56:57], v[142:143], v[56:57], v[88:89]
	v_pk_fma_f32 v[58:59], v[144:145], v[58:59], v[90:91]
	v_pk_fma_f32 v[60:61], v[146:147], v[60:61], v[92:93]
	v_pk_fma_f32 v[62:63], v[160:161], v[62:63], v[94:95]
	global_store_dwordx4 v168, v[56:59], s[18:19]
	global_store_dwordx4 v168, v[60:63], s[18:19] offset:16
	s_add_u32 s18, s18, 0x4000
	s_addc_u32 s19, s19, 0
	s_add_i32 s52, s52, s3
	s_cmpk_lt_i32 s52, 0x400
	s_cbranch_scc1 .Lmy_op1_tile
